# v20 + reversed K-loop priority: the half in its load segment runs at priority 1, the half issuing its MFMA block at 0
# baseline (speedup 1.0000x reference)
; #define PG8_STAGE(bufoff, gbase, voff) do { _Pragma("unroll") for (int _i = 0; _i < 2; ++_i) \
;         __builtin_amdgcn_global_load_lds((const unsigned*)((const char*)(gbase) + (voff)[_i]), (PG8_LAS unsigned*)(lds + (bufoff) + ldsw + _i * 8192), 16, 0, 0); } while (0)
; #define PG8_LDA(dst, b, h) do { _Pragma("unroll") for (int m = 0; m < 4; ++m) _Pragma("unroll") for (int k = 0; k < 2; ++k) dst[m][k] = *(const PG8_LAS bf16x8*)(lds + PG8_SA(b, h) + aoff + m * 2048 + k * 1024); } while (0)
; #define PG8_LDB(dst, b, h) do { _Pragma("unroll") for (int n = 0; n < 2; ++n) _Pragma("unroll") for (int k = 0; k < 2; ++k) dst[n][k] = *(const PG8_LAS bf16x8*)(lds + PG8_SB(b, h) + boff + n * 2048 + k * 1024); } while (0)
; #define PG8_MMA(ai, bj, At, Bt) do { __builtin_amdgcn_s_setprio(1); _Pragma("unroll") for (int m = 0; m < 4; ++m) _Pragma("unroll") for (int n = 0; n < 2; ++n) _Pragma("unroll") for (int k = 0; k < 2; ++k) \
;         acc[ai][bj][m][n] = __builtin_amdgcn_mfma_f32_16x16x32_bf16(Bt[n][k], At[m][k], acc[ai][bj][m][n], 0, 0, 0); __builtin_amdgcn_s_setprio(0); } while (0)
; #define PG8_WAIT_V(n) asm volatile("s_waitcnt vmcnt(" #n ")" ::: "memory")
; #define PG8_WAIT_L(n) asm volatile("s_waitcnt lgkmcnt(" #n ")" ::: "memory")
; #define PG8_BAR __builtin_amdgcn_s_barrier()
; #define PG8_SCHED __builtin_amdgcn_sched_barrier(0)
; template <class Epi, class Sched, bool ALIGN_EPI = false, bool SP2 = false>
; __device__ __forceinline__ void gemm_phase(PG8_LAS unsigned char* lds, const Gemm g, const Sched& S, const Epi& E) {
;     ...
;             PG8_LDB(B0, 0, 0); PG8_LDB(B1, 0, 1); PG8_SCHED; PG8_LDA(At, 0, 0); PG8_STAGE(PG8_SA(1, 1), a1 + hstep, voffA);
;             PG8_WAIT_V(8); PG8_WAIT_L(0); PG8_BAR; PG8_MMA(0, 0, At, B0); PG8_MMA(0, 1, At, B1); PG8_BAR; PG8_SCHED;
;             PG8_LDA(At, 0, 1); PG8_STAGE(PG8_SB(0, 0), b2, voffB); PG8_STAGE(PG8_SB(0, 1), b2 + hstepB, voffB); PG8_STAGE(PG8_SA(0, 0), a2, voffA);
;             PG8_WAIT_V(8); PG8_WAIT_L(0); PG8_BAR; PG8_MMA(1, 0, At, B0); PG8_MMA(1, 1, At, B1); PG8_BAR; PG8_SCHED;
.LBB0_192:
	ds_read_b128 v[146:149], v152
	ds_read_b128 v[156:159], v152 offset:1024
	ds_read_b128 v[160:163], v152 offset:2048
	ds_read_b128 v[164:167], v152 offset:3072
	ds_read_b128 v[168:171], v153
	ds_read_b128 v[172:175], v153 offset:1024
	ds_read_b128 v[176:179], v153 offset:2048
	ds_read_b128 v[180:183], v153 offset:3072
	s_add_u32 s22, s20, 0xfffc0080
	s_addc_u32 s23, s21, -1
	s_cmp_eq_u32 s75, 12
	s_cselect_b32 s25, s5, s23
	s_cselect_b32 s24, s13, s22
	s_cselect_b32 s23, s11, s74
	s_cselect_b32 s22, s19, s73
	v_lshl_add_u64 v[216:217], s[20:21], 0, v[138:139]
	s_add_i32 m0, s27, 0xc000
	ds_read_b128 v[184:187], v154
	ds_read_b128 v[188:191], v154 offset:1024
	ds_read_b128 v[192:195], v154 offset:2048
	ds_read_b128 v[196:199], v154 offset:3072
	ds_read_b128 v[200:203], v154 offset:4096
	ds_read_b128 v[204:207], v154 offset:5120
	ds_read_b128 v[208:211], v154 offset:6144
	ds_read_b128 v[212:215], v154 offset:7168
	global_load_lds_dwordx4 v[216:217], off
	v_lshl_add_u64 v[216:217], s[20:21], 0, v[140:141]
	s_add_i32 m0, s27, 0xe000
	s_nop 0
	global_load_lds_dwordx4 v[216:217], off
	s_waitcnt vmcnt(8)
	s_waitcnt lgkmcnt(0)
	s_barrier
	s_setprio 0
	v_mfma_f32_16x16x32_bf16 v[126:129], v[146:149], v[184:187], v[126:129]
	v_mfma_f32_16x16x32_bf16 v[122:125], v[160:163], v[184:187], v[122:125]
	v_mfma_f32_16x16x32_bf16 v[114:117], v[146:149], v[192:195], v[114:117]
	v_mfma_f32_16x16x32_bf16 v[106:109], v[160:163], v[192:195], v[106:109]
	v_mfma_f32_16x16x32_bf16 v[98:101], v[146:149], v[200:203], v[98:101]
	v_mfma_f32_16x16x32_bf16 v[90:93], v[160:163], v[200:203], v[90:93]
	v_mfma_f32_16x16x32_bf16 v[82:85], v[146:149], v[208:211], v[82:85]
	v_mfma_f32_16x16x32_bf16 v[74:77], v[160:163], v[208:211], v[74:77]
	v_mfma_f32_16x16x32_bf16 v[126:129], v[156:159], v[188:191], v[126:129]
	v_mfma_f32_16x16x32_bf16 v[122:125], v[164:167], v[188:191], v[122:125]
	v_mfma_f32_16x16x32_bf16 v[114:117], v[156:159], v[196:199], v[114:117]
	v_mfma_f32_16x16x32_bf16 v[106:109], v[164:167], v[196:199], v[106:109]
	v_mfma_f32_16x16x32_bf16 v[98:101], v[156:159], v[204:207], v[98:101]
	v_mfma_f32_16x16x32_bf16 v[90:93], v[164:167], v[204:207], v[90:93]
	v_mfma_f32_16x16x32_bf16 v[82:85], v[156:159], v[212:215], v[82:85]
	v_mfma_f32_16x16x32_bf16 v[74:77], v[164:167], v[212:215], v[74:77]
	v_mfma_f32_16x16x32_bf16 v[118:121], v[168:171], v[184:187], v[118:121]
	v_mfma_f32_16x16x32_bf16 v[110:113], v[176:179], v[184:187], v[110:113]
	v_mfma_f32_16x16x32_bf16 v[102:105], v[168:171], v[192:195], v[102:105]
	v_mfma_f32_16x16x32_bf16 v[94:97], v[176:179], v[192:195], v[94:97]
	v_mfma_f32_16x16x32_bf16 v[86:89], v[168:171], v[200:203], v[86:89]
	v_mfma_f32_16x16x32_bf16 v[78:81], v[176:179], v[200:203], v[78:81]
	v_mfma_f32_16x16x32_bf16 v[70:73], v[168:171], v[208:211], v[70:73]
	v_mfma_f32_16x16x32_bf16 v[66:69], v[176:179], v[208:211], v[66:69]
	v_mfma_f32_16x16x32_bf16 v[118:121], v[172:175], v[188:191], v[118:121]
	v_mfma_f32_16x16x32_bf16 v[110:113], v[180:183], v[188:191], v[110:113]
	v_mfma_f32_16x16x32_bf16 v[102:105], v[172:175], v[196:199], v[102:105]
	v_mfma_f32_16x16x32_bf16 v[94:97], v[180:183], v[196:199], v[94:97]
	v_mfma_f32_16x16x32_bf16 v[86:89], v[172:175], v[204:207], v[86:89]
	v_mfma_f32_16x16x32_bf16 v[78:81], v[180:183], v[204:207], v[78:81]
	v_mfma_f32_16x16x32_bf16 v[70:73], v[172:175], v[212:215], v[70:73]
	v_mfma_f32_16x16x32_bf16 v[66:69], v[180:183], v[212:215], v[66:69]
	s_barrier
	s_setprio 1
	s_add_i32 s76, s69, s26
	v_lshl_add_u64 v[216:217], s[22:23], 0, v[132:133]
	s_mov_b32 m0, s76
	ds_read_b128 v[184:187], v154 offset:16384
	ds_read_b128 v[188:191], v154 offset:17408
	ds_read_b128 v[192:195], v154 offset:18432
	ds_read_b128 v[196:199], v154 offset:19456
	ds_read_b128 v[200:203], v154 offset:20480
	ds_read_b128 v[204:207], v154 offset:21504
	ds_read_b128 v[208:211], v154 offset:22528
	ds_read_b128 v[212:215], v154 offset:23552
	global_load_lds_dwordx4 v[216:217], off
	s_add_i32 m0, s76, 0x2000
	s_add_u32 s76, s22, 0x10000
	v_lshl_add_u64 v[218:219], s[22:23], 0, v[136:137]
	s_addc_u32 s77, s23, 0
	s_add_i32 s78, s70, s26
	global_load_lds_dwordx4 v[218:219], off
	v_lshl_add_u64 v[220:221], s[76:77], 0, v[132:133]
	s_mov_b32 m0, s78
	v_lshl_add_u64 v[222:223], s[24:25], 0, v[134:135]
	global_load_lds_dwordx4 v[220:221], off
	v_lshl_add_u64 v[220:221], s[76:77], 0, v[136:137]
	s_add_i32 m0, s78, 0x2000
	s_nop 0
	global_load_lds_dwordx4 v[220:221], off
	v_lshl_add_u64 v[220:221], s[24:25], 0, v[130:131]
	s_mov_b32 m0, s27
	s_nop 0
	global_load_lds_dwordx4 v[220:221], off
	s_mov_b32 m0, s28
	s_nop 0
	global_load_lds_dwordx4 v[222:223], off
	s_waitcnt vmcnt(8)
	s_waitcnt lgkmcnt(0)
	s_barrier
; #define PG8_STAGE(bufoff, gbase, voff) do { _Pragma("unroll") for (int _i = 0; _i < 2; ++_i) \
;         __builtin_amdgcn_global_load_lds((const unsigned*)((const char*)(gbase) + (voff)[_i]), (PG8_LAS unsigned*)(lds + (bufoff) + ldsw + _i * 8192), 16, 0, 0); } while (0)
; #define PG8_LDA(dst, b, h) do { _Pragma("unroll") for (int m = 0; m < 4; ++m) _Pragma("unroll") for (int k = 0; k < 2; ++k) dst[m][k] = *(const PG8_LAS bf16x8*)(lds + PG8_SA(b, h) + aoff + m * 2048 + k * 1024); } while (0)
; #define PG8_LDB(dst, b, h) do { _Pragma("unroll") for (int n = 0; n < 2; ++n) _Pragma("unroll") for (int k = 0; k < 2; ++k) dst[n][k] = *(const PG8_LAS bf16x8*)(lds + PG8_SB(b, h) + boff + n * 2048 + k * 1024); } while (0)
; #define PG8_MMA(ai, bj, At, Bt) do { __builtin_amdgcn_s_setprio(1); _Pragma("unroll") for (int m = 0; m < 4; ++m) _Pragma("unroll") for (int n = 0; n < 2; ++n) _Pragma("unroll") for (int k = 0; k < 2; ++k) \
;         acc[ai][bj][m][n] = __builtin_amdgcn_mfma_f32_16x16x32_bf16(Bt[n][k], At[m][k], acc[ai][bj][m][n], 0, 0, 0); __builtin_amdgcn_s_setprio(0); } while (0)
; #define PG8_WAIT_V(n) asm volatile("s_waitcnt vmcnt(" #n ")" ::: "memory")
; #define PG8_WAIT_L(n) asm volatile("s_waitcnt lgkmcnt(" #n ")" ::: "memory")
; #define PG8_BAR __builtin_amdgcn_s_barrier()
; #define PG8_SCHED __builtin_amdgcn_sched_barrier(0)
; template <class Epi, class Sched, bool ALIGN_EPI = false, bool SP2 = false>
; __device__ __forceinline__ void gemm_phase(PG8_LAS unsigned char* lds, const Gemm g, const Sched& S, const Epi& E) {
;     ...
;             PG8_WAIT_V(8); PG8_WAIT_L(0); PG8_BAR; PG8_MMA(1, 0, At, B0); PG8_MMA(1, 1, At, B1); PG8_BAR; PG8_SCHED;
;             PG8_LDB(B0, 1, 0); PG8_LDB(B1, 1, 1); PG8_SCHED; PG8_LDA(At, 1, 0); PG8_STAGE(PG8_SA(0, 1), a2 + hstep, voffA);
;             PG8_WAIT_V(8); PG8_WAIT_L(0); PG8_BAR; PG8_MMA(0, 0, At, B0); PG8_MMA(0, 1, At, B1); PG8_BAR; PG8_SCHED;
	s_setprio 0
	v_mfma_f32_16x16x32_bf16 v[62:65], v[146:149], v[184:187], v[62:65]
	v_mfma_f32_16x16x32_bf16 v[58:61], v[160:163], v[184:187], v[58:61]
	v_mfma_f32_16x16x32_bf16 v[50:53], v[146:149], v[192:195], v[50:53]
	v_mfma_f32_16x16x32_bf16 v[42:45], v[160:163], v[192:195], v[42:45]
	v_mfma_f32_16x16x32_bf16 v[34:37], v[146:149], v[200:203], v[34:37]
	v_mfma_f32_16x16x32_bf16 v[26:29], v[160:163], v[200:203], v[26:29]
	v_mfma_f32_16x16x32_bf16 v[18:21], v[146:149], v[208:211], v[18:21]
	v_mfma_f32_16x16x32_bf16 v[10:13], v[160:163], v[208:211], v[10:13]
	v_mfma_f32_16x16x32_bf16 v[62:65], v[156:159], v[188:191], v[62:65]
	v_mfma_f32_16x16x32_bf16 v[58:61], v[164:167], v[188:191], v[58:61]
	v_mfma_f32_16x16x32_bf16 v[50:53], v[156:159], v[196:199], v[50:53]
	v_mfma_f32_16x16x32_bf16 v[42:45], v[164:167], v[196:199], v[42:45]
	v_mfma_f32_16x16x32_bf16 v[34:37], v[156:159], v[204:207], v[34:37]
	v_mfma_f32_16x16x32_bf16 v[26:29], v[164:167], v[204:207], v[26:29]
	v_mfma_f32_16x16x32_bf16 v[18:21], v[156:159], v[212:215], v[18:21]
	v_mfma_f32_16x16x32_bf16 v[10:13], v[164:167], v[212:215], v[10:13]
	v_mfma_f32_16x16x32_bf16 v[54:57], v[168:171], v[184:187], v[54:57]
	v_mfma_f32_16x16x32_bf16 v[46:49], v[176:179], v[184:187], v[46:49]
	v_mfma_f32_16x16x32_bf16 v[38:41], v[168:171], v[192:195], v[38:41]
	v_mfma_f32_16x16x32_bf16 v[30:33], v[176:179], v[192:195], v[30:33]
	v_mfma_f32_16x16x32_bf16 v[22:25], v[168:171], v[200:203], v[22:25]
	v_mfma_f32_16x16x32_bf16 v[14:17], v[176:179], v[200:203], v[14:17]
	v_mfma_f32_16x16x32_bf16 v[6:9], v[168:171], v[208:211], v[6:9]
	v_mfma_f32_16x16x32_bf16 v[2:5], v[176:179], v[208:211], v[2:5]
	v_mfma_f32_16x16x32_bf16 v[54:57], v[172:175], v[188:191], v[54:57]
	v_mfma_f32_16x16x32_bf16 v[46:49], v[180:183], v[188:191], v[46:49]
	v_mfma_f32_16x16x32_bf16 v[38:41], v[172:175], v[196:199], v[38:41]
	v_mfma_f32_16x16x32_bf16 v[30:33], v[180:183], v[196:199], v[30:33]
	v_mfma_f32_16x16x32_bf16 v[22:25], v[172:175], v[204:207], v[22:25]
	v_mfma_f32_16x16x32_bf16 v[14:17], v[180:183], v[204:207], v[14:17]
	v_mfma_f32_16x16x32_bf16 v[6:9], v[172:175], v[212:215], v[6:9]
	v_mfma_f32_16x16x32_bf16 v[2:5], v[180:183], v[212:215], v[2:5]
	s_barrier
	s_setprio 1
	s_add_i32 s76, 0, 0x18000
	v_add_u32_e32 v155, s76, v150
	s_add_i32 s77, 0, 0x1c000
	ds_read_b128 v[146:149], v155
	ds_read_b128 v[156:159], v155 offset:1024
	ds_read_b128 v[160:163], v155 offset:2048
	ds_read_b128 v[164:167], v155 offset:3072
	v_add_u32_e32 v155, s77, v150
	ds_read_b128 v[168:171], v155
	ds_read_b128 v[172:175], v155 offset:1024
	ds_read_b128 v[176:179], v155 offset:2048
	ds_read_b128 v[180:183], v155 offset:3072
	s_add_u32 s24, s24, 0x40000
	s_addc_u32 s25, s25, 0
	s_mov_b32 m0, s29
	v_lshl_add_u64 v[224:225], s[24:25], 0, v[130:131]
	ds_read_b128 v[184:187], v154 offset:32768
	ds_read_b128 v[188:191], v154 offset:33792
	ds_read_b128 v[192:195], v154 offset:34816
	ds_read_b128 v[196:199], v154 offset:35840
	ds_read_b128 v[200:203], v154 offset:36864
	ds_read_b128 v[204:207], v154 offset:37888
	ds_read_b128 v[208:211], v154 offset:38912
	ds_read_b128 v[212:215], v154 offset:39936
	global_load_lds_dwordx4 v[224:225], off
	v_lshl_add_u64 v[224:225], s[24:25], 0, v[134:135]
	s_mov_b32 m0, s30
	s_nop 0
	global_load_lds_dwordx4 v[224:225], off
	s_waitcnt vmcnt(8)
	s_waitcnt lgkmcnt(0)
	s_barrier
	s_setprio 0
	v_mfma_f32_16x16x32_bf16 v[126:129], v[146:149], v[184:187], v[126:129]
	v_mfma_f32_16x16x32_bf16 v[122:125], v[160:163], v[184:187], v[122:125]
	v_mfma_f32_16x16x32_bf16 v[114:117], v[146:149], v[192:195], v[114:117]
	v_mfma_f32_16x16x32_bf16 v[106:109], v[160:163], v[192:195], v[106:109]
	v_mfma_f32_16x16x32_bf16 v[98:101], v[146:149], v[200:203], v[98:101]
	v_mfma_f32_16x16x32_bf16 v[90:93], v[160:163], v[200:203], v[90:93]
	v_mfma_f32_16x16x32_bf16 v[82:85], v[146:149], v[208:211], v[82:85]
	v_mfma_f32_16x16x32_bf16 v[74:77], v[160:163], v[208:211], v[74:77]
	v_mfma_f32_16x16x32_bf16 v[126:129], v[156:159], v[188:191], v[126:129]
	v_mfma_f32_16x16x32_bf16 v[122:125], v[164:167], v[188:191], v[122:125]
	v_mfma_f32_16x16x32_bf16 v[114:117], v[156:159], v[196:199], v[114:117]
	v_mfma_f32_16x16x32_bf16 v[106:109], v[164:167], v[196:199], v[106:109]
	v_mfma_f32_16x16x32_bf16 v[98:101], v[156:159], v[204:207], v[98:101]
	v_mfma_f32_16x16x32_bf16 v[90:93], v[164:167], v[204:207], v[90:93]
	v_mfma_f32_16x16x32_bf16 v[82:85], v[156:159], v[212:215], v[82:85]
	v_mfma_f32_16x16x32_bf16 v[74:77], v[164:167], v[212:215], v[74:77]
	v_mfma_f32_16x16x32_bf16 v[118:121], v[168:171], v[184:187], v[118:121]
	v_mfma_f32_16x16x32_bf16 v[110:113], v[176:179], v[184:187], v[110:113]
	v_mfma_f32_16x16x32_bf16 v[102:105], v[168:171], v[192:195], v[102:105]
	v_mfma_f32_16x16x32_bf16 v[94:97], v[176:179], v[192:195], v[94:97]
	v_mfma_f32_16x16x32_bf16 v[86:89], v[168:171], v[200:203], v[86:89]
	v_mfma_f32_16x16x32_bf16 v[78:81], v[176:179], v[200:203], v[78:81]
	v_mfma_f32_16x16x32_bf16 v[70:73], v[168:171], v[208:211], v[70:73]
	v_mfma_f32_16x16x32_bf16 v[66:69], v[176:179], v[208:211], v[66:69]
	v_mfma_f32_16x16x32_bf16 v[118:121], v[172:175], v[188:191], v[118:121]
	v_mfma_f32_16x16x32_bf16 v[110:113], v[180:183], v[188:191], v[110:113]
	v_mfma_f32_16x16x32_bf16 v[102:105], v[172:175], v[196:199], v[102:105]
	v_mfma_f32_16x16x32_bf16 v[94:97], v[180:183], v[196:199], v[94:97]
	v_mfma_f32_16x16x32_bf16 v[86:89], v[172:175], v[204:207], v[86:89]
	v_mfma_f32_16x16x32_bf16 v[78:81], v[180:183], v[204:207], v[78:81]
	v_mfma_f32_16x16x32_bf16 v[70:73], v[172:175], v[212:215], v[70:73]
	v_mfma_f32_16x16x32_bf16 v[66:69], v[180:183], v[212:215], v[66:69]
	s_barrier
; #define PG8_STAGE(bufoff, gbase, voff) do { _Pragma("unroll") for (int _i = 0; _i < 2; ++_i) \
;         __builtin_amdgcn_global_load_lds((const unsigned*)((const char*)(gbase) + (voff)[_i]), (PG8_LAS unsigned*)(lds + (bufoff) + ldsw + _i * 8192), 16, 0, 0); } while (0)
; #define PG8_LDA(dst, b, h) do { _Pragma("unroll") for (int m = 0; m < 4; ++m) _Pragma("unroll") for (int k = 0; k < 2; ++k) dst[m][k] = *(const PG8_LAS bf16x8*)(lds + PG8_SA(b, h) + aoff + m * 2048 + k * 1024); } while (0)
; #define PG8_WAIT_V(n) asm volatile("s_waitcnt vmcnt(" #n ")" ::: "memory")
; template <class Epi, class Sched, bool ALIGN_EPI = false, bool SP2 = false>
; __device__ __forceinline__ void gemm_phase(PG8_LAS unsigned char* lds, const Gemm g, const Sched& S, const Epi& E) {
;     ...
;             PG8_LDA(At, 1, 1); PG8_STAGE(PG8_SB(1, 0), b3, voffB); PG8_STAGE(PG8_SB(1, 1), b3 + hstepB, voffB); PG8_STAGE(PG8_SA(1, 0), a3, voffA);
;             PG8_WAIT_V(8); PG8_WAIT_L(0); PG8_BAR; PG8_MMA(1, 0, At, B0); PG8_MMA(1, 1, At, B1); PG8_BAR; PG8_SCHED;
;             } else {
;             PG8_LDB(B0, 0, 0); PG8_SCHED; PG8_LDA(At, 0, 0); PG8_STAGE(PG8_SA(1, 1), a1 + hstep, voffA);
;             PG8_WAIT_L(8); PG8_BAR; PG8_WAIT_L(0); PG8_MMA(0, 0, At, B0); PG8_BAR; PG8_SCHED;
;             PG8_LDB(B1, 0, 1); PG8_STAGE(PG8_SB(0, 0), b2, voffB);
;             PG8_BAR; PG8_WAIT_L(0); PG8_MMA(0, 1, At, B1); PG8_BAR;
;             PG8_LDA(At, 0, 1); PG8_STAGE(PG8_SA(0, 0), a2, voffA);
;             PG8_BAR; PG8_WAIT_L(0); PG8_MMA(1, 0, At, B0); PG8_BAR; PG8_SCHED;
;             PG8_STAGE(PG8_SB(0, 1), b2 + hstepB, voffB);
;             PG8_WAIT_V(6); PG8_BAR; PG8_MMA(1, 1, At, B1); PG8_BAR;
;             PG8_LDB(B0, 1, 0); PG8_SCHED; PG8_LDA(At, 1, 0); PG8_STAGE(PG8_SA(0, 1), a2 + hstep, voffA);
;             PG8_WAIT_L(8); PG8_BAR; PG8_WAIT_L(0); PG8_MMA(0, 0, At, B0); PG8_BAR; PG8_SCHED;
;             PG8_LDB(B1, 1, 1); PG8_STAGE(PG8_SB(1, 0), b3, voffB);
;             PG8_BAR; PG8_WAIT_L(0); PG8_MMA(0, 1, At, B1); PG8_BAR;
;             PG8_LDA(At, 1, 1); PG8_STAGE(PG8_SA(1, 0), a3, voffA);
;             PG8_BAR; PG8_WAIT_L(0); PG8_MMA(1, 0, At, B0); PG8_BAR; PG8_SCHED;
;             PG8_STAGE(PG8_SB(1, 1), b3 + hstepB, voffB);
;             PG8_WAIT_V(6); PG8_BAR; PG8_MMA(1, 1, At, B1); PG8_BAR;
;             }
;         }
;         if constexpr (ALIGN_EPI) { if (wr == 0) PG8_BAR; }
	s_setprio 1
	s_add_i32 s24, s76, s26
	v_lshl_add_u64 v[216:217], v[216:217], 0, s[6:7]
	s_mov_b32 m0, s24
	ds_read_b128 v[184:187], v154 offset:49152
	ds_read_b128 v[188:191], v154 offset:50176
	ds_read_b128 v[192:195], v154 offset:51200
	ds_read_b128 v[196:199], v154 offset:52224
	ds_read_b128 v[200:203], v154 offset:53248
	ds_read_b128 v[204:207], v154 offset:54272
	ds_read_b128 v[208:211], v154 offset:55296
	ds_read_b128 v[212:215], v154 offset:56320
	global_load_lds_dwordx4 v[216:217], off
	s_add_i32 m0, s24, 0x2000
	s_add_u32 s22, s22, 0x10080
	v_lshl_add_u64 v[216:217], v[218:219], 0, s[6:7]
	s_addc_u32 s23, s23, 0
	s_add_i32 s24, s77, s26
	global_load_lds_dwordx4 v[216:217], off
	v_lshl_add_u64 v[216:217], s[22:23], 0, v[132:133]
	s_mov_b32 m0, s24
	s_nop 0
	global_load_lds_dwordx4 v[216:217], off
	v_lshl_add_u64 v[216:217], s[22:23], 0, v[136:137]
	s_add_i32 m0, s24, 0x2000
	s_nop 0
	global_load_lds_dwordx4 v[216:217], off
	v_lshl_add_u64 v[216:217], v[220:221], 0, s[6:7]
	s_mov_b32 m0, s33
	s_nop 0
	global_load_lds_dwordx4 v[216:217], off
	v_lshl_add_u64 v[216:217], v[222:223], 0, s[6:7]
	s_mov_b32 m0, s34
	s_nop 0
	global_load_lds_dwordx4 v[216:217], off
	s_waitcnt vmcnt(8)
	s_waitcnt lgkmcnt(0)
	s_barrier
	s_setprio 0
	v_mfma_f32_16x16x32_bf16 v[62:65], v[146:149], v[184:187], v[62:65]
	v_mfma_f32_16x16x32_bf16 v[58:61], v[160:163], v[184:187], v[58:61]
	v_mfma_f32_16x16x32_bf16 v[50:53], v[146:149], v[192:195], v[50:53]
	v_mfma_f32_16x16x32_bf16 v[42:45], v[160:163], v[192:195], v[42:45]
	v_mfma_f32_16x16x32_bf16 v[34:37], v[146:149], v[200:203], v[34:37]
	v_mfma_f32_16x16x32_bf16 v[26:29], v[160:163], v[200:203], v[26:29]
	v_mfma_f32_16x16x32_bf16 v[18:21], v[146:149], v[208:211], v[18:21]
	v_mfma_f32_16x16x32_bf16 v[10:13], v[160:163], v[208:211], v[10:13]
	v_mfma_f32_16x16x32_bf16 v[62:65], v[156:159], v[188:191], v[62:65]
	v_mfma_f32_16x16x32_bf16 v[58:61], v[164:167], v[188:191], v[58:61]
	v_mfma_f32_16x16x32_bf16 v[50:53], v[156:159], v[196:199], v[50:53]
	v_mfma_f32_16x16x32_bf16 v[42:45], v[164:167], v[196:199], v[42:45]
	v_mfma_f32_16x16x32_bf16 v[34:37], v[156:159], v[204:207], v[34:37]
	v_mfma_f32_16x16x32_bf16 v[26:29], v[164:167], v[204:207], v[26:29]
	v_mfma_f32_16x16x32_bf16 v[18:21], v[156:159], v[212:215], v[18:21]
	v_mfma_f32_16x16x32_bf16 v[10:13], v[164:167], v[212:215], v[10:13]
	v_mfma_f32_16x16x32_bf16 v[54:57], v[168:171], v[184:187], v[54:57]
	v_mfma_f32_16x16x32_bf16 v[46:49], v[176:179], v[184:187], v[46:49]
	v_mfma_f32_16x16x32_bf16 v[38:41], v[168:171], v[192:195], v[38:41]
	v_mfma_f32_16x16x32_bf16 v[30:33], v[176:179], v[192:195], v[30:33]
	v_mfma_f32_16x16x32_bf16 v[22:25], v[168:171], v[200:203], v[22:25]
	v_mfma_f32_16x16x32_bf16 v[14:17], v[176:179], v[200:203], v[14:17]
	v_mfma_f32_16x16x32_bf16 v[6:9], v[168:171], v[208:211], v[6:9]
	v_mfma_f32_16x16x32_bf16 v[2:5], v[176:179], v[208:211], v[2:5]
	v_mfma_f32_16x16x32_bf16 v[54:57], v[172:175], v[188:191], v[54:57]
	v_mfma_f32_16x16x32_bf16 v[46:49], v[180:183], v[188:191], v[46:49]
	v_mfma_f32_16x16x32_bf16 v[38:41], v[172:175], v[196:199], v[38:41]
	v_mfma_f32_16x16x32_bf16 v[30:33], v[180:183], v[196:199], v[30:33]
	v_mfma_f32_16x16x32_bf16 v[22:25], v[172:175], v[204:207], v[22:25]
	v_mfma_f32_16x16x32_bf16 v[14:17], v[180:183], v[204:207], v[14:17]
	v_mfma_f32_16x16x32_bf16 v[6:9], v[172:175], v[212:215], v[6:9]
	v_mfma_f32_16x16x32_bf16 v[2:5], v[180:183], v[212:215], v[2:5]
	s_barrier
	s_setprio 1
	s_add_i32 s75, s75, 2
	s_add_u32 s20, s20, 0x100
	s_addc_u32 s21, s21, 0
	s_add_u32 s73, s73, 0x100
	s_addc_u32 s74, s74, 0
	s_cmp_gt_u32 s75, 13
	s_cbranch_scc0 .LBB0_192
	s_and_b64 vcc, exec, s[8:9]
	s_cbranch_vccz .LBB0_195
	s_barrier

; #define GAS __attribute__((address_space(1)))
; #define LAS __attribute__((address_space(3)))
; __device__ __forceinline__ float fsigmoid(float x) { return __builtin_amdgcn_rcpf(1.f + __builtin_amdgcn_exp2f(-LOG2E * x)); }
; __device__ __forceinline__ f32x4 bf4_to_f32(u32x2 w) { return (f32x4){bflo(w.x), bfhi(w.x), bflo(w.y), bfhi(w.y)}; }
; __device__ __forceinline__ u32x2 f32_to_bf4(f32x4 v) { u32x2 w; w.x = cvtpk(v[0], v[1]); w.y = cvtpk(v[2], v[3]); return w; }
; __device__ __forceinline__ void prep_unit(LAS unsigned char* lds, const MixBufs& B, int b, int ch, int tid) {
;     ...
;     __syncthreads();
;     LAS unsigned char* XA = lds;
;     {
;         f32x4 cw[4], wv[4];
; #pragma unroll
;         for (int i = 0; i < 4; ++i) { cw[i] = *(const GAS f32x4*)(B.conv_w + i * 512 + 4 * gch); wv[i] = *(const GAS f32x4*)(B.w_v + (gch * 4 + i) * 4); }
;         const f32x4 cb = *(const GAS f32x4*)(B.conv_b + 4 * gch);
;         f32x4 x3 = bf4_to_f32(xr[0]), x2 = bf4_to_f32(xr[1]), x1 = bf4_to_f32(xr[2]);
; #pragma unroll
;         for (int s = 0; s < 16; ++s) { const int row = 16 * strip + s;
;             const f32x4 x0 = bf4_to_f32(xr[s + 3]);
;             f32x4 cv = cb + cw[0] * x3 + cw[1] * x2 + cw[2] * x1 + cw[3] * x0, xc;
; #pragma unroll
;             for (int e = 0; e < 4; ++e) xc[e] = cv[e] * fsigmoid(cv[e]);
;             const int sw = row & 7, within = (gch & 1) * 8;
;             *(LAS u32x2*)(XA + row * 2048 + ((((gch >> 1)) ^ sw) << 4) + within) = f32_to_bf4(xc);
;             *(LAS u32x2*)(XA + row * 2048 + (((64 + (gch >> 1)) ^ sw) << 4) + within) = xr[s + 3];
;             const f32x4 v = wv[0] * x0[0] + wv[1] * x0[1] + wv[2] * x0[2] + wv[3] * x0[3];
;             *(GAS u32x2*)(B.xcm + (t0 + row) * 512 + 4 * gch) = f32_to_bf4(xc); *(GAS u32x2*)(B.vm + (t0 + row) * 512 + 4 * gch) = f32_to_bf4(v);
;             x3 = x2; x2 = x1; x1 = x0; }
.LBB0_306:
	v_lshlrev_b32_e32 v2, 2, v59
	v_lshl_add_u64 v[28:29], s[64:65], 0, v[2:3]
	v_readlane_b32 s68, v241, 2
	v_add_co_u32_e32 v32, vcc, s21, v28
	v_lshlrev_b32_e32 v16, 6, v14
	v_readlane_b32 s72, v241, 6
	v_readlane_b32 s73, v241, 7
	v_addc_co_u32_e32 v33, vcc, 0, v29, vcc
	s_waitcnt vmcnt(26)
	v_cndmask_b32_e64 v92, v13, 0, s[2:3]
	v_cndmask_b32_e64 v80, v12, 0, s[2:3]
	s_waitcnt vmcnt(25)
	v_cndmask_b32_e64 v93, v11, 0, s[4:5]
	v_cndmask_b32_e64 v81, v10, 0, s[4:5]
	s_waitcnt vmcnt(24)
	v_cndmask_b32_e64 v101, v9, 0, s[6:7]
	v_cndmask_b32_e64 v87, v8, 0, s[6:7]
	s_barrier
	global_load_dwordx4 v[20:23], v2, s[64:65]
	global_load_dwordx4 v[4:7], v16, s[72:73] offset:48
	global_load_dwordx4 v[8:11], v16, s[72:73] offset:32
	global_load_dwordx4 v[12:15], v16, s[72:73]
	s_nop 0
	global_load_dwordx4 v[16:19], v16, s[72:73] offset:16
	s_nop 0
	global_load_dwordx4 v[24:27], v2, s[64:65] offset:2048
	global_load_dwordx4 v[28:31], v[32:33], off
	s_nop 0
	global_load_dwordx4 v[32:35], v[32:33], off offset:2048
	s_nop 0
	global_load_dwordx4 v[36:39], v2, s[66:67]
	v_lshlrev_b32_e32 v84, 16, v80
	v_and_b32_e32 v85, 0xffff0000, v80
	v_lshlrev_b32_e32 v90, 16, v81
	v_and_b32_e32 v91, 0xffff0000, v81
	v_lshlrev_b32_e32 v86, 16, v87
	v_and_b32_e32 v87, 0xffff0000, v87
	s_waitcnt vmcnt(32)
	v_and_b32_e32 v103, 0xffff0000, v82
	v_lshlrev_b32_e32 v80, 16, v82
	v_mov_b32_e32 v81, v103
	v_lshlrev_b32_e32 v2, 3, v99
	v_and_b32_e32 v41, 8, v2
	v_lshlrev_b32_e32 v106, 16, v92
	v_and_b32_e32 v107, 0xffff0000, v92
	v_lshlrev_b32_e32 v92, 16, v93
	v_and_b32_e32 v93, 0xffff0000, v93
	v_and_b32_e32 v109, 0xffff0000, v83
	v_and_b32_e32 v102, 16, v82
	v_and_b32_e32 v108, 16, v83
	v_readlane_b32 s36, v241, 18
	v_lshlrev_b64 v[74:75], 10, v[74:75]
	v_readlane_b32 s50, v241, 32
	v_readlane_b32 s51, v241, 33
	s_movk_i32 s2, 0x50
	s_lshl_b32 s4, s18, 7
	s_ashr_i32 s5, s4, 31
	s_lshl_b32 s3, s18, 4
	v_readlane_b32 s76, v241, 10
	v_readlane_b32 s77, v241, 11
	v_readlane_b32 s69, v241, 3
	v_readlane_b32 s70, v241, 4
	v_readlane_b32 s71, v241, 5
	v_readlane_b32 s74, v241, 8
	v_readlane_b32 s75, v241, 9
	v_readlane_b32 s78, v241, 12
	v_readlane_b32 s79, v241, 13
	v_readlane_b32 s80, v241, 14
	v_readlane_b32 s81, v241, 15
	v_readlane_b32 s82, v241, 16
	v_readlane_b32 s83, v241, 17
	v_readlane_b32 s37, v241, 19
	v_readlane_b32 s38, v241, 20
	v_readlane_b32 s39, v241, 21
	v_readlane_b32 s40, v241, 22
	v_readlane_b32 s41, v241, 23
	v_readlane_b32 s42, v241, 24
	v_readlane_b32 s43, v241, 25
	v_readlane_b32 s44, v241, 26
	v_readlane_b32 s45, v241, 27
	v_readlane_b32 s46, v241, 28
	v_readlane_b32 s47, v241, 29
	v_readlane_b32 s48, v241, 30
	v_readlane_b32 s49, v241, 31
	s_waitcnt vmcnt(0)
	v_pk_fma_f32 v[84:85], v[20:21], v[84:85], v[36:37]
	s_nop 0
	v_pk_fma_f32 v[84:85], v[24:25], v[90:91], v[84:85]
	v_pk_fma_f32 v[106:107], v[22:23], v[106:107], v[38:39]
	v_pk_fma_f32 v[84:85], v[28:29], v[86:87], v[84:85]
	v_pk_fma_f32 v[106:107], v[26:27], v[92:93], v[106:107]
	v_pk_fma_f32 v[84:85], v[32:33], v[80:81], v[84:85]
	v_pk_fma_f32 v[90:91], v[20:21], v[90:91], v[36:37]
	v_mul_f32_e32 v2, 0xbfb8aa3b, v84
	v_exp_f32_e32 v2, v2
	v_pk_fma_f32 v[90:91], v[24:25], v[86:87], v[90:91]
	v_pk_fma_f32 v[92:93], v[22:23], v[92:93], v[38:39]
	v_pk_fma_f32 v[90:91], v[28:29], v[80:81], v[90:91]
	v_add_f32_e32 v2, 1.0, v2
	v_rcp_f32_e32 v88, v2
	v_mul_f32_e32 v2, 0xbfb8aa3b, v85
	v_exp_f32_e32 v2, v2
	s_nop 0
	v_add_f32_e32 v2, 1.0, v2
	v_rcp_f32_e32 v89, v2
	s_nop 0
	v_pk_mul_f32 v[104:105], v[84:85], v[88:89]
	v_lshlrev_b32_e32 v88, 16, v101
	v_and_b32_e32 v89, 0xffff0000, v101
	v_lshlrev_b32_e32 v84, 16, v83
	v_mov_b32_e32 v85, v109
	v_pk_fma_f32 v[106:107], v[30:31], v[88:89], v[106:107]
	v_and_b32_e32 v101, 0x3f0, v58
	v_pk_fma_f32 v[106:107], v[34:35], v[84:85], v[106:107]
	v_cvt_pk_bf16_f32 v104, v104, v105
	v_mul_f32_e32 v2, 0xbfb8aa3b, v106
	v_exp_f32_e32 v2, v2
	v_pk_fma_f32 v[92:93], v[26:27], v[88:89], v[92:93]
	v_pk_fma_f32 v[88:89], v[22:23], v[88:89], v[38:39]
	v_pk_fma_f32 v[92:93], v[30:31], v[84:85], v[92:93]
	v_add_f32_e32 v2, 1.0, v2
	v_rcp_f32_e32 v110, v2
	v_mul_f32_e32 v2, 0xbfb8aa3b, v107
	v_exp_f32_e32 v2, v2
	v_pk_fma_f32 v[88:89], v[26:27], v[84:85], v[88:89]
	v_add_f32_e32 v2, 1.0, v2
	v_rcp_f32_e32 v111, v2
	v_lshl_add_u32 v2, v40, 11, 0
	v_add3_u32 v2, v2, v101, v41
	v_pk_mul_f32 v[106:107], v[106:107], v[110:111]
	s_nop 0
	v_cvt_pk_bf16_f32 v105, v106, v107
	ds_write2st64_b64 v2, v[104:105], v[82:83] offset1:2
	v_pk_mul_f32 v[82:83], v[102:103], v[18:19] op_sel:[1,0]
	v_pk_mul_f32 v[102:103], v[102:103], v[16:17] op_sel:[1,0]
	v_pk_fma_f32 v[82:83], v[80:81], v[14:15], v[82:83] op_sel_hi:[0,1,1]
	v_pk_fma_f32 v[102:103], v[80:81], v[12:13], v[102:103] op_sel_hi:[0,1,1]
	v_pk_fma_f32 v[82:83], v[84:85], v[10:11], v[82:83] op_sel_hi:[0,1,1]
	v_pk_fma_f32 v[102:103], v[84:85], v[8:9], v[102:103] op_sel_hi:[0,1,1]
	v_pk_fma_f32 v[82:83], v[108:109], v[6:7], v[82:83] op_sel:[1,0,0]
	v_pk_fma_f32 v[102:103], v[108:109], v[4:5], v[102:103] op_sel:[1,0,0]
	v_lshl_add_u64 v[106:107], s[50:51], 0, v[74:75]
	v_lshlrev_b32_e32 v2, 1, v59
	v_lshl_add_u64 v[74:75], s[0:1], 0, v[74:75]
	v_cvt_pk_bf16_f32 v102, v102, v103
	v_cvt_pk_bf16_f32 v103, v82, v83
	v_lshl_add_u64 v[74:75], v[74:75], 0, v[2:3]
	v_and_b32_e32 v83, 0xffff0000, v72
	global_store_dwordx2 v[74:75], v[102:103], off
	v_lshlrev_b32_e32 v74, 16, v72
	v_mov_b32_e32 v75, v83
	v_pk_fma_f32 v[90:91], v[32:33], v[74:75], v[90:91]
	v_lshl_add_u64 v[106:107], v[106:107], 0, v[2:3]
	v_mul_f32_e32 v59, 0xbfb8aa3b, v90
	v_exp_f32_e32 v59, v59
	global_store_dwordx2 v[106:107], v[104:105], off
	v_and_b32_e32 v105, 0xffff0000, v73
; #define GAS __attribute__((address_space(1)))
; #define LAS __attribute__((address_space(3)))
; __device__ __forceinline__ float fsigmoid(float x) { return __builtin_amdgcn_rcpf(1.f + __builtin_amdgcn_exp2f(-LOG2E * x)); }
; __device__ __forceinline__ f32x4 bf4_to_f32(u32x2 w) { return (f32x4){bflo(w.x), bfhi(w.x), bflo(w.y), bfhi(w.y)}; }
; __device__ __forceinline__ u32x2 f32_to_bf4(f32x4 v) { u32x2 w; w.x = cvtpk(v[0], v[1]); w.y = cvtpk(v[2], v[3]); return w; }
; __device__ __forceinline__ void prep_unit(LAS unsigned char* lds, const MixBufs& B, int b, int ch, int tid) {
;     ...
; #pragma unroll
;         for (int s = 0; s < 16; ++s) { const int row = 16 * strip + s;
;             const f32x4 x0 = bf4_to_f32(xr[s + 3]);
;             f32x4 cv = cb + cw[0] * x3 + cw[1] * x2 + cw[2] * x1 + cw[3] * x0, xc;
; #pragma unroll
;             for (int e = 0; e < 4; ++e) xc[e] = cv[e] * fsigmoid(cv[e]);
;             const int sw = row & 7, within = (gch & 1) * 8;
;             *(LAS u32x2*)(XA + row * 2048 + ((((gch >> 1)) ^ sw) << 4) + within) = f32_to_bf4(xc);
;             *(LAS u32x2*)(XA + row * 2048 + (((64 + (gch >> 1)) ^ sw) << 4) + within) = xr[s + 3];
;             const f32x4 v = wv[0] * x0[0] + wv[1] * x0[1] + wv[2] * x0[2] + wv[3] * x0[3];
;             *(GAS u32x2*)(B.xcm + (t0 + row) * 512 + 4 * gch) = f32_to_bf4(xc); *(GAS u32x2*)(B.vm + (t0 + row) * 512 + 4 * gch) = f32_to_bf4(v);
;             x3 = x2; x2 = x1; x1 = x0; }
	v_and_b32_e32 v82, 16, v72
	v_add_f32_e32 v59, 1.0, v59
	v_rcp_f32_e32 v102, v59
	v_mul_f32_e32 v59, 0xbfb8aa3b, v91
	v_exp_f32_e32 v59, v59
	v_and_b32_e32 v104, 16, v73
	v_pk_fma_f32 v[84:85], v[22:23], v[84:85], v[38:39]
	v_add_f32_e32 v59, 1.0, v59
	v_rcp_f32_e32 v103, v59
	s_nop 0
	v_pk_mul_f32 v[102:103], v[90:91], v[102:103]
	v_lshlrev_b32_e32 v90, 16, v73
	v_mov_b32_e32 v91, v105
	v_pk_fma_f32 v[92:93], v[34:35], v[90:91], v[92:93]
	v_cvt_pk_bf16_f32 v108, v102, v103
	v_mul_f32_e32 v59, 0xbfb8aa3b, v92
	v_exp_f32_e32 v59, v59
	v_bitop3_b32 v102, v58, 16, v94 bitop3:0x6c
	v_pk_fma_f32 v[88:89], v[30:31], v[90:91], v[88:89]
	v_pk_fma_f32 v[84:85], v[26:27], v[90:91], v[84:85]
	v_add_f32_e32 v59, 1.0, v59
	v_rcp_f32_e32 v106, v59
	v_mul_f32_e32 v59, 0xbfb8aa3b, v93
	v_exp_f32_e32 v59, v59
	s_nop 0
	v_add_f32_e32 v59, 1.0, v59
	v_rcp_f32_e32 v107, v59
	s_nop 0
	v_pk_mul_f32 v[92:93], v[92:93], v[106:107]
	v_or_b32_e32 v106, 1, v40
	v_lshl_add_u32 v59, v106, 11, 0
	v_cvt_pk_bf16_f32 v109, v92, v93
	v_add3_u32 v59, v59, v102, v41
	ds_write2st64_b64 v59, v[108:109], v[72:73] offset1:2
	v_pk_mul_f32 v[72:73], v[82:83], v[18:19] op_sel:[1,0]
	v_pk_mul_f32 v[82:83], v[82:83], v[16:17] op_sel:[1,0]
	v_pk_fma_f32 v[72:73], v[74:75], v[14:15], v[72:73] op_sel_hi:[0,1,1]
	v_pk_fma_f32 v[82:83], v[74:75], v[12:13], v[82:83] op_sel_hi:[0,1,1]
	v_ashrrev_i32_e32 v107, 31, v106
	v_pk_fma_f32 v[72:73], v[90:91], v[10:11], v[72:73] op_sel_hi:[0,1,1]
	v_pk_fma_f32 v[82:83], v[90:91], v[8:9], v[82:83] op_sel_hi:[0,1,1]
	v_lshl_add_u64 v[92:93], s[16:17], 0, v[106:107]
	v_pk_fma_f32 v[72:73], v[104:105], v[6:7], v[72:73] op_sel:[1,0,0]
	v_pk_fma_f32 v[82:83], v[104:105], v[4:5], v[82:83] op_sel:[1,0,0]
	v_lshlrev_b64 v[92:93], 10, v[92:93]
	v_cvt_pk_bf16_f32 v82, v82, v83
	v_cvt_pk_bf16_f32 v83, v72, v73
	v_lshl_add_u64 v[72:73], s[0:1], 0, v[92:93]
	v_lshl_add_u64 v[72:73], v[72:73], 0, v[2:3]
	global_store_dwordx2 v[72:73], v[82:83], off
	v_pk_fma_f32 v[82:83], v[20:21], v[86:87], v[36:37]
	v_and_b32_e32 v73, 0xffff0000, v70
	v_pk_fma_f32 v[82:83], v[24:25], v[80:81], v[82:83]
	v_lshl_add_u64 v[104:105], s[50:51], 0, v[92:93]
	v_lshlrev_b32_e32 v92, 16, v70
	v_mov_b32_e32 v93, v73
	v_pk_fma_f32 v[82:83], v[28:29], v[74:75], v[82:83]
	v_lshl_add_u64 v[104:105], v[104:105], 0, v[2:3]
	v_pk_fma_f32 v[82:83], v[32:33], v[92:93], v[82:83]
	global_store_dwordx2 v[104:105], v[108:109], off
	v_mul_f32_e32 v59, 0xbfb8aa3b, v82
	v_exp_f32_e32 v59, v59
	v_and_b32_e32 v105, 0xffff0000, v71
	v_and_b32_e32 v72, 16, v70
	v_and_b32_e32 v104, 16, v71
	v_add_f32_e32 v59, 1.0, v59
	v_rcp_f32_e32 v86, v59
	v_mul_f32_e32 v59, 0xbfb8aa3b, v83
	v_exp_f32_e32 v59, v59
	v_pk_fma_f32 v[90:91], v[22:23], v[90:91], v[38:39]
	v_add_f32_e32 v59, 1.0, v59
	v_rcp_f32_e32 v87, v59
	s_nop 0
	v_pk_mul_f32 v[82:83], v[82:83], v[86:87]
	v_lshlrev_b32_e32 v86, 16, v71
	v_mov_b32_e32 v87, v105
	v_pk_fma_f32 v[88:89], v[34:35], v[86:87], v[88:89]
	v_cvt_pk_bf16_f32 v82, v82, v83
	v_mul_f32_e32 v59, 0xbfb8aa3b, v88
	v_exp_f32_e32 v59, v59
	v_pk_fma_f32 v[84:85], v[30:31], v[86:87], v[84:85]
	v_pk_fma_f32 v[90:91], v[26:27], v[86:87], v[90:91]
	v_add_f32_e32 v59, 1.0, v59
	v_rcp_f32_e32 v106, v59
	v_mul_f32_e32 v59, 0xbfb8aa3b, v89
	v_exp_f32_e32 v59, v59
	s_nop 0
	v_add_f32_e32 v59, 1.0, v59
	v_rcp_f32_e32 v107, v59
	s_nop 0
	v_pk_mul_f32 v[88:89], v[88:89], v[106:107]
	v_or_b32_e32 v106, 2, v40
	v_cvt_pk_bf16_f32 v83, v88, v89
	v_lshl_add_u32 v59, v106, 11, 0
	v_bitop3_b32 v88, v58, 32, v94 bitop3:0x6c
	v_add3_u32 v59, v59, v88, v41
	ds_write2st64_b64 v59, v[82:83], v[70:71] offset1:2
	v_pk_mul_f32 v[70:71], v[72:73], v[18:19] op_sel:[1,0]
	v_pk_mul_f32 v[72:73], v[72:73], v[16:17] op_sel:[1,0]
	v_pk_fma_f32 v[70:71], v[92:93], v[14:15], v[70:71] op_sel_hi:[0,1,1]
	v_pk_fma_f32 v[72:73], v[92:93], v[12:13], v[72:73] op_sel_hi:[0,1,1]
	v_pk_fma_f32 v[70:71], v[86:87], v[10:11], v[70:71] op_sel_hi:[0,1,1]
	v_pk_fma_f32 v[72:73], v[86:87], v[8:9], v[72:73] op_sel_hi:[0,1,1]
	v_ashrrev_i32_e32 v107, 31, v106
	v_pk_fma_f32 v[70:71], v[104:105], v[6:7], v[70:71] op_sel:[1,0,0]
	v_pk_fma_f32 v[72:73], v[104:105], v[4:5], v[72:73] op_sel:[1,0,0]
	v_lshl_add_u64 v[104:105], s[16:17], 0, v[106:107]
	v_lshlrev_b64 v[104:105], 10, v[104:105]
	v_cvt_pk_bf16_f32 v72, v72, v73
	v_cvt_pk_bf16_f32 v73, v70, v71
	v_lshl_add_u64 v[70:71], s[0:1], 0, v[104:105]
	v_lshl_add_u64 v[70:71], v[70:71], 0, v[2:3]
	v_lshl_add_u64 v[106:107], s[50:51], 0, v[104:105]
	global_store_dwordx2 v[70:71], v[72:73], off
	v_pk_fma_f32 v[72:73], v[20:21], v[80:81], v[36:37]
	v_lshl_add_u64 v[106:107], v[106:107], 0, v[2:3]
	v_and_b32_e32 v71, 0xffff0000, v68
	v_pk_fma_f32 v[72:73], v[24:25], v[74:75], v[72:73]
	global_store_dwordx2 v[106:107], v[82:83], off
	v_lshlrev_b32_e32 v82, 16, v68
	v_mov_b32_e32 v83, v71
	v_pk_fma_f32 v[72:73], v[28:29], v[92:93], v[72:73]
	v_and_b32_e32 v105, 0xffff0000, v69
	v_pk_fma_f32 v[72:73], v[32:33], v[82:83], v[72:73]
	v_and_b32_e32 v70, 16, v68
	v_mul_f32_e32 v59, 0xbfb8aa3b, v72
	v_exp_f32_e32 v59, v59
	v_and_b32_e32 v104, 16, v69
	v_pk_fma_f32 v[86:87], v[22:23], v[86:87], v[38:39]
	v_add_f32_e32 v59, 1.0, v59
	v_rcp_f32_e32 v80, v59
	v_mul_f32_e32 v59, 0xbfb8aa3b, v73
	v_exp_f32_e32 v59, v59
	s_nop 0
	v_add_f32_e32 v59, 1.0, v59
	v_rcp_f32_e32 v81, v59
	s_nop 0
	v_pk_mul_f32 v[72:73], v[72:73], v[80:81]
	v_lshlrev_b32_e32 v80, 16, v69
	v_mov_b32_e32 v81, v105
	v_pk_fma_f32 v[84:85], v[34:35], v[80:81], v[84:85]
	v_cvt_pk_bf16_f32 v72, v72, v73
	v_mul_f32_e32 v59, 0xbfb8aa3b, v84
	v_exp_f32_e32 v59, v59
	v_pk_fma_f32 v[90:91], v[30:31], v[80:81], v[90:91]
	v_pk_fma_f32 v[86:87], v[26:27], v[80:81], v[86:87]
; #define GAS __attribute__((address_space(1)))
; #define LAS __attribute__((address_space(3)))
; __device__ __forceinline__ float fsigmoid(float x) { return __builtin_amdgcn_rcpf(1.f + __builtin_amdgcn_exp2f(-LOG2E * x)); }
; __device__ __forceinline__ f32x4 bf4_to_f32(u32x2 w) { return (f32x4){bflo(w.x), bfhi(w.x), bflo(w.y), bfhi(w.y)}; }
; __device__ __forceinline__ u32x2 f32_to_bf4(f32x4 v) { u32x2 w; w.x = cvtpk(v[0], v[1]); w.y = cvtpk(v[2], v[3]); return w; }
; __device__ __forceinline__ void prep_unit(LAS unsigned char* lds, const MixBufs& B, int b, int ch, int tid) {
;     ...
; #pragma unroll
;         for (int s = 0; s < 16; ++s) { const int row = 16 * strip + s;
;             const f32x4 x0 = bf4_to_f32(xr[s + 3]);
;             f32x4 cv = cb + cw[0] * x3 + cw[1] * x2 + cw[2] * x1 + cw[3] * x0, xc;
; #pragma unroll
;             for (int e = 0; e < 4; ++e) xc[e] = cv[e] * fsigmoid(cv[e]);
;             const int sw = row & 7, within = (gch & 1) * 8;
;             *(LAS u32x2*)(XA + row * 2048 + ((((gch >> 1)) ^ sw) << 4) + within) = f32_to_bf4(xc);
;             *(LAS u32x2*)(XA + row * 2048 + (((64 + (gch >> 1)) ^ sw) << 4) + within) = xr[s + 3];
;             const f32x4 v = wv[0] * x0[0] + wv[1] * x0[1] + wv[2] * x0[2] + wv[3] * x0[3];
;             *(GAS u32x2*)(B.xcm + (t0 + row) * 512 + 4 * gch) = f32_to_bf4(xc); *(GAS u32x2*)(B.vm + (t0 + row) * 512 + 4 * gch) = f32_to_bf4(v);
;             x3 = x2; x2 = x1; x1 = x0; }
	v_add_f32_e32 v59, 1.0, v59
	v_rcp_f32_e32 v106, v59
	v_mul_f32_e32 v59, 0xbfb8aa3b, v85
	v_exp_f32_e32 v59, v59
	s_nop 0
	v_add_f32_e32 v59, 1.0, v59
	v_rcp_f32_e32 v107, v59
	s_nop 0
	v_pk_mul_f32 v[84:85], v[84:85], v[106:107]
	v_or_b32_e32 v106, 3, v40
	v_cvt_pk_bf16_f32 v73, v84, v85
	v_lshl_add_u32 v59, v106, 11, 0
	v_bitop3_b32 v84, v58, 48, v94 bitop3:0x6c
	v_add3_u32 v59, v59, v84, v41
	ds_write2st64_b64 v59, v[72:73], v[68:69] offset1:2
	v_pk_mul_f32 v[68:69], v[70:71], v[18:19] op_sel:[1,0]
	v_pk_mul_f32 v[70:71], v[70:71], v[16:17] op_sel:[1,0]
	v_pk_fma_f32 v[68:69], v[82:83], v[14:15], v[68:69] op_sel_hi:[0,1,1]
	v_pk_fma_f32 v[70:71], v[82:83], v[12:13], v[70:71] op_sel_hi:[0,1,1]
	v_pk_fma_f32 v[68:69], v[80:81], v[10:11], v[68:69] op_sel_hi:[0,1,1]
	v_pk_fma_f32 v[70:71], v[80:81], v[8:9], v[70:71] op_sel_hi:[0,1,1]
	v_ashrrev_i32_e32 v107, 31, v106
	v_pk_fma_f32 v[68:69], v[104:105], v[6:7], v[68:69] op_sel:[1,0,0]
	v_pk_fma_f32 v[70:71], v[104:105], v[4:5], v[70:71] op_sel:[1,0,0]
	v_lshl_add_u64 v[104:105], s[16:17], 0, v[106:107]
	v_lshlrev_b64 v[104:105], 10, v[104:105]
	v_lshl_add_u64 v[106:107], s[50:51], 0, v[104:105]
	v_lshl_add_u64 v[106:107], v[106:107], 0, v[2:3]
	v_cvt_pk_bf16_f32 v70, v70, v71
	v_cvt_pk_bf16_f32 v71, v68, v69
	v_lshl_add_u64 v[68:69], s[0:1], 0, v[104:105]
	global_store_dwordx2 v[106:107], v[72:73], off
	v_lshl_add_u64 v[68:69], v[68:69], 0, v[2:3]
	v_pk_fma_f32 v[72:73], v[20:21], v[74:75], v[36:37]
	global_store_dwordx2 v[68:69], v[70:71], off
	v_and_b32_e32 v69, 0xffff0000, v66
	v_pk_fma_f32 v[72:73], v[24:25], v[92:93], v[72:73]
	v_lshlrev_b32_e32 v70, 16, v66
	v_mov_b32_e32 v71, v69
	v_pk_fma_f32 v[72:73], v[28:29], v[82:83], v[72:73]
	v_and_b32_e32 v105, 0xffff0000, v67
	v_pk_fma_f32 v[72:73], v[32:33], v[70:71], v[72:73]
	v_bitop3_b32 v85, v58, 64, v94 bitop3:0x6c
	v_mul_f32_e32 v59, 0xbfb8aa3b, v72
	v_exp_f32_e32 v59, v59
	v_and_b32_e32 v68, 16, v66
	v_and_b32_e32 v104, 16, v67
	v_pk_fma_f32 v[80:81], v[22:23], v[80:81], v[38:39]
	v_add_f32_e32 v59, 1.0, v59
	v_rcp_f32_e32 v74, v59
	v_mul_f32_e32 v59, 0xbfb8aa3b, v73
	v_exp_f32_e32 v59, v59
	s_nop 0
	v_add_f32_e32 v59, 1.0, v59
	v_rcp_f32_e32 v75, v59
	s_nop 0
	v_pk_mul_f32 v[74:75], v[72:73], v[74:75]
	v_lshlrev_b32_e32 v72, 16, v67
	v_mov_b32_e32 v73, v105
	v_pk_fma_f32 v[90:91], v[34:35], v[72:73], v[90:91]
	v_cvt_pk_bf16_f32 v74, v74, v75
	v_mul_f32_e32 v59, 0xbfb8aa3b, v90
	v_exp_f32_e32 v59, v59
	v_pk_fma_f32 v[86:87], v[30:31], v[72:73], v[86:87]
	v_pk_fma_f32 v[80:81], v[26:27], v[72:73], v[80:81]
	v_add_f32_e32 v59, 1.0, v59
	v_rcp_f32_e32 v106, v59
	v_mul_f32_e32 v59, 0xbfb8aa3b, v91
	v_exp_f32_e32 v59, v59
	s_nop 0
	v_add_f32_e32 v59, 1.0, v59
	v_rcp_f32_e32 v107, v59
	s_nop 0
	v_pk_mul_f32 v[90:91], v[90:91], v[106:107]
	v_or_b32_e32 v106, 4, v40
	v_lshl_add_u32 v59, v106, 11, 0
	v_cvt_pk_bf16_f32 v75, v90, v91
	v_add3_u32 v59, v59, v85, v41
	ds_write2st64_b64 v59, v[74:75], v[66:67] offset1:2
	v_pk_mul_f32 v[66:67], v[68:69], v[18:19] op_sel:[1,0]
	v_pk_mul_f32 v[68:69], v[68:69], v[16:17] op_sel:[1,0]
	v_pk_fma_f32 v[66:67], v[70:71], v[14:15], v[66:67] op_sel_hi:[0,1,1]
	v_pk_fma_f32 v[68:69], v[70:71], v[12:13], v[68:69] op_sel_hi:[0,1,1]
	v_ashrrev_i32_e32 v107, 31, v106
	v_pk_fma_f32 v[66:67], v[72:73], v[10:11], v[66:67] op_sel_hi:[0,1,1]
	v_pk_fma_f32 v[68:69], v[72:73], v[8:9], v[68:69] op_sel_hi:[0,1,1]
	v_lshl_add_u64 v[90:91], s[16:17], 0, v[106:107]
	v_pk_fma_f32 v[66:67], v[104:105], v[6:7], v[66:67] op_sel:[1,0,0]
	v_pk_fma_f32 v[68:69], v[104:105], v[4:5], v[68:69] op_sel:[1,0,0]
	v_lshlrev_b64 v[90:91], 10, v[90:91]
	v_cvt_pk_bf16_f32 v68, v68, v69
	v_cvt_pk_bf16_f32 v69, v66, v67
	v_lshl_add_u64 v[66:67], s[0:1], 0, v[90:91]
	v_lshl_add_u64 v[104:105], s[50:51], 0, v[90:91]
	v_lshl_add_u64 v[66:67], v[66:67], 0, v[2:3]
	v_lshl_add_u64 v[104:105], v[104:105], 0, v[2:3]
	global_store_dwordx2 v[66:67], v[68:69], off
	v_pk_fma_f32 v[68:69], v[20:21], v[92:93], v[36:37]
	global_store_dwordx2 v[104:105], v[74:75], off
	v_and_b32_e32 v75, 0xffff0000, v64
	v_pk_fma_f32 v[68:69], v[24:25], v[82:83], v[68:69]
	v_lshlrev_b32_e32 v66, 16, v64
	v_mov_b32_e32 v67, v75
	v_pk_fma_f32 v[68:69], v[28:29], v[70:71], v[68:69]
	v_and_b32_e32 v93, 0xffff0000, v65
	v_pk_fma_f32 v[68:69], v[32:33], v[66:67], v[68:69]
	v_and_b32_e32 v74, 16, v64
	v_mul_f32_e32 v59, 0xbfb8aa3b, v68
	v_exp_f32_e32 v59, v59
	v_and_b32_e32 v92, 16, v65
	v_pk_fma_f32 v[72:73], v[22:23], v[72:73], v[38:39]
	v_add_f32_e32 v59, 1.0, v59
	v_rcp_f32_e32 v90, v59
	v_mul_f32_e32 v59, 0xbfb8aa3b, v69
	v_exp_f32_e32 v59, v59
	s_nop 0
	v_add_f32_e32 v59, 1.0, v59
	v_rcp_f32_e32 v91, v59
	s_nop 0
	v_pk_mul_f32 v[90:91], v[68:69], v[90:91]
	v_lshlrev_b32_e32 v68, 16, v65
	v_mov_b32_e32 v69, v93
	v_pk_fma_f32 v[86:87], v[34:35], v[68:69], v[86:87]
	v_cvt_pk_bf16_f32 v90, v90, v91
	v_mul_f32_e32 v59, 0xbfb8aa3b, v86
	v_exp_f32_e32 v59, v59
	v_pk_fma_f32 v[80:81], v[30:31], v[68:69], v[80:81]
	v_pk_fma_f32 v[72:73], v[26:27], v[68:69], v[72:73]
	v_add_f32_e32 v59, 1.0, v59
	v_rcp_f32_e32 v104, v59
	v_mul_f32_e32 v59, 0xbfb8aa3b, v87
	v_exp_f32_e32 v59, v59
	s_nop 0
	v_add_f32_e32 v59, 1.0, v59
	v_rcp_f32_e32 v105, v59
	s_nop 0
	v_pk_mul_f32 v[86:87], v[86:87], v[104:105]
	v_or_b32_e32 v104, 5, v40
	v_cvt_pk_bf16_f32 v91, v86, v87
	v_lshl_add_u32 v59, v104, 11, 0
	v_bitop3_b32 v86, v58, s2, v94 bitop3:0x6c
	v_add3_u32 v59, v59, v86, v41
	ds_write2st64_b64 v59, v[90:91], v[64:65] offset1:2
	v_pk_mul_f32 v[64:65], v[74:75], v[18:19] op_sel:[1,0]
	v_pk_mul_f32 v[74:75], v[74:75], v[16:17] op_sel:[1,0]
	v_pk_fma_f32 v[64:65], v[66:67], v[14:15], v[64:65] op_sel_hi:[0,1,1]
; #define GAS __attribute__((address_space(1)))
; #define LAS __attribute__((address_space(3)))
; __device__ __forceinline__ float fsigmoid(float x) { return __builtin_amdgcn_rcpf(1.f + __builtin_amdgcn_exp2f(-LOG2E * x)); }
; __device__ __forceinline__ f32x4 bf4_to_f32(u32x2 w) { return (f32x4){bflo(w.x), bfhi(w.x), bflo(w.y), bfhi(w.y)}; }
; __device__ __forceinline__ u32x2 f32_to_bf4(f32x4 v) { u32x2 w; w.x = cvtpk(v[0], v[1]); w.y = cvtpk(v[2], v[3]); return w; }
; __device__ __forceinline__ void prep_unit(LAS unsigned char* lds, const MixBufs& B, int b, int ch, int tid) {
;     ...
; #pragma unroll
;         for (int s = 0; s < 16; ++s) { const int row = 16 * strip + s;
;             const f32x4 x0 = bf4_to_f32(xr[s + 3]);
;             f32x4 cv = cb + cw[0] * x3 + cw[1] * x2 + cw[2] * x1 + cw[3] * x0, xc;
; #pragma unroll
;             for (int e = 0; e < 4; ++e) xc[e] = cv[e] * fsigmoid(cv[e]);
;             const int sw = row & 7, within = (gch & 1) * 8;
;             *(LAS u32x2*)(XA + row * 2048 + ((((gch >> 1)) ^ sw) << 4) + within) = f32_to_bf4(xc);
;             *(LAS u32x2*)(XA + row * 2048 + (((64 + (gch >> 1)) ^ sw) << 4) + within) = xr[s + 3];
;             const f32x4 v = wv[0] * x0[0] + wv[1] * x0[1] + wv[2] * x0[2] + wv[3] * x0[3];
;             *(GAS u32x2*)(B.xcm + (t0 + row) * 512 + 4 * gch) = f32_to_bf4(xc); *(GAS u32x2*)(B.vm + (t0 + row) * 512 + 4 * gch) = f32_to_bf4(v);
;             x3 = x2; x2 = x1; x1 = x0; }
	v_pk_fma_f32 v[74:75], v[66:67], v[12:13], v[74:75] op_sel_hi:[0,1,1]
	v_pk_fma_f32 v[64:65], v[68:69], v[10:11], v[64:65] op_sel_hi:[0,1,1]
	v_pk_fma_f32 v[74:75], v[68:69], v[8:9], v[74:75] op_sel_hi:[0,1,1]
	v_ashrrev_i32_e32 v105, 31, v104
	v_pk_fma_f32 v[64:65], v[92:93], v[6:7], v[64:65] op_sel:[1,0,0]
	v_pk_fma_f32 v[74:75], v[92:93], v[4:5], v[74:75] op_sel:[1,0,0]
	v_lshl_add_u64 v[92:93], s[16:17], 0, v[104:105]
	v_lshlrev_b64 v[92:93], 10, v[92:93]
	v_cvt_pk_bf16_f32 v74, v74, v75
	v_cvt_pk_bf16_f32 v75, v64, v65
	v_lshl_add_u64 v[64:65], s[0:1], 0, v[92:93]
	v_lshl_add_u64 v[104:105], s[50:51], 0, v[92:93]
	v_lshl_add_u64 v[64:65], v[64:65], 0, v[2:3]
	v_lshl_add_u64 v[104:105], v[104:105], 0, v[2:3]
	global_store_dwordx2 v[64:65], v[74:75], off
	v_pk_fma_f32 v[74:75], v[20:21], v[82:83], v[36:37]
	global_store_dwordx2 v[104:105], v[90:91], off
	v_and_b32_e32 v91, 0xffff0000, v62
	v_pk_fma_f32 v[74:75], v[24:25], v[70:71], v[74:75]
	v_lshlrev_b32_e32 v64, 16, v62
	v_mov_b32_e32 v65, v91
	v_pk_fma_f32 v[74:75], v[28:29], v[66:67], v[74:75]
	v_and_b32_e32 v93, 0xffff0000, v63
	v_pk_fma_f32 v[74:75], v[32:33], v[64:65], v[74:75]
	s_movk_i32 s2, 0x60
	v_mul_f32_e32 v59, 0xbfb8aa3b, v74
	v_exp_f32_e32 v59, v59
	v_and_b32_e32 v90, 16, v62
	v_and_b32_e32 v92, 16, v63
	v_pk_fma_f32 v[70:71], v[20:21], v[70:71], v[36:37]
	v_add_f32_e32 v59, 1.0, v59
	v_rcp_f32_e32 v82, v59
	v_mul_f32_e32 v59, 0xbfb8aa3b, v75
	v_exp_f32_e32 v59, v59
	v_pk_fma_f32 v[70:71], v[24:25], v[66:67], v[70:71]
	v_pk_fma_f32 v[68:69], v[22:23], v[68:69], v[38:39]
	v_pk_fma_f32 v[70:71], v[28:29], v[64:65], v[70:71]
	v_add_f32_e32 v59, 1.0, v59
	v_rcp_f32_e32 v83, v59
	s_nop 0
	v_pk_mul_f32 v[82:83], v[74:75], v[82:83]
	v_lshlrev_b32_e32 v74, 16, v63
	v_mov_b32_e32 v75, v93
	v_pk_fma_f32 v[80:81], v[34:35], v[74:75], v[80:81]
	v_cvt_pk_bf16_f32 v82, v82, v83
	v_mul_f32_e32 v59, 0xbfb8aa3b, v80
	v_exp_f32_e32 v59, v59
	v_pk_fma_f32 v[72:73], v[30:31], v[74:75], v[72:73]
	v_pk_fma_f32 v[68:69], v[26:27], v[74:75], v[68:69]
	v_add_f32_e32 v59, 1.0, v59
	v_rcp_f32_e32 v104, v59
	v_mul_f32_e32 v59, 0xbfb8aa3b, v81
	v_exp_f32_e32 v59, v59
	s_nop 0
	v_add_f32_e32 v59, 1.0, v59
	v_rcp_f32_e32 v105, v59
	s_nop 0
	v_pk_mul_f32 v[80:81], v[80:81], v[104:105]
	v_or_b32_e32 v104, 6, v40
	v_cvt_pk_bf16_f32 v83, v80, v81
	v_lshl_add_u32 v59, v104, 11, 0
	v_bitop3_b32 v80, v58, s2, v94 bitop3:0x6c
	v_add3_u32 v59, v59, v80, v41
	ds_write2st64_b64 v59, v[82:83], v[62:63] offset1:2
	v_pk_mul_f32 v[62:63], v[90:91], v[18:19] op_sel:[1,0]
	v_pk_mul_f32 v[90:91], v[90:91], v[16:17] op_sel:[1,0]
	v_pk_fma_f32 v[62:63], v[64:65], v[14:15], v[62:63] op_sel_hi:[0,1,1]
	v_pk_fma_f32 v[90:91], v[64:65], v[12:13], v[90:91] op_sel_hi:[0,1,1]
	v_pk_fma_f32 v[62:63], v[74:75], v[10:11], v[62:63] op_sel_hi:[0,1,1]
	v_pk_fma_f32 v[90:91], v[74:75], v[8:9], v[90:91] op_sel_hi:[0,1,1]
	v_ashrrev_i32_e32 v105, 31, v104
	v_pk_fma_f32 v[62:63], v[92:93], v[6:7], v[62:63] op_sel:[1,0,0]
	v_pk_fma_f32 v[90:91], v[92:93], v[4:5], v[90:91] op_sel:[1,0,0]
	v_lshl_add_u64 v[92:93], s[16:17], 0, v[104:105]
	v_lshlrev_b64 v[92:93], 10, v[92:93]
	v_lshl_add_u64 v[104:105], s[50:51], 0, v[92:93]
	v_lshl_add_u64 v[104:105], v[104:105], 0, v[2:3]
	global_store_dwordx2 v[104:105], v[82:83], off
	v_cvt_pk_bf16_f32 v83, v62, v63
	v_lshl_add_u64 v[62:63], s[0:1], 0, v[92:93]
	v_cvt_pk_bf16_f32 v82, v90, v91
	v_lshl_add_u64 v[62:63], v[62:63], 0, v[2:3]
	global_store_dwordx2 v[62:63], v[82:83], off
	v_and_b32_e32 v83, 0xffff0000, v60
	v_lshlrev_b32_e32 v62, 16, v60
	v_mov_b32_e32 v63, v83
	v_pk_fma_f32 v[70:71], v[32:33], v[62:63], v[70:71]
	v_and_b32_e32 v93, 0xffff0000, v61
	v_mul_f32_e32 v59, 0xbfb8aa3b, v70
	v_exp_f32_e32 v59, v59
	s_movk_i32 s2, 0x70
	v_and_b32_e32 v82, 16, v60
	v_and_b32_e32 v92, 16, v61
	v_add_f32_e32 v59, 1.0, v59
	v_rcp_f32_e32 v90, v59
	v_mul_f32_e32 v59, 0xbfb8aa3b, v71
	v_exp_f32_e32 v59, v59
	v_pk_fma_f32 v[74:75], v[22:23], v[74:75], v[38:39]
	v_add_f32_e32 v59, 1.0, v59
	v_rcp_f32_e32 v91, v59
	s_nop 0
	v_pk_mul_f32 v[90:91], v[70:71], v[90:91]
	v_lshlrev_b32_e32 v70, 16, v61
	v_mov_b32_e32 v71, v93
	v_pk_fma_f32 v[72:73], v[34:35], v[70:71], v[72:73]
	v_cvt_pk_bf16_f32 v90, v90, v91
	v_mul_f32_e32 v59, 0xbfb8aa3b, v72
	v_exp_f32_e32 v59, v59
	v_pk_fma_f32 v[68:69], v[30:31], v[70:71], v[68:69]
	v_pk_fma_f32 v[74:75], v[26:27], v[70:71], v[74:75]
	v_add_f32_e32 v59, 1.0, v59
	v_rcp_f32_e32 v104, v59
	v_mul_f32_e32 v59, 0xbfb8aa3b, v73
	v_exp_f32_e32 v59, v59
	s_nop 0
	v_add_f32_e32 v59, 1.0, v59
	v_rcp_f32_e32 v105, v59
	s_nop 0
	v_pk_mul_f32 v[72:73], v[72:73], v[104:105]
	v_or_b32_e32 v104, 7, v40
	v_cvt_pk_bf16_f32 v91, v72, v73
	v_lshl_add_u32 v59, v104, 11, 0
	v_bitop3_b32 v72, v58, s2, v94 bitop3:0x6c
	v_add3_u32 v58, v59, v72, v41
	ds_write2st64_b64 v58, v[90:91], v[60:61] offset1:2
	v_pk_mul_f32 v[58:59], v[82:83], v[18:19] op_sel:[1,0]
	v_pk_mul_f32 v[60:61], v[82:83], v[16:17] op_sel:[1,0]
	v_pk_fma_f32 v[58:59], v[62:63], v[14:15], v[58:59] op_sel_hi:[0,1,1]
	v_pk_fma_f32 v[60:61], v[62:63], v[12:13], v[60:61] op_sel_hi:[0,1,1]
	v_ashrrev_i32_e32 v105, 31, v104
	v_pk_fma_f32 v[58:59], v[70:71], v[10:11], v[58:59] op_sel_hi:[0,1,1]
	v_pk_fma_f32 v[60:61], v[70:71], v[8:9], v[60:61] op_sel_hi:[0,1,1]
	v_lshl_add_u64 v[82:83], s[16:17], 0, v[104:105]
	v_pk_fma_f32 v[58:59], v[92:93], v[6:7], v[58:59] op_sel:[1,0,0]
	v_pk_fma_f32 v[60:61], v[92:93], v[4:5], v[60:61] op_sel:[1,0,0]
	v_lshlrev_b64 v[82:83], 10, v[82:83]
	v_cvt_pk_bf16_f32 v60, v60, v61
	v_cvt_pk_bf16_f32 v61, v58, v59
	v_lshl_add_u64 v[58:59], s[0:1], 0, v[82:83]
	v_lshl_add_u64 v[58:59], v[58:59], 0, v[2:3]
; #define GAS __attribute__((address_space(1)))
; #define LAS __attribute__((address_space(3)))
; __device__ __forceinline__ float fsigmoid(float x) { return __builtin_amdgcn_rcpf(1.f + __builtin_amdgcn_exp2f(-LOG2E * x)); }
; __device__ __forceinline__ f32x4 bf4_to_f32(u32x2 w) { return (f32x4){bflo(w.x), bfhi(w.x), bflo(w.y), bfhi(w.y)}; }
; __device__ __forceinline__ u32x2 f32_to_bf4(f32x4 v) { u32x2 w; w.x = cvtpk(v[0], v[1]); w.y = cvtpk(v[2], v[3]); return w; }
; __device__ __forceinline__ void prep_unit(LAS unsigned char* lds, const MixBufs& B, int b, int ch, int tid) {
;     ...
; #pragma unroll
;         for (int s = 0; s < 16; ++s) { const int row = 16 * strip + s;
;             const f32x4 x0 = bf4_to_f32(xr[s + 3]);
;             f32x4 cv = cb + cw[0] * x3 + cw[1] * x2 + cw[2] * x1 + cw[3] * x0, xc;
; #pragma unroll
;             for (int e = 0; e < 4; ++e) xc[e] = cv[e] * fsigmoid(cv[e]);
;             const int sw = row & 7, within = (gch & 1) * 8;
;             *(LAS u32x2*)(XA + row * 2048 + ((((gch >> 1)) ^ sw) << 4) + within) = f32_to_bf4(xc);
;             *(LAS u32x2*)(XA + row * 2048 + (((64 + (gch >> 1)) ^ sw) << 4) + within) = xr[s + 3];
;             const f32x4 v = wv[0] * x0[0] + wv[1] * x0[1] + wv[2] * x0[2] + wv[3] * x0[3];
;             *(GAS u32x2*)(B.xcm + (t0 + row) * 512 + 4 * gch) = f32_to_bf4(xc); *(GAS u32x2*)(B.vm + (t0 + row) * 512 + 4 * gch) = f32_to_bf4(v);
;             x3 = x2; x2 = x1; x1 = x0; }
	global_store_dwordx2 v[58:59], v[60:61], off
	v_pk_fma_f32 v[60:61], v[20:21], v[66:67], v[36:37]
	v_lshl_add_u64 v[92:93], s[50:51], 0, v[82:83]
	v_and_b32_e32 v83, 0xffff0000, v56
	v_pk_fma_f32 v[60:61], v[24:25], v[64:65], v[60:61]
	v_lshlrev_b32_e32 v58, 16, v56
	v_mov_b32_e32 v59, v83
	v_pk_fma_f32 v[60:61], v[28:29], v[62:63], v[60:61]
	v_lshl_add_u64 v[92:93], v[92:93], 0, v[2:3]
	v_pk_fma_f32 v[60:61], v[32:33], v[58:59], v[60:61]
	global_store_dwordx2 v[92:93], v[90:91], off
	v_mul_f32_e32 v66, 0xbfb8aa3b, v60
	v_mul_f32_e32 v67, 0xbfb8aa3b, v61
	v_exp_f32_e32 v66, v66
	v_exp_f32_e32 v67, v67
	v_and_b32_e32 v91, 0xffff0000, v57
	v_and_b32_e32 v82, 16, v56
	v_add_f32_e32 v66, 1.0, v66
	v_add_f32_e32 v67, 1.0, v67
	v_rcp_f32_e32 v66, v66
	v_rcp_f32_e32 v67, v67
	v_and_b32_e32 v90, 16, v57
	v_pk_fma_f32 v[64:65], v[20:21], v[64:65], v[36:37]
	v_pk_fma_f32 v[70:71], v[22:23], v[70:71], v[38:39]
	v_pk_mul_f32 v[66:67], v[60:61], v[66:67]
	v_lshlrev_b32_e32 v60, 16, v57
	v_mov_b32_e32 v61, v91
	v_pk_fma_f32 v[68:69], v[34:35], v[60:61], v[68:69]
	v_cvt_pk_bf16_f32 v66, v66, v67
	v_mul_f32_e32 v73, 0xbfb8aa3b, v68
	v_exp_f32_e32 v73, v73
	v_pk_fma_f32 v[64:65], v[24:25], v[62:63], v[64:65]
	v_pk_fma_f32 v[74:75], v[30:31], v[60:61], v[74:75]
	v_pk_fma_f32 v[64:65], v[28:29], v[58:59], v[64:65]
	v_add_f32_e32 v73, 1.0, v73
	v_rcp_f32_e32 v92, v73
	v_mul_f32_e32 v73, 0xbfb8aa3b, v69
	v_exp_f32_e32 v73, v73
	v_pk_fma_f32 v[62:63], v[20:21], v[62:63], v[36:37]
	v_pk_fma_f32 v[70:71], v[26:27], v[60:61], v[70:71]
	v_pk_fma_f32 v[62:63], v[24:25], v[58:59], v[62:63]
	v_add_f32_e32 v73, 1.0, v73
	v_rcp_f32_e32 v93, v73
	s_lshl_b32 s2, s18, 2
	v_pk_mul_f32 v[68:69], v[68:69], v[92:93]
	v_or_b32_e32 v92, 8, v40
	v_cvt_pk_bf16_f32 v67, v68, v69
	v_lshl_add_u32 v68, v92, 11, 0
	v_add3_u32 v68, v68, v101, v41
	ds_write2st64_b64 v68, v[66:67], v[56:57] offset1:2
	v_pk_mul_f32 v[56:57], v[82:83], v[18:19] op_sel:[1,0]
	v_pk_mul_f32 v[68:69], v[82:83], v[16:17] op_sel:[1,0]
	v_ashrrev_i32_e32 v93, 31, v92
	v_pk_fma_f32 v[56:57], v[58:59], v[14:15], v[56:57] op_sel_hi:[0,1,1]
	v_pk_fma_f32 v[68:69], v[58:59], v[12:13], v[68:69] op_sel_hi:[0,1,1]
	v_lshl_add_u64 v[82:83], s[16:17], 0, v[92:93]
	v_pk_fma_f32 v[56:57], v[60:61], v[10:11], v[56:57] op_sel_hi:[0,1,1]
	v_pk_fma_f32 v[68:69], v[60:61], v[8:9], v[68:69] op_sel_hi:[0,1,1]
	v_lshlrev_b64 v[82:83], 10, v[82:83]
	v_pk_fma_f32 v[56:57], v[90:91], v[6:7], v[56:57] op_sel:[1,0,0]
	v_pk_fma_f32 v[68:69], v[90:91], v[4:5], v[68:69] op_sel:[1,0,0]
	v_lshl_add_u64 v[90:91], s[50:51], 0, v[82:83]
	v_lshl_add_u64 v[90:91], v[90:91], 0, v[2:3]
	global_store_dwordx2 v[90:91], v[66:67], off
	v_cvt_pk_bf16_f32 v67, v56, v57
	v_lshl_add_u64 v[56:57], s[0:1], 0, v[82:83]
	v_cvt_pk_bf16_f32 v66, v68, v69
	v_lshl_add_u64 v[56:57], v[56:57], 0, v[2:3]
	global_store_dwordx2 v[56:57], v[66:67], off
	v_and_b32_e32 v67, 0xffff0000, v54
	v_lshlrev_b32_e32 v56, 16, v54
	v_mov_b32_e32 v57, v67
	v_pk_fma_f32 v[64:65], v[32:33], v[56:57], v[64:65]
	v_and_b32_e32 v83, 0xffff0000, v55
	v_mul_f32_e32 v68, 0xbfb8aa3b, v64
	v_mul_f32_e32 v69, 0xbfb8aa3b, v65
	v_exp_f32_e32 v68, v68
	v_exp_f32_e32 v69, v69
	v_and_b32_e32 v66, 16, v54
	v_and_b32_e32 v82, 16, v55
	v_add_f32_e32 v68, 1.0, v68
	v_add_f32_e32 v69, 1.0, v69
	v_rcp_f32_e32 v68, v68
	v_rcp_f32_e32 v69, v69
	v_pk_fma_f32 v[62:63], v[28:29], v[56:57], v[62:63]
	v_pk_fma_f32 v[58:59], v[20:21], v[58:59], v[36:37]
	v_pk_fma_f32 v[60:61], v[22:23], v[60:61], v[38:39]
	v_pk_mul_f32 v[68:69], v[64:65], v[68:69]
	v_lshlrev_b32_e32 v64, 16, v55
	v_mov_b32_e32 v65, v83
	v_pk_fma_f32 v[74:75], v[34:35], v[64:65], v[74:75]
	v_cvt_pk_bf16_f32 v68, v68, v69
	v_mul_f32_e32 v73, 0xbfb8aa3b, v74
	v_exp_f32_e32 v73, v73
	v_pk_fma_f32 v[70:71], v[30:31], v[64:65], v[70:71]
	v_pk_fma_f32 v[58:59], v[24:25], v[56:57], v[58:59]
	v_pk_fma_f32 v[60:61], v[26:27], v[64:65], v[60:61]
	v_add_f32_e32 v73, 1.0, v73
	v_rcp_f32_e32 v90, v73
	v_mul_f32_e32 v73, 0xbfb8aa3b, v75
	v_exp_f32_e32 v73, v73
	s_nop 0
	v_add_f32_e32 v73, 1.0, v73
	v_rcp_f32_e32 v91, v73
	s_nop 0
	v_pk_mul_f32 v[74:75], v[74:75], v[90:91]
	v_or_b32_e32 v90, 9, v40
	v_lshl_add_u32 v73, v90, 11, 0
	v_cvt_pk_bf16_f32 v69, v74, v75
	v_add3_u32 v73, v73, v102, v41
	ds_write2st64_b64 v73, v[68:69], v[54:55] offset1:2
	v_pk_mul_f32 v[54:55], v[66:67], v[18:19] op_sel:[1,0]
	v_pk_mul_f32 v[66:67], v[66:67], v[16:17] op_sel:[1,0]
	v_pk_fma_f32 v[54:55], v[56:57], v[14:15], v[54:55] op_sel_hi:[0,1,1]
	v_pk_fma_f32 v[66:67], v[56:57], v[12:13], v[66:67] op_sel_hi:[0,1,1]
	v_ashrrev_i32_e32 v91, 31, v90
	v_pk_fma_f32 v[54:55], v[64:65], v[10:11], v[54:55] op_sel_hi:[0,1,1]
	v_pk_fma_f32 v[66:67], v[64:65], v[8:9], v[66:67] op_sel_hi:[0,1,1]
	v_lshl_add_u64 v[74:75], s[16:17], 0, v[90:91]
	v_pk_fma_f32 v[54:55], v[82:83], v[6:7], v[54:55] op_sel:[1,0,0]
	v_pk_fma_f32 v[66:67], v[82:83], v[4:5], v[66:67] op_sel:[1,0,0]
	v_lshlrev_b64 v[74:75], 10, v[74:75]
	v_cvt_pk_bf16_f32 v66, v66, v67
	v_cvt_pk_bf16_f32 v67, v54, v55
	v_lshl_add_u64 v[54:55], s[0:1], 0, v[74:75]
	v_lshl_add_u64 v[54:55], v[54:55], 0, v[2:3]
	global_store_dwordx2 v[54:55], v[66:67], off
	v_and_b32_e32 v67, 0xffff0000, v52
	v_lshl_add_u64 v[82:83], s[50:51], 0, v[74:75]
	v_lshlrev_b32_e32 v54, 16, v52
	v_mov_b32_e32 v55, v67
	v_lshl_add_u64 v[82:83], v[82:83], 0, v[2:3]
	v_pk_fma_f32 v[62:63], v[32:33], v[54:55], v[62:63]
	global_store_dwordx2 v[82:83], v[68:69], off
	v_mul_f32_e32 v68, 0xbfb8aa3b, v62
	v_mul_f32_e32 v69, 0xbfb8aa3b, v63
	v_exp_f32_e32 v68, v68
	v_exp_f32_e32 v69, v69
	v_and_b32_e32 v75, 0xffff0000, v53
	v_and_b32_e32 v66, 16, v52
	v_add_f32_e32 v68, 1.0, v68
; #define GAS __attribute__((address_space(1)))
; #define LAS __attribute__((address_space(3)))
; __device__ __forceinline__ float fsigmoid(float x) { return __builtin_amdgcn_rcpf(1.f + __builtin_amdgcn_exp2f(-LOG2E * x)); }
; __device__ __forceinline__ f32x4 bf4_to_f32(u32x2 w) { return (f32x4){bflo(w.x), bfhi(w.x), bflo(w.y), bfhi(w.y)}; }
; __device__ __forceinline__ u32x2 f32_to_bf4(f32x4 v) { u32x2 w; w.x = cvtpk(v[0], v[1]); w.y = cvtpk(v[2], v[3]); return w; }
; __device__ __forceinline__ void prep_unit(LAS unsigned char* lds, const MixBufs& B, int b, int ch, int tid) {
;     ...
; #pragma unroll
;         for (int s = 0; s < 16; ++s) { const int row = 16 * strip + s;
;             const f32x4 x0 = bf4_to_f32(xr[s + 3]);
;             f32x4 cv = cb + cw[0] * x3 + cw[1] * x2 + cw[2] * x1 + cw[3] * x0, xc;
; #pragma unroll
;             for (int e = 0; e < 4; ++e) xc[e] = cv[e] * fsigmoid(cv[e]);
;             const int sw = row & 7, within = (gch & 1) * 8;
;             *(LAS u32x2*)(XA + row * 2048 + ((((gch >> 1)) ^ sw) << 4) + within) = f32_to_bf4(xc);
;             *(LAS u32x2*)(XA + row * 2048 + (((64 + (gch >> 1)) ^ sw) << 4) + within) = xr[s + 3];
;             const f32x4 v = wv[0] * x0[0] + wv[1] * x0[1] + wv[2] * x0[2] + wv[3] * x0[3];
;             *(GAS u32x2*)(B.xcm + (t0 + row) * 512 + 4 * gch) = f32_to_bf4(xc); *(GAS u32x2*)(B.vm + (t0 + row) * 512 + 4 * gch) = f32_to_bf4(v);
;             x3 = x2; x2 = x1; x1 = x0; }
	v_add_f32_e32 v69, 1.0, v69
	v_rcp_f32_e32 v68, v68
	v_rcp_f32_e32 v69, v69
	v_and_b32_e32 v74, 16, v53
	v_pk_fma_f32 v[58:59], v[28:29], v[54:55], v[58:59]
	v_pk_fma_f32 v[56:57], v[20:21], v[56:57], v[36:37]
	v_pk_mul_f32 v[68:69], v[62:63], v[68:69]
	v_lshlrev_b32_e32 v62, 16, v53
	v_mov_b32_e32 v63, v75
	v_pk_fma_f32 v[70:71], v[34:35], v[62:63], v[70:71]
	v_cvt_pk_bf16_f32 v68, v68, v69
	v_mul_f32_e32 v73, 0xbfb8aa3b, v70
	v_exp_f32_e32 v73, v73
	v_pk_fma_f32 v[60:61], v[30:31], v[62:63], v[60:61]
	v_pk_fma_f32 v[56:57], v[24:25], v[54:55], v[56:57]
	v_pk_fma_f32 v[64:65], v[22:23], v[64:65], v[38:39]
	v_add_f32_e32 v73, 1.0, v73
	v_rcp_f32_e32 v82, v73
	v_mul_f32_e32 v73, 0xbfb8aa3b, v71
	v_exp_f32_e32 v73, v73
	v_pk_fma_f32 v[64:65], v[26:27], v[62:63], v[64:65]
	v_add_f32_e32 v73, 1.0, v73
	v_rcp_f32_e32 v83, v73
	s_nop 0
	v_pk_mul_f32 v[70:71], v[70:71], v[82:83]
	v_or_b32_e32 v82, 10, v40
	v_cvt_pk_bf16_f32 v69, v70, v71
	v_lshl_add_u32 v70, v82, 11, 0
	v_add3_u32 v70, v70, v88, v41
	ds_write2st64_b64 v70, v[68:69], v[52:53] offset1:2
	v_pk_mul_f32 v[52:53], v[66:67], v[18:19] op_sel:[1,0]
	v_pk_mul_f32 v[66:67], v[66:67], v[16:17] op_sel:[1,0]
	v_pk_fma_f32 v[52:53], v[54:55], v[14:15], v[52:53] op_sel_hi:[0,1,1]
	v_pk_fma_f32 v[66:67], v[54:55], v[12:13], v[66:67] op_sel_hi:[0,1,1]
	v_ashrrev_i32_e32 v83, 31, v82
	v_pk_fma_f32 v[52:53], v[62:63], v[10:11], v[52:53] op_sel_hi:[0,1,1]
	v_pk_fma_f32 v[66:67], v[62:63], v[8:9], v[66:67] op_sel_hi:[0,1,1]
	v_lshl_add_u64 v[70:71], s[16:17], 0, v[82:83]
	v_pk_fma_f32 v[52:53], v[74:75], v[6:7], v[52:53] op_sel:[1,0,0]
	v_pk_fma_f32 v[66:67], v[74:75], v[4:5], v[66:67] op_sel:[1,0,0]
	v_lshlrev_b64 v[70:71], 10, v[70:71]
	v_cvt_pk_bf16_f32 v66, v66, v67
	v_cvt_pk_bf16_f32 v67, v52, v53
	v_lshl_add_u64 v[52:53], s[0:1], 0, v[70:71]
	v_lshl_add_u64 v[52:53], v[52:53], 0, v[2:3]
	global_store_dwordx2 v[52:53], v[66:67], off
	v_and_b32_e32 v67, 0xffff0000, v50
	v_lshl_add_u64 v[74:75], s[50:51], 0, v[70:71]
	v_lshlrev_b32_e32 v52, 16, v50
	v_mov_b32_e32 v53, v67
	v_lshl_add_u64 v[74:75], v[74:75], 0, v[2:3]
	v_pk_fma_f32 v[58:59], v[32:33], v[52:53], v[58:59]
	global_store_dwordx2 v[74:75], v[68:69], off
	v_mul_f32_e32 v68, 0xbfb8aa3b, v58
	v_mul_f32_e32 v69, 0xbfb8aa3b, v59
	v_exp_f32_e32 v68, v68
	v_exp_f32_e32 v69, v69
	v_and_b32_e32 v71, 0xffff0000, v51
	v_and_b32_e32 v66, 16, v50
	v_add_f32_e32 v68, 1.0, v68
	v_add_f32_e32 v69, 1.0, v69
	v_rcp_f32_e32 v68, v68
	v_rcp_f32_e32 v69, v69
	v_and_b32_e32 v70, 16, v51
	v_pk_fma_f32 v[56:57], v[28:29], v[52:53], v[56:57]
	v_pk_fma_f32 v[54:55], v[20:21], v[54:55], v[36:37]
	v_pk_mul_f32 v[68:69], v[58:59], v[68:69]
	v_lshlrev_b32_e32 v58, 16, v51
	v_mov_b32_e32 v59, v71
	v_pk_fma_f32 v[60:61], v[34:35], v[58:59], v[60:61]
	v_cvt_pk_bf16_f32 v68, v68, v69
	v_mul_f32_e32 v73, 0xbfb8aa3b, v60
	v_exp_f32_e32 v73, v73
	v_pk_fma_f32 v[64:65], v[30:31], v[58:59], v[64:65]
	v_pk_fma_f32 v[54:55], v[24:25], v[52:53], v[54:55]
	v_pk_fma_f32 v[62:63], v[22:23], v[62:63], v[38:39]
	v_add_f32_e32 v73, 1.0, v73
	v_rcp_f32_e32 v74, v73
	v_mul_f32_e32 v73, 0xbfb8aa3b, v61
	v_exp_f32_e32 v73, v73
	v_pk_fma_f32 v[62:63], v[26:27], v[58:59], v[62:63]
	v_add_f32_e32 v73, 1.0, v73
	v_rcp_f32_e32 v75, v73
	s_nop 0
	v_pk_mul_f32 v[60:61], v[60:61], v[74:75]
	v_or_b32_e32 v74, 11, v40
	v_cvt_pk_bf16_f32 v69, v60, v61
	v_lshl_add_u32 v60, v74, 11, 0
	v_add3_u32 v60, v60, v84, v41
	ds_write2st64_b64 v60, v[68:69], v[50:51] offset1:2
	v_pk_mul_f32 v[50:51], v[66:67], v[18:19] op_sel:[1,0]
	v_pk_mul_f32 v[60:61], v[66:67], v[16:17] op_sel:[1,0]
	v_pk_fma_f32 v[50:51], v[52:53], v[14:15], v[50:51] op_sel_hi:[0,1,1]
	v_pk_fma_f32 v[60:61], v[52:53], v[12:13], v[60:61] op_sel_hi:[0,1,1]
	v_ashrrev_i32_e32 v75, 31, v74
	v_pk_fma_f32 v[50:51], v[58:59], v[10:11], v[50:51] op_sel_hi:[0,1,1]
	v_pk_fma_f32 v[60:61], v[58:59], v[8:9], v[60:61] op_sel_hi:[0,1,1]
	v_lshl_add_u64 v[66:67], s[16:17], 0, v[74:75]
	v_pk_fma_f32 v[50:51], v[70:71], v[6:7], v[50:51] op_sel:[1,0,0]
	v_pk_fma_f32 v[60:61], v[70:71], v[4:5], v[60:61] op_sel:[1,0,0]
	v_lshlrev_b64 v[66:67], 10, v[66:67]
	v_cvt_pk_bf16_f32 v60, v60, v61
	v_cvt_pk_bf16_f32 v61, v50, v51
	v_lshl_add_u64 v[50:51], s[0:1], 0, v[66:67]
	v_lshl_add_u64 v[50:51], v[50:51], 0, v[2:3]
	global_store_dwordx2 v[50:51], v[60:61], off
	v_and_b32_e32 v61, 0xffff0000, v48
	v_lshlrev_b32_e32 v50, 16, v48
	v_mov_b32_e32 v51, v61
	v_pk_fma_f32 v[56:57], v[32:33], v[50:51], v[56:57]
	v_lshl_add_u64 v[70:71], s[50:51], 0, v[66:67]
	v_mul_f32_e32 v66, 0xbfb8aa3b, v56
	v_mul_f32_e32 v67, 0xbfb8aa3b, v57
	v_exp_f32_e32 v66, v66
	v_exp_f32_e32 v67, v67
	v_lshl_add_u64 v[70:71], v[70:71], 0, v[2:3]
	global_store_dwordx2 v[70:71], v[68:69], off
	v_add_f32_e32 v66, 1.0, v66
	v_add_f32_e32 v67, 1.0, v67
	v_rcp_f32_e32 v66, v66
	v_rcp_f32_e32 v67, v67
	v_and_b32_e32 v69, 0xffff0000, v49
	v_and_b32_e32 v60, 16, v48
	v_and_b32_e32 v68, 16, v49
	v_pk_mul_f32 v[66:67], v[56:57], v[66:67]
	v_lshlrev_b32_e32 v56, 16, v49
	v_mov_b32_e32 v57, v69
	v_pk_fma_f32 v[64:65], v[34:35], v[56:57], v[64:65]
	v_cvt_pk_bf16_f32 v66, v66, v67
	v_mul_f32_e32 v70, 0xbfb8aa3b, v64
	v_mul_f32_e32 v71, 0xbfb8aa3b, v65
	v_exp_f32_e32 v70, v70
	v_exp_f32_e32 v71, v71
	v_pk_fma_f32 v[54:55], v[28:29], v[50:51], v[54:55]
	v_pk_fma_f32 v[62:63], v[30:31], v[56:57], v[62:63]
	v_add_f32_e32 v70, 1.0, v70
	v_add_f32_e32 v71, 1.0, v71
	v_rcp_f32_e32 v70, v70
	v_rcp_f32_e32 v71, v71
	v_pk_fma_f32 v[52:53], v[20:21], v[52:53], v[36:37]
	v_pk_fma_f32 v[58:59], v[22:23], v[58:59], v[38:39]
	v_pk_fma_f32 v[52:53], v[24:25], v[50:51], v[52:53]
	v_pk_mul_f32 v[64:65], v[64:65], v[70:71]
; #define GAS __attribute__((address_space(1)))
; #define LAS __attribute__((address_space(3)))
; __device__ __forceinline__ float fsigmoid(float x) { return __builtin_amdgcn_rcpf(1.f + __builtin_amdgcn_exp2f(-LOG2E * x)); }
; __device__ __forceinline__ f32x4 bf4_to_f32(u32x2 w) { return (f32x4){bflo(w.x), bfhi(w.x), bflo(w.y), bfhi(w.y)}; }
; __device__ __forceinline__ u32x2 f32_to_bf4(f32x4 v) { u32x2 w; w.x = cvtpk(v[0], v[1]); w.y = cvtpk(v[2], v[3]); return w; }
; __device__ __forceinline__ void prep_unit(LAS unsigned char* lds, const MixBufs& B, int b, int ch, int tid) {
;     ...
; #pragma unroll
;         for (int s = 0; s < 16; ++s) { const int row = 16 * strip + s;
;             const f32x4 x0 = bf4_to_f32(xr[s + 3]);
;             f32x4 cv = cb + cw[0] * x3 + cw[1] * x2 + cw[2] * x1 + cw[3] * x0, xc;
; #pragma unroll
;             for (int e = 0; e < 4; ++e) xc[e] = cv[e] * fsigmoid(cv[e]);
;             const int sw = row & 7, within = (gch & 1) * 8;
;             *(LAS u32x2*)(XA + row * 2048 + ((((gch >> 1)) ^ sw) << 4) + within) = f32_to_bf4(xc);
;             *(LAS u32x2*)(XA + row * 2048 + (((64 + (gch >> 1)) ^ sw) << 4) + within) = xr[s + 3];
;             const f32x4 v = wv[0] * x0[0] + wv[1] * x0[1] + wv[2] * x0[2] + wv[3] * x0[3];
;             *(GAS u32x2*)(B.xcm + (t0 + row) * 512 + 4 * gch) = f32_to_bf4(xc); *(GAS u32x2*)(B.vm + (t0 + row) * 512 + 4 * gch) = f32_to_bf4(v);
;             x3 = x2; x2 = x1; x1 = x0; }
	v_or_b32_e32 v70, 12, v40
	v_cvt_pk_bf16_f32 v67, v64, v65
	v_lshl_add_u32 v64, v70, 11, 0
	v_add3_u32 v64, v64, v85, v41
	ds_write2st64_b64 v64, v[66:67], v[48:49] offset1:2
	v_pk_mul_f32 v[48:49], v[60:61], v[18:19] op_sel:[1,0]
	v_pk_mul_f32 v[60:61], v[60:61], v[16:17] op_sel:[1,0]
	v_pk_fma_f32 v[48:49], v[50:51], v[14:15], v[48:49] op_sel_hi:[0,1,1]
	v_pk_fma_f32 v[60:61], v[50:51], v[12:13], v[60:61] op_sel_hi:[0,1,1]
	v_ashrrev_i32_e32 v71, 31, v70
	v_pk_fma_f32 v[48:49], v[56:57], v[10:11], v[48:49] op_sel_hi:[0,1,1]
	v_pk_fma_f32 v[60:61], v[56:57], v[8:9], v[60:61] op_sel_hi:[0,1,1]
	v_lshl_add_u64 v[64:65], s[16:17], 0, v[70:71]
	v_pk_fma_f32 v[48:49], v[68:69], v[6:7], v[48:49] op_sel:[1,0,0]
	v_pk_fma_f32 v[60:61], v[68:69], v[4:5], v[60:61] op_sel:[1,0,0]
	v_lshlrev_b64 v[64:65], 10, v[64:65]
	v_cvt_pk_bf16_f32 v60, v60, v61
	v_cvt_pk_bf16_f32 v61, v48, v49
	v_lshl_add_u64 v[48:49], s[0:1], 0, v[64:65]
	v_lshl_add_u64 v[48:49], v[48:49], 0, v[2:3]
	global_store_dwordx2 v[48:49], v[60:61], off
	v_and_b32_e32 v61, 0xffff0000, v46
	v_lshlrev_b32_e32 v48, 16, v46
	v_mov_b32_e32 v49, v61
	v_pk_fma_f32 v[54:55], v[32:33], v[48:49], v[54:55]
	v_lshl_add_u64 v[68:69], s[50:51], 0, v[64:65]
	v_mul_f32_e32 v64, 0xbfb8aa3b, v54
	v_mul_f32_e32 v65, 0xbfb8aa3b, v55
	v_exp_f32_e32 v64, v64
	v_exp_f32_e32 v65, v65
	v_lshl_add_u64 v[68:69], v[68:69], 0, v[2:3]
	global_store_dwordx2 v[68:69], v[66:67], off
	v_add_f32_e32 v64, 1.0, v64
	v_add_f32_e32 v65, 1.0, v65
	v_rcp_f32_e32 v64, v64
	v_rcp_f32_e32 v65, v65
	v_and_b32_e32 v67, 0xffff0000, v47
	v_and_b32_e32 v60, 16, v46
	v_and_b32_e32 v66, 16, v47
	v_pk_mul_f32 v[64:65], v[54:55], v[64:65]
	v_lshlrev_b32_e32 v54, 16, v47
	v_mov_b32_e32 v55, v67
	v_pk_fma_f32 v[62:63], v[34:35], v[54:55], v[62:63]
	v_cvt_pk_bf16_f32 v64, v64, v65
	v_mul_f32_e32 v68, 0xbfb8aa3b, v62
	v_mul_f32_e32 v69, 0xbfb8aa3b, v63
	v_exp_f32_e32 v68, v68
	v_exp_f32_e32 v69, v69
	v_pk_fma_f32 v[52:53], v[28:29], v[48:49], v[52:53]
	v_pk_fma_f32 v[58:59], v[26:27], v[56:57], v[58:59]
	v_add_f32_e32 v68, 1.0, v68
	v_add_f32_e32 v69, 1.0, v69
	v_rcp_f32_e32 v68, v68
	v_rcp_f32_e32 v69, v69
	v_pk_fma_f32 v[58:59], v[30:31], v[54:55], v[58:59]
	v_pk_fma_f32 v[20:21], v[20:21], v[50:51], v[36:37]
	v_pk_fma_f32 v[22:23], v[22:23], v[56:57], v[38:39]
	v_pk_mul_f32 v[62:63], v[62:63], v[68:69]
	v_or_b32_e32 v68, 13, v40
	v_cvt_pk_bf16_f32 v65, v62, v63
	v_lshl_add_u32 v62, v68, 11, 0
	v_add3_u32 v62, v62, v86, v41
	ds_write2st64_b64 v62, v[64:65], v[46:47] offset1:2
	v_pk_mul_f32 v[46:47], v[60:61], v[18:19] op_sel:[1,0]
	v_pk_mul_f32 v[60:61], v[60:61], v[16:17] op_sel:[1,0]
	v_pk_fma_f32 v[46:47], v[48:49], v[14:15], v[46:47] op_sel_hi:[0,1,1]
	v_pk_fma_f32 v[60:61], v[48:49], v[12:13], v[60:61] op_sel_hi:[0,1,1]
	v_ashrrev_i32_e32 v69, 31, v68
	v_pk_fma_f32 v[46:47], v[54:55], v[10:11], v[46:47] op_sel_hi:[0,1,1]
	v_pk_fma_f32 v[60:61], v[54:55], v[8:9], v[60:61] op_sel_hi:[0,1,1]
	v_lshl_add_u64 v[62:63], s[16:17], 0, v[68:69]
	v_pk_fma_f32 v[46:47], v[66:67], v[6:7], v[46:47] op_sel:[1,0,0]
	v_pk_fma_f32 v[60:61], v[66:67], v[4:5], v[60:61] op_sel:[1,0,0]
	v_lshlrev_b64 v[62:63], 10, v[62:63]
	v_cvt_pk_bf16_f32 v60, v60, v61
	v_cvt_pk_bf16_f32 v61, v46, v47
	v_lshl_add_u64 v[46:47], s[0:1], 0, v[62:63]
	v_lshl_add_u64 v[46:47], v[46:47], 0, v[2:3]
	global_store_dwordx2 v[46:47], v[60:61], off
	v_and_b32_e32 v61, 0xffff0000, v44
	v_lshlrev_b32_e32 v46, 16, v44
	v_mov_b32_e32 v47, v61
	v_pk_fma_f32 v[52:53], v[32:33], v[46:47], v[52:53]
	v_lshl_add_u64 v[66:67], s[50:51], 0, v[62:63]
	v_mul_f32_e32 v62, 0xbfb8aa3b, v52
	v_mul_f32_e32 v63, 0xbfb8aa3b, v53
	v_exp_f32_e32 v62, v62
	v_exp_f32_e32 v63, v63
	v_lshl_add_u64 v[66:67], v[66:67], 0, v[2:3]
	global_store_dwordx2 v[66:67], v[64:65], off
	v_add_f32_e32 v62, 1.0, v62
	v_add_f32_e32 v63, 1.0, v63
	v_rcp_f32_e32 v62, v62
	v_rcp_f32_e32 v63, v63
	v_and_b32_e32 v65, 0xffff0000, v45
	v_and_b32_e32 v60, 16, v44
	v_and_b32_e32 v64, 16, v45
	v_pk_mul_f32 v[52:53], v[52:53], v[62:63]
	v_lshlrev_b32_e32 v62, 16, v45
	v_mov_b32_e32 v63, v65
	v_pk_fma_f32 v[58:59], v[34:35], v[62:63], v[58:59]
	v_cvt_pk_bf16_f32 v52, v52, v53
	v_mul_f32_e32 v66, 0xbfb8aa3b, v58
	v_mul_f32_e32 v67, 0xbfb8aa3b, v59
	v_exp_f32_e32 v66, v66
	v_exp_f32_e32 v67, v67
	v_pk_fma_f32 v[20:21], v[24:25], v[48:49], v[20:21]
	v_pk_fma_f32 v[22:23], v[26:27], v[54:55], v[22:23]
	v_add_f32_e32 v66, 1.0, v66
	v_add_f32_e32 v67, 1.0, v67
	v_rcp_f32_e32 v66, v66
	v_rcp_f32_e32 v67, v67
	v_pk_fma_f32 v[20:21], v[28:29], v[46:47], v[20:21]
	v_and_b32_e32 v29, 0xffff0000, v43
	v_pk_fma_f32 v[22:23], v[30:31], v[62:63], v[22:23]
	v_pk_mul_f32 v[58:59], v[58:59], v[66:67]
	v_or_b32_e32 v66, 14, v40
	v_lshl_add_u32 v40, v66, 11, 0
	v_cvt_pk_bf16_f32 v53, v58, v59
	v_add3_u32 v40, v40, v80, v41
	ds_write2st64_b64 v40, v[52:53], v[44:45] offset1:2
	v_pk_mul_f32 v[44:45], v[60:61], v[18:19] op_sel:[1,0]
	v_pk_mul_f32 v[58:59], v[60:61], v[16:17] op_sel:[1,0]
	v_ashrrev_i32_e32 v67, 31, v66
	v_pk_fma_f32 v[44:45], v[46:47], v[14:15], v[44:45] op_sel_hi:[0,1,1]
	v_pk_fma_f32 v[58:59], v[46:47], v[12:13], v[58:59] op_sel_hi:[0,1,1]
	v_lshl_add_u64 v[60:61], s[16:17], 0, v[66:67]
	v_pk_fma_f32 v[44:45], v[62:63], v[10:11], v[44:45] op_sel_hi:[0,1,1]
	v_pk_fma_f32 v[58:59], v[62:63], v[8:9], v[58:59] op_sel_hi:[0,1,1]
	v_lshlrev_b64 v[60:61], 10, v[60:61]
	v_pk_fma_f32 v[44:45], v[64:65], v[6:7], v[44:45] op_sel:[1,0,0]
	v_pk_fma_f32 v[58:59], v[64:65], v[4:5], v[58:59] op_sel:[1,0,0]
	v_lshl_add_u64 v[64:65], s[50:51], 0, v[60:61]
	v_lshl_add_u64 v[64:65], v[64:65], 0, v[2:3]
	global_store_dwordx2 v[64:65], v[52:53], off
; #define GAS __attribute__((address_space(1)))
; #define LAS __attribute__((address_space(3)))
; #define MFMA16(a, b, c) __builtin_amdgcn_mfma_f32_16x16x32_bf16((a), (b), (c), 0, 0, 0)
; __device__ __forceinline__ float fsigmoid(float x) { return __builtin_amdgcn_rcpf(1.f + __builtin_amdgcn_exp2f(-LOG2E * x)); }
; __device__ __forceinline__ void prep_unit(LAS unsigned char* lds, const MixBufs& B, int b, int ch, int tid) {
;     ...
;         for (int s = 0; s < 16; ++s) { const int row = 16 * strip + s;
;             const f32x4 x0 = bf4_to_f32(xr[s + 3]);
;             f32x4 cv = cb + cw[0] * x3 + cw[1] * x2 + cw[2] * x1 + cw[3] * x0, xc;
; #pragma unroll
;             for (int e = 0; e < 4; ++e) xc[e] = cv[e] * fsigmoid(cv[e]);
;             const int sw = row & 7, within = (gch & 1) * 8;
;             *(LAS u32x2*)(XA + row * 2048 + ((((gch >> 1)) ^ sw) << 4) + within) = f32_to_bf4(xc);
;             *(LAS u32x2*)(XA + row * 2048 + (((64 + (gch >> 1)) ^ sw) << 4) + within) = xr[s + 3];
;             const f32x4 v = wv[0] * x0[0] + wv[1] * x0[1] + wv[2] * x0[2] + wv[3] * x0[3];
;             *(GAS u32x2*)(B.xcm + (t0 + row) * 512 + 4 * gch) = f32_to_bf4(xc); *(GAS u32x2*)(B.vm + (t0 + row) * 512 + 4 * gch) = f32_to_bf4(v);
;             x3 = x2; x2 = x1; x1 = x0; }
;     }
;     __syncthreads();
;     LAS float* GP = (LAS float*)lds;
;     LAS float* GATES = (LAS float*)(lds + 32768);
;     {
;         f32x4 acc[4];
; #pragma unroll
;         for (int mt = 0; mt < 4; ++mt) acc[mt] = (f32x4){0.f, 0.f, 0.f, 0.f};
; #pragma unroll
;         for (int i = 0; i < 4; ++i) { const int ks = 4 * w + i;
;             const bf16x8 bw = *(const GAS bf16x8*)(B.WcmT + (size_t)(lane & 15) * 1024 + ks * 32 + 8 * (lane >> 4));
; #pragma unroll
;             for (int mt = 0; mt < 4; ++mt) { const int row = 16 * mt + (lane & 15);
;                 const bf16x8 a = *(const LAS bf16x8*)(XA + row * 2048 + (((4 * ks + (lane >> 4)) ^ (row & 7)) << 4)); acc[mt] = MFMA16(a, bw, acc[mt]); } }
;         __syncthreads();
; #pragma unroll
;         for (int mt = 0; mt < 4; ++mt) *(LAS f32x4*)(GP + ((w * 4 + mt) * 64 + lane) * 4) = acc[mt];
;     }
;     __syncthreads();
;     { const int t = tid >> 3, jg = tid & 7, mt = t >> 4, tl = t & 15, ls = jg + 16 * (tl >> 2), rg = tl & 3;
;       float s = B.b_if[jg];
	v_cvt_pk_bf16_f32 v53, v44, v45
	v_lshl_add_u64 v[44:45], s[0:1], 0, v[60:61]
	v_cvt_pk_bf16_f32 v52, v58, v59
	v_lshl_add_u64 v[44:45], v[44:45], 0, v[2:3]
	global_store_dwordx2 v[44:45], v[52:53], off
	v_and_b32_e32 v53, 0xffff0000, v42
	v_lshlrev_b32_e32 v44, 16, v42
	v_mov_b32_e32 v45, v53
	v_pk_fma_f32 v[20:21], v[32:33], v[44:45], v[20:21]
	v_and_b32_e32 v52, 16, v42
	v_mul_f32_e32 v24, 0xbfb8aa3b, v20
	v_mul_f32_e32 v25, 0xbfb8aa3b, v21
	v_exp_f32_e32 v24, v24
	v_exp_f32_e32 v25, v25
	v_pk_mul_f32 v[16:17], v[52:53], v[16:17] op_sel:[1,0]
	v_pk_mul_f32 v[18:19], v[52:53], v[18:19] op_sel:[1,0]
	v_add_f32_e32 v24, 1.0, v24
	v_add_f32_e32 v25, 1.0, v25
	v_rcp_f32_e32 v24, v24
	v_rcp_f32_e32 v25, v25
	v_pk_fma_f32 v[12:13], v[44:45], v[12:13], v[16:17] op_sel_hi:[0,1,1]
	v_and_b32_e32 v28, 16, v43
	v_pk_fma_f32 v[14:15], v[44:45], v[14:15], v[18:19] op_sel_hi:[0,1,1]
	v_pk_mul_f32 v[20:21], v[20:21], v[24:25]
	v_lshlrev_b32_e32 v24, 16, v43
	v_mov_b32_e32 v25, v29
	v_pk_fma_f32 v[22:23], v[34:35], v[24:25], v[22:23]
	v_cvt_pk_bf16_f32 v20, v20, v21
	v_mul_f32_e32 v25, 0xbfb8aa3b, v22
	v_exp_f32_e32 v25, v25
	v_lshrrev_b32_e32 v30, 4, v97
	v_and_b32_e32 v31, 7, v99
	v_add_f32_e32 v25, 1.0, v25
	v_rcp_f32_e32 v26, v25
	v_mul_f32_e32 v25, 0xbfb8aa3b, v23
	v_exp_f32_e32 v25, v25
	s_nop 0
	v_add_f32_e32 v25, 1.0, v25
	v_rcp_f32_e32 v27, v25
	v_pk_fma_f32 v[8:9], v[24:25], v[8:9], v[12:13] op_sel_hi:[0,1,1]
	v_pk_fma_f32 v[10:11], v[24:25], v[10:11], v[14:15] op_sel_hi:[0,1,1]
	v_pk_fma_f32 v[4:5], v[28:29], v[4:5], v[8:9] op_sel:[1,0,0]
	v_pk_mul_f32 v[22:23], v[22:23], v[26:27]
	v_or_b32_e32 v26, 15, v79
	v_ashrrev_i32_e32 v27, 31, v26
	v_lshl_add_u64 v[8:9], s[16:17], 0, v[26:27]
	v_pk_fma_f32 v[6:7], v[28:29], v[6:7], v[10:11] op_sel:[1,0,0]
	v_lshlrev_b64 v[8:9], 10, v[8:9]
	v_lshl_add_u64 v[10:11], s[50:51], 0, v[8:9]
	v_cvt_pk_bf16_f32 v4, v4, v5
	v_cvt_pk_bf16_f32 v5, v6, v7
	v_lshl_add_u64 v[6:7], s[0:1], 0, v[8:9]
	v_lshl_add_u64 v[10:11], v[10:11], 0, v[2:3]
	v_lshl_add_u64 v[6:7], v[6:7], 0, v[2:3]
	v_lshlrev_b32_e32 v2, 11, v100
	global_store_dwordx2 v[6:7], v[4:5], off
	v_lshl_add_u64 v[4:5], s[8:9], 0, v[2:3]
	v_and_b32_e32 v6, 48, v97
	v_mov_b32_e32 v7, v3
	v_cvt_pk_bf16_f32 v21, v22, v23
	v_lshl_add_u32 v22, v26, 11, 0
	v_lshl_add_u64 v[4:5], v[4:5], 0, v[6:7]
	v_add3_u32 v22, v22, v72, v41
	v_lshl_add_u64 v[6:7], s[4:5], 1, v[4:5]
	global_load_dwordx4 v[128:131], v[6:7], off offset:64
	global_load_dwordx4 v[132:135], v[6:7], off offset:128
	global_load_dwordx4 v[136:139], v[6:7], off offset:192
	v_lshlrev_b32_e32 v141, 2, v31
	global_load_dword v140, v141, s[76:77]
	ds_write2st64_b64 v22, v[20:21], v[42:43] offset1:2
	global_store_dwordx2 v[10:11], v[20:21], off
	s_waitcnt lgkmcnt(0)
	s_barrier
	global_load_dwordx4 v[6:9], v[6:7], off
	v_bitop3_b32 v10, s3, v31, v30 bitop3:0x36
	s_or_b32 s3, s2, 1
	v_add_u32_e32 v2, 0, v2
	s_lshl_b32 s4, s3, 5
	s_lshl_b32 s3, s3, 2
	v_lshl_add_u32 v22, v10, 4, v2
	v_bitop3_b32 v26, s3, v31, v30 bitop3:0x36
	v_add_u32_e32 v18, 0x10000, v22
	v_lshl_add_u32 v32, v26, 4, v2
	ds_read_b128 v[10:13], v22
	ds_read_b128 v[26:29], v32
	ds_read_b128 v[14:17], v22 offset:32768
	ds_read_b128 v[18:21], v18
	v_add_u32_e32 v22, 0x18000, v22
	ds_read_b128 v[22:25], v22
	s_ashr_i32 s5, s4, 31
	s_waitcnt vmcnt(0) lgkmcnt(4)
	v_mfma_f32_16x16x32_bf16 v[10:13], v[10:13], v[6:9], 0
	s_or_b32 s3, s2, 2
	s_waitcnt lgkmcnt(2)
	v_mfma_f32_16x16x32_bf16 v[14:17], v[14:17], v[6:9], 0
	s_waitcnt lgkmcnt(1)
	v_mfma_f32_16x16x32_bf16 v[18:21], v[18:21], v[6:9], 0
	s_waitcnt lgkmcnt(0)
	v_mfma_f32_16x16x32_bf16 v[6:9], v[22:25], v[6:9], 0
	v_lshl_add_u64 v[22:23], s[4:5], 1, v[4:5]
	s_nop 0
	s_lshl_b32 s4, s3, 5
	s_waitcnt vmcnt(0)
	v_mfma_f32_16x16x32_bf16 v[10:13], v[26:29], v[128:131], v[10:13]
	ds_read_b128 v[26:29], v32 offset:32768
	s_ashr_i32 s5, s4, 31
	s_lshl_b32 s3, s3, 2
	s_waitcnt lgkmcnt(0)
	v_mfma_f32_16x16x32_bf16 v[14:17], v[26:29], v[128:131], v[14:17]
	v_add_u32_e32 v26, 0x10000, v32
	ds_read_b128 v[26:29], v26
	s_waitcnt lgkmcnt(0)
	v_mfma_f32_16x16x32_bf16 v[18:21], v[26:29], v[128:131], v[18:21]
	v_add_u32_e32 v26, 0x18000, v32
	ds_read_b128 v[26:29], v26
	s_waitcnt lgkmcnt(0)
	v_mfma_f32_16x16x32_bf16 v[6:9], v[26:29], v[128:131], v[6:9]
	v_lshl_add_u64 v[22:23], s[4:5], 1, v[4:5]
	s_nop 0
	v_bitop3_b32 v26, s3, v31, v30 bitop3:0x36
	v_lshl_add_u32 v32, v26, 4, v2
	ds_read_b128 v[26:29], v32
	s_waitcnt vmcnt(0) lgkmcnt(0)
	v_mfma_f32_16x16x32_bf16 v[10:13], v[26:29], v[132:135], v[10:13]
	ds_read_b128 v[26:29], v32 offset:32768
	s_or_b32 s3, s2, 3
	s_lshl_b32 s4, s3, 5
	s_waitcnt lgkmcnt(0)
	v_mfma_f32_16x16x32_bf16 v[14:17], v[26:29], v[132:135], v[14:17]
	v_add_u32_e32 v26, 0x10000, v32
	ds_read_b128 v[26:29], v26
	s_ashr_i32 s5, s4, 31
	s_waitcnt lgkmcnt(0)
	v_mfma_f32_16x16x32_bf16 v[18:21], v[26:29], v[132:135], v[18:21]
	v_add_u32_e32 v26, 0x18000, v32
	ds_read_b128 v[26:29], v26
	v_lshl_add_u64 v[4:5], s[4:5], 1, v[4:5]
	s_waitcnt lgkmcnt(0)
	v_mfma_f32_16x16x32_bf16 v[6:9], v[26:29], v[132:135], v[6:9]
	s_nop 0
	s_lshl_b32 s3, s3, 2
	v_bitop3_b32 v4, s3, v31, v30 bitop3:0x36
	v_lshl_add_u32 v2, v4, 4, v2
	ds_read_b128 v[26:29], v2
	s_waitcnt vmcnt(0) lgkmcnt(0)
	v_mfma_f32_16x16x32_bf16 v[10:13], v[26:29], v[136:139], v[10:13]
	ds_read_b128 v[26:29], v2 offset:32768
	v_add_u32_e32 v4, 0x10000, v2
	v_add_u32_e32 v2, 0x18000, v2
	s_waitcnt lgkmcnt(0)
	v_mfma_f32_16x16x32_bf16 v[14:17], v[26:29], v[136:139], v[14:17]
	ds_read_b128 v[26:29], v4
	s_lshl_b32 s3, s18, 12
	s_add_i32 s3, s3, 0
	s_waitcnt lgkmcnt(0)
	v_mfma_f32_16x16x32_bf16 v[18:21], v[26:29], v[136:139], v[18:21]
	ds_read_b128 v[26:29], v2
	v_add_u32_e32 v2, s3, v78
	s_waitcnt lgkmcnt(0)
	v_mfma_f32_16x16x32_bf16 v[4:7], v[26:29], v[136:139], v[6:9]
	s_barrier
; #define LAS __attribute__((address_space(3)))
; __device__ __forceinline__ float fexp(float x) { return __builtin_amdgcn_exp2f(x * LOG2E); }
; __device__ __forceinline__ float flogsig(float x) { return fminf(x, 0.f) - __logf(1.f + fexp(-fabsf(x))); }
; __device__ __forceinline__ void prep_unit(LAS unsigned char* lds, const MixBufs& B, int b, int ch, int tid) {
;     ...
; #pragma unroll
;         for (int mt = 0; mt < 4; ++mt) *(LAS f32x4*)(GP + ((w * 4 + mt) * 64 + lane) * 4) = acc[mt];
;     }
;     __syncthreads();
;     { const int t = tid >> 3, jg = tid & 7, mt = t >> 4, tl = t & 15, ls = jg + 16 * (tl >> 2), rg = tl & 3;
;       float s = B.b_if[jg];
; #pragma unroll
;       for (int ww = 0; ww < 8; ++ww) s += GP[((ww * 4 + mt) * 64 + ls) * 4 + rg];
;       GATES[t * 8 + jg] = s; }
;     __syncthreads();
;     if (w < 4) {
;         const int h = w;
;         const float liv = GATES[lane * 8 + h], lfv = flogsig(GATES[lane * 8 + 4 + h]);
;         float fc = lfv;
; #pragma unroll
;         for (int o = 1; o < 64; o <<= 1) { const float u = __shfl_up(fc, o); if (lane >= o) fc += u; }
;         const float fl = __shfl(fc, 63);
;         const float a = fl - fc + liv;
;         float mx = a;
; #pragma unroll
;         for (int o = 1; o < 64; o <<= 1) mx = fmaxf(mx, __shfl_xor(mx, o));
;         B.li[(t0 + lane) * 4 + h] = liv; B.fcum[(t0 + lane) * 4 + h] = fc; B.wgt[(t0 + lane) * 4 + h] = fexp(a - mx);
;         if (lane == 0) { B.flast[((size_t)b * NCH + ch) * 4 + h] = fl; B.mloc[((size_t)b * NCH + ch) * 4 + h] = mx; }
;     }
	s_setprio 1
	ds_write_b128 v2, v[10:13]
	ds_write_b128 v2, v[14:17] offset:1024
	s_nop 0
	ds_write_b128 v2, v[18:21] offset:2048
	s_nop 2
	ds_write_b128 v2, v[4:7] offset:3072
	v_lshlrev_b32_e32 v4, 2, v31
	s_waitcnt lgkmcnt(0)
	s_barrier
	s_nop 0
	v_lshlrev_b32_e32 v2, 2, v79
	v_lshrrev_b32_e32 v4, 1, v99
	v_and_b32_e32 v2, 48, v2
	v_and_b32_e32 v5, 0xfffffc0, v4
	v_or3_b32 v2, v5, v2, v31
	v_and_b32_e32 v4, 12, v4
	v_lshlrev_b32_e32 v2, 4, v2
	v_add3_u32 v2, 0, v4, v2
	ds_read2st64_b32 v[4:5], v2 offset1:16
	s_cmp_gt_i32 s18, 3
	s_waitcnt vmcnt(0) lgkmcnt(0)
	v_add_f32_e32 v4, v140, v4
	v_add_f32_e32 v6, v4, v5
	ds_read2st64_b32 v[4:5], v2 offset0:32 offset1:48
	s_waitcnt lgkmcnt(0)
	v_add_f32_e32 v4, v6, v4
	v_add_f32_e32 v6, v4, v5
	ds_read2st64_b32 v[4:5], v2 offset0:64 offset1:80
	s_waitcnt lgkmcnt(0)
	v_add_f32_e32 v4, v6, v4
	v_add_f32_e32 v6, v4, v5
	ds_read2st64_b32 v[4:5], v2 offset0:96 offset1:112
	s_waitcnt lgkmcnt(0)
	v_add_f32_e32 v2, v6, v4
	v_add_f32_e32 v2, v2, v5
	ds_write_b32 v98, v2 offset:32768
	s_waitcnt lgkmcnt(0)
	s_barrier
	s_cbranch_scc1 .LBB0_292
	s_add_i32 s2, s2, 0
	v_lshl_add_u32 v2, v97, 5, s2
	v_add_u32_e32 v2, 0x8000, v2
	ds_read2_b32 v[4:5], v2 offset1:4
	v_xor_b32_e32 v7, 2, v95
	s_ashr_i32 s19, s18, 31
	s_waitcnt lgkmcnt(0)
	v_max_f32_e32 v2, v5, v5
	v_mul_f32_e64 v5, |v5|, s22
	v_exp_f32_e32 v5, v5
	v_min_f32_e32 v2, 0, v2
	v_add_f32_e32 v5, 1.0, v5
	v_cmp_gt_f32_e32 vcc, s23, v5
	s_nop 1
	v_cndmask_b32_e64 v6, 0, 32, vcc
	v_ldexp_f32 v5, v5, v6
	v_log_f32_e32 v5, v5
	s_nop 0
	v_mul_f32_e32 v6, 0x3f317217, v5
	v_fma_f32 v6, v5, s24, -v6
	v_fmac_f32_e32 v6, 0x3377d1cf, v5
	v_fmac_f32_e32 v6, 0x3f317217, v5
	v_cmp_lt_f32_e64 s[2:3], |v5|, s25
	s_nop 1
	v_cndmask_b32_e64 v5, v5, v6, s[2:3]
	v_cndmask_b32_e32 v6, 0, v1, vcc
	v_sub_f32_e32 v5, v5, v6
	v_sub_f32_e32 v2, v2, v5
	v_and_b32_e32 v5, 64, v95
	v_add_u32_e32 v6, -1, v95
	v_cmp_lt_i32_e32 vcc, v6, v5
	s_nop 1
	v_cndmask_b32_e32 v6, v6, v95, vcc
	v_lshlrev_b32_e32 v6, 2, v6
	ds_bpermute_b32 v6, v6, v2
	v_cmp_eq_u32_e32 vcc, 0, v97
	s_waitcnt lgkmcnt(0)
	v_add_f32_e32 v6, v2, v6
	v_cndmask_b32_e32 v2, v6, v2, vcc
	v_add_u32_e32 v6, -2, v95
	v_cmp_lt_i32_e64 s[2:3], v6, v5
	s_nop 1
	v_cndmask_b32_e64 v6, v6, v95, s[2:3]
	v_lshlrev_b32_e32 v6, 2, v6
	ds_bpermute_b32 v6, v6, v2
	v_cmp_gt_u32_e64 s[2:3], 2, v97
	s_waitcnt lgkmcnt(0)
	v_add_f32_e32 v6, v2, v6
	v_cndmask_b32_e64 v2, v6, v2, s[2:3]
	v_add_u32_e32 v6, -4, v95
	v_cmp_lt_i32_e64 s[2:3], v6, v5
	s_nop 1
	v_cndmask_b32_e64 v6, v6, v95, s[2:3]
	v_lshlrev_b32_e32 v6, 2, v6
	ds_bpermute_b32 v6, v6, v2
	v_cmp_gt_u32_e64 s[2:3], 4, v97
	s_waitcnt lgkmcnt(0)
	v_add_f32_e32 v6, v2, v6
	v_cndmask_b32_e64 v2, v6, v2, s[2:3]
	v_add_u32_e32 v6, -8, v95
	v_cmp_lt_i32_e64 s[2:3], v6, v5
	s_nop 1
	v_cndmask_b32_e64 v6, v6, v95, s[2:3]
	v_lshlrev_b32_e32 v6, 2, v6
	ds_bpermute_b32 v6, v6, v2
	v_cmp_gt_u32_e64 s[2:3], 8, v97
	s_waitcnt lgkmcnt(0)
	v_add_f32_e32 v6, v2, v6
	v_cndmask_b32_e64 v2, v6, v2, s[2:3]
	v_add_u32_e32 v6, -16, v95
	v_cmp_lt_i32_e64 s[2:3], v6, v5
	s_nop 1
	v_cndmask_b32_e64 v6, v6, v95, s[2:3]
	v_lshlrev_b32_e32 v6, 2, v6
	ds_bpermute_b32 v6, v6, v2
	v_cmp_gt_u32_e64 s[2:3], 16, v97
	s_waitcnt lgkmcnt(0)
	v_add_f32_e32 v6, v2, v6
	v_cndmask_b32_e64 v2, v6, v2, s[2:3]
	v_subrev_u32_e32 v6, 32, v95
	v_cmp_lt_i32_e64 s[2:3], v6, v5
	v_add_u32_e32 v5, 64, v5
	s_nop 0
	v_cndmask_b32_e64 v6, v6, v95, s[2:3]
	v_lshlrev_b32_e32 v6, 2, v6
	ds_bpermute_b32 v6, v6, v2
	v_cmp_gt_u32_e64 s[2:3], 32, v97
	s_waitcnt lgkmcnt(0)
	v_add_f32_e32 v6, v2, v6
	v_cndmask_b32_e64 v10, v6, v2, s[2:3]
	ds_bpermute_b32 v2, v96, v10
	s_waitcnt lgkmcnt(0)
	v_sub_f32_e32 v6, v2, v10
	v_add_f32_e32 v11, v4, v6
	v_xor_b32_e32 v6, 1, v95
	v_cmp_lt_i32_e64 s[2:3], v6, v5
	s_nop 1
	v_cndmask_b32_e64 v6, v95, v6, s[2:3]
	v_lshlrev_b32_e32 v6, 2, v6
	ds_bpermute_b32 v6, v6, v11
	v_cmp_lt_i32_e64 s[2:3], v7, v5
	s_waitcnt lgkmcnt(0)
	v_max_f32_e32 v6, v6, v6
	v_cndmask_b32_e64 v7, v95, v7, s[2:3]
	v_max_f32_e32 v6, v11, v6
	v_lshlrev_b32_e32 v7, 2, v7
	ds_bpermute_b32 v7, v7, v6
	s_waitcnt lgkmcnt(0)
	v_max_f32_e32 v7, v7, v7
	v_max_f32_e32 v6, v6, v7
	v_xor_b32_e32 v7, 4, v95
	v_cmp_lt_i32_e64 s[2:3], v7, v5
	s_nop 1
	v_cndmask_b32_e64 v7, v95, v7, s[2:3]
	v_lshlrev_b32_e32 v7, 2, v7
	ds_bpermute_b32 v7, v7, v6
	s_waitcnt lgkmcnt(0)
	v_max_f32_e32 v7, v7, v7
	v_max_f32_e32 v6, v6, v7
	v_xor_b32_e32 v7, 8, v95
	v_cmp_lt_i32_e64 s[2:3], v7, v5
	s_nop 1
	v_cndmask_b32_e64 v7, v95, v7, s[2:3]
	v_lshlrev_b32_e32 v7, 2, v7
	ds_bpermute_b32 v7, v7, v6
	s_waitcnt lgkmcnt(0)
	v_max_f32_e32 v7, v7, v7
	v_max_f32_e32 v6, v6, v7
	v_xor_b32_e32 v7, 16, v95
	v_cmp_lt_i32_e64 s[2:3], v7, v5
	s_nop 1
	v_cndmask_b32_e64 v7, v95, v7, s[2:3]
	v_lshlrev_b32_e32 v7, 2, v7
	ds_bpermute_b32 v7, v7, v6
	s_waitcnt lgkmcnt(0)
	v_max_f32_e32 v7, v7, v7
	v_max_f32_e32 v6, v6, v7
	v_xor_b32_e32 v7, 32, v95
	v_cmp_lt_i32_e64 s[2:3], v7, v5
	s_nop 1
	v_cndmask_b32_e64 v5, v95, v7, s[2:3]
	v_lshlrev_b32_e32 v5, 2, v5
	ds_bpermute_b32 v5, v5, v6
	v_mov_b32_e32 v7, s17
	v_readlane_b32 s2, v241, 59
	v_readlane_b32 s3, v241, 60
	s_waitcnt lgkmcnt(0)
	v_max_f32_e32 v5, v5, v5
	v_max_f32_e32 v5, v6, v5
	v_or_b32_e32 v6, s16, v97
	v_lshl_add_u64 v[6:7], v[6:7], 2, s[18:19]
	v_lshlrev_b64 v[6:7], 2, v[6:7]
	v_lshl_add_u64 v[8:9], s[2:3], 0, v[6:7]
	global_store_dword v[8:9], v4, off
	v_sub_f32_e32 v4, v11, v5
	v_readlane_b32 s2, v241, 61
	v_mul_f32_e32 v4, 0x3fb8aa3b, v4
	v_readlane_b32 s3, v241, 62
	v_exp_f32_e32 v4, v4
	s_nop 0
	v_lshl_add_u64 v[8:9], s[2:3], 0, v[6:7]
	v_readlane_b32 s2, v241, 63
	v_readlane_b32 s3, v240, 0
	global_store_dword v[8:9], v10, off
	s_nop 0
	v_lshl_add_u64 v[6:7], s[2:3], 0, v[6:7]
	global_store_dword v[6:7], v4, off
	s_and_saveexec_b64 s[2:3], vcc
	s_cbranch_execz .LBB0_291
	s_lshl_b64 s[4:5], s[14:15], 7
	s_lshl_b32 s6, s27, 2
	s_or_b32 s4, s4, s6
	s_add_u32 s4, s4, s18
	s_addc_u32 s5, s5, s19
	s_lshl_b64 s[4:5], s[4:5], 2
	v_readlane_b32 s6, v240, 1
	v_readlane_b32 s7, v240, 2
	s_add_u32 s6, s6, s4
	s_addc_u32 s7, s7, s5
	s_nop 2
	global_store_dword v3, v2, s[6:7]
	v_readlane_b32 s6, v240, 3
	v_readlane_b32 s7, v240, 4
	s_add_u32 s4, s6, s4
	s_addc_u32 s5, s7, s5
	global_store_dword v3, v5, s[4:5]
	s_branch .LBB0_291

; #define LAS __attribute__((address_space(3)))
; __device__ __forceinline__ f32x4 bf4_to_f32(u32x2 w) { return (f32x4){bflo(w.x), bfhi(w.x), bflo(w.y), bfhi(w.y)}; }
; __device__ __forceinline__ u32x2 f32_to_bf4(f32x4 v) { u32x2 w; w.x = cvtpk(v[0], v[1]); w.y = cvtpk(v[2], v[3]); return w; }
; __device__ __forceinline__ void ml_stage_k(LAS unsigned char* lds, int offK, const LAS float* WL, const u32x2 (&xr)[4], int cg, int ts) {
;     f32x4 wk[4];
; #pragma unroll
;     for (int j = 0; j < 4; ++j) wk[j] = *(const LAS f32x4*)(WL + WL_WK + (cg * 4 + j) * 4);
; #pragma unroll
;     for (int i = 0; i < 4; ++i) { const f32x4 xc = bf4_to_f32(xr[i]);
;         const f32x4 k = wk[0] * xc[0] + wk[1] * xc[1] + wk[2] * xc[2] + wk[3] * xc[3];
;         *(LAS u32x2*)(lds + offK + (4 * ts + i) * GP128 + 8 * cg) = f32_to_bf4(k); }
; }
.LBB0_405:
	v_mov_b32_e32 v18, s5
	ds_read_b64 v[58:59], v18 offset:35120
	ds_read_b128 v[18:21], v140 offset:39936
	ds_read_b128 v[22:25], v140 offset:39952
	ds_read_b128 v[26:29], v140 offset:39968
	ds_read_b128 v[30:33], v140 offset:39984
	s_waitcnt vmcnt(11)
	v_and_b32_e32 v36, 0xffff0000, v86
	v_lshlrev_b32_e32 v34, 16, v86
	s_waitcnt lgkmcnt(2)
	v_pk_mul_f32 v[42:43], v[24:25], v[36:37] op_sel_hi:[1,0]
	v_pk_mul_f32 v[36:37], v[22:23], v[36:37] op_sel_hi:[1,0]
	v_lshlrev_b32_e32 v38, 16, v87
	v_pk_fma_f32 v[42:43], v[20:21], v[34:35], v[42:43] op_sel_hi:[1,0,1]
	v_pk_fma_f32 v[34:35], v[18:19], v[34:35], v[36:37] op_sel_hi:[1,0,1]
	v_and_b32_e32 v40, 0xffff0000, v87
	s_waitcnt lgkmcnt(1)
	v_pk_fma_f32 v[34:35], v[26:27], v[38:39], v[34:35] op_sel_hi:[1,0,1]
	v_pk_fma_f32 v[36:37], v[28:29], v[38:39], v[42:43] op_sel_hi:[1,0,1]
	s_waitcnt lgkmcnt(0)
	v_pk_fma_f32 v[34:35], v[30:31], v[40:41], v[34:35] op_sel_hi:[1,0,1]
	v_pk_fma_f32 v[36:37], v[32:33], v[40:41], v[36:37] op_sel_hi:[1,0,1]
	s_waitcnt vmcnt(10)
	v_and_b32_e32 v38, 0xffff0000, v84
	v_cvt_pk_bf16_f32 v34, v34, v35
	v_cvt_pk_bf16_f32 v35, v36, v37
	v_lshlrev_b32_e32 v36, 16, v84
	v_pk_mul_f32 v[44:45], v[24:25], v[38:39] op_sel_hi:[1,0]
	v_pk_mul_f32 v[38:39], v[22:23], v[38:39] op_sel_hi:[1,0]
	v_lshlrev_b32_e32 v40, 16, v85
	v_pk_fma_f32 v[44:45], v[20:21], v[36:37], v[44:45] op_sel_hi:[1,0,1]
	v_pk_fma_f32 v[36:37], v[18:19], v[36:37], v[38:39] op_sel_hi:[1,0,1]
	v_and_b32_e32 v42, 0xffff0000, v85
	v_pk_fma_f32 v[36:37], v[26:27], v[40:41], v[36:37] op_sel_hi:[1,0,1]
	v_pk_fma_f32 v[38:39], v[28:29], v[40:41], v[44:45] op_sel_hi:[1,0,1]
	v_pk_fma_f32 v[36:37], v[30:31], v[42:43], v[36:37] op_sel_hi:[1,0,1]
	v_pk_fma_f32 v[38:39], v[32:33], v[42:43], v[38:39] op_sel_hi:[1,0,1]
	v_cvt_pk_bf16_f32 v36, v36, v37
	v_cvt_pk_bf16_f32 v37, v38, v39
	ds_write2_b64 v147, v[34:35], v[36:37] offset1:34
	s_waitcnt vmcnt(9)
	v_and_b32_e32 v36, 0xffff0000, v82
	v_lshlrev_b32_e32 v34, 16, v82
	v_pk_mul_f32 v[42:43], v[24:25], v[36:37] op_sel_hi:[1,0]
	v_pk_mul_f32 v[36:37], v[22:23], v[36:37] op_sel_hi:[1,0]
	v_lshlrev_b32_e32 v38, 16, v83
	v_pk_fma_f32 v[42:43], v[20:21], v[34:35], v[42:43] op_sel_hi:[1,0,1]
	v_pk_fma_f32 v[34:35], v[18:19], v[34:35], v[36:37] op_sel_hi:[1,0,1]
	v_and_b32_e32 v40, 0xffff0000, v83
	v_pk_fma_f32 v[34:35], v[26:27], v[38:39], v[34:35] op_sel_hi:[1,0,1]
	v_pk_fma_f32 v[36:37], v[28:29], v[38:39], v[42:43] op_sel_hi:[1,0,1]
	v_pk_fma_f32 v[34:35], v[30:31], v[40:41], v[34:35] op_sel_hi:[1,0,1]
	v_pk_fma_f32 v[36:37], v[32:33], v[40:41], v[36:37] op_sel_hi:[1,0,1]
	s_waitcnt vmcnt(8)
	v_and_b32_e32 v38, 0xffff0000, v80
	v_cvt_pk_bf16_f32 v34, v34, v35
	v_cvt_pk_bf16_f32 v35, v36, v37
	v_lshlrev_b32_e32 v36, 16, v80
	v_pk_mul_f32 v[24:25], v[24:25], v[38:39] op_sel_hi:[1,0]
	v_pk_mul_f32 v[22:23], v[22:23], v[38:39] op_sel_hi:[1,0]
	v_lshlrev_b32_e32 v40, 16, v81
	v_pk_fma_f32 v[20:21], v[20:21], v[36:37], v[24:25] op_sel_hi:[1,0,1]
	v_pk_fma_f32 v[18:19], v[18:19], v[36:37], v[22:23] op_sel_hi:[1,0,1]
	v_and_b32_e32 v42, 0xffff0000, v81
	v_pk_fma_f32 v[18:19], v[26:27], v[40:41], v[18:19] op_sel_hi:[1,0,1]
	v_pk_fma_f32 v[20:21], v[28:29], v[40:41], v[20:21] op_sel_hi:[1,0,1]
	v_pk_fma_f32 v[18:19], v[30:31], v[42:43], v[18:19] op_sel_hi:[1,0,1]
	v_pk_fma_f32 v[20:21], v[32:33], v[42:43], v[20:21] op_sel_hi:[1,0,1]
	v_cvt_pk_bf16_f32 v18, v18, v19
	v_cvt_pk_bf16_f32 v19, v20, v21
	ds_write2_b64 v147, v[34:35], v[18:19] offset0:68 offset1:102
	s_waitcnt vmcnt(7)
	ds_write_b128 v141, v[10:13] offset:17408
	s_waitcnt vmcnt(6)
	ds_write_b128 v141, v[14:17] offset:26112
	s_and_saveexec_b64 s[18:19], s[2:3]
	ds_write_b32 v145, v144 offset:34816
	s_or_b64 exec, exec, s[18:19]
	s_waitcnt lgkmcnt(0)
	s_barrier
	ds_read_b128 v[10:13], v146 offset:34816
	ds_read_b128 v[14:17], v146 offset:34832
	ds_read_b64_tr_b16 v[18:19], v136
	ds_read_b64_tr_b16 v[20:21], v136 offset:1088
	s_waitcnt vmcnt(5)
	v_lshlrev_b32_e32 v70, 16, v79
	s_waitcnt lgkmcnt(1)
	v_lshlrev_b32_e32 v22, 16, v18
	v_and_b32_e32 v23, 0xffff0000, v18
	v_pk_mul_f32 v[10:11], v[10:11], v[22:23]
	s_nop 0
	v_cvt_pk_bf16_f32 v18, v10, v11
	v_lshlrev_b32_e32 v10, 16, v19
	v_and_b32_e32 v11, 0xffff0000, v19
	v_pk_mul_f32 v[10:11], v[12:13], v[10:11]
	s_nop 0
	v_cvt_pk_bf16_f32 v19, v10, v11
	s_waitcnt lgkmcnt(0)
	v_lshlrev_b32_e32 v10, 16, v20
	v_and_b32_e32 v11, 0xffff0000, v20
	v_pk_mul_f32 v[10:11], v[14:15], v[10:11]
	s_nop 0
	v_cvt_pk_bf16_f32 v20, v10, v11
	v_lshlrev_b32_e32 v10, 16, v21
	v_and_b32_e32 v11, 0xffff0000, v21
	v_pk_mul_f32 v[10:11], v[16:17], v[10:11]
	s_nop 0
	v_cvt_pk_bf16_f32 v21, v10, v11
	ds_read_b64_tr_b16 v[12:13], v143 offset:18496
	ds_read_b64_tr_b16 v[10:11], v143 offset:17408
	ds_read_b64_tr_b16 v[14:15], v143 offset:17440
	s_waitcnt lgkmcnt(1)
	v_mfma_f32_16x16x32_bf16 v[46:49], v[18:21], v[10:13], 0
	ds_read_b64_tr_b16 v[16:17], v143 offset:18528
	ds_read_b64_tr_b16 v[10:11], v143 offset:17472
	ds_read_b64_tr_b16 v[12:13], v143 offset:18560
	s_waitcnt lgkmcnt(0)
	v_mfma_f32_16x16x32_bf16 v[38:41], v[18:21], v[10:13], 0
	ds_read_b64_tr_b16 v[10:11], v143 offset:17504
	ds_read_b64_tr_b16 v[12:13], v143 offset:18592
	s_waitcnt lgkmcnt(0)
	v_mfma_f32_16x16x32_bf16 v[34:37], v[18:21], v[10:13], 0
	ds_read_b64_tr_b16 v[10:11], v143 offset:17536
	ds_read_b64_tr_b16 v[12:13], v143 offset:18624
	s_waitcnt lgkmcnt(0)
	v_mfma_f32_16x16x32_bf16 v[30:33], v[18:21], v[10:13], 0
	ds_read_b64_tr_b16 v[10:11], v143 offset:17568
	ds_read_b64_tr_b16 v[12:13], v143 offset:18656
	s_waitcnt lgkmcnt(0)
	v_mfma_f32_16x16x32_bf16 v[26:29], v[18:21], v[10:13], 0
	ds_read_b64_tr_b16 v[10:11], v143 offset:17600
	ds_read_b64_tr_b16 v[12:13], v143 offset:18688
	s_waitcnt lgkmcnt(0)
	v_mfma_f32_16x16x32_bf16 v[22:25], v[18:21], v[10:13], 0
	ds_read_b64_tr_b16 v[10:11], v143 offset:17632
	ds_read_b64_tr_b16 v[12:13], v143 offset:18720
	ds_read_b128 v[54:57], v146 offset:34944
	ds_read_b128 v[50:53], v146 offset:34960
	ds_read_b64_tr_b16 v[60:61], v136 offset:8704
	ds_read_b64_tr_b16 v[62:63], v136 offset:9792
	s_waitcnt lgkmcnt(1)
	v_lshlrev_b32_e32 v64, 16, v60
	v_and_b32_e32 v65, 0xffff0000, v60
	v_lshlrev_b32_e32 v60, 16, v61
	v_and_b32_e32 v61, 0xffff0000, v61
	v_pk_mul_f32 v[54:55], v[54:55], v[64:65]
	v_pk_mul_f32 v[56:57], v[56:57], v[60:61]
	v_cvt_pk_bf16_f32 v54, v54, v55
	v_cvt_pk_bf16_f32 v55, v56, v57
	s_waitcnt lgkmcnt(0)
	v_lshlrev_b32_e32 v56, 16, v62
	v_and_b32_e32 v57, 0xffff0000, v62
	v_pk_mul_f32 v[50:51], v[50:51], v[56:57]
	v_mfma_f32_16x16x32_bf16 v[42:45], v[18:21], v[14:17], 0
	v_cvt_pk_bf16_f32 v56, v50, v51
	v_lshlrev_b32_e32 v50, 16, v63
	v_and_b32_e32 v51, 0xffff0000, v63
	v_pk_mul_f32 v[50:51], v[52:53], v[50:51]
	v_mov_b64_e32 v[16:17], s[10:11]
	v_cvt_pk_bf16_f32 v57, v50, v51
	ds_read_b64_tr_b16 v[50:51], v143 offset:26112
	ds_read_b64_tr_b16 v[52:53], v143 offset:27200
	s_waitcnt lgkmcnt(0)
	v_mfma_f32_16x16x32_bf16 v[46:49], v[54:57], v[50:53], v[46:49]
	ds_read_b64_tr_b16 v[50:51], v143 offset:26144
	ds_read_b64_tr_b16 v[52:53], v143 offset:27232
	v_mov_b64_e32 v[14:15], s[8:9]
	v_and_b32_e32 v64, 0xffff0000, v78
	s_waitcnt lgkmcnt(0)
	v_mfma_f32_16x16x32_bf16 v[42:45], v[54:57], v[50:53], v[42:45]
	ds_read_b64_tr_b16 v[50:51], v143 offset:26176
	ds_read_b64_tr_b16 v[52:53], v143 offset:27264
	s_waitcnt lgkmcnt(0)
	v_mfma_f32_16x16x32_bf16 v[38:41], v[54:57], v[50:53], v[38:41]
	ds_read_b64_tr_b16 v[50:51], v143 offset:26208
	ds_read_b64_tr_b16 v[52:53], v143 offset:27296
	s_waitcnt lgkmcnt(0)
	v_mfma_f32_16x16x32_bf16 v[34:37], v[54:57], v[50:53], v[34:37]
	ds_read_b64_tr_b16 v[50:51], v143 offset:26240
	ds_read_b64_tr_b16 v[52:53], v143 offset:27328
	s_waitcnt lgkmcnt(0)
	v_mfma_f32_16x16x32_bf16 v[30:33], v[54:57], v[50:53], v[30:33]
	ds_read_b64_tr_b16 v[50:51], v143 offset:26272
	ds_read_b64_tr_b16 v[52:53], v143 offset:27360
	s_waitcnt lgkmcnt(0)
	v_mfma_f32_16x16x32_bf16 v[26:29], v[54:57], v[50:53], v[26:29]
	ds_read_b64_tr_b16 v[50:51], v143 offset:26304
	ds_read_b64_tr_b16 v[52:53], v143 offset:27392
	s_waitcnt lgkmcnt(0)
	v_mfma_f32_16x16x32_bf16 v[22:25], v[54:57], v[50:53], v[22:25]
	ds_read_b64_tr_b16 v[50:51], v143 offset:26336
	ds_read_b64_tr_b16 v[52:53], v143 offset:27424
	v_mfma_f32_16x16x32_bf16 v[10:13], v[18:21], v[10:13], 0
	v_mfma_f32_16x16x32_bf16 v[18:21], v[18:21], v[14:17], 0
	s_waitcnt lgkmcnt(0)
	v_mfma_f32_16x16x32_bf16 v[50:53], v[54:57], v[50:53], v[10:13]
	v_mfma_f32_16x16x32_bf16 v[10:13], v[54:57], v[14:17], v[18:21]
	v_mov_b32_e32 v14, s5
	ds_read_b64 v[14:15], v14 offset:35128
	s_nop 2
	ds_read_b128 v[16:19], v140 offset:39936
	ds_read_b128 v[54:57], v140 offset:39952
	ds_read_b128 v[60:63], v140 offset:39968
	ds_read_b128 v[80:83], v140 offset:39984
	v_lshlrev_b32_e32 v20, 16, v78
	v_and_b32_e32 v78, 0xffff0000, v79
	s_waitcnt lgkmcnt(2)
	v_pk_mul_f32 v[84:85], v[64:65], v[56:57] op_sel_hi:[0,1]
	v_pk_mul_f32 v[64:65], v[64:65], v[54:55] op_sel_hi:[0,1]
	v_pk_fma_f32 v[84:85], v[20:21], v[18:19], v[84:85] op_sel_hi:[0,1,1]
	v_pk_fma_f32 v[20:21], v[20:21], v[16:17], v[64:65] op_sel_hi:[0,1,1]
	s_waitcnt lgkmcnt(1)
	v_pk_fma_f32 v[20:21], v[70:71], v[60:61], v[20:21] op_sel_hi:[0,1,1]
	v_pk_fma_f32 v[64:65], v[70:71], v[62:63], v[84:85] op_sel_hi:[0,1,1]
	s_waitcnt lgkmcnt(0)
	v_pk_fma_f32 v[64:65], v[78:79], v[82:83], v[64:65] op_sel_hi:[0,1,1]
	v_pk_fma_f32 v[20:21], v[78:79], v[80:81], v[20:21] op_sel_hi:[0,1,1]
	s_waitcnt vmcnt(4)
	v_and_b32_e32 v70, 0xffff0000, v72
	v_cvt_pk_bf16_f32 v20, v20, v21
	v_cvt_pk_bf16_f32 v21, v64, v65
	v_lshlrev_b32_e32 v64, 16, v72
	v_pk_mul_f32 v[84:85], v[70:71], v[56:57] op_sel_hi:[0,1]
	v_pk_mul_f32 v[86:87], v[70:71], v[54:55] op_sel_hi:[0,1]
	v_lshlrev_b32_e32 v72, 16, v73
	v_pk_fma_f32 v[84:85], v[64:65], v[18:19], v[84:85] op_sel_hi:[0,1,1]
	v_pk_fma_f32 v[64:65], v[64:65], v[16:17], v[86:87] op_sel_hi:[0,1,1]
	v_and_b32_e32 v78, 0xffff0000, v73
	v_pk_fma_f32 v[64:65], v[72:73], v[60:61], v[64:65] op_sel_hi:[0,1,1]
	v_pk_fma_f32 v[72:73], v[72:73], v[62:63], v[84:85] op_sel_hi:[0,1,1]
	v_pk_fma_f32 v[72:73], v[78:79], v[82:83], v[72:73] op_sel_hi:[0,1,1]
	v_pk_fma_f32 v[64:65], v[78:79], v[80:81], v[64:65] op_sel_hi:[0,1,1]
	v_cvt_pk_bf16_f32 v64, v64, v65
	v_cvt_pk_bf16_f32 v65, v72, v73
	ds_write2_b64 v150, v[20:21], v[64:65] offset1:34
	s_waitcnt vmcnt(3)
	v_and_b32_e32 v64, 0xffff0000, v68
	v_lshlrev_b32_e32 v20, 16, v68
	v_pk_mul_f32 v[72:73], v[64:65], v[56:57] op_sel_hi:[0,1]
	v_pk_mul_f32 v[64:65], v[64:65], v[54:55] op_sel_hi:[0,1]
	v_lshlrev_b32_e32 v68, 16, v69
	v_pk_fma_f32 v[72:73], v[20:21], v[18:19], v[72:73] op_sel_hi:[0,1,1]
	v_pk_fma_f32 v[20:21], v[20:21], v[16:17], v[64:65] op_sel_hi:[0,1,1]
	v_and_b32_e32 v70, 0xffff0000, v69
	v_pk_fma_f32 v[20:21], v[68:69], v[60:61], v[20:21] op_sel_hi:[0,1,1]
	v_pk_fma_f32 v[64:65], v[68:69], v[62:63], v[72:73] op_sel_hi:[0,1,1]
	v_pk_fma_f32 v[64:65], v[70:71], v[82:83], v[64:65] op_sel_hi:[0,1,1]
	v_pk_fma_f32 v[20:21], v[70:71], v[80:81], v[20:21] op_sel_hi:[0,1,1]
	v_cvt_pk_bf16_f32 v20, v20, v21
	v_cvt_pk_bf16_f32 v21, v64, v65
	s_waitcnt vmcnt(2)
	v_lshlrev_b32_e32 v64, 16, v66
	v_and_b32_e32 v66, 0xffff0000, v66
	v_pk_mul_f32 v[56:57], v[66:67], v[56:57] op_sel_hi:[0,1]
	v_pk_mul_f32 v[54:55], v[66:67], v[54:55] op_sel_hi:[0,1]
	v_lshlrev_b32_e32 v68, 16, v67
	v_pk_fma_f32 v[18:19], v[64:65], v[18:19], v[56:57] op_sel_hi:[0,1,1]
	v_pk_fma_f32 v[16:17], v[64:65], v[16:17], v[54:55] op_sel_hi:[0,1,1]
	v_and_b32_e32 v70, 0xffff0000, v67
	v_pk_fma_f32 v[16:17], v[68:69], v[60:61], v[16:17] op_sel_hi:[0,1,1]
	v_pk_fma_f32 v[18:19], v[68:69], v[62:63], v[18:19] op_sel_hi:[0,1,1]
	v_pk_fma_f32 v[18:19], v[70:71], v[82:83], v[18:19] op_sel_hi:[0,1,1]
	v_pk_fma_f32 v[16:17], v[70:71], v[80:81], v[16:17] op_sel_hi:[0,1,1]
	v_cvt_pk_bf16_f32 v16, v16, v17
	v_cvt_pk_bf16_f32 v17, v18, v19
	ds_write2_b64 v150, v[20:21], v[16:17] offset0:68 offset1:102
	s_waitcnt vmcnt(1)
	ds_write_b128 v141, v[2:5] offset:62464
	s_waitcnt vmcnt(0)
	ds_write_b128 v142, v[6:9] offset:8704
	s_and_saveexec_b64 s[18:19], s[2:3]
	ds_write_b32 v139, v137
	s_or_b64 exec, exec, s[18:19]
	v_add_f32_e32 v2, v138, v58
	v_max_f32_e32 v3, v59, v59
	v_max_f32_e32 v6, v2, v3
	v_sub_f32_e32 v2, v2, v6
	v_mul_f32_e32 v2, 0x3fb8aa3b, v2
	v_exp_f32_e32 v54, v2
	v_sub_f32_e32 v2, v59, v6
	v_mul_f32_e32 v2, 0x3fb8aa3b, v2
	v_exp_f32_e32 v56, v2
	s_waitcnt lgkmcnt(0)
	s_barrier
	v_pk_mul_f32 v[2:3], v[56:57], v[48:49] op_sel_hi:[0,1]
	v_pk_fma_f32 v[122:123], v[122:123], v[54:55], v[2:3] op_sel_hi:[1,0,1]
	v_pk_mul_f32 v[2:3], v[56:57], v[44:45] op_sel_hi:[0,1]
	v_pk_fma_f32 v[118:119], v[118:119], v[54:55], v[2:3] op_sel_hi:[1,0,1]
	v_pk_mul_f32 v[2:3], v[56:57], v[40:41] op_sel_hi:[0,1]
	v_pk_fma_f32 v[114:115], v[114:115], v[54:55], v[2:3] op_sel_hi:[1,0,1]
	v_pk_mul_f32 v[2:3], v[56:57], v[36:37] op_sel_hi:[0,1]
	v_pk_fma_f32 v[88:89], v[110:111], v[54:55], v[2:3] op_sel_hi:[1,0,1]
	v_pk_mul_f32 v[2:3], v[56:57], v[32:33] op_sel_hi:[0,1]
	v_pk_fma_f32 v[84:85], v[106:107], v[54:55], v[2:3] op_sel_hi:[1,0,1]
	v_pk_mul_f32 v[2:3], v[56:57], v[28:29] op_sel_hi:[0,1]
	v_pk_mul_f32 v[4:5], v[56:57], v[46:47] op_sel_hi:[0,1]
	v_pk_fma_f32 v[80:81], v[102:103], v[54:55], v[2:3] op_sel_hi:[1,0,1]
	v_pk_mul_f32 v[2:3], v[56:57], v[24:25] op_sel_hi:[0,1]
	v_pk_fma_f32 v[90:91], v[124:125], v[54:55], v[4:5] op_sel_hi:[1,0,1]
	v_pk_mul_f32 v[4:5], v[56:57], v[42:43] op_sel_hi:[0,1]
	v_pk_fma_f32 v[72:73], v[98:99], v[54:55], v[2:3] op_sel_hi:[1,0,1]
	v_pk_mul_f32 v[2:3], v[56:57], v[52:53] op_sel_hi:[0,1]
	v_pk_fma_f32 v[92:93], v[120:121], v[54:55], v[4:5] op_sel_hi:[1,0,1]
	v_pk_mul_f32 v[4:5], v[56:57], v[38:39] op_sel_hi:[0,1]
	v_pk_fma_f32 v[66:67], v[96:97], v[54:55], v[2:3] op_sel_hi:[1,0,1]
	v_add_f32_e32 v2, v6, v14
	v_max_f32_e32 v3, v15, v15
	v_pk_fma_f32 v[86:87], v[116:117], v[54:55], v[4:5] op_sel_hi:[1,0,1]
	v_pk_mul_f32 v[4:5], v[56:57], v[34:35] op_sel_hi:[0,1]
	v_max_f32_e32 v3, v2, v3
	v_pk_fma_f32 v[82:83], v[112:113], v[54:55], v[4:5] op_sel_hi:[1,0,1]
	v_pk_mul_f32 v[4:5], v[56:57], v[30:31] op_sel_hi:[0,1]
	v_sub_f32_e32 v2, v2, v3
	v_pk_fma_f32 v[78:79], v[108:109], v[54:55], v[4:5] op_sel_hi:[1,0,1]
	v_pk_mul_f32 v[4:5], v[56:57], v[26:27] op_sel_hi:[0,1]
	v_mul_f32_e32 v2, 0x3fb8aa3b, v2
	v_pk_fma_f32 v[68:69], v[104:105], v[54:55], v[4:5] op_sel_hi:[1,0,1]
	v_pk_mul_f32 v[4:5], v[56:57], v[22:23] op_sel_hi:[0,1]
	v_exp_f32_e32 v58, v2
	v_sub_f32_e32 v2, v15, v3
	v_pk_fma_f32 v[64:65], v[100:101], v[54:55], v[4:5] op_sel_hi:[1,0,1]
	v_pk_mul_f32 v[4:5], v[56:57], v[50:51] op_sel_hi:[0,1]
	v_mul_f32_e32 v2, 0x3fb8aa3b, v2
	v_pk_fma_f32 v[62:63], v[94:95], v[54:55], v[4:5] op_sel_hi:[1,0,1]
	v_exp_f32_e32 v60, v2
	ds_read_b128 v[2:5], v127
	ds_read_b128 v[6:9], v127 offset:16
	ds_read_b64_tr_b16 v[14:15], v136 offset:45056
	ds_read_b64_tr_b16 v[16:17], v136 offset:46144
	s_lshl_b32 s2, s14, 2
	s_add_i32 s2, s2, s4
	s_mul_hi_i32 s3, s2, 3
	s_waitcnt lgkmcnt(1)
	v_lshlrev_b32_e32 v18, 16, v14
	v_and_b32_e32 v19, 0xffff0000, v14
	v_pk_mul_f32 v[2:3], v[2:3], v[18:19]
	s_mul_i32 s2, s2, 3
	v_cvt_pk_bf16_f32 v46, v2, v3
	v_lshlrev_b32_e32 v2, 16, v15
	v_and_b32_e32 v3, 0xffff0000, v15
	v_pk_mul_f32 v[2:3], v[4:5], v[2:3]
	s_ashr_i32 s4, s73, 31
	v_cvt_pk_bf16_f32 v47, v2, v3
	s_waitcnt lgkmcnt(0)
	v_lshlrev_b32_e32 v2, 16, v16
	v_and_b32_e32 v3, 0xffff0000, v16
	v_pk_mul_f32 v[2:3], v[6:7], v[2:3]
	s_add_u32 s20, s2, s73
	v_cvt_pk_bf16_f32 v48, v2, v3
	v_lshlrev_b32_e32 v2, 16, v17
	v_and_b32_e32 v3, 0xffff0000, v17
	v_pk_mul_f32 v[2:3], v[8:9], v[2:3]
	s_addc_u32 s21, s3, s4
	v_cvt_pk_bf16_f32 v49, v2, v3
	ds_read_b64_tr_b16 v[4:5], v128 offset:63552
	ds_read_b64_tr_b16 v[2:3], v128 offset:62464
	ds_read_b64_tr_b16 v[6:7], v128 offset:62496
	s_waitcnt lgkmcnt(1)
	v_mfma_f32_16x16x32_bf16 v[38:41], v[46:49], v[2:5], 0
	ds_read_b64_tr_b16 v[8:9], v128 offset:63584
	ds_read_b64_tr_b16 v[2:3], v128 offset:62528
	ds_read_b64_tr_b16 v[4:5], v128 offset:63616
	s_ashr_i32 s17, s16, 31
	s_waitcnt lgkmcnt(0)
	v_mfma_f32_16x16x32_bf16 v[34:37], v[46:49], v[2:5], 0
	ds_read_b64_tr_b16 v[2:3], v128 offset:62560
	ds_read_b64_tr_b16 v[4:5], v128 offset:63648
	s_lshl_b64 s[2:3], s[20:21], 16
	s_lshl_b64 s[4:5], s[16:17], 13
	s_waitcnt lgkmcnt(0)
	v_mfma_f32_16x16x32_bf16 v[30:33], v[46:49], v[2:5], 0
	ds_read_b64_tr_b16 v[2:3], v128 offset:62592
	ds_read_b64_tr_b16 v[4:5], v128 offset:63680
	v_readlane_b32 s18, v241, 36
	v_readlane_b32 s19, v241, 37
	s_waitcnt lgkmcnt(0)
	v_mfma_f32_16x16x32_bf16 v[26:29], v[46:49], v[2:5], 0
	ds_read_b64_tr_b16 v[2:3], v128 offset:62624
	ds_read_b64_tr_b16 v[4:5], v128 offset:63712
	s_add_u32 s4, s18, s4
	s_addc_u32 s5, s19, s5
	s_waitcnt lgkmcnt(0)
	v_mfma_f32_16x16x32_bf16 v[22:25], v[46:49], v[2:5], 0
	ds_read_b64_tr_b16 v[2:3], v128 offset:62656
	ds_read_b64_tr_b16 v[4:5], v128 offset:63744
	s_add_u32 s2, s4, s2
	s_addc_u32 s3, s5, s3
	s_waitcnt lgkmcnt(0)
	v_mfma_f32_16x16x32_bf16 v[18:21], v[46:49], v[2:5], 0
	ds_read_b64_tr_b16 v[2:3], v128 offset:62688
	ds_read_b64_tr_b16 v[4:5], v128 offset:63776
	v_lshlrev_b32_e32 v70, 4, v134
	s_mov_b64 s[4:5], 0
	s_waitcnt lgkmcnt(0)
	v_mfma_f32_16x16x32_bf16 v[14:17], v[46:49], v[2:5], 0
	v_mov_b64_e32 v[2:3], s[8:9]
	v_mov_b64_e32 v[4:5], s[10:11]
	v_mfma_f32_16x16x32_bf16 v[42:45], v[46:49], v[6:9], 0
	s_nop 0
	v_mfma_f32_16x16x32_bf16 v[6:9], v[46:49], v[2:5], 0
	ds_read_b128 v[50:53], v127 offset:128
	ds_read_b128 v[46:49], v127 offset:144
	ds_read_b64_tr_b16 v[94:95], v136 offset:53760
	ds_read_b64_tr_b16 v[96:97], v136 offset:54848
	s_waitcnt lgkmcnt(1)
	v_lshlrev_b32_e32 v98, 16, v94
	v_and_b32_e32 v99, 0xffff0000, v94
	v_lshlrev_b32_e32 v94, 16, v95
	v_and_b32_e32 v95, 0xffff0000, v95
	v_pk_mul_f32 v[50:51], v[50:51], v[98:99]
	v_pk_mul_f32 v[52:53], v[52:53], v[94:95]
	v_cvt_pk_bf16_f32 v50, v50, v51
	v_cvt_pk_bf16_f32 v51, v52, v53
	s_waitcnt lgkmcnt(0)
; #define GAS __attribute__((address_space(1)))
; __device__ __forceinline__ void ml_loc_unit(LAS unsigned char* lds, const MixBufs& B, int b, int h, int seg, int tid) {
;     ...
;     for (int cp = 0; cp < 4; ++cp) { const int ch0 = 8 * seg + 2 * cp; MLL_BODY(0, ch0, cp < 3); MLL_BODY(1, ch0 + 1, cp < 3); }
;     __syncthreads();
;     ...
;     const size_t u = ((size_t)b * 4 + h) * 3 + seg;
; #pragma unroll
;     for (int vt = 0; vt < 8; ++vt) *(GAS f32x4*)(B.Lm + (((u * 8 + w) * 8 + vt) * 64 + lane) * 4) = C[vt];
;     if (c == 0) *(GAS f32x4*)(B.nL + u * 128 + 16 * w + 4 * g) = nv;
	v_lshlrev_b32_e32 v52, 16, v96
	v_and_b32_e32 v53, 0xffff0000, v96
	v_pk_mul_f32 v[46:47], v[46:47], v[52:53]
	s_nop 0
	v_cvt_pk_bf16_f32 v52, v46, v47
	v_lshlrev_b32_e32 v46, 16, v97
	v_and_b32_e32 v47, 0xffff0000, v97
	v_pk_mul_f32 v[46:47], v[48:49], v[46:47]
	s_nop 0
	v_cvt_pk_bf16_f32 v53, v46, v47
	ds_read_b64_tr_b16 v[48:49], v135 offset:63552
	ds_read_b64_tr_b16 v[46:47], v135 offset:62464
	ds_read_b64_tr_b16 v[94:95], v135 offset:62496
	s_waitcnt lgkmcnt(1)
	v_mfma_f32_16x16x32_bf16 v[38:41], v[50:53], v[46:49], v[38:41]
	ds_read_b64_tr_b16 v[96:97], v135 offset:63584
	ds_read_b64_tr_b16 v[46:47], v135 offset:62528
	ds_read_b64_tr_b16 v[48:49], v135 offset:63616
	s_nop 4
	v_pk_mul_f32 v[40:41], v[60:61], v[40:41] op_sel_hi:[0,1]
	s_waitcnt lgkmcnt(0)
	v_mfma_f32_16x16x32_bf16 v[34:37], v[50:53], v[46:49], v[34:37]
	ds_read_b64_tr_b16 v[46:47], v135 offset:62560
	ds_read_b64_tr_b16 v[48:49], v135 offset:63648
	v_pk_mul_f32 v[38:39], v[60:61], v[38:39] op_sel_hi:[0,1]
	v_pk_fma_f32 v[40:41], v[122:123], v[58:59], v[40:41] op_sel_hi:[1,0,1]
	s_waitcnt lgkmcnt(0)
	v_mfma_f32_16x16x32_bf16 v[30:33], v[50:53], v[46:49], v[30:33]
	ds_read_b64_tr_b16 v[46:47], v135 offset:62592
	ds_read_b64_tr_b16 v[48:49], v135 offset:63680
	v_pk_fma_f32 v[38:39], v[90:91], v[58:59], v[38:39] op_sel_hi:[1,0,1]
	v_pk_mul_f32 v[36:37], v[60:61], v[36:37] op_sel_hi:[0,1]
	s_waitcnt lgkmcnt(0)
	v_mfma_f32_16x16x32_bf16 v[26:29], v[50:53], v[46:49], v[26:29]
	ds_read_b64_tr_b16 v[46:47], v135 offset:62624
	ds_read_b64_tr_b16 v[48:49], v135 offset:63712
	v_pk_mul_f32 v[34:35], v[60:61], v[34:35] op_sel_hi:[0,1]
	v_pk_mul_f32 v[32:33], v[60:61], v[32:33] op_sel_hi:[0,1]
	s_waitcnt lgkmcnt(0)
	v_mfma_f32_16x16x32_bf16 v[22:25], v[50:53], v[46:49], v[22:25]
	ds_read_b64_tr_b16 v[46:47], v135 offset:62656
	ds_read_b64_tr_b16 v[48:49], v135 offset:63744
	v_pk_mul_f32 v[30:31], v[60:61], v[30:31] op_sel_hi:[0,1]
	v_pk_fma_f32 v[36:37], v[114:115], v[58:59], v[36:37] op_sel_hi:[1,0,1]
	s_waitcnt lgkmcnt(0)
	v_mfma_f32_16x16x32_bf16 v[18:21], v[50:53], v[46:49], v[18:21]
	ds_read_b64_tr_b16 v[46:47], v135 offset:62688
	ds_read_b64_tr_b16 v[48:49], v135 offset:63776
	v_pk_fma_f32 v[34:35], v[86:87], v[58:59], v[34:35] op_sel_hi:[1,0,1]
	v_pk_fma_f32 v[32:33], v[88:89], v[58:59], v[32:33] op_sel_hi:[1,0,1]
	v_mfma_f32_16x16x32_bf16 v[42:45], v[50:53], v[94:97], v[42:45]
	v_fma_f32 v30, v82, v58, v30
	v_fma_f32 v31, v83, v58, v31
	s_waitcnt lgkmcnt(0)
	s_barrier
	s_setprio 0
	v_mfma_f32_16x16x32_bf16 v[14:17], v[50:53], v[46:49], v[14:17]
	s_nop 2
	v_mul_f32_e64 v44, v60, v44
	v_mul_f32_e64 v45, v60, v45
	v_pk_mul_f32 v[42:43], v[60:61], v[42:43] op_sel_hi:[0,1]
	v_pk_fma_f32 v[44:45], v[118:119], v[58:59], v[44:45] op_sel_hi:[1,0,1]
	v_pk_fma_f32 v[42:43], v[92:93], v[58:59], v[42:43] op_sel_hi:[1,0,1]
	v_mfma_f32_16x16x32_bf16 v[6:9], v[50:53], v[2:5], v[6:9]
	v_lshl_add_u64 v[2:3], s[2:3], 0, v[70:71]
	global_store_dwordx4 v70, v[38:41], s[2:3]
	global_store_dwordx4 v70, v[42:45], s[2:3] offset:1024
	global_store_dwordx4 v70, v[34:37], s[2:3] offset:2048
	global_store_dwordx4 v70, v[30:33], s[2:3] offset:3072
	s_movk_i32 s2, 0x1000
	v_add_co_u32_e32 v2, vcc, s2, v2
	v_pk_mul_f32 v[28:29], v[60:61], v[28:29] op_sel_hi:[0,1]
	v_pk_mul_f32 v[26:27], v[60:61], v[26:27] op_sel_hi:[0,1]
	v_pk_mul_f32 v[14:15], v[60:61], v[14:15] op_sel_hi:[0,1]
	v_addc_co_u32_e32 v3, vcc, 0, v3, vcc
	v_pk_fma_f32 v[28:29], v[84:85], v[58:59], v[28:29] op_sel_hi:[1,0,1]
	v_pk_fma_f32 v[26:27], v[78:79], v[58:59], v[26:27] op_sel_hi:[1,0,1]
	v_pk_mul_f32 v[24:25], v[60:61], v[24:25] op_sel_hi:[0,1]
	v_pk_mul_f32 v[22:23], v[60:61], v[22:23] op_sel_hi:[0,1]
	v_pk_mul_f32 v[20:21], v[60:61], v[20:21] op_sel_hi:[0,1]
	v_pk_mul_f32 v[18:19], v[60:61], v[18:19] op_sel_hi:[0,1]
	v_pk_mul_f32 v[16:17], v[60:61], v[16:17] op_sel_hi:[0,1]
	v_pk_fma_f32 v[14:15], v[62:63], v[58:59], v[14:15] op_sel_hi:[1,0,1]
	v_cmp_eq_u32_e32 vcc, 0, v132
	s_mov_b64 s[2:3], 0
	v_pk_fma_f32 v[24:25], v[80:81], v[58:59], v[24:25] op_sel_hi:[1,0,1]
	v_pk_fma_f32 v[22:23], v[68:69], v[58:59], v[22:23] op_sel_hi:[1,0,1]
	v_pk_fma_f32 v[20:21], v[72:73], v[58:59], v[20:21] op_sel_hi:[1,0,1]
	v_pk_fma_f32 v[18:19], v[64:65], v[58:59], v[18:19] op_sel_hi:[1,0,1]
	v_pk_fma_f32 v[16:17], v[66:67], v[58:59], v[16:17] op_sel_hi:[1,0,1]
	global_store_dwordx4 v[2:3], v[26:29], off
	global_store_dwordx4 v[2:3], v[22:25], off offset:1024
	global_store_dwordx4 v[2:3], v[18:21], off offset:2048
	global_store_dwordx4 v[2:3], v[14:17], off offset:3072
	s_and_saveexec_b64 s[18:19], vcc
	s_xor_b64 s[18:19], exec, s[18:19]
	s_cbranch_execz .LBB0_411
	s_lshl_b64 s[4:5], s[20:21], 9
	v_readlane_b32 s6, v240, 5
	s_add_u32 s6, s6, s4
	v_readlane_b32 s4, v240, 6
	s_addc_u32 s15, s4, s5
	s_lshl_b32 s4, s16, 4
	v_mov_b32_e32 v57, v56
	v_mov_b32_e32 v2, v56
	v_mov_b32_e32 v3, v56
	s_ashr_i32 s5, s4, 31
	v_mov_b32_e32 v55, v54
	v_pk_mul_f32 v[2:3], v[2:3], v[12:13]
	v_pk_mul_f32 v[4:5], v[56:57], v[10:11]
	v_mov_b32_e32 v10, v54
	v_mov_b32_e32 v11, v54
	s_lshl_b64 s[4:5], s[4:5], 2
	v_mov_b32_e32 v61, v60
	v_pk_fma_f32 v[2:3], v[76:77], v[10:11], v[2:3]
	v_pk_fma_f32 v[10:11], v[74:75], v[54:55], v[4:5]
	v_mov_b32_e32 v4, v60
	v_mov_b32_e32 v5, v60
	s_add_u32 s4, s6, s4
	v_mov_b32_e32 v59, v58
	v_pk_mul_f32 v[4:5], v[4:5], v[8:9]
	v_pk_mul_f32 v[6:7], v[60:61], v[6:7]
	v_mov_b32_e32 v8, v58
	v_mov_b32_e32 v9, v58
	s_addc_u32 s5, s15, s5
	v_lshlrev_b32_e32 v70, 4, v133
	v_pk_fma_f32 v[4:5], v[2:3], v[8:9], v[4:5]
	v_pk_fma_f32 v[2:3], v[10:11], v[58:59], v[6:7]
	v_lshl_add_u64 v[14:15], s[4:5], 0, v[70:71]
	s_mov_b64 s[4:5], exec

; #define LAS __attribute__((address_space(3)))
; #define MFMA16(a, b, c) __builtin_amdgcn_mfma_f32_16x16x32_bf16((a), (b), (c), 0, 0, 0)
; __device__ __forceinline__ float bflo(unsigned w) { return __uint_as_float(w << 16); }
; __device__ __forceinline__ float bfhi(unsigned w) { return __uint_as_float(w & 0xffff0000u); }
; template <bool FULL> __device__ __forceinline__ void gla_unit(LAS unsigned char* lds, const MixBufs& B, int b, int h, int seg, int tid) {
;     ...
;         { const v4u ee = re[st]; const f32x4 e0 = (f32x4){bflo(ee.x), bfhi(ee.x), bflo(ee.y), bfhi(ee.y)}, e1 = (f32x4){bflo(ee.z), bfhi(ee.z), bflo(ee.w), bfhi(ee.w)};
;           f32x4 i0, i1;
; #pragma unroll
;           for (int e = 0; e < 4; ++e) { i0[e] = __builtin_amdgcn_rcpf(e0[e]); i1[e] = __builtin_amdgcn_rcpf(e1[e]); }
;           *(LAS v4u*)(lds + okf + lr * GP64 + lc * 16) = mul_bf8(rk[st], i0, i1);
;           if (FULL) { *(LAS v4u*)(lds + G_KB + lr * GP64 + lc * 16) = mul_bf8(rk[st], e0, e1);
;                       *(LAS v4u*)(lds + G_QF + lr * GP64 + lc * 16) = mul_bf8(rq[st], e0, e1); *(LAS v4u*)(lds + G_QB + lr * GP64 + lc * 16) = mul_bf8(rq[st], i0, i1); } }
;         *(LAS v4u*)(lds + ov + vr * GP128 + vc * 16) = rv0[st]; *(LAS v4u*)(lds + ov + (vr + 32) * GP128 + vc * 16) = rv1[st];
;         if (tid < 64) DLc[tid] = rdl[st];
;     ...
; #pragma unroll
;         for (int ks = 0; ks < 2; ++ks) { const bf16x8 kf = frag_tr(lds + okf, GP64, 32 * ks, 16 * kt, lane);
; #pragma unroll
;             for (int j = 0; j < 4; ++j) S[j] = MFMA16(kf, vfr[j][ks], S[j]); }
;         { const f32x4 dl = *(const LAS f32x4*)(DLc + 16 * kt + 4 * g);
; #pragma unroll
;           for (int j = 0; j < 4; ++j) S[j] *= dl; }
.LBB0_442:
	s_or_b64 exec, exec, s[18:19]
	s_waitcnt lgkmcnt(0)
	s_barrier
	ds_read_b64_tr_b16 v[72:73], v98 offset:18432
	ds_read_b64_tr_b16 v[74:75], v98 offset:19008
	ds_read_b64_tr_b16 v[76:77], v94 offset:36864
	ds_read_b64_tr_b16 v[78:79], v94 offset:37952
	ds_read_b64_tr_b16 v[100:101], v94 offset:36896
	ds_read_b64_tr_b16 v[102:103], v94 offset:37984
	ds_read_b64_tr_b16 v[104:105], v94 offset:36928
	v_pk_mul_f32 v[56:57], v[56:57], v[64:65]
	v_pk_mul_f32 v[54:55], v[54:55], v[62:63]
	v_pk_mul_f32 v[52:53], v[52:53], v[64:65]
	v_pk_mul_f32 v[50:51], v[50:51], v[62:63]
	s_waitcnt lgkmcnt(3)
	v_mfma_f32_16x16x32_bf16 v[54:57], v[72:75], v[76:79], v[54:57]
	ds_read_b64_tr_b16 v[76:77], v98 offset:23040
	ds_read_b64_tr_b16 v[78:79], v98 offset:23616
	ds_read_b64_tr_b16 v[106:107], v94 offset:38016
	v_pk_mul_f32 v[60:61], v[60:61], v[64:65]
	v_pk_mul_f32 v[58:59], v[58:59], v[62:63]
	s_waitcnt lgkmcnt(4)
	v_mfma_f32_16x16x32_bf16 v[50:53], v[72:75], v[100:103], v[50:53]
	ds_read_b64_tr_b16 v[100:101], v95 offset:36864
	ds_read_b64_tr_b16 v[102:103], v95 offset:37952
	v_pk_mul_f32 v[64:65], v[68:69], v[64:65]
	v_pk_mul_f32 v[62:63], v[66:67], v[62:63]
	s_waitcnt lgkmcnt(2)
	v_mfma_f32_16x16x32_bf16 v[58:61], v[72:75], v[104:107], v[58:61]
	ds_read_b64_tr_b16 v[104:105], v94 offset:45568
	s_waitcnt vmcnt(10)
	v_lshlrev_b32_e32 v70, 16, v46
	s_waitcnt lgkmcnt(1)
	v_mfma_f32_16x16x32_bf16 v[66:69], v[72:75], v[100:103], v[62:65]
	ds_read_b64_tr_b16 v[106:107], v94 offset:46656
	ds_read_b64_tr_b16 v[72:73], v94 offset:45600
	s_waitcnt lgkmcnt(1)
	v_mfma_f32_16x16x32_bf16 v[62:65], v[76:79], v[104:107], v[54:57]
	ds_read_b64_tr_b16 v[74:75], v94 offset:46688
	s_nop 1
	ds_read_b64_tr_b16 v[54:55], v94 offset:45632
	s_waitcnt lgkmcnt(1)
	v_mfma_f32_16x16x32_bf16 v[50:53], v[76:79], v[72:75], v[50:53]
	ds_read_b64_tr_b16 v[56:57], v94 offset:46720
	ds_read_b64_tr_b16 v[72:73], v95 offset:45568
	s_waitcnt lgkmcnt(1)
	v_mfma_f32_16x16x32_bf16 v[54:57], v[76:79], v[54:57], v[58:61]
	ds_read_b64_tr_b16 v[74:75], v95 offset:46656
	s_nop 1
	ds_read_b128 v[58:61], v92
	s_waitcnt lgkmcnt(1)
	v_mfma_f32_16x16x32_bf16 v[66:69], v[76:79], v[72:75], v[66:69]
	v_and_b32_e32 v72, 0xffff0000, v46
	v_lshlrev_b32_e32 v73, 16, v47
	v_and_b32_e32 v75, 0xffff0000, v47
	v_lshlrev_b32_e32 v47, 16, v48
	v_and_b32_e32 v74, 0xffff0000, v48
	v_rcp_f32_e32 v46, v70
	v_rcp_f32_e32 v48, v47
	v_rcp_f32_e32 v47, v72
	v_lshlrev_b32_e32 v76, 16, v49
	v_and_b32_e32 v77, 0xffff0000, v49
	v_rcp_f32_e32 v72, v73
	v_rcp_f32_e32 v73, v75
	v_rcp_f32_e32 v49, v74
	v_rcp_f32_e32 v74, v76
	v_rcp_f32_e32 v75, v77
	v_lshlrev_b32_e32 v76, 16, v30
	v_and_b32_e32 v77, 0xffff0000, v30
	v_pk_mul_f32 v[46:47], v[46:47], v[76:77]
	s_nop 0
	v_cvt_pk_bf16_f32 v30, v46, v47
	v_lshlrev_b32_e32 v46, 16, v31
	v_and_b32_e32 v47, 0xffff0000, v31
	v_pk_mul_f32 v[46:47], v[72:73], v[46:47]
	s_nop 0
	v_cvt_pk_bf16_f32 v31, v46, v47
	v_lshlrev_b32_e32 v46, 16, v32
	v_and_b32_e32 v47, 0xffff0000, v32
	v_pk_mul_f32 v[46:47], v[48:49], v[46:47]
	s_nop 0
	v_cvt_pk_bf16_f32 v32, v46, v47
	v_lshlrev_b32_e32 v46, 16, v33
	v_and_b32_e32 v47, 0xffff0000, v33
	v_pk_mul_f32 v[46:47], v[74:75], v[46:47]
	s_nop 0
	v_cvt_pk_bf16_f32 v33, v46, v47
	ds_write_b128 v82, v[30:33]
	s_waitcnt vmcnt(9)
	ds_write_b128 v87, v[34:37] offset:63488
	s_waitcnt vmcnt(8)
	ds_write_b128 v84, v[38:41] offset:8704
	s_and_saveexec_b64 s[16:17], s[2:3]
	v_add_u32_e32 v30, 0x16c00, v86
	ds_write_b32 v30, v97
	s_or_b64 exec, exec, s[16:17]
	s_waitcnt lgkmcnt(0)
	s_barrier
	ds_read_b64_tr_b16 v[34:35], v93
	ds_read_b64_tr_b16 v[36:37], v93 offset:576
	v_pk_mul_f32 v[32:33], v[64:65], v[60:61]
	v_pk_mul_f32 v[30:31], v[62:63], v[58:59]
	ds_read_b64_tr_b16 v[38:39], v94 offset:63488
	ds_read_b64_tr_b16 v[40:41], v94 offset:64576
	ds_read_b64_tr_b16 v[46:47], v94 offset:63520
	ds_read_b64_tr_b16 v[48:49], v94 offset:64608
	ds_read_b64_tr_b16 v[62:63], v94 offset:63552
	ds_read_b64_tr_b16 v[72:73], v93 offset:4608
	ds_read_b64_tr_b16 v[74:75], v93 offset:5184
	s_waitcnt lgkmcnt(5)
	v_mfma_f32_16x16x32_bf16 v[30:33], v[34:37], v[38:41], v[30:33]
	ds_read_b64_tr_b16 v[64:65], v94 offset:64640
	ds_read_b64_tr_b16 v[38:39], v95 offset:63488
	ds_read_b64_tr_b16 v[40:41], v95 offset:64576
	v_pk_mul_f32 v[52:53], v[52:53], v[60:61]
	v_pk_mul_f32 v[50:51], v[50:51], v[58:59]
	s_waitcnt lgkmcnt(6)
	s_nop 0
	v_mfma_f32_16x16x32_bf16 v[46:49], v[34:37], v[46:49], v[50:53]
	s_nop 2
	v_mul_f32_e64 v52, v56, v60
	v_mul_f32_e64 v53, v57, v61
	v_pk_mul_f32 v[50:51], v[54:55], v[58:59]
	v_pk_mul_f32 v[56:57], v[68:69], v[60:61]
	v_pk_mul_f32 v[54:55], v[66:67], v[58:59]
	ds_read_b64_tr_b16 v[58:59], v90 offset:64576
	s_waitcnt lgkmcnt(3)
	v_mfma_f32_16x16x32_bf16 v[50:53], v[34:37], v[62:65], v[50:53]
	s_waitcnt lgkmcnt(1)
	v_mfma_f32_16x16x32_bf16 v[60:63], v[34:37], v[38:41], v[54:57]
	s_nop 2
	ds_read_b64_tr_b16 v[56:57], v90 offset:63488
	ds_read_b64_tr_b16 v[40:41], v90 offset:64608
	ds_read_b64_tr_b16 v[38:39], v90 offset:63520
	ds_read_b64_tr_b16 v[54:55], v90 offset:63552
	s_waitcnt lgkmcnt(3)
	v_mfma_f32_16x16x32_bf16 v[34:37], v[72:75], v[56:59], v[30:33]
	ds_read_b64_tr_b16 v[56:57], v90 offset:64640
	ds_read_b64_tr_b16 v[58:59], v88 offset:64576
	s_waitcnt lgkmcnt(3)
	v_mfma_f32_16x16x32_bf16 v[30:33], v[72:75], v[38:41], v[46:49]
	s_waitcnt lgkmcnt(1)
	v_mfma_f32_16x16x32_bf16 v[38:41], v[72:75], v[54:57], v[50:53]
	ds_read_b64_tr_b16 v[56:57], v88 offset:63488
	ds_read_b128 v[46:49], v96
	s_waitcnt vmcnt(6)
	v_lshlrev_b32_e32 v54, 16, v14
	v_and_b32_e32 v55, 0xffff0000, v14
	s_waitcnt lgkmcnt(1)
	v_mfma_f32_16x16x32_bf16 v[50:53], v[72:75], v[56:59], v[60:63]
	v_lshlrev_b32_e32 v56, 16, v15
	v_and_b32_e32 v57, 0xffff0000, v15
	v_lshlrev_b32_e32 v15, 16, v16
	v_and_b32_e32 v58, 0xffff0000, v16
	v_rcp_f32_e32 v14, v54
	v_rcp_f32_e32 v16, v15
	v_rcp_f32_e32 v15, v55
	v_lshlrev_b32_e32 v59, 16, v17
	v_rcp_f32_e32 v54, v56
	v_rcp_f32_e32 v55, v57
	v_and_b32_e32 v60, 0xffff0000, v17
	v_rcp_f32_e32 v17, v58
	v_rcp_f32_e32 v56, v59
	v_lshlrev_b32_e32 v58, 16, v2
	v_and_b32_e32 v59, 0xffff0000, v2
	v_pk_mul_f32 v[14:15], v[14:15], v[58:59]
	v_rcp_f32_e32 v57, v60
	v_cvt_pk_bf16_f32 v2, v14, v15
	v_lshlrev_b32_e32 v14, 16, v3
	v_and_b32_e32 v15, 0xffff0000, v3
	v_pk_mul_f32 v[14:15], v[54:55], v[14:15]
	s_nop 0
	v_cvt_pk_bf16_f32 v3, v14, v15
	v_lshlrev_b32_e32 v14, 16, v4
	v_and_b32_e32 v15, 0xffff0000, v4
	v_pk_mul_f32 v[14:15], v[16:17], v[14:15]
	s_nop 0
	v_cvt_pk_bf16_f32 v4, v14, v15
	v_lshlrev_b32_e32 v14, 16, v5
	v_and_b32_e32 v15, 0xffff0000, v5
	v_pk_mul_f32 v[14:15], v[56:57], v[14:15]
	s_nop 0
	v_cvt_pk_bf16_f32 v5, v14, v15
	ds_write_b128 v91, v[2:5] offset:18432
	s_waitcnt vmcnt(5)
	ds_write_b128 v87, v[6:9] offset:36864
	s_waitcnt vmcnt(4)
	ds_write_b128 v87, v[10:13] offset:45568
	s_and_saveexec_b64 s[16:17], s[2:3]
	v_add_u32_e32 v2, 0x14000, v86
	ds_write_b32 v2, v89
	s_or_b64 exec, exec, s[16:17]
	s_waitcnt lgkmcnt(0)
	s_barrier
; #define GAS __attribute__((address_space(1)))
; #define LAS __attribute__((address_space(3)))
; #define MFMA16(a, b, c) __builtin_amdgcn_mfma_f32_16x16x32_bf16((a), (b), (c), 0, 0, 0)
; __device__ __forceinline__ float bflo(unsigned w) { return __uint_as_float(w << 16); }
; __device__ __forceinline__ float bfhi(unsigned w) { return __uint_as_float(w & 0xffff0000u); }
; template <bool FULL> __device__ __forceinline__ void gla_unit(LAS unsigned char* lds, const MixBufs& B, int b, int h, int seg, int tid) {
;     ...
;         { const v4u ee = re[st]; const f32x4 e0 = (f32x4){bflo(ee.x), bfhi(ee.x), bflo(ee.y), bfhi(ee.y)}, e1 = (f32x4){bflo(ee.z), bfhi(ee.z), bflo(ee.w), bfhi(ee.w)};
;           f32x4 i0, i1;
; #pragma unroll
;           for (int e = 0; e < 4; ++e) { i0[e] = __builtin_amdgcn_rcpf(e0[e]); i1[e] = __builtin_amdgcn_rcpf(e1[e]); }
;           *(LAS v4u*)(lds + okf + lr * GP64 + lc * 16) = mul_bf8(rk[st], i0, i1);
;           if (FULL) { *(LAS v4u*)(lds + G_KB + lr * GP64 + lc * 16) = mul_bf8(rk[st], e0, e1);
;                       *(LAS v4u*)(lds + G_QF + lr * GP64 + lc * 16) = mul_bf8(rq[st], e0, e1); *(LAS v4u*)(lds + G_QB + lr * GP64 + lc * 16) = mul_bf8(rq[st], i0, i1); } }
;         *(LAS v4u*)(lds + ov + vr * GP128 + vc * 16) = rv0[st]; *(LAS v4u*)(lds + ov + (vr + 32) * GP128 + vc * 16) = rv1[st];
;         if (tid < 64) DLc[tid] = rdl[st];
;     ...
; #pragma unroll
;         for (int ks = 0; ks < 2; ++ks) { const bf16x8 kf = frag_tr(lds + okf, GP64, 32 * ks, 16 * kt, lane);
; #pragma unroll
;             for (int j = 0; j < 4; ++j) S[j] = MFMA16(kf, vfr[j][ks], S[j]); }
;         { const f32x4 dl = *(const LAS f32x4*)(DLc + 16 * kt + 4 * g);
; #pragma unroll
;           for (int j = 0; j < 4; ++j) S[j] *= dl; }
;     }
;     __syncthreads();
;     ...
;     if (!FULL) { const size_t u = ((size_t)b * 4 + h) * 3 + seg;
; #pragma unroll
;         for (int j = 0; j < 4; ++j) *(GAS f32x4*)(B.Lg + (((u * 8 + w) * 4 + j) * 64 + lane) * 4) = S[j]; }
	ds_read_b64_tr_b16 v[6:7], v98 offset:18432
	ds_read_b64_tr_b16 v[8:9], v98 offset:19008
	v_pk_mul_f32 v[2:3], v[34:35], v[46:47]
	v_pk_mul_f32 v[12:13], v[32:33], v[48:49]
	ds_read_b64_tr_b16 v[14:15], v94 offset:36864
	ds_read_b64_tr_b16 v[16:17], v94 offset:37952
	v_pk_mul_f32 v[10:11], v[30:31], v[46:47]
	ds_read_b64_tr_b16 v[30:31], v94 offset:36896
	ds_read_b64_tr_b16 v[32:33], v94 offset:37984
	ds_read_b64_tr_b16 v[34:35], v94 offset:36928
	v_pk_mul_f32 v[4:5], v[36:37], v[48:49]
	ds_read_b64_tr_b16 v[54:55], v98 offset:23040
	ds_read_b64_tr_b16 v[56:57], v98 offset:23616
	ds_read_b64_tr_b16 v[36:37], v94 offset:38016
	s_waitcnt lgkmcnt(4)
	v_mfma_f32_16x16x32_bf16 v[10:13], v[6:9], v[30:33], v[10:13]
	ds_read_b64_tr_b16 v[30:31], v95 offset:36864
	ds_read_b64_tr_b16 v[32:33], v95 offset:37952
	v_mfma_f32_16x16x32_bf16 v[2:5], v[6:9], v[14:17], v[2:5]
	v_mul_f32_e64 v16, v40, v48
	v_mul_f32_e64 v17, v41, v49
	v_pk_mul_f32 v[14:15], v[38:39], v[46:47]
	v_pk_mul_f32 v[40:41], v[52:53], v[48:49]
	v_pk_mul_f32 v[38:39], v[50:51], v[46:47]
	s_waitcnt lgkmcnt(2)
	v_mfma_f32_16x16x32_bf16 v[34:37], v[6:9], v[34:37], v[14:17]
	s_nop 2
	ds_read_b64_tr_b16 v[14:15], v94 offset:45568
	s_waitcnt lgkmcnt(1)
	v_mfma_f32_16x16x32_bf16 v[30:33], v[6:9], v[30:33], v[38:41]
	ds_read_b64_tr_b16 v[16:17], v94 offset:46656
	ds_read_b64_tr_b16 v[6:7], v94 offset:45600
	ds_read_b64_tr_b16 v[8:9], v94 offset:46688
	ds_read_b64_tr_b16 v[38:39], v94 offset:45632
	ds_read_b64_tr_b16 v[40:41], v94 offset:46720
	ds_read_b64_tr_b16 v[46:47], v95 offset:45568
	s_waitcnt lgkmcnt(5)
	v_mfma_f32_16x16x32_bf16 v[14:17], v[54:57], v[14:17], v[2:5]
	s_waitcnt lgkmcnt(3)
	v_mfma_f32_16x16x32_bf16 v[2:5], v[54:57], v[6:9], v[10:13]
	ds_read_b64_tr_b16 v[48:49], v95 offset:46656
	s_nop 1
	ds_read_b128 v[10:13], v92
	s_waitcnt lgkmcnt(3)
	v_mfma_f32_16x16x32_bf16 v[6:9], v[54:57], v[38:41], v[34:37]
	s_waitcnt vmcnt(2)
	v_lshlrev_b32_e32 v38, 16, v43
	v_and_b32_e32 v39, 0xffff0000, v43
	v_rcp_f32_e32 v38, v38
	v_lshlrev_b32_e32 v34, 16, v42
	v_and_b32_e32 v35, 0xffff0000, v42
	v_rcp_f32_e32 v34, v34
	v_rcp_f32_e32 v35, v35
	v_rcp_f32_e32 v39, v39
	v_lshlrev_b32_e32 v36, 16, v44
	v_and_b32_e32 v37, 0xffff0000, v44
	v_lshlrev_b32_e32 v42, 16, v18
	v_and_b32_e32 v43, 0xffff0000, v18
	v_rcp_f32_e32 v36, v36
	v_rcp_f32_e32 v37, v37
	v_pk_mul_f32 v[34:35], v[34:35], v[42:43]
	v_lshlrev_b32_e32 v40, 16, v45
	v_and_b32_e32 v41, 0xffff0000, v45
	v_cvt_pk_bf16_f32 v18, v34, v35
	v_lshlrev_b32_e32 v34, 16, v19
	v_and_b32_e32 v35, 0xffff0000, v19
	v_rcp_f32_e32 v40, v40
	v_rcp_f32_e32 v41, v41
	v_pk_mul_f32 v[34:35], v[38:39], v[34:35]
	s_waitcnt lgkmcnt(1)
	v_mfma_f32_16x16x32_bf16 v[30:33], v[54:57], v[46:49], v[30:33]
	v_cvt_pk_bf16_f32 v19, v34, v35
	v_lshlrev_b32_e32 v34, 16, v20
	v_and_b32_e32 v35, 0xffff0000, v20
	v_pk_mul_f32 v[34:35], v[36:37], v[34:35]
	s_nop 0
	v_cvt_pk_bf16_f32 v20, v34, v35
	v_lshlrev_b32_e32 v34, 16, v21
	v_and_b32_e32 v35, 0xffff0000, v21
	v_pk_mul_f32 v[34:35], v[40:41], v[34:35]
	s_nop 0
	v_cvt_pk_bf16_f32 v21, v34, v35
	ds_write_b128 v82, v[18:21]
	s_waitcnt vmcnt(1)
	ds_write_b128 v87, v[22:25] offset:63488
	s_waitcnt vmcnt(0)
	ds_write_b128 v84, v[26:29] offset:8704
	s_and_saveexec_b64 s[16:17], s[2:3]
	v_add_u32_e32 v18, 0x16c00, v86
	ds_write_b32 v18, v83
	s_or_b64 exec, exec, s[16:17]
	s_waitcnt lgkmcnt(0)
	s_barrier
	ds_read_b64_tr_b16 v[18:19], v93
	ds_read_b64_tr_b16 v[20:21], v93 offset:576
	v_pk_mul_f32 v[16:17], v[16:17], v[12:13]
	v_pk_mul_f32 v[14:15], v[14:15], v[10:11]
	ds_read_b64_tr_b16 v[22:23], v94 offset:63488
	ds_read_b64_tr_b16 v[24:25], v94 offset:64576
	ds_read_b64_tr_b16 v[26:27], v94 offset:63520
	ds_read_b64_tr_b16 v[28:29], v94 offset:64608
	ds_read_b64_tr_b16 v[34:35], v94 offset:63552
	ds_read_b64_tr_b16 v[38:39], v93 offset:4608
	ds_read_b64_tr_b16 v[40:41], v93 offset:5184
	s_waitcnt lgkmcnt(5)
	v_mfma_f32_16x16x32_bf16 v[14:17], v[18:21], v[22:25], v[14:17]
	ds_read_b64_tr_b16 v[36:37], v94 offset:64640
	ds_read_b64_tr_b16 v[22:23], v95 offset:63488
	ds_read_b64_tr_b16 v[24:25], v95 offset:64576
	v_pk_mul_f32 v[4:5], v[4:5], v[12:13]
	v_pk_mul_f32 v[2:3], v[2:3], v[10:11]
	v_pk_mul_f32 v[8:9], v[8:9], v[12:13]
	v_pk_mul_f32 v[6:7], v[6:7], v[10:11]
	s_waitcnt lgkmcnt(6)
	v_mfma_f32_16x16x32_bf16 v[2:5], v[18:21], v[26:29], v[2:5]
	v_mul_f32_e64 v12, v32, v12
	v_mul_f32_e64 v13, v33, v13
	v_pk_mul_f32 v[10:11], v[30:31], v[10:11]
	ds_read_b64_tr_b16 v[26:27], v90 offset:64576
	s_waitcnt lgkmcnt(3)
	v_mfma_f32_16x16x32_bf16 v[6:9], v[18:21], v[34:37], v[6:9]
	s_lshl_b32 s5, s14, 2
	s_waitcnt lgkmcnt(1)
	v_mfma_f32_16x16x32_bf16 v[10:13], v[18:21], v[22:25], v[10:13]
	ds_read_b64_tr_b16 v[24:25], v90 offset:63488
	ds_read_b64_tr_b16 v[18:19], v90 offset:64608
	s_waitcnt lgkmcnt(1)
	v_mfma_f32_16x16x32_bf16 v[20:23], v[38:41], v[24:27], v[14:17]
	s_nop 2
	ds_read_b64_tr_b16 v[16:17], v90 offset:63520
	ds_read_b64_tr_b16 v[14:15], v90 offset:63552
	s_waitcnt lgkmcnt(1)
	v_mfma_f32_16x16x32_bf16 v[2:5], v[38:41], v[16:19], v[2:5]
	ds_read_b64_tr_b16 v[16:17], v90 offset:64640
	ds_read_b64_tr_b16 v[26:27], v88 offset:64576
	ds_read_b64_tr_b16 v[24:25], v88 offset:63488
	v_and_b32_e32 v18, 0xfc, v85
	v_lshlrev_b32_e32 v70, 2, v18
	s_waitcnt lgkmcnt(2)
	v_mfma_f32_16x16x32_bf16 v[6:9], v[38:41], v[14:17], v[6:9]
	ds_read_b128 v[14:17], v96
	s_waitcnt lgkmcnt(0)
	s_barrier
	s_setprio 0
	v_mfma_f32_16x16x32_bf16 v[10:13], v[38:41], v[24:27], v[10:13]
	v_mul_f32_e64 v24, v2, v14
	v_mul_f32_e64 v25, v3, v15
	v_pk_mul_f32 v[22:23], v[22:23], v[16:17]
	v_pk_mul_f32 v[20:21], v[20:21], v[14:15]
	v_pk_mul_f32 v[26:27], v[4:5], v[16:17]
	s_nop 2
	v_pk_mul_f32 v[2:3], v[10:11], v[14:15]
	v_mov_b32_e32 v10, s72
	v_pk_mul_f32 v[8:9], v[8:9], v[16:17]
	v_readfirstlane_b32 s6, v10
	s_bfe_i64 s[2:3], s[6:7], 0x80000
	s_add_i32 s2, s5, s2
	s_mul_hi_i32 s3, s2, 3
	s_mul_i32 s2, s2, 3
	s_ashr_i32 s5, s73, 31
	s_add_u32 s2, s2, s73
	s_addc_u32 s3, s3, s5
	s_ashr_i32 s5, s4, 31
	s_lshl_b64 s[2:3], s[2:3], 15
	s_lshl_b64 s[4:5], s[4:5], 12
	s_add_u32 s4, s30, s4
	s_addc_u32 s5, s31, s5
	s_add_u32 s2, s4, s2
	s_addc_u32 s3, s5, s3
	v_pk_mul_f32 v[6:7], v[6:7], v[14:15]
	v_lshl_add_u64 v[10:11], s[2:3], 0, v[70:71]
	global_store_dwordx4 v70, v[20:23], s[2:3]
	global_store_dwordx4 v70, v[24:27], s[2:3] offset:1024
	global_store_dwordx4 v70, v[6:9], s[2:3] offset:2048
	s_mov_b64 s[2:3], 0xc00
	v_pk_mul_f32 v[4:5], v[12:13], v[16:17]
	v_lshl_add_u64 v[14:15], v[10:11], 0, s[2:3]
	s_mov_b64 s[4:5], -1

; #define LAS __attribute__((address_space(3)))
; __device__ __forceinline__ f32x4 bf4_to_f32(u32x2 w) { return (f32x4){bflo(w.x), bfhi(w.x), bflo(w.y), bfhi(w.y)}; }
; __device__ __forceinline__ u32x2 f32_to_bf4(f32x4 v) { u32x2 w; w.x = cvtpk(v[0], v[1]); w.y = cvtpk(v[2], v[3]); return w; }
; __device__ __forceinline__ void ml_stage_k(LAS unsigned char* lds, int offK, const LAS float* WL, const u32x2 (&xr)[4], int cg, int ts) {
;     f32x4 wk[4];
; #pragma unroll
;     for (int j = 0; j < 4; ++j) wk[j] = *(const LAS f32x4*)(WL + WL_WK + (cg * 4 + j) * 4);
; #pragma unroll
;     for (int i = 0; i < 4; ++i) { const f32x4 xc = bf4_to_f32(xr[i]);
;         const f32x4 k = wk[0] * xc[0] + wk[1] * xc[1] + wk[2] * xc[2] + wk[3] * xc[3];
;         *(LAS u32x2*)(lds + offK + (4 * ts + i) * GP128 + 8 * cg) = f32_to_bf4(k); }
; }
.LBB0_494:
	v_mov_b32_e32 v18, s15
	ds_read_b64 v[18:19], v18 offset:35120
	ds_read_b128 v[20:23], v140 offset:39936
	ds_read_b128 v[24:27], v140 offset:39952
	ds_read_b128 v[28:31], v140 offset:39968
	ds_read_b128 v[32:35], v140 offset:39984
	v_and_b32_e32 v38, 0xffff0000, v88
	v_lshlrev_b32_e32 v36, 16, v88
	s_waitcnt lgkmcnt(2)
	v_pk_mul_f32 v[44:45], v[26:27], v[38:39] op_sel_hi:[1,0]
	v_pk_mul_f32 v[38:39], v[24:25], v[38:39] op_sel_hi:[1,0]
	v_lshlrev_b32_e32 v40, 16, v89
	v_pk_fma_f32 v[44:45], v[22:23], v[36:37], v[44:45] op_sel_hi:[1,0,1]
	v_pk_fma_f32 v[36:37], v[20:21], v[36:37], v[38:39] op_sel_hi:[1,0,1]
	v_and_b32_e32 v42, 0xffff0000, v89
	s_waitcnt lgkmcnt(1)
	v_pk_fma_f32 v[36:37], v[28:29], v[40:41], v[36:37] op_sel_hi:[1,0,1]
	v_pk_fma_f32 v[38:39], v[30:31], v[40:41], v[44:45] op_sel_hi:[1,0,1]
	s_waitcnt lgkmcnt(0)
	v_pk_fma_f32 v[36:37], v[32:33], v[42:43], v[36:37] op_sel_hi:[1,0,1]
	v_pk_fma_f32 v[38:39], v[34:35], v[42:43], v[38:39] op_sel_hi:[1,0,1]
	v_and_b32_e32 v40, 0xffff0000, v84
	v_cvt_pk_bf16_f32 v36, v36, v37
	v_cvt_pk_bf16_f32 v37, v38, v39
	v_lshlrev_b32_e32 v38, 16, v84
	v_pk_mul_f32 v[46:47], v[26:27], v[40:41] op_sel_hi:[1,0]
	v_pk_mul_f32 v[40:41], v[24:25], v[40:41] op_sel_hi:[1,0]
	v_lshlrev_b32_e32 v42, 16, v85
	v_pk_fma_f32 v[46:47], v[22:23], v[38:39], v[46:47] op_sel_hi:[1,0,1]
	v_pk_fma_f32 v[38:39], v[20:21], v[38:39], v[40:41] op_sel_hi:[1,0,1]
	v_and_b32_e32 v44, 0xffff0000, v85
	v_pk_fma_f32 v[38:39], v[28:29], v[42:43], v[38:39] op_sel_hi:[1,0,1]
	v_pk_fma_f32 v[40:41], v[30:31], v[42:43], v[46:47] op_sel_hi:[1,0,1]
	v_pk_fma_f32 v[38:39], v[32:33], v[44:45], v[38:39] op_sel_hi:[1,0,1]
	v_pk_fma_f32 v[40:41], v[34:35], v[44:45], v[40:41] op_sel_hi:[1,0,1]
	v_cvt_pk_bf16_f32 v38, v38, v39
	v_cvt_pk_bf16_f32 v39, v40, v41
	ds_write2_b64 v143, v[36:37], v[38:39] offset1:34
	v_and_b32_e32 v38, 0xffff0000, v82
	v_lshlrev_b32_e32 v36, 16, v82
	v_pk_mul_f32 v[44:45], v[26:27], v[38:39] op_sel_hi:[1,0]
	v_pk_mul_f32 v[38:39], v[24:25], v[38:39] op_sel_hi:[1,0]
	v_lshlrev_b32_e32 v40, 16, v83
	v_pk_fma_f32 v[44:45], v[22:23], v[36:37], v[44:45] op_sel_hi:[1,0,1]
	v_pk_fma_f32 v[36:37], v[20:21], v[36:37], v[38:39] op_sel_hi:[1,0,1]
	v_and_b32_e32 v42, 0xffff0000, v83
	v_pk_fma_f32 v[36:37], v[28:29], v[40:41], v[36:37] op_sel_hi:[1,0,1]
	v_pk_fma_f32 v[38:39], v[30:31], v[40:41], v[44:45] op_sel_hi:[1,0,1]
	v_pk_fma_f32 v[36:37], v[32:33], v[42:43], v[36:37] op_sel_hi:[1,0,1]
	v_pk_fma_f32 v[38:39], v[34:35], v[42:43], v[38:39] op_sel_hi:[1,0,1]
	v_and_b32_e32 v40, 0xffff0000, v80
	v_cvt_pk_bf16_f32 v36, v36, v37
	v_cvt_pk_bf16_f32 v37, v38, v39
	v_lshlrev_b32_e32 v38, 16, v80
	v_pk_mul_f32 v[26:27], v[26:27], v[40:41] op_sel_hi:[1,0]
	v_pk_mul_f32 v[24:25], v[24:25], v[40:41] op_sel_hi:[1,0]
	v_lshlrev_b32_e32 v42, 16, v81
	v_pk_fma_f32 v[22:23], v[22:23], v[38:39], v[26:27] op_sel_hi:[1,0,1]
	v_pk_fma_f32 v[20:21], v[20:21], v[38:39], v[24:25] op_sel_hi:[1,0,1]
	v_and_b32_e32 v44, 0xffff0000, v81
	v_pk_fma_f32 v[20:21], v[28:29], v[42:43], v[20:21] op_sel_hi:[1,0,1]
	v_pk_fma_f32 v[22:23], v[30:31], v[42:43], v[22:23] op_sel_hi:[1,0,1]
	v_pk_fma_f32 v[20:21], v[32:33], v[44:45], v[20:21] op_sel_hi:[1,0,1]
	v_pk_fma_f32 v[22:23], v[34:35], v[44:45], v[22:23] op_sel_hi:[1,0,1]
	v_cvt_pk_bf16_f32 v20, v20, v21
	v_cvt_pk_bf16_f32 v21, v22, v23
	ds_write2_b64 v143, v[36:37], v[20:21] offset0:68 offset1:102
	ds_write_b128 v141, v[10:13] offset:17408
	ds_write_b128 v141, v[14:17] offset:26112
	s_and_saveexec_b64 s[4:5], s[2:3]
	ds_write_b32 v146, v79 offset:34816
	s_or_b64 exec, exec, s[4:5]
	v_add_f32_e32 v10, v87, v18
	v_max_f32_e32 v11, v19, v19
	v_max_f32_e32 v59, v10, v11
	v_sub_f32_e32 v10, v10, v59
	v_mul_f32_e32 v10, 0x3fb8aa3b, v10
	v_exp_f32_e32 v58, v10
	v_sub_f32_e32 v10, v19, v59
	v_mul_f32_e32 v10, 0x3fb8aa3b, v10
	v_exp_f32_e32 v60, v10
	s_waitcnt lgkmcnt(0)
	s_barrier
	ds_read_b128 v[10:13], v145 offset:34816
	ds_read_b128 v[14:17], v145 offset:34832
	ds_read_b64_tr_b16 v[18:19], v137
	ds_read_b64_tr_b16 v[20:21], v137 offset:1088
	s_mov_b32 s4, 0x3f803f80
	s_mov_b32 s6, s4
	s_mov_b32 s7, s4
	s_waitcnt lgkmcnt(1)
	v_lshlrev_b32_e32 v22, 16, v18
	v_and_b32_e32 v23, 0xffff0000, v18
	v_pk_mul_f32 v[10:11], v[10:11], v[22:23]
	s_mov_b32 s5, s4
	v_cvt_pk_bf16_f32 v50, v10, v11
	v_lshlrev_b32_e32 v10, 16, v19
	v_and_b32_e32 v11, 0xffff0000, v19
	v_pk_mul_f32 v[10:11], v[12:13], v[10:11]
	s_waitcnt vmcnt(5)
	v_lshlrev_b32_e32 v82, 16, v73
	v_cvt_pk_bf16_f32 v51, v10, v11
	s_waitcnt lgkmcnt(0)
	v_lshlrev_b32_e32 v10, 16, v20
	v_and_b32_e32 v11, 0xffff0000, v20
	v_pk_mul_f32 v[10:11], v[14:15], v[10:11]
	v_and_b32_e32 v84, 0xffff0000, v73
	v_cvt_pk_bf16_f32 v52, v10, v11
	v_lshlrev_b32_e32 v10, 16, v21
	v_and_b32_e32 v11, 0xffff0000, v21
	v_pk_mul_f32 v[10:11], v[16:17], v[10:11]
	v_add_u32_e32 v61, 0xb000, v143
	v_cvt_pk_bf16_f32 v53, v10, v11
	ds_read_b64_tr_b16 v[12:13], v144 offset:18496
	ds_read_b64_tr_b16 v[10:11], v144 offset:17408
	ds_read_b64_tr_b16 v[14:15], v144 offset:17440
	s_waitcnt lgkmcnt(1)
	v_mfma_f32_16x16x32_bf16 v[46:49], v[50:53], v[10:13], 0
	ds_read_b64_tr_b16 v[16:17], v144 offset:18528
	ds_read_b64_tr_b16 v[10:11], v144 offset:17472
	ds_read_b64_tr_b16 v[12:13], v144 offset:18560
	s_waitcnt lgkmcnt(0)
	v_mfma_f32_16x16x32_bf16 v[38:41], v[50:53], v[10:13], 0
	ds_read_b64_tr_b16 v[10:11], v144 offset:17504
	ds_read_b64_tr_b16 v[12:13], v144 offset:18592
	s_waitcnt lgkmcnt(0)
	v_mfma_f32_16x16x32_bf16 v[34:37], v[50:53], v[10:13], 0
	ds_read_b64_tr_b16 v[10:11], v144 offset:17536
	ds_read_b64_tr_b16 v[12:13], v144 offset:18624
	s_waitcnt lgkmcnt(0)
; #define LAS __attribute__((address_space(3)))
; __device__ __forceinline__ f32x4 bf4_to_f32(u32x2 w) { return (f32x4){bflo(w.x), bfhi(w.x), bflo(w.y), bfhi(w.y)}; }
; __device__ __forceinline__ u32x2 f32_to_bf4(f32x4 v) { u32x2 w; w.x = cvtpk(v[0], v[1]); w.y = cvtpk(v[2], v[3]); return w; }
; __device__ __forceinline__ void ml_stage_k(LAS unsigned char* lds, int offK, const LAS float* WL, const u32x2 (&xr)[4], int cg, int ts) {
;     f32x4 wk[4];
; #pragma unroll
;     for (int j = 0; j < 4; ++j) wk[j] = *(const LAS f32x4*)(WL + WL_WK + (cg * 4 + j) * 4);
; #pragma unroll
;     for (int i = 0; i < 4; ++i) { const f32x4 xc = bf4_to_f32(xr[i]);
;         const f32x4 k = wk[0] * xc[0] + wk[1] * xc[1] + wk[2] * xc[2] + wk[3] * xc[3];
;         *(LAS u32x2*)(lds + offK + (4 * ts + i) * GP128 + 8 * cg) = f32_to_bf4(k); }
; }
	v_mfma_f32_16x16x32_bf16 v[30:33], v[50:53], v[10:13], 0
	ds_read_b64_tr_b16 v[10:11], v144 offset:17568
	ds_read_b64_tr_b16 v[12:13], v144 offset:18656
	s_waitcnt lgkmcnt(0)
	v_mfma_f32_16x16x32_bf16 v[26:29], v[50:53], v[10:13], 0
	ds_read_b64_tr_b16 v[10:11], v144 offset:17600
	ds_read_b64_tr_b16 v[12:13], v144 offset:18688
	s_waitcnt lgkmcnt(0)
	v_mfma_f32_16x16x32_bf16 v[22:25], v[50:53], v[10:13], 0
	ds_read_b64_tr_b16 v[10:11], v144 offset:17632
	ds_read_b64_tr_b16 v[12:13], v144 offset:18720
	s_waitcnt lgkmcnt(0)
	v_mfma_f32_16x16x32_bf16 v[18:21], v[50:53], v[10:13], 0
	v_mov_b64_e32 v[12:13], s[6:7]
	v_mov_b64_e32 v[10:11], s[4:5]
	v_mfma_f32_16x16x32_bf16 v[42:45], v[50:53], v[14:17], 0
	s_nop 0
	v_mfma_f32_16x16x32_bf16 v[14:17], v[50:53], v[10:13], 0
	ds_read_b128 v[54:57], v145 offset:34944
	ds_read_b128 v[50:53], v145 offset:34960
	ds_read_b64_tr_b16 v[62:63], v137 offset:8704
	ds_read_b64_tr_b16 v[64:65], v137 offset:9792
	s_waitcnt lgkmcnt(1)
	v_lshlrev_b32_e32 v78, 16, v62
	v_and_b32_e32 v79, 0xffff0000, v62
	v_lshlrev_b32_e32 v62, 16, v63
	v_and_b32_e32 v63, 0xffff0000, v63
	v_pk_mul_f32 v[54:55], v[54:55], v[78:79]
	v_pk_mul_f32 v[56:57], v[56:57], v[62:63]
	v_cvt_pk_bf16_f32 v54, v54, v55
	v_cvt_pk_bf16_f32 v55, v56, v57
	s_waitcnt lgkmcnt(0)
	v_lshlrev_b32_e32 v56, 16, v64
	v_and_b32_e32 v57, 0xffff0000, v64
	v_pk_mul_f32 v[50:51], v[50:51], v[56:57]
	s_nop 0
	v_cvt_pk_bf16_f32 v56, v50, v51
	v_lshlrev_b32_e32 v50, 16, v65
	v_and_b32_e32 v51, 0xffff0000, v65
	v_pk_mul_f32 v[50:51], v[52:53], v[50:51]
	s_nop 0
	v_cvt_pk_bf16_f32 v57, v50, v51
	ds_read_b64_tr_b16 v[50:51], v144 offset:26112
	ds_read_b64_tr_b16 v[52:53], v144 offset:27200
	s_waitcnt lgkmcnt(0)
	v_mfma_f32_16x16x32_bf16 v[46:49], v[54:57], v[50:53], v[46:49]
	ds_read_b64_tr_b16 v[50:51], v144 offset:26144
	ds_read_b64_tr_b16 v[52:53], v144 offset:27232
	s_waitcnt lgkmcnt(0)
	v_mfma_f32_16x16x32_bf16 v[42:45], v[54:57], v[50:53], v[42:45]
	ds_read_b64_tr_b16 v[50:51], v144 offset:26176
	ds_read_b64_tr_b16 v[52:53], v144 offset:27264
	s_waitcnt lgkmcnt(0)
	v_mfma_f32_16x16x32_bf16 v[38:41], v[54:57], v[50:53], v[38:41]
	ds_read_b64_tr_b16 v[50:51], v144 offset:26208
	ds_read_b64_tr_b16 v[52:53], v144 offset:27296
	s_waitcnt lgkmcnt(0)
	v_mfma_f32_16x16x32_bf16 v[34:37], v[54:57], v[50:53], v[34:37]
	ds_read_b64_tr_b16 v[50:51], v144 offset:26240
	ds_read_b64_tr_b16 v[52:53], v144 offset:27328
	s_waitcnt lgkmcnt(0)
	v_mfma_f32_16x16x32_bf16 v[30:33], v[54:57], v[50:53], v[30:33]
	ds_read_b64_tr_b16 v[50:51], v144 offset:26272
	ds_read_b64_tr_b16 v[52:53], v144 offset:27360
	s_waitcnt lgkmcnt(0)
	v_mfma_f32_16x16x32_bf16 v[26:29], v[54:57], v[50:53], v[26:29]
	ds_read_b64_tr_b16 v[50:51], v144 offset:26304
	ds_read_b64_tr_b16 v[52:53], v144 offset:27392
	s_waitcnt lgkmcnt(0)
	v_mfma_f32_16x16x32_bf16 v[22:25], v[54:57], v[50:53], v[22:25]
	ds_read_b64_tr_b16 v[50:51], v144 offset:26336
	ds_read_b64_tr_b16 v[52:53], v144 offset:27424
	v_mfma_f32_16x16x32_bf16 v[10:13], v[54:57], v[10:13], v[14:17]
	s_nop 2
	v_mov_b32_e32 v14, s15
	s_waitcnt lgkmcnt(0)
	v_mfma_f32_16x16x32_bf16 v[18:21], v[54:57], v[50:53], v[18:21]
	ds_read_b64 v[14:15], v14 offset:35128
	ds_read_b128 v[50:53], v140 offset:39936
	ds_read_b128 v[54:57], v140 offset:39952
	ds_read_b128 v[62:65], v140 offset:39968
	ds_read_b128 v[78:81], v140 offset:39984
	v_lshlrev_b32_e32 v16, 16, v72
	v_and_b32_e32 v72, 0xffff0000, v72
	s_waitcnt lgkmcnt(2)
	v_pk_mul_f32 v[86:87], v[72:73], v[56:57] op_sel_hi:[0,1]
	v_pk_mul_f32 v[72:73], v[72:73], v[54:55] op_sel_hi:[0,1]
	v_pk_fma_f32 v[86:87], v[16:17], v[52:53], v[86:87] op_sel_hi:[0,1,1]
	v_pk_fma_f32 v[16:17], v[16:17], v[50:51], v[72:73] op_sel_hi:[0,1,1]
	s_waitcnt lgkmcnt(1)
	v_pk_fma_f32 v[16:17], v[82:83], v[62:63], v[16:17] op_sel_hi:[0,1,1]
	v_pk_fma_f32 v[72:73], v[82:83], v[64:65], v[86:87] op_sel_hi:[0,1,1]
	s_waitcnt lgkmcnt(0)
	v_pk_fma_f32 v[72:73], v[84:85], v[80:81], v[72:73] op_sel_hi:[0,1,1]
	v_pk_fma_f32 v[16:17], v[84:85], v[78:79], v[16:17] op_sel_hi:[0,1,1]
	v_cvt_pk_bf16_f32 v16, v16, v17
	v_cvt_pk_bf16_f32 v17, v72, v73
	s_waitcnt vmcnt(4)
	v_lshlrev_b32_e32 v72, 16, v70
	v_and_b32_e32 v70, 0xffff0000, v70
	v_lshlrev_b32_e32 v82, 16, v71
	v_and_b32_e32 v84, 0xffff0000, v71
	v_pk_mul_f32 v[86:87], v[70:71], v[56:57] op_sel_hi:[0,1]
	v_pk_mul_f32 v[70:71], v[70:71], v[54:55] op_sel_hi:[0,1]
	v_pk_fma_f32 v[86:87], v[72:73], v[52:53], v[86:87] op_sel_hi:[0,1,1]
	v_pk_fma_f32 v[70:71], v[72:73], v[50:51], v[70:71] op_sel_hi:[0,1,1]
	v_pk_fma_f32 v[70:71], v[82:83], v[62:63], v[70:71] op_sel_hi:[0,1,1]
	v_pk_fma_f32 v[72:73], v[82:83], v[64:65], v[86:87] op_sel_hi:[0,1,1]
	v_pk_fma_f32 v[72:73], v[84:85], v[80:81], v[72:73] op_sel_hi:[0,1,1]
	v_pk_fma_f32 v[70:71], v[84:85], v[78:79], v[70:71] op_sel_hi:[0,1,1]
	v_cvt_pk_bf16_f32 v70, v70, v71
	v_cvt_pk_bf16_f32 v71, v72, v73
	ds_write2_b64 v61, v[16:17], v[70:71] offset1:34
	s_waitcnt vmcnt(3)
	v_lshlrev_b32_e32 v16, 16, v68
	v_and_b32_e32 v68, 0xffff0000, v68
	v_lshlrev_b32_e32 v70, 16, v69
	v_and_b32_e32 v72, 0xffff0000, v69
	v_pk_mul_f32 v[82:83], v[68:69], v[56:57] op_sel_hi:[0,1]
	v_pk_mul_f32 v[68:69], v[68:69], v[54:55] op_sel_hi:[0,1]
	v_pk_fma_f32 v[82:83], v[16:17], v[52:53], v[82:83] op_sel_hi:[0,1,1]
	v_pk_fma_f32 v[16:17], v[16:17], v[50:51], v[68:69] op_sel_hi:[0,1,1]
	v_pk_fma_f32 v[16:17], v[70:71], v[62:63], v[16:17] op_sel_hi:[0,1,1]
	v_pk_fma_f32 v[68:69], v[70:71], v[64:65], v[82:83] op_sel_hi:[0,1,1]
	v_pk_fma_f32 v[68:69], v[72:73], v[80:81], v[68:69] op_sel_hi:[0,1,1]
	v_pk_fma_f32 v[16:17], v[72:73], v[78:79], v[16:17] op_sel_hi:[0,1,1]
	v_cvt_pk_bf16_f32 v16, v16, v17
	v_cvt_pk_bf16_f32 v17, v68, v69
	s_waitcnt vmcnt(2)
	v_lshlrev_b32_e32 v68, 16, v66
	v_and_b32_e32 v66, 0xffff0000, v66
	v_pk_mul_f32 v[56:57], v[66:67], v[56:57] op_sel_hi:[0,1]
	v_pk_mul_f32 v[54:55], v[66:67], v[54:55] op_sel_hi:[0,1]
	v_lshlrev_b32_e32 v70, 16, v67
	v_pk_fma_f32 v[52:53], v[68:69], v[52:53], v[56:57] op_sel_hi:[0,1,1]
	v_pk_fma_f32 v[50:51], v[68:69], v[50:51], v[54:55] op_sel_hi:[0,1,1]
	v_and_b32_e32 v72, 0xffff0000, v67
	v_pk_fma_f32 v[50:51], v[70:71], v[62:63], v[50:51] op_sel_hi:[0,1,1]
	v_pk_fma_f32 v[52:53], v[70:71], v[64:65], v[52:53] op_sel_hi:[0,1,1]
	v_pk_fma_f32 v[52:53], v[72:73], v[80:81], v[52:53] op_sel_hi:[0,1,1]
	v_pk_fma_f32 v[50:51], v[72:73], v[78:79], v[50:51] op_sel_hi:[0,1,1]
	v_cvt_pk_bf16_f32 v50, v50, v51
	v_cvt_pk_bf16_f32 v51, v52, v53
	ds_write2_b64 v61, v[16:17], v[50:51] offset0:68 offset1:102
	s_waitcnt vmcnt(1)
	ds_write_b128 v141, v[2:5] offset:62464
	s_waitcnt vmcnt(0)
	ds_write_b128 v142, v[6:9] offset:8704
	s_and_saveexec_b64 s[16:17], s[2:3]
	ds_write_b32 v139, v138
	s_or_b64 exec, exec, s[16:17]
	v_pk_mul_f32 v[2:3], v[60:61], v[48:49] op_sel_hi:[0,1]
	v_pk_fma_f32 v[124:125], v[124:125], v[58:59], v[2:3] op_sel_hi:[1,0,1]
	v_pk_mul_f32 v[2:3], v[60:61], v[44:45] op_sel_hi:[0,1]
	v_pk_fma_f32 v[94:95], v[120:121], v[58:59], v[2:3] op_sel_hi:[1,0,1]
	v_pk_mul_f32 v[2:3], v[60:61], v[40:41] op_sel_hi:[0,1]
	v_pk_fma_f32 v[92:93], v[116:117], v[58:59], v[2:3] op_sel_hi:[1,0,1]
	v_pk_mul_f32 v[2:3], v[60:61], v[36:37] op_sel_hi:[0,1]
	v_pk_fma_f32 v[86:87], v[112:113], v[58:59], v[2:3] op_sel_hi:[1,0,1]
	v_pk_mul_f32 v[2:3], v[60:61], v[32:33] op_sel_hi:[0,1]
	v_pk_fma_f32 v[82:83], v[108:109], v[58:59], v[2:3] op_sel_hi:[1,0,1]
	v_pk_mul_f32 v[2:3], v[60:61], v[28:29] op_sel_hi:[0,1]
	v_pk_mul_f32 v[4:5], v[60:61], v[46:47] op_sel_hi:[0,1]
	v_pk_fma_f32 v[78:79], v[104:105], v[58:59], v[2:3] op_sel_hi:[1,0,1]
	v_pk_mul_f32 v[2:3], v[60:61], v[24:25] op_sel_hi:[0,1]
	v_pk_fma_f32 v[88:89], v[126:127], v[58:59], v[4:5] op_sel_hi:[1,0,1]
	v_pk_mul_f32 v[4:5], v[60:61], v[42:43] op_sel_hi:[0,1]
	v_pk_fma_f32 v[70:71], v[100:101], v[58:59], v[2:3] op_sel_hi:[1,0,1]
	v_pk_mul_f32 v[2:3], v[60:61], v[20:21] op_sel_hi:[0,1]
	v_pk_fma_f32 v[90:91], v[122:123], v[58:59], v[4:5] op_sel_hi:[1,0,1]
	v_pk_mul_f32 v[4:5], v[60:61], v[38:39] op_sel_hi:[0,1]
	v_pk_fma_f32 v[66:67], v[98:99], v[58:59], v[2:3] op_sel_hi:[1,0,1]
	v_add_f32_e32 v2, v59, v14
	v_max_f32_e32 v3, v15, v15
	v_pk_fma_f32 v[84:85], v[118:119], v[58:59], v[4:5] op_sel_hi:[1,0,1]
	v_pk_mul_f32 v[4:5], v[60:61], v[34:35] op_sel_hi:[0,1]
	v_max_f32_e32 v3, v2, v3
	v_pk_fma_f32 v[80:81], v[114:115], v[58:59], v[4:5] op_sel_hi:[1,0,1]
	v_pk_mul_f32 v[4:5], v[60:61], v[30:31] op_sel_hi:[0,1]
	v_sub_f32_e32 v2, v2, v3
	v_pk_fma_f32 v[72:73], v[110:111], v[58:59], v[4:5] op_sel_hi:[1,0,1]
	v_pk_mul_f32 v[4:5], v[60:61], v[26:27] op_sel_hi:[0,1]
	v_mul_f32_e32 v2, 0x3fb8aa3b, v2
	v_pk_fma_f32 v[68:69], v[106:107], v[58:59], v[4:5] op_sel_hi:[1,0,1]
	v_pk_mul_f32 v[4:5], v[60:61], v[22:23] op_sel_hi:[0,1]
	v_exp_f32_e32 v54, v2
	v_sub_f32_e32 v2, v15, v3
	v_pk_fma_f32 v[64:65], v[102:103], v[58:59], v[4:5] op_sel_hi:[1,0,1]
	v_pk_mul_f32 v[4:5], v[60:61], v[18:19] op_sel_hi:[0,1]
	v_mul_f32_e32 v2, 0x3fb8aa3b, v2
	v_add_u32_e32 v55, 0x13800, v145
	v_pk_fma_f32 v[62:63], v[96:97], v[58:59], v[4:5] op_sel_hi:[1,0,1]
	v_exp_f32_e32 v56, v2
	s_waitcnt lgkmcnt(0)
	s_barrier
	ds_read_b128 v[2:5], v55
	ds_read_b128 v[6:9], v55 offset:16
	ds_read_b64_tr_b16 v[14:15], v137 offset:45056
	ds_read_b64_tr_b16 v[16:17], v137 offset:46144
	s_lshl_b64 s[2:3], s[8:9], 2
	s_add_u32 s2, s2, s10
	s_addc_u32 s3, s3, s11
	s_waitcnt lgkmcnt(1)
	v_lshlrev_b32_e32 v18, 16, v14
	v_and_b32_e32 v19, 0xffff0000, v14
	v_pk_mul_f32 v[2:3], v[2:3], v[18:19]
	s_mul_i32 s3, s3, 3
	v_cvt_pk_bf16_f32 v46, v2, v3
	v_lshlrev_b32_e32 v2, 16, v15
	v_and_b32_e32 v3, 0xffff0000, v15
	v_pk_mul_f32 v[2:3], v[4:5], v[2:3]
	s_nop 0
	v_cvt_pk_bf16_f32 v47, v2, v3
	s_waitcnt lgkmcnt(0)
	v_lshlrev_b32_e32 v2, 16, v16
	v_and_b32_e32 v3, 0xffff0000, v16
	v_pk_mul_f32 v[2:3], v[6:7], v[2:3]
	s_nop 0
	v_cvt_pk_bf16_f32 v48, v2, v3
	v_lshlrev_b32_e32 v2, 16, v17
	v_and_b32_e32 v3, 0xffff0000, v17
	v_pk_mul_f32 v[2:3], v[8:9], v[2:3]
	s_nop 0
	v_cvt_pk_bf16_f32 v49, v2, v3
	ds_read_b64_tr_b16 v[4:5], v128 offset:63552
	ds_read_b64_tr_b16 v[2:3], v128 offset:62464
	ds_read_b64_tr_b16 v[6:7], v128 offset:62496
	s_waitcnt lgkmcnt(1)
	v_mfma_f32_16x16x32_bf16 v[38:41], v[46:49], v[2:5], 0
	ds_read_b64_tr_b16 v[8:9], v128 offset:63584
	ds_read_b64_tr_b16 v[2:3], v128 offset:62528
	ds_read_b64_tr_b16 v[4:5], v128 offset:63616
	s_waitcnt lgkmcnt(0)
	v_mfma_f32_16x16x32_bf16 v[34:37], v[46:49], v[2:5], 0
	ds_read_b64_tr_b16 v[2:3], v128 offset:62560
	ds_read_b64_tr_b16 v[4:5], v128 offset:63648
	s_waitcnt lgkmcnt(0)
	v_mfma_f32_16x16x32_bf16 v[30:33], v[46:49], v[2:5], 0
	ds_read_b64_tr_b16 v[2:3], v128 offset:62592
	ds_read_b64_tr_b16 v[4:5], v128 offset:63680
	s_waitcnt lgkmcnt(0)
	v_mfma_f32_16x16x32_bf16 v[26:29], v[46:49], v[2:5], 0
	ds_read_b64_tr_b16 v[2:3], v128 offset:62624
	ds_read_b64_tr_b16 v[4:5], v128 offset:63712
	s_waitcnt lgkmcnt(0)
	v_mfma_f32_16x16x32_bf16 v[22:25], v[46:49], v[2:5], 0
	ds_read_b64_tr_b16 v[2:3], v128 offset:62656
	ds_read_b64_tr_b16 v[4:5], v128 offset:63744
	s_waitcnt lgkmcnt(0)
	v_mfma_f32_16x16x32_bf16 v[18:21], v[46:49], v[2:5], 0
	ds_read_b64_tr_b16 v[2:3], v128 offset:62688
	ds_read_b64_tr_b16 v[4:5], v128 offset:63776
	s_waitcnt lgkmcnt(0)
; #define GAS __attribute__((address_space(1)))
; __device__ __forceinline__ void ml_loc_unit(LAS unsigned char* lds, const MixBufs& B, int b, int h, int seg, int tid) {
;     ...
;     for (int cp = 0; cp < 4; ++cp) { const int ch0 = 8 * seg + 2 * cp; MLL_BODY(0, ch0, cp < 3); MLL_BODY(1, ch0 + 1, cp < 3); }
;     __syncthreads();
;     ...
;     const size_t u = ((size_t)b * 4 + h) * 3 + seg;
; #pragma unroll
;     for (int vt = 0; vt < 8; ++vt) *(GAS f32x4*)(B.Lm + (((u * 8 + w) * 8 + vt) * 64 + lane) * 4) = C[vt];
;     if (c == 0) *(GAS f32x4*)(B.nL + u * 128 + 16 * w + 4 * g) = nv;
	v_mfma_f32_16x16x32_bf16 v[14:17], v[46:49], v[2:5], 0
	v_mov_b64_e32 v[2:3], s[4:5]
	v_mov_b64_e32 v[4:5], s[6:7]
	s_mul_hi_u32 s4, s2, 3
	v_mfma_f32_16x16x32_bf16 v[42:45], v[46:49], v[6:9], 0
	s_add_i32 s4, s4, s3
	s_mul_i32 s2, s2, 3
	s_ashr_i32 s3, s24, 31
	v_mfma_f32_16x16x32_bf16 v[6:9], v[46:49], v[2:5], 0
	ds_read_b128 v[50:53], v55 offset:128
	ds_read_b128 v[46:49], v55 offset:144
	ds_read_b64_tr_b16 v[96:97], v137 offset:53760
	ds_read_b64_tr_b16 v[98:99], v137 offset:54848
	s_add_u32 s10, s2, s24
	s_addc_u32 s11, s4, s3
	s_ashr_i32 s15, s14, 31
	s_waitcnt lgkmcnt(1)
	v_lshlrev_b32_e32 v100, 16, v96
	v_and_b32_e32 v101, 0xffff0000, v96
	v_lshlrev_b32_e32 v96, 16, v97
	v_and_b32_e32 v97, 0xffff0000, v97
	v_pk_mul_f32 v[50:51], v[50:51], v[100:101]
	v_pk_mul_f32 v[52:53], v[52:53], v[96:97]
	v_cvt_pk_bf16_f32 v50, v50, v51
	v_cvt_pk_bf16_f32 v51, v52, v53
	s_waitcnt lgkmcnt(0)
	v_lshlrev_b32_e32 v52, 16, v98
	v_and_b32_e32 v53, 0xffff0000, v98
	v_pk_mul_f32 v[46:47], v[46:47], v[52:53]
	s_lshl_b64 s[2:3], s[10:11], 16
	v_cvt_pk_bf16_f32 v52, v46, v47
	v_lshlrev_b32_e32 v46, 16, v99
	v_and_b32_e32 v47, 0xffff0000, v99
	v_pk_mul_f32 v[46:47], v[48:49], v[46:47]
	s_lshl_b64 s[4:5], s[14:15], 13
	v_cvt_pk_bf16_f32 v53, v46, v47
	ds_read_b64_tr_b16 v[48:49], v136 offset:63552
	ds_read_b64_tr_b16 v[46:47], v136 offset:62464
	ds_read_b64_tr_b16 v[96:97], v136 offset:62496
	s_waitcnt lgkmcnt(1)
	v_mfma_f32_16x16x32_bf16 v[38:41], v[50:53], v[46:49], v[38:41]
	ds_read_b64_tr_b16 v[98:99], v136 offset:63584
	ds_read_b64_tr_b16 v[46:47], v136 offset:62528
	ds_read_b64_tr_b16 v[48:49], v136 offset:63616
	v_readlane_b32 s6, v241, 36
	s_waitcnt lgkmcnt(0)
	v_mfma_f32_16x16x32_bf16 v[34:37], v[50:53], v[46:49], v[34:37]
	ds_read_b64_tr_b16 v[46:47], v136 offset:62560
	ds_read_b64_tr_b16 v[48:49], v136 offset:63648
	v_readlane_b32 s7, v241, 37
	s_add_u32 s4, s6, s4
	s_waitcnt lgkmcnt(0)
	v_mfma_f32_16x16x32_bf16 v[30:33], v[50:53], v[46:49], v[30:33]
	ds_read_b64_tr_b16 v[46:47], v136 offset:62592
	ds_read_b64_tr_b16 v[48:49], v136 offset:63680
	s_addc_u32 s5, s7, s5
	v_pk_mul_f32 v[40:41], v[56:57], v[40:41] op_sel_hi:[0,1]
	s_waitcnt lgkmcnt(0)
	v_mfma_f32_16x16x32_bf16 v[26:29], v[50:53], v[46:49], v[26:29]
	ds_read_b64_tr_b16 v[46:47], v136 offset:62624
	ds_read_b64_tr_b16 v[48:49], v136 offset:63712
	v_pk_mul_f32 v[38:39], v[56:57], v[38:39] op_sel_hi:[0,1]
	s_add_u32 s2, s4, s2
	s_waitcnt lgkmcnt(0)
	v_mfma_f32_16x16x32_bf16 v[22:25], v[50:53], v[46:49], v[22:25]
	ds_read_b64_tr_b16 v[46:47], v136 offset:62656
	ds_read_b64_tr_b16 v[48:49], v136 offset:63744
	v_pk_fma_f32 v[40:41], v[124:125], v[54:55], v[40:41] op_sel_hi:[1,0,1]
	v_pk_fma_f32 v[38:39], v[88:89], v[54:55], v[38:39] op_sel_hi:[1,0,1]
	s_waitcnt lgkmcnt(0)
	v_mfma_f32_16x16x32_bf16 v[18:21], v[50:53], v[46:49], v[18:21]
	ds_read_b64_tr_b16 v[46:47], v136 offset:62688
	ds_read_b64_tr_b16 v[48:49], v136 offset:63776
	v_pk_mul_f32 v[36:37], v[56:57], v[36:37] op_sel_hi:[0,1]
	v_pk_mul_f32 v[34:35], v[56:57], v[34:35] op_sel_hi:[0,1]
	s_waitcnt lgkmcnt(0)
	v_mfma_f32_16x16x32_bf16 v[14:17], v[50:53], v[46:49], v[14:17]
	v_mul_f32_e64 v32, v56, v32
	v_mul_f32_e64 v33, v56, v33
	v_pk_mul_f32 v[30:31], v[56:57], v[30:31] op_sel_hi:[0,1]
	s_addc_u32 s3, s5, s3
	v_mfma_f32_16x16x32_bf16 v[42:45], v[50:53], v[96:99], v[42:45]
	s_nop 2
	v_mul_f32_e64 v16, v56, v16
	v_mul_f32_e64 v17, v56, v17
	v_pk_fma_f32 v[48:49], v[66:67], v[54:55], v[16:17] op_sel_hi:[1,0,1]
	v_lshlrev_b32_e32 v16, 4, v135
	v_mov_b32_e32 v17, 0
	v_pk_fma_f32 v[36:37], v[92:93], v[54:55], v[36:37] op_sel_hi:[1,0,1]
	v_pk_mul_f32 v[44:45], v[56:57], v[44:45] op_sel_hi:[0,1]
	v_pk_mul_f32 v[42:43], v[56:57], v[42:43] op_sel_hi:[0,1]
	v_pk_fma_f32 v[44:45], v[94:95], v[54:55], v[44:45] op_sel_hi:[1,0,1]
	v_pk_fma_f32 v[42:43], v[90:91], v[54:55], v[42:43] op_sel_hi:[1,0,1]
	v_pk_fma_f32 v[34:35], v[84:85], v[54:55], v[34:35] op_sel_hi:[1,0,1]
	v_pk_fma_f32 v[32:33], v[86:87], v[54:55], v[32:33] op_sel_hi:[1,0,1]
	v_pk_fma_f32 v[30:31], v[80:81], v[54:55], v[30:31] op_sel_hi:[1,0,1]
	v_mfma_f32_16x16x32_bf16 v[6:9], v[50:53], v[2:5], v[6:9]
	s_barrier
	s_setprio 1
	v_lshl_add_u64 v[2:3], s[2:3], 0, v[16:17]
	global_store_dwordx4 v16, v[38:41], s[2:3]
	global_store_dwordx4 v16, v[42:45], s[2:3] offset:1024
	global_store_dwordx4 v16, v[34:37], s[2:3] offset:2048
	global_store_dwordx4 v16, v[30:33], s[2:3] offset:3072
	s_movk_i32 s2, 0x1000
	v_add_co_u32_e32 v2, vcc, s2, v2
	v_pk_mul_f32 v[28:29], v[56:57], v[28:29] op_sel_hi:[0,1]
	v_pk_mul_f32 v[26:27], v[56:57], v[26:27] op_sel_hi:[0,1]
	v_addc_co_u32_e32 v3, vcc, 0, v3, vcc
	v_pk_fma_f32 v[28:29], v[82:83], v[54:55], v[28:29] op_sel_hi:[1,0,1]
	v_pk_fma_f32 v[26:27], v[72:73], v[54:55], v[26:27] op_sel_hi:[1,0,1]
	v_pk_mul_f32 v[24:25], v[56:57], v[24:25] op_sel_hi:[0,1]
	v_pk_mul_f32 v[22:23], v[56:57], v[22:23] op_sel_hi:[0,1]
	v_pk_mul_f32 v[20:21], v[56:57], v[20:21] op_sel_hi:[0,1]
	v_pk_mul_f32 v[18:19], v[56:57], v[18:19] op_sel_hi:[0,1]
	v_pk_mul_f32 v[14:15], v[56:57], v[14:15] op_sel_hi:[0,1]
	v_cmp_eq_u32_e32 vcc, 0, v1
	s_mov_b64 s[2:3], 0
	s_mov_b64 s[4:5], 0
	v_pk_fma_f32 v[24:25], v[78:79], v[54:55], v[24:25] op_sel_hi:[1,0,1]
	v_pk_fma_f32 v[22:23], v[68:69], v[54:55], v[22:23] op_sel_hi:[1,0,1]
	v_pk_fma_f32 v[20:21], v[70:71], v[54:55], v[20:21] op_sel_hi:[1,0,1]
	v_pk_fma_f32 v[18:19], v[64:65], v[54:55], v[18:19] op_sel_hi:[1,0,1]
	v_pk_fma_f32 v[46:47], v[62:63], v[54:55], v[14:15] op_sel_hi:[1,0,1]
	global_store_dwordx4 v[2:3], v[26:29], off
	global_store_dwordx4 v[2:3], v[22:25], off offset:1024
	global_store_dwordx4 v[2:3], v[18:21], off offset:2048
	global_store_dwordx4 v[2:3], v[46:49], off offset:3072
	s_and_saveexec_b64 s[6:7], vcc
	s_xor_b64 s[6:7], exec, s[6:7]
	s_cbranch_execz .LBB0_500
	s_lshl_b64 s[4:5], s[10:11], 9
	s_add_u32 s9, s28, s4
	s_addc_u32 s10, s29, s5
	s_lshl_b32 s4, s14, 4
	v_mov_b32_e32 v61, v60
	v_mov_b32_e32 v2, v60
	v_mov_b32_e32 v3, v60
	s_ashr_i32 s5, s4, 31
	v_mov_b32_e32 v59, v58
	v_pk_mul_f32 v[2:3], v[2:3], v[12:13]
	v_pk_mul_f32 v[4:5], v[60:61], v[10:11]
	v_mov_b32_e32 v10, v58
	v_mov_b32_e32 v11, v58
	s_lshl_b64 s[4:5], s[4:5], 2
	v_mov_b32_e32 v57, v56
	v_pk_fma_f32 v[2:3], v[76:77], v[10:11], v[2:3]
	v_pk_fma_f32 v[10:11], v[74:75], v[58:59], v[4:5]
	v_mov_b32_e32 v4, v56
	v_mov_b32_e32 v5, v56
	s_add_u32 s4, s9, s4
	v_mov_b32_e32 v55, v54
	v_pk_mul_f32 v[4:5], v[4:5], v[8:9]
	v_pk_mul_f32 v[6:7], v[56:57], v[6:7]
	v_mov_b32_e32 v8, v54
	v_mov_b32_e32 v9, v54
	s_addc_u32 s5, s10, s5
	v_lshlrev_b32_e32 v16, 4, v134
	v_pk_fma_f32 v[4:5], v[2:3], v[8:9], v[4:5]
	v_pk_fma_f32 v[2:3], v[10:11], v[54:55], v[6:7]
	v_lshl_add_u64 v[14:15], s[4:5], 0, v[16:17]
	s_mov_b64 s[4:5], exec

; #define LAS __attribute__((address_space(3)))
; #define MFMA16(a, b, c) __builtin_amdgcn_mfma_f32_16x16x32_bf16((a), (b), (c), 0, 0, 0)
; __device__ __forceinline__ float bflo(unsigned w) { return __uint_as_float(w << 16); }
; __device__ __forceinline__ float bfhi(unsigned w) { return __uint_as_float(w & 0xffff0000u); }
; template <bool FULL> __device__ __forceinline__ void gla_unit(LAS unsigned char* lds, const MixBufs& B, int b, int h, int seg, int tid) {
;     ...
;         { const v4u ee = re[st]; const f32x4 e0 = (f32x4){bflo(ee.x), bfhi(ee.x), bflo(ee.y), bfhi(ee.y)}, e1 = (f32x4){bflo(ee.z), bfhi(ee.z), bflo(ee.w), bfhi(ee.w)};
;           f32x4 i0, i1;
; #pragma unroll
;           for (int e = 0; e < 4; ++e) { i0[e] = __builtin_amdgcn_rcpf(e0[e]); i1[e] = __builtin_amdgcn_rcpf(e1[e]); }
;           *(LAS v4u*)(lds + okf + lr * GP64 + lc * 16) = mul_bf8(rk[st], i0, i1);
;           if (FULL) { *(LAS v4u*)(lds + G_KB + lr * GP64 + lc * 16) = mul_bf8(rk[st], e0, e1);
;                       *(LAS v4u*)(lds + G_QF + lr * GP64 + lc * 16) = mul_bf8(rq[st], e0, e1); *(LAS v4u*)(lds + G_QB + lr * GP64 + lc * 16) = mul_bf8(rq[st], i0, i1); } }
;         *(LAS v4u*)(lds + ov + vr * GP128 + vc * 16) = rv0[st]; *(LAS v4u*)(lds + ov + (vr + 32) * GP128 + vc * 16) = rv1[st];
;         if (tid < 64) DLc[tid] = rdl[st];
;     ...
; #pragma unroll
;         for (int ks = 0; ks < 2; ++ks) { const bf16x8 kf = frag_tr(lds + okf, GP64, 32 * ks, 16 * kt, lane);
; #pragma unroll
;             for (int j = 0; j < 4; ++j) S[j] = MFMA16(kf, vfr[j][ks], S[j]); }
;         { const f32x4 dl = *(const LAS f32x4*)(DLc + 16 * kt + 4 * g);
; #pragma unroll
;           for (int j = 0; j < 4; ++j) S[j] *= dl; }
.LBB0_531:
	s_or_b64 exec, exec, s[10:11]
	s_waitcnt lgkmcnt(3)
	v_pk_mul_f32 v[68:69], v[68:69], v[56:57]
	v_pk_mul_f32 v[66:67], v[66:67], v[54:55]
	v_pk_mul_f32 v[74:75], v[64:65], v[56:57]
	v_pk_mul_f32 v[72:73], v[62:63], v[54:55]
	s_waitcnt lgkmcnt(0)
	s_barrier
	ds_read_b64_tr_b16 v[76:77], v97 offset:18432
	ds_read_b64_tr_b16 v[78:79], v97 offset:19008
	ds_read_b64_tr_b16 v[80:81], v94 offset:36864
	ds_read_b64_tr_b16 v[82:83], v94 offset:37952
	ds_read_b64_tr_b16 v[98:99], v94 offset:36896
	ds_read_b64_tr_b16 v[100:101], v94 offset:37984
	ds_read_b64_tr_b16 v[102:103], v94 offset:36928
	ds_read_b64_tr_b16 v[106:107], v97 offset:23040
	ds_read_b64_tr_b16 v[108:109], v97 offset:23616
	ds_read_b128 v[62:65], v92
	s_waitcnt lgkmcnt(6)
	v_mfma_f32_16x16x32_bf16 v[66:69], v[76:79], v[80:83], v[66:69]
	ds_read_b64_tr_b16 v[80:81], v94 offset:45568
	ds_read_b64_tr_b16 v[110:111], v94 offset:45600
	ds_read_b64_tr_b16 v[114:115], v94 offset:45632
	ds_read_b64_tr_b16 v[104:105], v94 offset:38016
	v_pk_mul_f32 v[52:53], v[52:53], v[56:57]
	v_pk_mul_f32 v[50:51], v[50:51], v[54:55]
	s_waitcnt lgkmcnt(8)
	v_mfma_f32_16x16x32_bf16 v[72:75], v[76:79], v[98:101], v[72:75]
	ds_read_b64_tr_b16 v[98:99], v95 offset:36864
	v_pk_mul_f32 v[56:57], v[60:61], v[56:57]
	v_pk_mul_f32 v[54:55], v[58:59], v[54:55]
	s_waitcnt lgkmcnt(1)
	v_mfma_f32_16x16x32_bf16 v[50:53], v[76:79], v[102:105], v[50:53]
	ds_read_b64_tr_b16 v[100:101], v95 offset:37952
	ds_read_b64_tr_b16 v[102:103], v95 offset:45568
	ds_read_b64_tr_b16 v[104:105], v95 offset:46656
	ds_read_b64_tr_b16 v[82:83], v94 offset:46656
	ds_read_b64_tr_b16 v[112:113], v94 offset:46688
	ds_read_b64_tr_b16 v[116:117], v94 offset:46720
	s_waitcnt lgkmcnt(5)
	v_mfma_f32_16x16x32_bf16 v[76:79], v[76:79], v[98:101], v[54:57]
	s_waitcnt lgkmcnt(1)
	v_mfma_f32_16x16x32_bf16 v[58:61], v[106:109], v[110:113], v[72:75]
	s_waitcnt vmcnt(10)
	s_nop 1
	v_lshlrev_b32_e32 v72, 16, v46
	v_and_b32_e32 v73, 0xffff0000, v46
	v_lshlrev_b32_e32 v74, 16, v47
	v_and_b32_e32 v75, 0xffff0000, v47
	v_lshlrev_b32_e32 v47, 16, v48
	s_waitcnt lgkmcnt(0)
	v_mfma_f32_16x16x32_bf16 v[54:57], v[106:109], v[114:117], v[50:53]
	v_rcp_f32_e32 v46, v72
	v_rcp_f32_e32 v72, v74
	v_mfma_f32_16x16x32_bf16 v[50:53], v[106:109], v[102:105], v[76:79]
	s_nop 2
	v_and_b32_e32 v76, 0xffff0000, v48
	v_rcp_f32_e32 v48, v47
	v_rcp_f32_e32 v47, v73
	v_lshlrev_b32_e32 v77, 16, v49
	v_rcp_f32_e32 v73, v75
	v_and_b32_e32 v78, 0xffff0000, v49
	v_rcp_f32_e32 v49, v76
	v_rcp_f32_e32 v74, v77
	v_lshlrev_b32_e32 v76, 16, v34
	v_and_b32_e32 v77, 0xffff0000, v34
	v_pk_mul_f32 v[46:47], v[46:47], v[76:77]
	v_rcp_f32_e32 v75, v78
	v_cvt_pk_bf16_f32 v34, v46, v47
	v_lshlrev_b32_e32 v46, 16, v35
	v_and_b32_e32 v47, 0xffff0000, v35
	v_pk_mul_f32 v[46:47], v[72:73], v[46:47]
	v_mfma_f32_16x16x32_bf16 v[66:69], v[106:109], v[80:83], v[66:69]
	v_cvt_pk_bf16_f32 v35, v46, v47
	v_lshlrev_b32_e32 v46, 16, v36
	v_and_b32_e32 v47, 0xffff0000, v36
	v_pk_mul_f32 v[46:47], v[48:49], v[46:47]
	s_nop 0
	v_cvt_pk_bf16_f32 v36, v46, v47
	v_lshlrev_b32_e32 v46, 16, v37
	v_and_b32_e32 v47, 0xffff0000, v37
	v_pk_mul_f32 v[46:47], v[74:75], v[46:47]
	s_nop 0
	v_cvt_pk_bf16_f32 v37, v46, v47
	ds_write_b128 v70, v[34:37]
	s_waitcnt vmcnt(9)
	ds_write_b128 v86, v[38:41] offset:63488
	s_waitcnt vmcnt(8)
	ds_write_b128 v84, v[42:45] offset:8704
	s_and_saveexec_b64 s[6:7], s[2:3]
	v_add_u32_e32 v34, 0x16c00, v85
	ds_write_b32 v34, v91
	s_or_b64 exec, exec, s[6:7]
	v_pk_mul_f32 v[36:37], v[68:69], v[64:65]
	v_pk_mul_f32 v[34:35], v[66:67], v[62:63]
	s_waitcnt lgkmcnt(0)
	s_barrier
	ds_read_b64_tr_b16 v[38:39], v93
	ds_read_b64_tr_b16 v[40:41], v93 offset:576
	ds_read_b64_tr_b16 v[42:43], v94 offset:63488
	ds_read_b64_tr_b16 v[44:45], v94 offset:64576
	ds_read_b64_tr_b16 v[46:47], v94 offset:63520
	ds_read_b64_tr_b16 v[48:49], v94 offset:64608
	ds_read_b64_tr_b16 v[66:67], v94 offset:63552
	ds_read_b64_tr_b16 v[74:75], v88 offset:64576
	ds_read_b64_tr_b16 v[76:77], v93 offset:4608
	ds_read_b64_tr_b16 v[78:79], v93 offset:5184
	v_pk_mul_f32 v[60:61], v[60:61], v[64:65]
	v_pk_mul_f32 v[58:59], v[58:59], v[62:63]
	s_waitcnt lgkmcnt(6)
	v_mfma_f32_16x16x32_bf16 v[42:45], v[38:41], v[42:45], v[34:37]
	ds_read_b64_tr_b16 v[68:69], v94 offset:64640
	s_nop 1
	ds_read_b64_tr_b16 v[34:35], v95 offset:63488
	ds_read_b64_tr_b16 v[36:37], v95 offset:64576
	v_pk_mul_f32 v[56:57], v[56:57], v[64:65]
	v_pk_mul_f32 v[54:55], v[54:55], v[62:63]
	s_waitcnt lgkmcnt(7)
	v_mfma_f32_16x16x32_bf16 v[46:49], v[38:41], v[46:49], v[58:61]
	s_nop 2
	ds_read_b64_tr_b16 v[60:61], v87 offset:64576
	ds_read_b64_tr_b16 v[58:59], v87 offset:63488
	v_pk_mul_f32 v[52:53], v[52:53], v[64:65]
	v_pk_mul_f32 v[50:51], v[50:51], v[62:63]
	s_waitcnt lgkmcnt(4)
	v_mfma_f32_16x16x32_bf16 v[54:57], v[38:41], v[66:69], v[54:57]
	s_waitcnt lgkmcnt(2)
	v_mfma_f32_16x16x32_bf16 v[38:41], v[38:41], v[34:37], v[50:53]
	ds_read_b64_tr_b16 v[62:63], v87 offset:64608
	ds_read_b64_tr_b16 v[64:65], v87 offset:63552
	ds_read_b128 v[34:37], v96
	s_waitcnt lgkmcnt(3)
	v_mfma_f32_16x16x32_bf16 v[50:53], v[76:79], v[58:61], v[42:45]
	ds_read_b64_tr_b16 v[60:61], v87 offset:63520
	ds_read_b64_tr_b16 v[66:67], v87 offset:64640
	ds_read_b64_tr_b16 v[72:73], v88 offset:63488
	s_waitcnt vmcnt(6)
	v_and_b32_e32 v58, 0xffff0000, v16
	s_waitcnt lgkmcnt(1)
	v_mfma_f32_16x16x32_bf16 v[42:45], v[76:79], v[64:67], v[54:57]
	v_lshlrev_b32_e32 v59, 16, v17
	s_nop 1
	v_lshlrev_b32_e32 v54, 16, v14
	v_and_b32_e32 v55, 0xffff0000, v14
	v_lshlrev_b32_e32 v56, 16, v15
	v_and_b32_e32 v57, 0xffff0000, v15
	v_lshlrev_b32_e32 v15, 16, v16
	v_rcp_f32_e32 v14, v54
	v_rcp_f32_e32 v16, v15
	v_rcp_f32_e32 v15, v55
	v_rcp_f32_e32 v54, v56
	v_rcp_f32_e32 v55, v57
	v_mfma_f32_16x16x32_bf16 v[46:49], v[76:79], v[60:63], v[46:49]
	v_and_b32_e32 v60, 0xffff0000, v17
	v_rcp_f32_e32 v17, v58
	v_rcp_f32_e32 v56, v59
	v_lshlrev_b32_e32 v58, 16, v2
	v_and_b32_e32 v59, 0xffff0000, v2
	v_pk_mul_f32 v[14:15], v[14:15], v[58:59]
	v_rcp_f32_e32 v57, v60
	v_cvt_pk_bf16_f32 v2, v14, v15
	v_lshlrev_b32_e32 v14, 16, v3
	v_and_b32_e32 v15, 0xffff0000, v3
	v_pk_mul_f32 v[14:15], v[54:55], v[14:15]
	s_waitcnt lgkmcnt(0)
	v_mfma_f32_16x16x32_bf16 v[38:41], v[76:79], v[72:75], v[38:41]
	v_cvt_pk_bf16_f32 v3, v14, v15
	v_lshlrev_b32_e32 v14, 16, v4
	v_and_b32_e32 v15, 0xffff0000, v4
	v_pk_mul_f32 v[14:15], v[16:17], v[14:15]
	s_nop 0
	v_cvt_pk_bf16_f32 v4, v14, v15
	v_lshlrev_b32_e32 v14, 16, v5
	v_and_b32_e32 v15, 0xffff0000, v5
	v_pk_mul_f32 v[14:15], v[56:57], v[14:15]
	s_nop 0
	v_cvt_pk_bf16_f32 v5, v14, v15
	ds_write_b128 v90, v[2:5] offset:18432
	s_waitcnt vmcnt(5)
	ds_write_b128 v86, v[6:9] offset:36864
	s_waitcnt vmcnt(4)
	ds_write_b128 v86, v[10:13] offset:45568
	s_and_saveexec_b64 s[6:7], s[2:3]
	v_add_u32_e32 v2, 0x14000, v85
	ds_write_b32 v2, v71
	s_or_b64 exec, exec, s[6:7]
	v_pk_mul_f32 v[8:9], v[52:53], v[36:37]
	v_pk_mul_f32 v[6:7], v[50:51], v[34:35]
	v_pk_mul_f32 v[12:13], v[48:49], v[36:37]
	v_pk_mul_f32 v[10:11], v[46:47], v[34:35]
	s_waitcnt lgkmcnt(0)
	s_barrier
; #define GAS __attribute__((address_space(1)))
; #define LAS __attribute__((address_space(3)))
; #define MFMA16(a, b, c) __builtin_amdgcn_mfma_f32_16x16x32_bf16((a), (b), (c), 0, 0, 0)
; __device__ __forceinline__ float bflo(unsigned w) { return __uint_as_float(w << 16); }
; __device__ __forceinline__ float bfhi(unsigned w) { return __uint_as_float(w & 0xffff0000u); }
; template <bool FULL> __device__ __forceinline__ void gla_unit(LAS unsigned char* lds, const MixBufs& B, int b, int h, int seg, int tid) {
;     ...
;         { const v4u ee = re[st]; const f32x4 e0 = (f32x4){bflo(ee.x), bfhi(ee.x), bflo(ee.y), bfhi(ee.y)}, e1 = (f32x4){bflo(ee.z), bfhi(ee.z), bflo(ee.w), bfhi(ee.w)};
;           f32x4 i0, i1;
; #pragma unroll
;           for (int e = 0; e < 4; ++e) { i0[e] = __builtin_amdgcn_rcpf(e0[e]); i1[e] = __builtin_amdgcn_rcpf(e1[e]); }
;           *(LAS v4u*)(lds + okf + lr * GP64 + lc * 16) = mul_bf8(rk[st], i0, i1);
;           if (FULL) { *(LAS v4u*)(lds + G_KB + lr * GP64 + lc * 16) = mul_bf8(rk[st], e0, e1);
;                       *(LAS v4u*)(lds + G_QF + lr * GP64 + lc * 16) = mul_bf8(rq[st], e0, e1); *(LAS v4u*)(lds + G_QB + lr * GP64 + lc * 16) = mul_bf8(rq[st], i0, i1); } }
;         *(LAS v4u*)(lds + ov + vr * GP128 + vc * 16) = rv0[st]; *(LAS v4u*)(lds + ov + (vr + 32) * GP128 + vc * 16) = rv1[st];
;         if (tid < 64) DLc[tid] = rdl[st];
;     ...
; #pragma unroll
;         for (int ks = 0; ks < 2; ++ks) { const bf16x8 kf = frag_tr(lds + okf, GP64, 32 * ks, 16 * kt, lane);
; #pragma unroll
;             for (int j = 0; j < 4; ++j) S[j] = MFMA16(kf, vfr[j][ks], S[j]); }
;         { const f32x4 dl = *(const LAS f32x4*)(DLc + 16 * kt + 4 * g);
; #pragma unroll
;           for (int j = 0; j < 4; ++j) S[j] *= dl; }
;     }
;     __syncthreads();
;     ...
;     if (!FULL) { const size_t u = ((size_t)b * 4 + h) * 3 + seg;
; #pragma unroll
;         for (int j = 0; j < 4; ++j) *(GAS f32x4*)(B.Lg + (((u * 8 + w) * 4 + j) * 64 + lane) * 4) = S[j]; }
	ds_read_b64_tr_b16 v[14:15], v97 offset:18432
	ds_read_b64_tr_b16 v[16:17], v97 offset:19008
	ds_read_b64_tr_b16 v[46:47], v94 offset:36864
	ds_read_b64_tr_b16 v[48:49], v94 offset:37952
	ds_read_b64_tr_b16 v[50:51], v94 offset:36896
	ds_read_b64_tr_b16 v[52:53], v94 offset:37984
	ds_read_b64_tr_b16 v[54:55], v94 offset:36928
	ds_read_b64_tr_b16 v[58:59], v97 offset:23040
	ds_read_b64_tr_b16 v[60:61], v97 offset:23616
	ds_read_b128 v[2:5], v92
	s_waitcnt lgkmcnt(6)
	v_mfma_f32_16x16x32_bf16 v[6:9], v[14:17], v[46:49], v[6:9]
	ds_read_b64_tr_b16 v[46:47], v94 offset:45568
	ds_read_b64_tr_b16 v[62:63], v94 offset:45600
	ds_read_b64_tr_b16 v[66:67], v94 offset:45632
	ds_read_b64_tr_b16 v[56:57], v94 offset:38016
	ds_read_b64_tr_b16 v[48:49], v95 offset:36864
	v_pk_mul_f32 v[44:45], v[44:45], v[36:37]
	v_pk_mul_f32 v[42:43], v[42:43], v[34:35]
	s_waitcnt lgkmcnt(9)
	v_mfma_f32_16x16x32_bf16 v[10:13], v[14:17], v[50:53], v[10:13]
	v_mul_f32_e64 v36, v40, v36
	v_mul_f32_e64 v37, v41, v37
	v_pk_mul_f32 v[34:35], v[38:39], v[34:35]
	s_waitcnt vmcnt(2)
	v_lshlrev_b32_e32 v39, 16, v30
	s_waitcnt lgkmcnt(1)
	v_mfma_f32_16x16x32_bf16 v[42:45], v[14:17], v[54:57], v[42:45]
	ds_read_b64_tr_b16 v[50:51], v95 offset:37952
	ds_read_b64_tr_b16 v[52:53], v95 offset:45568
	ds_read_b64_tr_b16 v[54:55], v95 offset:46656
	v_and_b32_e32 v40, 0xffff0000, v30
	v_lshlrev_b32_e32 v41, 16, v31
	s_waitcnt lgkmcnt(2)
	v_mfma_f32_16x16x32_bf16 v[72:75], v[14:17], v[48:51], v[34:37]
	ds_read_b64_tr_b16 v[48:49], v94 offset:46656
	ds_read_b64_tr_b16 v[64:65], v94 offset:46688
	ds_read_b64_tr_b16 v[68:69], v94 offset:46720
	v_rcp_f32_e32 v30, v39
	v_and_b32_e32 v38, 0xfc, v89
	s_waitcnt lgkmcnt(2)
	v_mfma_f32_16x16x32_bf16 v[34:37], v[58:61], v[46:49], v[6:9]
	s_waitcnt lgkmcnt(0)
	v_mfma_f32_16x16x32_bf16 v[6:9], v[58:61], v[66:69], v[42:45]
	s_nop 2
	v_and_b32_e32 v43, 0xffff0000, v31
	v_lshlrev_b32_e32 v31, 16, v32
	v_and_b32_e32 v42, 0xffff0000, v32
	v_rcp_f32_e32 v32, v31
	v_rcp_f32_e32 v31, v40
	v_lshlrev_b32_e32 v44, 16, v33
	v_and_b32_e32 v45, 0xffff0000, v33
	v_rcp_f32_e32 v40, v41
	v_rcp_f32_e32 v41, v43
	v_rcp_f32_e32 v33, v42
	v_rcp_f32_e32 v42, v44
	v_rcp_f32_e32 v43, v45
	v_lshlrev_b32_e32 v44, 16, v18
	v_and_b32_e32 v45, 0xffff0000, v18
	v_pk_mul_f32 v[30:31], v[30:31], v[44:45]
	v_mfma_f32_16x16x32_bf16 v[14:17], v[58:61], v[62:65], v[10:13]
	v_cvt_pk_bf16_f32 v18, v30, v31
	v_lshlrev_b32_e32 v30, 16, v19
	v_and_b32_e32 v31, 0xffff0000, v19
	v_pk_mul_f32 v[30:31], v[40:41], v[30:31]
	v_mfma_f32_16x16x32_bf16 v[10:13], v[58:61], v[52:55], v[72:75]
	v_cvt_pk_bf16_f32 v19, v30, v31
	v_lshlrev_b32_e32 v30, 16, v20
	v_and_b32_e32 v31, 0xffff0000, v20
	v_pk_mul_f32 v[30:31], v[32:33], v[30:31]
	s_nop 0
	v_cvt_pk_bf16_f32 v20, v30, v31
	v_lshlrev_b32_e32 v30, 16, v21
	v_and_b32_e32 v31, 0xffff0000, v21
	v_pk_mul_f32 v[30:31], v[42:43], v[30:31]
	s_nop 0
	v_cvt_pk_bf16_f32 v21, v30, v31
	ds_write_b128 v70, v[18:21]
	s_waitcnt vmcnt(1)
	ds_write_b128 v86, v[22:25] offset:63488
	s_waitcnt vmcnt(0)
	ds_write_b128 v84, v[26:29] offset:8704
	s_and_saveexec_b64 s[6:7], s[2:3]
	v_add_u32_e32 v18, 0x16c00, v85
	ds_write_b32 v18, v1
	s_or_b64 exec, exec, s[6:7]
	v_pk_mul_f32 v[20:21], v[36:37], v[4:5]
	v_pk_mul_f32 v[18:19], v[34:35], v[2:3]
	s_waitcnt lgkmcnt(0)
	s_barrier
	ds_read_b64_tr_b16 v[22:23], v93
	ds_read_b64_tr_b16 v[24:25], v93 offset:576
	ds_read_b64_tr_b16 v[26:27], v94 offset:63488
	ds_read_b64_tr_b16 v[28:29], v94 offset:64576
	ds_read_b64_tr_b16 v[30:31], v94 offset:63520
	ds_read_b64_tr_b16 v[32:33], v94 offset:64608
	ds_read_b64_tr_b16 v[34:35], v94 offset:63552
	ds_read_b64_tr_b16 v[42:43], v88 offset:64576
	ds_read_b64_tr_b16 v[44:45], v93 offset:4608
	ds_read_b64_tr_b16 v[46:47], v93 offset:5184
	v_pk_mul_f32 v[16:17], v[16:17], v[4:5]
	v_pk_mul_f32 v[14:15], v[14:15], v[2:3]
	s_waitcnt lgkmcnt(6)
	v_mfma_f32_16x16x32_bf16 v[18:21], v[22:25], v[26:29], v[18:21]
	ds_read_b64_tr_b16 v[36:37], v94 offset:64640
	ds_read_b64_tr_b16 v[26:27], v95 offset:63488
	ds_read_b64_tr_b16 v[28:29], v95 offset:64576
	v_pk_mul_f32 v[12:13], v[12:13], v[4:5]
	v_pk_mul_f32 v[8:9], v[8:9], v[4:5]
	s_waitcnt lgkmcnt(7)
	v_mfma_f32_16x16x32_bf16 v[14:17], v[22:25], v[30:33], v[14:17]
	ds_read_b64_tr_b16 v[32:33], v87 offset:64576
	ds_read_b64_tr_b16 v[30:31], v87 offset:63488
	v_pk_mul_f32 v[6:7], v[6:7], v[2:3]
	v_pk_mul_f32 v[10:11], v[10:11], v[2:3]
	s_mov_b32 s7, 0
	s_waitcnt lgkmcnt(4)
	v_mfma_f32_16x16x32_bf16 v[4:7], v[22:25], v[34:37], v[6:9]
	s_lshl_b64 s[2:3], s[8:9], 2
	s_waitcnt lgkmcnt(2)
	v_mfma_f32_16x16x32_bf16 v[8:11], v[22:25], v[26:29], v[10:13]
	ds_read_b64_tr_b16 v[22:23], v87 offset:64608
	s_nop 1
	ds_read_b64_tr_b16 v[12:13], v87 offset:63552
	ds_read_b128 v[24:27], v96
	s_waitcnt lgkmcnt(3)
	v_mfma_f32_16x16x32_bf16 v[28:31], v[44:47], v[30:33], v[18:21]
	s_nop 2
	ds_read_b64_tr_b16 v[20:21], v87 offset:63520
	s_waitcnt lgkmcnt(0)
	v_mfma_f32_16x16x32_bf16 v[16:19], v[44:47], v[20:23], v[14:17]
	s_nop 2
	ds_read_b64_tr_b16 v[14:15], v87 offset:64640
	ds_read_b64_tr_b16 v[40:41], v88 offset:63488
	s_waitcnt lgkmcnt(0)
	s_barrier
	s_setprio 0
	v_mfma_f32_16x16x32_bf16 v[2:5], v[44:47], v[12:15], v[4:7]
	v_mul_f32_e64 v12, v30, v26
	v_mul_f32_e64 v13, v31, v27
	v_pk_mul_f32 v[18:19], v[18:19], v[26:27]
	v_pk_mul_f32 v[16:17], v[16:17], v[24:25]
	v_mfma_f32_16x16x32_bf16 v[6:9], v[44:47], v[40:43], v[8:11]
	s_nop 2
	v_mul_f32_e64 v20, v2, v24
	v_mul_f32_e64 v21, v3, v25
	v_pk_mul_f32 v[22:23], v[4:5], v[26:27]
	v_pk_mul_f32 v[10:11], v[28:29], v[24:25]
	s_nop 0
	v_pk_mul_f32 v[2:3], v[6:7], v[24:25]
	v_mov_b32_e32 v6, s25
	v_mov_b32_e32 v7, 0
	v_readfirstlane_b32 s6, v6
	s_bfe_i64 s[6:7], s[6:7], 0x80000
	s_add_u32 s2, s2, s6
	s_addc_u32 s3, s3, s7
	s_mul_i32 s3, s3, 3
	s_mul_hi_u32 s5, s2, 3
	s_add_i32 s5, s5, s3
	s_mul_i32 s2, s2, 3
	s_ashr_i32 s3, s24, 31
	s_add_u32 s2, s2, s24
	s_addc_u32 s3, s5, s3
	s_ashr_i32 s5, s4, 31
	s_lshl_b64 s[2:3], s[2:3], 15
	s_lshl_b64 s[4:5], s[4:5], 12
	s_add_u32 s4, s30, s4
	s_addc_u32 s5, s31, s5
	s_add_u32 s2, s4, s2
	s_addc_u32 s3, s5, s3
	v_lshlrev_b32_e32 v6, 2, v38
	v_pk_mul_f32 v[4:5], v[8:9], v[26:27]
	v_lshl_add_u64 v[8:9], s[2:3], 0, v[6:7]
	global_store_dwordx4 v6, v[10:13], s[2:3]
	global_store_dwordx4 v6, v[16:19], s[2:3] offset:1024
	global_store_dwordx4 v6, v[20:23], s[2:3] offset:2048
	s_mov_b64 s[2:3], 0xc00
	v_lshl_add_u64 v[14:15], v[8:9], 0, s[2:3]
	s_mov_b64 s[4:5], -1

; #define PG8_STAGE(bufoff, gbase, voff) do { _Pragma("unroll") for (int _i = 0; _i < 2; ++_i) \
;         __builtin_amdgcn_global_load_lds((const unsigned*)((const char*)(gbase) + (voff)[_i]), (PG8_LAS unsigned*)(lds + (bufoff) + ldsw + _i * 8192), 16, 0, 0); } while (0)
; #define PG8_LDA(dst, b, h) do { _Pragma("unroll") for (int m = 0; m < 4; ++m) _Pragma("unroll") for (int k = 0; k < 2; ++k) dst[m][k] = *(const PG8_LAS bf16x8*)(lds + PG8_SA(b, h) + aoff + m * 2048 + k * 1024); } while (0)
; #define PG8_LDB(dst, b, h) do { _Pragma("unroll") for (int n = 0; n < 2; ++n) _Pragma("unroll") for (int k = 0; k < 2; ++k) dst[n][k] = *(const PG8_LAS bf16x8*)(lds + PG8_SB(b, h) + boff + n * 2048 + k * 1024); } while (0)
; #define PG8_MMA(ai, bj, At, Bt) do { __builtin_amdgcn_s_setprio(1); _Pragma("unroll") for (int m = 0; m < 4; ++m) _Pragma("unroll") for (int n = 0; n < 2; ++n) _Pragma("unroll") for (int k = 0; k < 2; ++k) \
;         acc[ai][bj][m][n] = __builtin_amdgcn_mfma_f32_16x16x32_bf16(Bt[n][k], At[m][k], acc[ai][bj][m][n], 0, 0, 0); __builtin_amdgcn_s_setprio(0); } while (0)
; #define PG8_WAIT_V(n) asm volatile("s_waitcnt vmcnt(" #n ")" ::: "memory")
; #define PG8_WAIT_L(n) asm volatile("s_waitcnt lgkmcnt(" #n ")" ::: "memory")
; #define PG8_BAR __builtin_amdgcn_s_barrier()
; #define PG8_SCHED __builtin_amdgcn_sched_barrier(0)
; template <class Epi, class Sched, bool ALIGN_EPI = false, bool SP2 = false>
; __device__ __forceinline__ void gemm_phase(PG8_LAS unsigned char* lds, const Gemm g, const Sched& S, const Epi& E) {
;     ...
;             const bool last = (t == nt - 2);
;             const char* a1 = cA + (size_t)(t + 1) * kstep;
;             const char* a2 = last ? nA : cA + (size_t)(t + 2) * kstep; const char* b2 = last ? nB : cB + (size_t)(t + 2) * kstep;
;             const char* a3 = a2 + kstep; const char* b3 = b2 + kstep;
;             if (last && has_next) S.a_ready(nxt);
;             if constexpr (SP2) {
;             PG8_LDB(B0, 0, 0); PG8_LDB(B1, 0, 1); PG8_SCHED; PG8_LDA(At, 0, 0); PG8_STAGE(PG8_SA(1, 1), a1 + hstep, voffA);
;             PG8_WAIT_V(8); PG8_WAIT_L(0); PG8_BAR; PG8_MMA(0, 0, At, B0); PG8_MMA(0, 1, At, B1); PG8_BAR; PG8_SCHED;
;             PG8_LDA(At, 0, 1); PG8_STAGE(PG8_SB(0, 0), b2, voffB); PG8_STAGE(PG8_SB(0, 1), b2 + hstepB, voffB); PG8_STAGE(PG8_SA(0, 0), a2, voffA);
.LBB0_1094:
	v_add_u32_e32 v3, s46, v224
	ds_read_b128 v[134:137], v3
	ds_read_b128 v[138:141], v3 offset:1024
	ds_read_b128 v[142:145], v3 offset:2048
	ds_read_b128 v[146:149], v3 offset:3072
	v_add_u32_e32 v3, s47, v224
	s_add_u32 s26, s22, s24
	ds_read_b128 v[150:153], v3
	ds_read_b128 v[154:157], v3 offset:1024
	ds_read_b128 v[158:161], v3 offset:2048
	ds_read_b128 v[162:165], v3 offset:3072
	s_addc_u32 s27, s23, s25
	s_add_u32 s26, s26, 0x100
	s_addc_u32 s27, s27, 0
	s_add_u32 s58, s62, s24
	s_addc_u32 s59, s63, s25
	s_cmpk_eq_i32 s24, 0x700
	s_cselect_b32 s29, s17, s27
	s_cselect_b32 s28, s54, s26
	s_cselect_b32 s27, s56, s59
	s_cselect_b32 s26, s57, s58
	v_lshl_add_u64 v[4:5], v[214:215], 0, s[24:25]
	s_add_i32 m0, s33, 0xc000
	ds_read_b128 v[166:169], v226
	ds_read_b128 v[170:173], v226 offset:1024
	ds_read_b128 v[174:177], v226 offset:2048
	ds_read_b128 v[178:181], v226 offset:3072
	ds_read_b128 v[182:185], v226 offset:4096
	ds_read_b128 v[186:189], v226 offset:5120
	ds_read_b128 v[190:193], v226 offset:6144
	ds_read_b128 v[194:197], v226 offset:7168
	global_load_lds_dwordx4 v[4:5], off
	v_lshl_add_u64 v[4:5], v[216:217], 0, s[24:25]
	s_add_i32 m0, s33, 0xe000
	s_nop 0
	global_load_lds_dwordx4 v[4:5], off
	s_waitcnt vmcnt(8)
	s_waitcnt lgkmcnt(0)
	s_barrier
	s_setprio 0
	v_mfma_f32_16x16x32_bf16 v[130:133], v[134:137], v[166:169], v[130:133]
	v_mfma_f32_16x16x32_bf16 v[126:129], v[142:145], v[166:169], v[126:129]
	v_mfma_f32_16x16x32_bf16 v[114:117], v[134:137], v[174:177], v[114:117]
	v_mfma_f32_16x16x32_bf16 v[110:113], v[142:145], v[174:177], v[110:113]
	v_mfma_f32_16x16x32_bf16 v[98:101], v[134:137], v[182:185], v[98:101]
	v_mfma_f32_16x16x32_bf16 v[94:97], v[142:145], v[182:185], v[94:97]
	v_mfma_f32_16x16x32_bf16 v[82:85], v[134:137], v[190:193], v[82:85]
	v_mfma_f32_16x16x32_bf16 v[78:81], v[142:145], v[190:193], v[78:81]
	v_mfma_f32_16x16x32_bf16 v[130:133], v[138:141], v[170:173], v[130:133]
	v_mfma_f32_16x16x32_bf16 v[126:129], v[146:149], v[170:173], v[126:129]
	v_mfma_f32_16x16x32_bf16 v[114:117], v[138:141], v[178:181], v[114:117]
	v_mfma_f32_16x16x32_bf16 v[110:113], v[146:149], v[178:181], v[110:113]
	v_mfma_f32_16x16x32_bf16 v[98:101], v[138:141], v[186:189], v[98:101]
	v_mfma_f32_16x16x32_bf16 v[94:97], v[146:149], v[186:189], v[94:97]
	v_mfma_f32_16x16x32_bf16 v[82:85], v[138:141], v[194:197], v[82:85]
	v_mfma_f32_16x16x32_bf16 v[78:81], v[146:149], v[194:197], v[78:81]
	v_mfma_f32_16x16x32_bf16 v[122:125], v[150:153], v[166:169], v[122:125]
	v_mfma_f32_16x16x32_bf16 v[118:121], v[158:161], v[166:169], v[118:121]
	v_mfma_f32_16x16x32_bf16 v[106:109], v[150:153], v[174:177], v[106:109]
	v_mfma_f32_16x16x32_bf16 v[102:105], v[158:161], v[174:177], v[102:105]
	v_mfma_f32_16x16x32_bf16 v[90:93], v[150:153], v[182:185], v[90:93]
	v_mfma_f32_16x16x32_bf16 v[86:89], v[158:161], v[182:185], v[86:89]
	v_mfma_f32_16x16x32_bf16 v[74:77], v[150:153], v[190:193], v[74:77]
	v_mfma_f32_16x16x32_bf16 v[70:73], v[158:161], v[190:193], v[70:73]
	v_mfma_f32_16x16x32_bf16 v[122:125], v[154:157], v[170:173], v[122:125]
	v_mfma_f32_16x16x32_bf16 v[118:121], v[162:165], v[170:173], v[118:121]
	v_mfma_f32_16x16x32_bf16 v[106:109], v[154:157], v[178:181], v[106:109]
	v_mfma_f32_16x16x32_bf16 v[102:105], v[162:165], v[178:181], v[102:105]
	v_mfma_f32_16x16x32_bf16 v[90:93], v[154:157], v[186:189], v[90:93]
	v_mfma_f32_16x16x32_bf16 v[86:89], v[162:165], v[186:189], v[86:89]
	v_mfma_f32_16x16x32_bf16 v[74:77], v[154:157], v[194:197], v[74:77]
	v_mfma_f32_16x16x32_bf16 v[70:73], v[162:165], v[194:197], v[70:73]
	s_barrier
	s_setprio 1
	s_add_i32 s58, s46, s31
	v_lshl_add_u64 v[218:219], s[26:27], 0, v[200:201]
	s_mov_b32 m0, s58
	ds_read_b128 v[166:169], v226 offset:16384
	ds_read_b128 v[170:173], v226 offset:17408
	ds_read_b128 v[174:177], v226 offset:18432
	ds_read_b128 v[178:181], v226 offset:19456
	ds_read_b128 v[182:185], v226 offset:20480
	ds_read_b128 v[186:189], v226 offset:21504
	ds_read_b128 v[190:193], v226 offset:22528
	ds_read_b128 v[194:197], v226 offset:23552
	global_load_lds_dwordx4 v[218:219], off
	s_add_i32 m0, s58, 0x2000
	s_add_u32 s58, s26, 0x10000
	v_lshl_add_u64 v[220:221], s[26:27], 0, v[204:205]
	s_addc_u32 s59, s27, 0
	s_add_i32 s65, s47, s31
	global_load_lds_dwordx4 v[220:221], off
	v_lshl_add_u64 v[4:5], s[58:59], 0, v[200:201]
	s_mov_b32 m0, s65
	v_lshl_add_u64 v[228:229], s[28:29], 0, v[198:199]
	global_load_lds_dwordx4 v[4:5], off
	v_lshl_add_u64 v[4:5], s[58:59], 0, v[204:205]
	s_add_i32 m0, s65, 0x2000
	v_lshl_add_u64 v[230:231], s[28:29], 0, v[202:203]
	global_load_lds_dwordx4 v[4:5], off
	s_mov_b32 m0, s33
	s_nop 0
	global_load_lds_dwordx4 v[228:229], off
	s_mov_b32 m0, s34
	s_nop 0
	global_load_lds_dwordx4 v[230:231], off
	s_waitcnt vmcnt(8)
	s_waitcnt lgkmcnt(0)
	s_barrier
; #define PG8_STAGE(bufoff, gbase, voff) do { _Pragma("unroll") for (int _i = 0; _i < 2; ++_i) \
;         __builtin_amdgcn_global_load_lds((const unsigned*)((const char*)(gbase) + (voff)[_i]), (PG8_LAS unsigned*)(lds + (bufoff) + ldsw + _i * 8192), 16, 0, 0); } while (0)
; #define PG8_LDA(dst, b, h) do { _Pragma("unroll") for (int m = 0; m < 4; ++m) _Pragma("unroll") for (int k = 0; k < 2; ++k) dst[m][k] = *(const PG8_LAS bf16x8*)(lds + PG8_SA(b, h) + aoff + m * 2048 + k * 1024); } while (0)
; #define PG8_LDB(dst, b, h) do { _Pragma("unroll") for (int n = 0; n < 2; ++n) _Pragma("unroll") for (int k = 0; k < 2; ++k) dst[n][k] = *(const PG8_LAS bf16x8*)(lds + PG8_SB(b, h) + boff + n * 2048 + k * 1024); } while (0)
; #define PG8_MMA(ai, bj, At, Bt) do { __builtin_amdgcn_s_setprio(1); _Pragma("unroll") for (int m = 0; m < 4; ++m) _Pragma("unroll") for (int n = 0; n < 2; ++n) _Pragma("unroll") for (int k = 0; k < 2; ++k) \
;         acc[ai][bj][m][n] = __builtin_amdgcn_mfma_f32_16x16x32_bf16(Bt[n][k], At[m][k], acc[ai][bj][m][n], 0, 0, 0); __builtin_amdgcn_s_setprio(0); } while (0)
; #define PG8_WAIT_V(n) asm volatile("s_waitcnt vmcnt(" #n ")" ::: "memory")
; #define PG8_WAIT_L(n) asm volatile("s_waitcnt lgkmcnt(" #n ")" ::: "memory")
; #define PG8_BAR __builtin_amdgcn_s_barrier()
; #define PG8_SCHED __builtin_amdgcn_sched_barrier(0)
; template <class Epi, class Sched, bool ALIGN_EPI = false, bool SP2 = false>
; __device__ __forceinline__ void gemm_phase(PG8_LAS unsigned char* lds, const Gemm g, const Sched& S, const Epi& E) {
;     ...
;             PG8_WAIT_V(8); PG8_WAIT_L(0); PG8_BAR; PG8_MMA(1, 0, At, B0); PG8_MMA(1, 1, At, B1); PG8_BAR; PG8_SCHED;
;             PG8_LDB(B0, 1, 0); PG8_LDB(B1, 1, 1); PG8_SCHED; PG8_LDA(At, 1, 0); PG8_STAGE(PG8_SA(0, 1), a2 + hstep, voffA);
;             PG8_WAIT_V(8); PG8_WAIT_L(0); PG8_BAR; PG8_MMA(0, 0, At, B0); PG8_MMA(0, 1, At, B1); PG8_BAR; PG8_SCHED;
	s_setprio 0
	v_mfma_f32_16x16x32_bf16 v[66:69], v[134:137], v[166:169], v[66:69]
	v_mfma_f32_16x16x32_bf16 v[62:65], v[142:145], v[166:169], v[62:65]
	v_mfma_f32_16x16x32_bf16 v[50:53], v[134:137], v[174:177], v[50:53]
	v_mfma_f32_16x16x32_bf16 v[46:49], v[142:145], v[174:177], v[46:49]
	v_mfma_f32_16x16x32_bf16 v[34:37], v[134:137], v[182:185], v[34:37]
	v_mfma_f32_16x16x32_bf16 v[30:33], v[142:145], v[182:185], v[30:33]
	v_mfma_f32_16x16x32_bf16 v[18:21], v[134:137], v[190:193], v[18:21]
	v_mfma_f32_16x16x32_bf16 v[14:17], v[142:145], v[190:193], v[14:17]
	v_mfma_f32_16x16x32_bf16 v[66:69], v[138:141], v[170:173], v[66:69]
	v_mfma_f32_16x16x32_bf16 v[62:65], v[146:149], v[170:173], v[62:65]
	v_mfma_f32_16x16x32_bf16 v[50:53], v[138:141], v[178:181], v[50:53]
	v_mfma_f32_16x16x32_bf16 v[46:49], v[146:149], v[178:181], v[46:49]
	v_mfma_f32_16x16x32_bf16 v[34:37], v[138:141], v[186:189], v[34:37]
	v_mfma_f32_16x16x32_bf16 v[30:33], v[146:149], v[186:189], v[30:33]
	v_mfma_f32_16x16x32_bf16 v[18:21], v[138:141], v[194:197], v[18:21]
	v_mfma_f32_16x16x32_bf16 v[14:17], v[146:149], v[194:197], v[14:17]
	v_mfma_f32_16x16x32_bf16 v[58:61], v[150:153], v[166:169], v[58:61]
	v_mfma_f32_16x16x32_bf16 v[54:57], v[158:161], v[166:169], v[54:57]
	v_mfma_f32_16x16x32_bf16 v[42:45], v[150:153], v[174:177], v[42:45]
	v_mfma_f32_16x16x32_bf16 v[38:41], v[158:161], v[174:177], v[38:41]
	v_mfma_f32_16x16x32_bf16 v[26:29], v[150:153], v[182:185], v[26:29]
	v_mfma_f32_16x16x32_bf16 v[22:25], v[158:161], v[182:185], v[22:25]
	v_mfma_f32_16x16x32_bf16 v[10:13], v[150:153], v[190:193], v[10:13]
	v_mfma_f32_16x16x32_bf16 v[4:7], v[158:161], v[190:193], v[6:9]
	v_mfma_f32_16x16x32_bf16 v[58:61], v[154:157], v[170:173], v[58:61]
	v_mfma_f32_16x16x32_bf16 v[54:57], v[162:165], v[170:173], v[54:57]
	v_mfma_f32_16x16x32_bf16 v[42:45], v[154:157], v[178:181], v[42:45]
	v_mfma_f32_16x16x32_bf16 v[38:41], v[162:165], v[178:181], v[38:41]
	v_mfma_f32_16x16x32_bf16 v[26:29], v[154:157], v[186:189], v[26:29]
	v_mfma_f32_16x16x32_bf16 v[22:25], v[162:165], v[186:189], v[22:25]
	v_mfma_f32_16x16x32_bf16 v[10:13], v[154:157], v[194:197], v[10:13]
	v_mfma_f32_16x16x32_bf16 v[4:7], v[162:165], v[194:197], v[4:7]
	s_barrier
	s_setprio 1
	s_add_i32 s58, 0, 0x18000
	v_add_u32_e32 v3, s58, v224
	s_add_i32 s59, 0, 0x1c000
	ds_read_b128 v[134:137], v3
	ds_read_b128 v[138:141], v3 offset:1024
	ds_read_b128 v[142:145], v3 offset:2048
	ds_read_b128 v[146:149], v3 offset:3072
	v_add_u32_e32 v3, s59, v224
	ds_read_b128 v[150:153], v3
	ds_read_b128 v[154:157], v3 offset:1024
	ds_read_b128 v[158:161], v3 offset:2048
	ds_read_b128 v[162:165], v3 offset:3072
	s_add_u32 s28, s28, 0x40000
	s_addc_u32 s29, s29, 0
	s_mov_b32 m0, s35
	v_lshl_add_u64 v[8:9], s[28:29], 0, v[198:199]
	ds_read_b128 v[166:169], v226 offset:32768
	ds_read_b128 v[170:173], v226 offset:33792
	ds_read_b128 v[174:177], v226 offset:34816
	ds_read_b128 v[178:181], v226 offset:35840
	ds_read_b128 v[182:185], v226 offset:36864
	ds_read_b128 v[186:189], v226 offset:37888
	ds_read_b128 v[190:193], v226 offset:38912
	ds_read_b128 v[194:197], v226 offset:39936
	global_load_lds_dwordx4 v[8:9], off
	v_lshl_add_u64 v[8:9], s[28:29], 0, v[202:203]
	s_mov_b32 m0, s36
	s_nop 0
	global_load_lds_dwordx4 v[8:9], off
	s_waitcnt vmcnt(8)
	s_waitcnt lgkmcnt(0)
	s_barrier
	s_setprio 0
	v_mfma_f32_16x16x32_bf16 v[130:133], v[134:137], v[166:169], v[130:133]
	v_mfma_f32_16x16x32_bf16 v[126:129], v[142:145], v[166:169], v[126:129]
	v_mfma_f32_16x16x32_bf16 v[114:117], v[134:137], v[174:177], v[114:117]
	v_mfma_f32_16x16x32_bf16 v[110:113], v[142:145], v[174:177], v[110:113]
	v_mfma_f32_16x16x32_bf16 v[98:101], v[134:137], v[182:185], v[98:101]
	v_mfma_f32_16x16x32_bf16 v[94:97], v[142:145], v[182:185], v[94:97]
	v_mfma_f32_16x16x32_bf16 v[82:85], v[134:137], v[190:193], v[82:85]
	v_mfma_f32_16x16x32_bf16 v[78:81], v[142:145], v[190:193], v[78:81]
	v_mfma_f32_16x16x32_bf16 v[130:133], v[138:141], v[170:173], v[130:133]
	v_mfma_f32_16x16x32_bf16 v[126:129], v[146:149], v[170:173], v[126:129]
	v_mfma_f32_16x16x32_bf16 v[114:117], v[138:141], v[178:181], v[114:117]
	v_mfma_f32_16x16x32_bf16 v[110:113], v[146:149], v[178:181], v[110:113]
	v_mfma_f32_16x16x32_bf16 v[98:101], v[138:141], v[186:189], v[98:101]
	v_mfma_f32_16x16x32_bf16 v[94:97], v[146:149], v[186:189], v[94:97]
	v_mfma_f32_16x16x32_bf16 v[82:85], v[138:141], v[194:197], v[82:85]
	v_mfma_f32_16x16x32_bf16 v[78:81], v[146:149], v[194:197], v[78:81]
	v_mfma_f32_16x16x32_bf16 v[122:125], v[150:153], v[166:169], v[122:125]
	v_mfma_f32_16x16x32_bf16 v[118:121], v[158:161], v[166:169], v[118:121]
	v_mfma_f32_16x16x32_bf16 v[106:109], v[150:153], v[174:177], v[106:109]
	v_mfma_f32_16x16x32_bf16 v[102:105], v[158:161], v[174:177], v[102:105]
	v_mfma_f32_16x16x32_bf16 v[90:93], v[150:153], v[182:185], v[90:93]
	v_mfma_f32_16x16x32_bf16 v[86:89], v[158:161], v[182:185], v[86:89]
	v_mfma_f32_16x16x32_bf16 v[74:77], v[150:153], v[190:193], v[74:77]
	v_mfma_f32_16x16x32_bf16 v[70:73], v[158:161], v[190:193], v[70:73]
	v_mfma_f32_16x16x32_bf16 v[122:125], v[154:157], v[170:173], v[122:125]
	v_mfma_f32_16x16x32_bf16 v[118:121], v[162:165], v[170:173], v[118:121]
	v_mfma_f32_16x16x32_bf16 v[106:109], v[154:157], v[178:181], v[106:109]
	v_mfma_f32_16x16x32_bf16 v[102:105], v[162:165], v[178:181], v[102:105]
	v_mfma_f32_16x16x32_bf16 v[90:93], v[154:157], v[186:189], v[90:93]
	v_mfma_f32_16x16x32_bf16 v[86:89], v[162:165], v[186:189], v[86:89]
	v_mfma_f32_16x16x32_bf16 v[74:77], v[154:157], v[194:197], v[74:77]
	v_mfma_f32_16x16x32_bf16 v[70:73], v[162:165], v[194:197], v[70:73]
	s_barrier
; #define PG8_STAGE(bufoff, gbase, voff) do { _Pragma("unroll") for (int _i = 0; _i < 2; ++_i) \
;         __builtin_amdgcn_global_load_lds((const unsigned*)((const char*)(gbase) + (voff)[_i]), (PG8_LAS unsigned*)(lds + (bufoff) + ldsw + _i * 8192), 16, 0, 0); } while (0)
; #define PG8_LDA(dst, b, h) do { _Pragma("unroll") for (int m = 0; m < 4; ++m) _Pragma("unroll") for (int k = 0; k < 2; ++k) dst[m][k] = *(const PG8_LAS bf16x8*)(lds + PG8_SA(b, h) + aoff + m * 2048 + k * 1024); } while (0)
; #define PG8_MMA(ai, bj, At, Bt) do { __builtin_amdgcn_s_setprio(1); _Pragma("unroll") for (int m = 0; m < 4; ++m) _Pragma("unroll") for (int n = 0; n < 2; ++n) _Pragma("unroll") for (int k = 0; k < 2; ++k) \
;         acc[ai][bj][m][n] = __builtin_amdgcn_mfma_f32_16x16x32_bf16(Bt[n][k], At[m][k], acc[ai][bj][m][n], 0, 0, 0); __builtin_amdgcn_s_setprio(0); } while (0)
; #define PG8_WAIT_V(n) asm volatile("s_waitcnt vmcnt(" #n ")" ::: "memory")
; #define PG8_WAIT_L(n) asm volatile("s_waitcnt lgkmcnt(" #n ")" ::: "memory")
; #define PG8_BAR __builtin_amdgcn_s_barrier()
; #define PG8_SCHED __builtin_amdgcn_sched_barrier(0)
; template <class Epi, class Sched, bool ALIGN_EPI = false, bool SP2 = false>
; __device__ __forceinline__ void gemm_phase(PG8_LAS unsigned char* lds, const Gemm g, const Sched& S, const Epi& E) {
;     ...
;             PG8_LDA(At, 1, 1); PG8_STAGE(PG8_SB(1, 0), b3, voffB); PG8_STAGE(PG8_SB(1, 1), b3 + hstepB, voffB); PG8_STAGE(PG8_SA(1, 0), a3, voffA);
;             PG8_WAIT_V(8); PG8_WAIT_L(0); PG8_BAR; PG8_MMA(1, 0, At, B0); PG8_MMA(1, 1, At, B1); PG8_BAR; PG8_SCHED;
	s_setprio 1
	s_add_i32 s28, s58, s31
	v_lshl_add_u64 v[8:9], v[218:219], 0, s[10:11]
	s_mov_b32 m0, s28
	ds_read_b128 v[166:169], v226 offset:49152
	ds_read_b128 v[170:173], v226 offset:50176
	ds_read_b128 v[174:177], v226 offset:51200
	ds_read_b128 v[178:181], v226 offset:52224
	ds_read_b128 v[182:185], v226 offset:53248
	ds_read_b128 v[186:189], v226 offset:54272
	ds_read_b128 v[190:193], v226 offset:55296
	ds_read_b128 v[194:197], v226 offset:56320
	global_load_lds_dwordx4 v[8:9], off
	s_add_i32 m0, s28, 0x2000
	s_add_u32 s26, s26, 0x10080
	v_lshl_add_u64 v[8:9], v[220:221], 0, s[10:11]
	s_addc_u32 s27, s27, 0
	s_add_i32 s28, s59, s31
	global_load_lds_dwordx4 v[8:9], off
	v_lshl_add_u64 v[8:9], s[26:27], 0, v[200:201]
	s_mov_b32 m0, s28
	s_nop 0
	global_load_lds_dwordx4 v[8:9], off
	v_lshl_add_u64 v[8:9], s[26:27], 0, v[204:205]
	s_add_i32 m0, s28, 0x2000
	s_nop 0
	global_load_lds_dwordx4 v[8:9], off
	v_lshl_add_u64 v[8:9], v[228:229], 0, s[10:11]
	s_mov_b32 m0, s39
	s_nop 0
	global_load_lds_dwordx4 v[8:9], off
	v_lshl_add_u64 v[8:9], v[230:231], 0, s[10:11]
	s_mov_b32 m0, s42
	s_nop 0
	global_load_lds_dwordx4 v[8:9], off
	s_waitcnt vmcnt(8)
	s_waitcnt lgkmcnt(0)
	s_barrier
	s_setprio 0
	v_mfma_f32_16x16x32_bf16 v[66:69], v[134:137], v[166:169], v[66:69]
	v_mfma_f32_16x16x32_bf16 v[62:65], v[142:145], v[166:169], v[62:65]
	v_mfma_f32_16x16x32_bf16 v[50:53], v[134:137], v[174:177], v[50:53]
	v_mfma_f32_16x16x32_bf16 v[46:49], v[142:145], v[174:177], v[46:49]
	v_mfma_f32_16x16x32_bf16 v[34:37], v[134:137], v[182:185], v[34:37]
	v_mfma_f32_16x16x32_bf16 v[30:33], v[142:145], v[182:185], v[30:33]
	v_mfma_f32_16x16x32_bf16 v[18:21], v[134:137], v[190:193], v[18:21]
	v_mfma_f32_16x16x32_bf16 v[14:17], v[142:145], v[190:193], v[14:17]
	v_mfma_f32_16x16x32_bf16 v[66:69], v[138:141], v[170:173], v[66:69]
	v_mfma_f32_16x16x32_bf16 v[62:65], v[146:149], v[170:173], v[62:65]
	v_mfma_f32_16x16x32_bf16 v[50:53], v[138:141], v[178:181], v[50:53]
	v_mfma_f32_16x16x32_bf16 v[46:49], v[146:149], v[178:181], v[46:49]
	v_mfma_f32_16x16x32_bf16 v[34:37], v[138:141], v[186:189], v[34:37]
	v_mfma_f32_16x16x32_bf16 v[30:33], v[146:149], v[186:189], v[30:33]
	v_mfma_f32_16x16x32_bf16 v[18:21], v[138:141], v[194:197], v[18:21]
	v_mfma_f32_16x16x32_bf16 v[14:17], v[146:149], v[194:197], v[14:17]
	v_mfma_f32_16x16x32_bf16 v[58:61], v[150:153], v[166:169], v[58:61]
	v_mfma_f32_16x16x32_bf16 v[54:57], v[158:161], v[166:169], v[54:57]
	v_mfma_f32_16x16x32_bf16 v[42:45], v[150:153], v[174:177], v[42:45]
	v_mfma_f32_16x16x32_bf16 v[38:41], v[158:161], v[174:177], v[38:41]
	v_mfma_f32_16x16x32_bf16 v[26:29], v[150:153], v[182:185], v[26:29]
	v_mfma_f32_16x16x32_bf16 v[22:25], v[158:161], v[182:185], v[22:25]
	v_mfma_f32_16x16x32_bf16 v[8:11], v[150:153], v[190:193], v[10:13]
	v_mfma_f32_16x16x32_bf16 v[4:7], v[158:161], v[190:193], v[4:7]
	v_mfma_f32_16x16x32_bf16 v[58:61], v[154:157], v[170:173], v[58:61]
	v_mfma_f32_16x16x32_bf16 v[54:57], v[162:165], v[170:173], v[54:57]
	v_mfma_f32_16x16x32_bf16 v[42:45], v[154:157], v[178:181], v[42:45]
	v_mfma_f32_16x16x32_bf16 v[38:41], v[162:165], v[178:181], v[38:41]
	v_mfma_f32_16x16x32_bf16 v[26:29], v[154:157], v[186:189], v[26:29]
	v_mfma_f32_16x16x32_bf16 v[22:25], v[162:165], v[186:189], v[22:25]
	v_mfma_f32_16x16x32_bf16 v[10:13], v[154:157], v[194:197], v[8:11]
	v_mfma_f32_16x16x32_bf16 v[6:9], v[162:165], v[194:197], v[4:7]
	s_barrier
	s_setprio 1
	s_add_i32 s64, s64, 2
	s_add_u32 s24, s24, 0x100
	s_addc_u32 s25, s25, 0
	s_cmp_gt_u32 s64, 13
	s_cbranch_scc1 .LBB0_1097

; #define PG8_STAGE(bufoff, gbase, voff) do { _Pragma("unroll") for (int _i = 0; _i < 2; ++_i) \
;         __builtin_amdgcn_global_load_lds((const unsigned*)((const char*)(gbase) + (voff)[_i]), (PG8_LAS unsigned*)(lds + (bufoff) + ldsw + _i * 8192), 16, 0, 0); } while (0)
; #define PG8_LDA(dst, b, h) do { _Pragma("unroll") for (int m = 0; m < 4; ++m) _Pragma("unroll") for (int k = 0; k < 2; ++k) dst[m][k] = *(const PG8_LAS bf16x8*)(lds + PG8_SA(b, h) + aoff + m * 2048 + k * 1024); } while (0)
; #define PG8_LDB(dst, b, h) do { _Pragma("unroll") for (int n = 0; n < 2; ++n) _Pragma("unroll") for (int k = 0; k < 2; ++k) dst[n][k] = *(const PG8_LAS bf16x8*)(lds + PG8_SB(b, h) + boff + n * 2048 + k * 1024); } while (0)
; #define PG8_MMA(ai, bj, At, Bt) do { __builtin_amdgcn_s_setprio(1); _Pragma("unroll") for (int m = 0; m < 4; ++m) _Pragma("unroll") for (int n = 0; n < 2; ++n) _Pragma("unroll") for (int k = 0; k < 2; ++k) \
;         acc[ai][bj][m][n] = __builtin_amdgcn_mfma_f32_16x16x32_bf16(Bt[n][k], At[m][k], acc[ai][bj][m][n], 0, 0, 0); __builtin_amdgcn_s_setprio(0); } while (0)
; #define PG8_WAIT_V(n) asm volatile("s_waitcnt vmcnt(" #n ")" ::: "memory")
; #define PG8_WAIT_L(n) asm volatile("s_waitcnt lgkmcnt(" #n ")" ::: "memory")
; #define PG8_BAR __builtin_amdgcn_s_barrier()
; #define PG8_SCHED __builtin_amdgcn_sched_barrier(0)
; template <class Epi, class Sched, bool ALIGN_EPI = false, bool SP2 = false>
; __device__ __forceinline__ void gemm_phase(PG8_LAS unsigned char* lds, const Gemm g, const Sched& S, const Epi& E) {
;     ...
;             const bool last = (t == nt - 2);
;             const char* a1 = cA + (size_t)(t + 1) * kstep;
;             const char* a2 = last ? nA : cA + (size_t)(t + 2) * kstep; const char* b2 = last ? nB : cB + (size_t)(t + 2) * kstep;
;             const char* a3 = a2 + kstep; const char* b3 = b2 + kstep;
;             if (last && has_next) S.a_ready(nxt);
;             if constexpr (SP2) {
;             PG8_LDB(B0, 0, 0); PG8_LDB(B1, 0, 1); PG8_SCHED; PG8_LDA(At, 0, 0); PG8_STAGE(PG8_SA(1, 1), a1 + hstep, voffA);
;             PG8_WAIT_V(8); PG8_WAIT_L(0); PG8_BAR; PG8_MMA(0, 0, At, B0); PG8_MMA(0, 1, At, B1); PG8_BAR; PG8_SCHED;
;             PG8_LDA(At, 0, 1); PG8_STAGE(PG8_SB(0, 0), b2, voffB); PG8_STAGE(PG8_SB(0, 1), b2 + hstepB, voffB); PG8_STAGE(PG8_SA(0, 0), a2, voffA);
.LBB0_1180:
	v_add_u32_e32 v144, s55, v142
	ds_read_b128 v[154:157], v144
	ds_read_b128 v[158:161], v144 offset:1024
	ds_read_b128 v[162:165], v144 offset:2048
	ds_read_b128 v[166:169], v144 offset:3072
	v_add_u32_e32 v144, s56, v142
	s_add_u32 s34, s10, s28
	ds_read_b128 v[170:173], v144
	ds_read_b128 v[174:177], v144 offset:1024
	ds_read_b128 v[178:181], v144 offset:2048
	ds_read_b128 v[182:185], v144 offset:3072
	s_addc_u32 s35, s11, s29
	s_add_u32 s34, s34, 0x100
	s_addc_u32 s35, s35, 0
	s_add_u32 s61, s25, s28
	s_addc_u32 s62, s57, s29
	s_cmpk_eq_i32 s28, 0x700
	s_cselect_b32 s37, s21, s35
	s_cselect_b32 s36, s58, s34
	s_cselect_b32 s35, s19, s62
	s_cselect_b32 s34, s59, s61
	v_lshl_add_u64 v[144:145], v[138:139], 0, s[28:29]
	s_add_i32 m0, s39, 0xc000
	ds_read_b128 v[186:189], v143
	ds_read_b128 v[190:193], v143 offset:1024
	ds_read_b128 v[194:197], v143 offset:2048
	ds_read_b128 v[198:201], v143 offset:3072
	ds_read_b128 v[202:205], v143 offset:4096
	ds_read_b128 v[206:209], v143 offset:5120
	ds_read_b128 v[216:219], v143 offset:6144
	ds_read_b128 v[224:227], v143 offset:7168
	global_load_lds_dwordx4 v[144:145], off
	v_lshl_add_u64 v[144:145], v[140:141], 0, s[28:29]
	s_add_i32 m0, s39, 0xe000
	s_nop 0
	global_load_lds_dwordx4 v[144:145], off
	s_waitcnt vmcnt(8)
	s_waitcnt lgkmcnt(0)
	s_barrier
	s_setprio 0
	v_mfma_f32_16x16x32_bf16 v[150:153], v[154:157], v[186:189], v[150:153]
	v_mfma_f32_16x16x32_bf16 v[144:147], v[162:165], v[186:189], v[146:149]
	v_mfma_f32_16x16x32_bf16 v[110:113], v[154:157], v[194:197], v[110:113]
	v_mfma_f32_16x16x32_bf16 v[106:109], v[162:165], v[194:197], v[106:109]
	v_mfma_f32_16x16x32_bf16 v[94:97], v[154:157], v[202:205], v[94:97]
	v_mfma_f32_16x16x32_bf16 v[90:93], v[162:165], v[202:205], v[90:93]
	v_mfma_f32_16x16x32_bf16 v[78:81], v[154:157], v[216:219], v[78:81]
	v_mfma_f32_16x16x32_bf16 v[74:77], v[162:165], v[216:219], v[74:77]
	v_mfma_f32_16x16x32_bf16 v[150:153], v[158:161], v[190:193], v[150:153]
	v_mfma_f32_16x16x32_bf16 v[144:147], v[166:169], v[190:193], v[144:147]
	v_mfma_f32_16x16x32_bf16 v[110:113], v[158:161], v[198:201], v[110:113]
	v_mfma_f32_16x16x32_bf16 v[106:109], v[166:169], v[198:201], v[106:109]
	v_mfma_f32_16x16x32_bf16 v[94:97], v[158:161], v[206:209], v[94:97]
	v_mfma_f32_16x16x32_bf16 v[90:93], v[166:169], v[206:209], v[90:93]
	v_mfma_f32_16x16x32_bf16 v[78:81], v[158:161], v[224:227], v[78:81]
	v_mfma_f32_16x16x32_bf16 v[74:77], v[166:169], v[224:227], v[74:77]
	v_mfma_f32_16x16x32_bf16 v[118:121], v[170:173], v[186:189], v[118:121]
	v_mfma_f32_16x16x32_bf16 v[114:117], v[178:181], v[186:189], v[114:117]
	v_mfma_f32_16x16x32_bf16 v[102:105], v[170:173], v[194:197], v[102:105]
	v_mfma_f32_16x16x32_bf16 v[98:101], v[178:181], v[194:197], v[98:101]
	v_mfma_f32_16x16x32_bf16 v[86:89], v[170:173], v[202:205], v[86:89]
	v_mfma_f32_16x16x32_bf16 v[82:85], v[178:181], v[202:205], v[82:85]
	v_mfma_f32_16x16x32_bf16 v[70:73], v[170:173], v[216:219], v[70:73]
	v_mfma_f32_16x16x32_bf16 v[66:69], v[178:181], v[216:219], v[66:69]
	v_mfma_f32_16x16x32_bf16 v[118:121], v[174:177], v[190:193], v[118:121]
	v_mfma_f32_16x16x32_bf16 v[114:117], v[182:185], v[190:193], v[114:117]
	v_mfma_f32_16x16x32_bf16 v[102:105], v[174:177], v[198:201], v[102:105]
	v_mfma_f32_16x16x32_bf16 v[98:101], v[182:185], v[198:201], v[98:101]
	v_mfma_f32_16x16x32_bf16 v[86:89], v[174:177], v[206:209], v[86:89]
	v_mfma_f32_16x16x32_bf16 v[82:85], v[182:185], v[206:209], v[82:85]
	v_mfma_f32_16x16x32_bf16 v[70:73], v[174:177], v[224:227], v[70:73]
	v_mfma_f32_16x16x32_bf16 v[66:69], v[182:185], v[224:227], v[66:69]
	s_barrier
	s_setprio 1
	s_add_i32 s61, s55, s38
	v_lshl_add_u64 v[210:211], s[34:35], 0, v[124:125]
	s_mov_b32 m0, s61
	ds_read_b128 v[186:189], v143 offset:16384
	ds_read_b128 v[190:193], v143 offset:17408
	ds_read_b128 v[194:197], v143 offset:18432
	ds_read_b128 v[198:201], v143 offset:19456
	ds_read_b128 v[202:205], v143 offset:20480
	ds_read_b128 v[206:209], v143 offset:21504
	ds_read_b128 v[216:219], v143 offset:22528
	ds_read_b128 v[224:227], v143 offset:23552
	global_load_lds_dwordx4 v[210:211], off
	s_add_i32 m0, s61, 0x2000
	s_add_u32 s62, s34, 0x10000
	v_lshl_add_u64 v[220:221], s[34:35], 0, v[128:129]
	s_addc_u32 s63, s35, 0
	s_add_i32 s61, s56, s38
	global_load_lds_dwordx4 v[220:221], off
	v_lshl_add_u64 v[148:149], s[62:63], 0, v[124:125]
	s_mov_b32 m0, s61
	v_lshl_add_u64 v[228:229], s[36:37], 0, v[122:123]
	global_load_lds_dwordx4 v[148:149], off
	v_lshl_add_u64 v[148:149], s[62:63], 0, v[128:129]
	s_add_i32 m0, s61, 0x2000
	v_lshl_add_u64 v[230:231], s[36:37], 0, v[126:127]
	global_load_lds_dwordx4 v[148:149], off
	s_mov_b32 m0, s39
	s_nop 0
	global_load_lds_dwordx4 v[228:229], off
	s_mov_b32 m0, s42
	s_nop 0
	global_load_lds_dwordx4 v[230:231], off
	s_waitcnt vmcnt(8)
	s_waitcnt lgkmcnt(0)
	s_barrier
; #define PG8_STAGE(bufoff, gbase, voff) do { _Pragma("unroll") for (int _i = 0; _i < 2; ++_i) \
;         __builtin_amdgcn_global_load_lds((const unsigned*)((const char*)(gbase) + (voff)[_i]), (PG8_LAS unsigned*)(lds + (bufoff) + ldsw + _i * 8192), 16, 0, 0); } while (0)
; #define PG8_LDA(dst, b, h) do { _Pragma("unroll") for (int m = 0; m < 4; ++m) _Pragma("unroll") for (int k = 0; k < 2; ++k) dst[m][k] = *(const PG8_LAS bf16x8*)(lds + PG8_SA(b, h) + aoff + m * 2048 + k * 1024); } while (0)
; #define PG8_LDB(dst, b, h) do { _Pragma("unroll") for (int n = 0; n < 2; ++n) _Pragma("unroll") for (int k = 0; k < 2; ++k) dst[n][k] = *(const PG8_LAS bf16x8*)(lds + PG8_SB(b, h) + boff + n * 2048 + k * 1024); } while (0)
; #define PG8_MMA(ai, bj, At, Bt) do { __builtin_amdgcn_s_setprio(1); _Pragma("unroll") for (int m = 0; m < 4; ++m) _Pragma("unroll") for (int n = 0; n < 2; ++n) _Pragma("unroll") for (int k = 0; k < 2; ++k) \
;         acc[ai][bj][m][n] = __builtin_amdgcn_mfma_f32_16x16x32_bf16(Bt[n][k], At[m][k], acc[ai][bj][m][n], 0, 0, 0); __builtin_amdgcn_s_setprio(0); } while (0)
; #define PG8_WAIT_V(n) asm volatile("s_waitcnt vmcnt(" #n ")" ::: "memory")
; #define PG8_WAIT_L(n) asm volatile("s_waitcnt lgkmcnt(" #n ")" ::: "memory")
; #define PG8_BAR __builtin_amdgcn_s_barrier()
; #define PG8_SCHED __builtin_amdgcn_sched_barrier(0)
; template <class Epi, class Sched, bool ALIGN_EPI = false, bool SP2 = false>
; __device__ __forceinline__ void gemm_phase(PG8_LAS unsigned char* lds, const Gemm g, const Sched& S, const Epi& E) {
;     ...
;             PG8_WAIT_V(8); PG8_WAIT_L(0); PG8_BAR; PG8_MMA(1, 0, At, B0); PG8_MMA(1, 1, At, B1); PG8_BAR; PG8_SCHED;
;             PG8_LDB(B0, 1, 0); PG8_LDB(B1, 1, 1); PG8_SCHED; PG8_LDA(At, 1, 0); PG8_STAGE(PG8_SA(0, 1), a2 + hstep, voffA);
;             PG8_WAIT_V(8); PG8_WAIT_L(0); PG8_BAR; PG8_MMA(0, 0, At, B0); PG8_MMA(0, 1, At, B1); PG8_BAR; PG8_SCHED;
	s_setprio 0
	v_mfma_f32_16x16x32_bf16 v[62:65], v[154:157], v[186:189], v[62:65]
	v_mfma_f32_16x16x32_bf16 v[58:61], v[162:165], v[186:189], v[58:61]
	v_mfma_f32_16x16x32_bf16 v[46:49], v[154:157], v[194:197], v[46:49]
	v_mfma_f32_16x16x32_bf16 v[42:45], v[162:165], v[194:197], v[42:45]
	v_mfma_f32_16x16x32_bf16 v[30:33], v[154:157], v[202:205], v[30:33]
	v_mfma_f32_16x16x32_bf16 v[26:29], v[162:165], v[202:205], v[26:29]
	v_mfma_f32_16x16x32_bf16 v[14:17], v[154:157], v[216:219], v[14:17]
	v_mfma_f32_16x16x32_bf16 v[10:13], v[162:165], v[216:219], v[10:13]
	v_mfma_f32_16x16x32_bf16 v[62:65], v[158:161], v[190:193], v[62:65]
	v_mfma_f32_16x16x32_bf16 v[58:61], v[166:169], v[190:193], v[58:61]
	v_mfma_f32_16x16x32_bf16 v[46:49], v[158:161], v[198:201], v[46:49]
	v_mfma_f32_16x16x32_bf16 v[42:45], v[166:169], v[198:201], v[42:45]
	v_mfma_f32_16x16x32_bf16 v[30:33], v[158:161], v[206:209], v[30:33]
	v_mfma_f32_16x16x32_bf16 v[26:29], v[166:169], v[206:209], v[26:29]
	v_mfma_f32_16x16x32_bf16 v[14:17], v[158:161], v[224:227], v[14:17]
	v_mfma_f32_16x16x32_bf16 v[10:13], v[166:169], v[224:227], v[10:13]
	v_mfma_f32_16x16x32_bf16 v[54:57], v[170:173], v[186:189], v[54:57]
	v_mfma_f32_16x16x32_bf16 v[50:53], v[178:181], v[186:189], v[50:53]
	v_mfma_f32_16x16x32_bf16 v[38:41], v[170:173], v[194:197], v[38:41]
	v_mfma_f32_16x16x32_bf16 v[34:37], v[178:181], v[194:197], v[34:37]
	v_mfma_f32_16x16x32_bf16 v[22:25], v[170:173], v[202:205], v[22:25]
	v_mfma_f32_16x16x32_bf16 v[18:21], v[178:181], v[202:205], v[18:21]
	v_mfma_f32_16x16x32_bf16 v[6:9], v[170:173], v[216:219], v[6:9]
	v_mfma_f32_16x16x32_bf16 v[2:5], v[178:181], v[216:219], v[2:5]
	v_mfma_f32_16x16x32_bf16 v[54:57], v[174:177], v[190:193], v[54:57]
	v_mfma_f32_16x16x32_bf16 v[50:53], v[182:185], v[190:193], v[50:53]
	v_mfma_f32_16x16x32_bf16 v[38:41], v[174:177], v[198:201], v[38:41]
	v_mfma_f32_16x16x32_bf16 v[34:37], v[182:185], v[198:201], v[34:37]
	v_mfma_f32_16x16x32_bf16 v[22:25], v[174:177], v[206:209], v[22:25]
	v_mfma_f32_16x16x32_bf16 v[18:21], v[182:185], v[206:209], v[18:21]
	v_mfma_f32_16x16x32_bf16 v[6:9], v[174:177], v[224:227], v[6:9]
	v_mfma_f32_16x16x32_bf16 v[2:5], v[182:185], v[224:227], v[2:5]
	s_barrier
	s_setprio 1
	s_add_i32 s61, 0, 0x18000
	v_add_u32_e32 v148, s61, v142
	s_add_i32 s62, 0, 0x1c000
	ds_read_b128 v[154:157], v148
	ds_read_b128 v[158:161], v148 offset:1024
	ds_read_b128 v[162:165], v148 offset:2048
	ds_read_b128 v[166:169], v148 offset:3072
	v_add_u32_e32 v148, s62, v142
	ds_read_b128 v[170:173], v148
	ds_read_b128 v[174:177], v148 offset:1024
	ds_read_b128 v[178:181], v148 offset:2048
	ds_read_b128 v[182:185], v148 offset:3072
	s_add_u32 s36, s36, 0x40000
	s_addc_u32 s37, s37, 0
	s_mov_b32 m0, s44
	v_lshl_add_u64 v[148:149], s[36:37], 0, v[122:123]
	ds_read_b128 v[186:189], v143 offset:32768
	ds_read_b128 v[190:193], v143 offset:33792
	ds_read_b128 v[194:197], v143 offset:34816
	ds_read_b128 v[198:201], v143 offset:35840
	ds_read_b128 v[202:205], v143 offset:36864
	ds_read_b128 v[206:209], v143 offset:37888
	ds_read_b128 v[216:219], v143 offset:38912
	ds_read_b128 v[224:227], v143 offset:39936
	global_load_lds_dwordx4 v[148:149], off
	v_lshl_add_u64 v[148:149], s[36:37], 0, v[126:127]
	s_mov_b32 m0, s45
	s_nop 0
	global_load_lds_dwordx4 v[148:149], off
	s_waitcnt vmcnt(8)
	s_waitcnt lgkmcnt(0)
	s_barrier
	s_setprio 0
	v_mfma_f32_16x16x32_bf16 v[148:151], v[154:157], v[186:189], v[150:153]
	v_mfma_f32_16x16x32_bf16 v[144:147], v[162:165], v[186:189], v[144:147]
	v_mfma_f32_16x16x32_bf16 v[110:113], v[154:157], v[194:197], v[110:113]
	v_mfma_f32_16x16x32_bf16 v[106:109], v[162:165], v[194:197], v[106:109]
	v_mfma_f32_16x16x32_bf16 v[94:97], v[154:157], v[202:205], v[94:97]
	v_mfma_f32_16x16x32_bf16 v[90:93], v[162:165], v[202:205], v[90:93]
	v_mfma_f32_16x16x32_bf16 v[78:81], v[154:157], v[216:219], v[78:81]
	v_mfma_f32_16x16x32_bf16 v[74:77], v[162:165], v[216:219], v[74:77]
	v_mfma_f32_16x16x32_bf16 v[150:153], v[158:161], v[190:193], v[148:151]
	v_mfma_f32_16x16x32_bf16 v[146:149], v[166:169], v[190:193], v[144:147]
	v_mfma_f32_16x16x32_bf16 v[110:113], v[158:161], v[198:201], v[110:113]
	v_mfma_f32_16x16x32_bf16 v[106:109], v[166:169], v[198:201], v[106:109]
	v_mfma_f32_16x16x32_bf16 v[94:97], v[158:161], v[206:209], v[94:97]
	v_mfma_f32_16x16x32_bf16 v[90:93], v[166:169], v[206:209], v[90:93]
	v_mfma_f32_16x16x32_bf16 v[78:81], v[158:161], v[224:227], v[78:81]
	v_mfma_f32_16x16x32_bf16 v[74:77], v[166:169], v[224:227], v[74:77]
	v_mfma_f32_16x16x32_bf16 v[118:121], v[170:173], v[186:189], v[118:121]
	v_mfma_f32_16x16x32_bf16 v[114:117], v[178:181], v[186:189], v[114:117]
	v_mfma_f32_16x16x32_bf16 v[102:105], v[170:173], v[194:197], v[102:105]
	v_mfma_f32_16x16x32_bf16 v[98:101], v[178:181], v[194:197], v[98:101]
	v_mfma_f32_16x16x32_bf16 v[86:89], v[170:173], v[202:205], v[86:89]
	v_mfma_f32_16x16x32_bf16 v[82:85], v[178:181], v[202:205], v[82:85]
	v_mfma_f32_16x16x32_bf16 v[70:73], v[170:173], v[216:219], v[70:73]
	v_mfma_f32_16x16x32_bf16 v[66:69], v[178:181], v[216:219], v[66:69]
	v_mfma_f32_16x16x32_bf16 v[118:121], v[174:177], v[190:193], v[118:121]
	v_mfma_f32_16x16x32_bf16 v[114:117], v[182:185], v[190:193], v[114:117]
	v_mfma_f32_16x16x32_bf16 v[102:105], v[174:177], v[198:201], v[102:105]
	v_mfma_f32_16x16x32_bf16 v[98:101], v[182:185], v[198:201], v[98:101]
	v_mfma_f32_16x16x32_bf16 v[86:89], v[174:177], v[206:209], v[86:89]
	v_mfma_f32_16x16x32_bf16 v[82:85], v[182:185], v[206:209], v[82:85]
	v_mfma_f32_16x16x32_bf16 v[70:73], v[174:177], v[224:227], v[70:73]
	v_mfma_f32_16x16x32_bf16 v[66:69], v[182:185], v[224:227], v[66:69]
	s_barrier
; #define PG8_STAGE(bufoff, gbase, voff) do { _Pragma("unroll") for (int _i = 0; _i < 2; ++_i) \
;         __builtin_amdgcn_global_load_lds((const unsigned*)((const char*)(gbase) + (voff)[_i]), (PG8_LAS unsigned*)(lds + (bufoff) + ldsw + _i * 8192), 16, 0, 0); } while (0)
; #define PG8_LDA(dst, b, h) do { _Pragma("unroll") for (int m = 0; m < 4; ++m) _Pragma("unroll") for (int k = 0; k < 2; ++k) dst[m][k] = *(const PG8_LAS bf16x8*)(lds + PG8_SA(b, h) + aoff + m * 2048 + k * 1024); } while (0)
; #define PG8_MMA(ai, bj, At, Bt) do { __builtin_amdgcn_s_setprio(1); _Pragma("unroll") for (int m = 0; m < 4; ++m) _Pragma("unroll") for (int n = 0; n < 2; ++n) _Pragma("unroll") for (int k = 0; k < 2; ++k) \
;         acc[ai][bj][m][n] = __builtin_amdgcn_mfma_f32_16x16x32_bf16(Bt[n][k], At[m][k], acc[ai][bj][m][n], 0, 0, 0); __builtin_amdgcn_s_setprio(0); } while (0)
; #define PG8_WAIT_V(n) asm volatile("s_waitcnt vmcnt(" #n ")" ::: "memory")
; #define PG8_WAIT_L(n) asm volatile("s_waitcnt lgkmcnt(" #n ")" ::: "memory")
; #define PG8_BAR __builtin_amdgcn_s_barrier()
; #define PG8_SCHED __builtin_amdgcn_sched_barrier(0)
; template <class Epi, class Sched, bool ALIGN_EPI = false, bool SP2 = false>
; __device__ __forceinline__ void gemm_phase(PG8_LAS unsigned char* lds, const Gemm g, const Sched& S, const Epi& E) {
;     ...
;             PG8_LDA(At, 1, 1); PG8_STAGE(PG8_SB(1, 0), b3, voffB); PG8_STAGE(PG8_SB(1, 1), b3 + hstepB, voffB); PG8_STAGE(PG8_SA(1, 0), a3, voffA);
;             PG8_WAIT_V(8); PG8_WAIT_L(0); PG8_BAR; PG8_MMA(1, 0, At, B0); PG8_MMA(1, 1, At, B1); PG8_BAR; PG8_SCHED;
;     ...
; #pragma unroll
;         for (int a = 0; a < 2; ++a)
; #pragma unroll
;             for (int b = 0; b < 2; ++b)
; #pragma unroll
;                 for (int m = 0; m < 4; ++m)
; #pragma unroll
;                     for (int n = 0; n < 2; ++n) acc[a][b][m][n] = (f32x4){0.f, 0.f, 0.f, 0.f};
	s_setprio 1
	s_add_i32 s36, s61, s38
	v_lshl_add_u64 v[144:145], v[210:211], 0, s[16:17]
	s_mov_b32 m0, s36
	ds_read_b128 v[186:189], v143 offset:49152
	ds_read_b128 v[190:193], v143 offset:50176
	ds_read_b128 v[194:197], v143 offset:51200
	ds_read_b128 v[198:201], v143 offset:52224
	ds_read_b128 v[202:205], v143 offset:53248
	ds_read_b128 v[206:209], v143 offset:54272
	ds_read_b128 v[216:219], v143 offset:55296
	ds_read_b128 v[224:227], v143 offset:56320
	global_load_lds_dwordx4 v[144:145], off
	s_add_i32 m0, s36, 0x2000
	s_add_u32 s34, s34, 0x10080
	v_lshl_add_u64 v[144:145], v[220:221], 0, s[16:17]
	s_addc_u32 s35, s35, 0
	s_add_i32 s36, s62, s38
	global_load_lds_dwordx4 v[144:145], off
	v_lshl_add_u64 v[144:145], s[34:35], 0, v[124:125]
	s_mov_b32 m0, s36
	s_nop 0
	global_load_lds_dwordx4 v[144:145], off
	v_lshl_add_u64 v[144:145], s[34:35], 0, v[128:129]
	s_add_i32 m0, s36, 0x2000
	s_nop 0
	global_load_lds_dwordx4 v[144:145], off
	v_lshl_add_u64 v[144:145], v[228:229], 0, s[16:17]
	s_mov_b32 m0, s46
	s_nop 0
	global_load_lds_dwordx4 v[144:145], off
	v_lshl_add_u64 v[144:145], v[230:231], 0, s[16:17]
	s_mov_b32 m0, s47
	s_nop 0
	global_load_lds_dwordx4 v[144:145], off
	s_waitcnt vmcnt(8)
	s_waitcnt lgkmcnt(0)
	s_barrier
	s_setprio 0
	v_mfma_f32_16x16x32_bf16 v[62:65], v[154:157], v[186:189], v[62:65]
	v_mfma_f32_16x16x32_bf16 v[58:61], v[162:165], v[186:189], v[58:61]
	v_mfma_f32_16x16x32_bf16 v[46:49], v[154:157], v[194:197], v[46:49]
	v_mfma_f32_16x16x32_bf16 v[42:45], v[162:165], v[194:197], v[42:45]
	v_mfma_f32_16x16x32_bf16 v[30:33], v[154:157], v[202:205], v[30:33]
	v_mfma_f32_16x16x32_bf16 v[26:29], v[162:165], v[202:205], v[26:29]
	v_mfma_f32_16x16x32_bf16 v[14:17], v[154:157], v[216:219], v[14:17]
	v_mfma_f32_16x16x32_bf16 v[10:13], v[162:165], v[216:219], v[10:13]
	v_mfma_f32_16x16x32_bf16 v[62:65], v[158:161], v[190:193], v[62:65]
	v_mfma_f32_16x16x32_bf16 v[58:61], v[166:169], v[190:193], v[58:61]
	v_mfma_f32_16x16x32_bf16 v[46:49], v[158:161], v[198:201], v[46:49]
	v_mfma_f32_16x16x32_bf16 v[42:45], v[166:169], v[198:201], v[42:45]
	v_mfma_f32_16x16x32_bf16 v[30:33], v[158:161], v[206:209], v[30:33]
	v_mfma_f32_16x16x32_bf16 v[26:29], v[166:169], v[206:209], v[26:29]
	v_mfma_f32_16x16x32_bf16 v[14:17], v[158:161], v[224:227], v[14:17]
	v_mfma_f32_16x16x32_bf16 v[10:13], v[166:169], v[224:227], v[10:13]
	v_mfma_f32_16x16x32_bf16 v[54:57], v[170:173], v[186:189], v[54:57]
	v_mfma_f32_16x16x32_bf16 v[50:53], v[178:181], v[186:189], v[50:53]
	v_mfma_f32_16x16x32_bf16 v[38:41], v[170:173], v[194:197], v[38:41]
	v_mfma_f32_16x16x32_bf16 v[34:37], v[178:181], v[194:197], v[34:37]
	v_mfma_f32_16x16x32_bf16 v[22:25], v[170:173], v[202:205], v[22:25]
	v_mfma_f32_16x16x32_bf16 v[18:21], v[178:181], v[202:205], v[18:21]
	v_mfma_f32_16x16x32_bf16 v[6:9], v[170:173], v[216:219], v[6:9]
	v_mfma_f32_16x16x32_bf16 v[2:5], v[178:181], v[216:219], v[2:5]
	v_mfma_f32_16x16x32_bf16 v[54:57], v[174:177], v[190:193], v[54:57]
	v_mfma_f32_16x16x32_bf16 v[50:53], v[182:185], v[190:193], v[50:53]
	v_mfma_f32_16x16x32_bf16 v[38:41], v[174:177], v[198:201], v[38:41]
	v_mfma_f32_16x16x32_bf16 v[34:37], v[182:185], v[198:201], v[34:37]
	v_mfma_f32_16x16x32_bf16 v[22:25], v[174:177], v[206:209], v[22:25]
	v_mfma_f32_16x16x32_bf16 v[18:21], v[182:185], v[206:209], v[18:21]
	v_mfma_f32_16x16x32_bf16 v[6:9], v[174:177], v[224:227], v[6:9]
	v_mfma_f32_16x16x32_bf16 v[2:5], v[182:185], v[224:227], v[2:5]
	s_barrier
	s_setprio 1
	s_add_i32 s60, s60, 2
	s_add_u32 s28, s28, 0x100
	s_addc_u32 s29, s29, 0
	s_cmp_gt_u32 s60, 13
	s_cbranch_scc0 .LBB0_1180
	s_add_u32 s28, s25, 0xffffff00
	s_addc_u32 s29, s57, -1
	s_andn2_b64 vcc, exec, s[8:9]
	s_cbranch_vccnz .LBB0_1171
	v_mov_b32_e32 v2, 0
	s_mov_b32 s0, s18
	s_mov_b32 s14, s20
	s_mov_b64 s[10:11], s[26:27]
	s_mov_b32 s54, s24
	v_mov_b32_e32 v3, v2
	v_mov_b32_e32 v4, v2
	v_mov_b32_e32 v5, v2
	v_mov_b32_e32 v6, v2
	v_mov_b32_e32 v7, v2
	v_mov_b32_e32 v8, v2
	v_mov_b32_e32 v9, v2
	v_mov_b32_e32 v18, v2
	v_mov_b32_e32 v19, v2
	v_mov_b32_e32 v20, v2
	v_mov_b32_e32 v21, v2
	v_mov_b32_e32 v22, v2
	v_mov_b32_e32 v23, v2
	v_mov_b32_e32 v24, v2
	v_mov_b32_e32 v25, v2
	v_mov_b32_e32 v34, v2
	v_mov_b32_e32 v35, v2
	v_mov_b32_e32 v36, v2
	v_mov_b32_e32 v37, v2
	v_mov_b32_e32 v38, v2
	v_mov_b32_e32 v39, v2
	v_mov_b32_e32 v40, v2
	v_mov_b32_e32 v41, v2
	v_mov_b32_e32 v50, v2
	v_mov_b32_e32 v51, v2
	v_mov_b32_e32 v52, v2
	v_mov_b32_e32 v53, v2
	v_mov_b32_e32 v54, v2
	v_mov_b32_e32 v55, v2
	v_mov_b32_e32 v56, v2
	v_mov_b32_e32 v57, v2
	v_mov_b32_e32 v10, v2
	v_mov_b32_e32 v11, v2
	v_mov_b32_e32 v12, v2
	v_mov_b32_e32 v13, v2
	v_mov_b32_e32 v14, v2
	v_mov_b32_e32 v15, v2
	v_mov_b32_e32 v16, v2
	v_mov_b32_e32 v17, v2
	v_mov_b32_e32 v26, v2
	v_mov_b32_e32 v27, v2
	v_mov_b32_e32 v28, v2
	v_mov_b32_e32 v29, v2
	v_mov_b32_e32 v30, v2
	v_mov_b32_e32 v31, v2
	v_mov_b32_e32 v32, v2
	v_mov_b32_e32 v33, v2
	v_mov_b32_e32 v42, v2
	v_mov_b32_e32 v43, v2
	v_mov_b32_e32 v44, v2
	v_mov_b32_e32 v45, v2
	v_mov_b32_e32 v46, v2
	v_mov_b32_e32 v47, v2
	v_mov_b32_e32 v48, v2
	v_mov_b32_e32 v49, v2
	v_mov_b32_e32 v58, v2
	v_mov_b32_e32 v59, v2
	v_mov_b32_e32 v60, v2
	v_mov_b32_e32 v61, v2
	v_mov_b32_e32 v62, v2
	v_mov_b32_e32 v63, v2
	v_mov_b32_e32 v64, v2
	v_mov_b32_e32 v65, v2
	v_mov_b32_e32 v66, v2
	v_mov_b32_e32 v67, v2
	v_mov_b32_e32 v68, v2
	v_mov_b32_e32 v69, v2
	v_mov_b32_e32 v70, v2
	v_mov_b32_e32 v71, v2
	v_mov_b32_e32 v72, v2
	v_mov_b32_e32 v73, v2
	v_mov_b32_e32 v82, v2
	v_mov_b32_e32 v83, v2
	v_mov_b32_e32 v84, v2
	v_mov_b32_e32 v85, v2
	v_mov_b32_e32 v86, v2
	v_mov_b32_e32 v87, v2
	v_mov_b32_e32 v88, v2
	v_mov_b32_e32 v89, v2
	v_mov_b32_e32 v98, v2
	v_mov_b32_e32 v99, v2
	v_mov_b32_e32 v100, v2
	v_mov_b32_e32 v101, v2
	v_mov_b32_e32 v102, v2
	v_mov_b32_e32 v103, v2
	v_mov_b32_e32 v104, v2
	v_mov_b32_e32 v105, v2
	v_mov_b32_e32 v114, v2
	v_mov_b32_e32 v115, v2
	v_mov_b32_e32 v116, v2
	v_mov_b32_e32 v117, v2
	v_mov_b32_e32 v118, v2
	v_mov_b32_e32 v119, v2
	v_mov_b32_e32 v120, v2
	v_mov_b32_e32 v121, v2
	v_mov_b32_e32 v74, v2
	v_mov_b32_e32 v75, v2
	v_mov_b32_e32 v76, v2
	v_mov_b32_e32 v77, v2
	v_mov_b32_e32 v78, v2
	v_mov_b32_e32 v79, v2
	v_mov_b32_e32 v80, v2
	v_mov_b32_e32 v81, v2
	v_mov_b32_e32 v90, v2
	v_mov_b32_e32 v91, v2
	v_mov_b32_e32 v92, v2
	v_mov_b32_e32 v93, v2
	v_mov_b32_e32 v94, v2
	v_mov_b32_e32 v95, v2
	v_mov_b32_e32 v96, v2
	v_mov_b32_e32 v97, v2
	v_mov_b32_e32 v106, v2
	v_mov_b32_e32 v107, v2
	v_mov_b32_e32 v108, v2
	v_mov_b32_e32 v109, v2
	v_mov_b32_e32 v110, v2
	v_mov_b32_e32 v111, v2
	v_mov_b32_e32 v112, v2
	v_mov_b32_e32 v113, v2
	v_mov_b32_e32 v146, v2
	v_mov_b32_e32 v147, v2
	v_mov_b32_e32 v148, v2
	v_mov_b32_e32 v149, v2
	v_mov_b32_e32 v150, v2
	v_mov_b32_e32 v151, v2
	v_mov_b32_e32 v152, v2
	v_mov_b32_e32 v153, v2
	s_andn2_b64 vcc, exec, s[6:7]
	s_cbranch_vccnz .LBB0_1172

; #define PG8_STAGE(bufoff, gbase, voff) do { _Pragma("unroll") for (int _i = 0; _i < 2; ++_i) \
;         __builtin_amdgcn_global_load_lds((const unsigned*)((const char*)(gbase) + (voff)[_i]), (PG8_LAS unsigned*)(lds + (bufoff) + ldsw + _i * 8192), 16, 0, 0); } while (0)
; #define PG8_LDA(dst, b, h) do { _Pragma("unroll") for (int m = 0; m < 4; ++m) _Pragma("unroll") for (int k = 0; k < 2; ++k) dst[m][k] = *(const PG8_LAS bf16x8*)(lds + PG8_SA(b, h) + aoff + m * 2048 + k * 1024); } while (0)
; #define PG8_LDB(dst, b, h) do { _Pragma("unroll") for (int n = 0; n < 2; ++n) _Pragma("unroll") for (int k = 0; k < 2; ++k) dst[n][k] = *(const PG8_LAS bf16x8*)(lds + PG8_SB(b, h) + boff + n * 2048 + k * 1024); } while (0)
; #define PG8_MMA(ai, bj, At, Bt) do { __builtin_amdgcn_s_setprio(1); _Pragma("unroll") for (int m = 0; m < 4; ++m) _Pragma("unroll") for (int n = 0; n < 2; ++n) _Pragma("unroll") for (int k = 0; k < 2; ++k) \
;         acc[ai][bj][m][n] = __builtin_amdgcn_mfma_f32_16x16x32_bf16(Bt[n][k], At[m][k], acc[ai][bj][m][n], 0, 0, 0); __builtin_amdgcn_s_setprio(0); } while (0)
; #define PG8_WAIT_V(n) asm volatile("s_waitcnt vmcnt(" #n ")" ::: "memory")
; #define PG8_WAIT_L(n) asm volatile("s_waitcnt lgkmcnt(" #n ")" ::: "memory")
; #define PG8_BAR __builtin_amdgcn_s_barrier()
; #define PG8_SCHED __builtin_amdgcn_sched_barrier(0)
; template <class Epi, class Sched, bool ALIGN_EPI = false, bool SP2 = false>
; __device__ __forceinline__ void gemm_phase(PG8_LAS unsigned char* lds, const Gemm g, const Sched& S, const Epi& E) {
;     ...
;             const bool last = (t == nt - 2);
;             const char* a1 = cA + (size_t)(t + 1) * kstep;
;             const char* a2 = last ? nA : cA + (size_t)(t + 2) * kstep; const char* b2 = last ? nB : cB + (size_t)(t + 2) * kstep;
;             const char* a3 = a2 + kstep; const char* b3 = b2 + kstep;
;             if (last && has_next) S.a_ready(nxt);
;             if constexpr (SP2) {
;             PG8_LDB(B0, 0, 0); PG8_LDB(B1, 0, 1); PG8_SCHED; PG8_LDA(At, 0, 0); PG8_STAGE(PG8_SA(1, 1), a1 + hstep, voffA);
;             PG8_WAIT_V(8); PG8_WAIT_L(0); PG8_BAR; PG8_MMA(0, 0, At, B0); PG8_MMA(0, 1, At, B1); PG8_BAR; PG8_SCHED;
;             PG8_LDA(At, 0, 1); PG8_STAGE(PG8_SB(0, 0), b2, voffB); PG8_STAGE(PG8_SB(0, 1), b2 + hstepB, voffB); PG8_STAGE(PG8_SA(0, 0), a2, voffA);
.LBB0_1313:
	ds_read_b128 v[146:149], v154
	ds_read_b128 v[158:161], v154 offset:1024
	ds_read_b128 v[162:165], v154 offset:2048
	ds_read_b128 v[166:169], v154 offset:3072
	ds_read_b128 v[170:173], v155
	ds_read_b128 v[174:177], v155 offset:1024
	ds_read_b128 v[178:181], v155 offset:2048
	ds_read_b128 v[182:185], v155 offset:3072
	s_add_u32 s40, s38, 0xfffc0080
	s_addc_u32 s41, s39, -1
	s_cmp_eq_u32 s61, 12
	s_cselect_b32 s43, s9, s41
	s_cselect_b32 s42, s27, s40
	s_cselect_b32 s41, s25, s60
	s_cselect_b32 s40, s37, s59
	v_lshl_add_u64 v[150:151], s[38:39], 0, v[138:139]
	s_add_i32 m0, s31, 0xc000
	ds_read_b128 v[186:189], v156
	ds_read_b128 v[190:193], v156 offset:1024
	ds_read_b128 v[194:197], v156 offset:2048
	ds_read_b128 v[198:201], v156 offset:3072
	ds_read_b128 v[202:205], v156 offset:4096
	ds_read_b128 v[206:209], v156 offset:5120
	ds_read_b128 v[210:213], v156 offset:6144
	ds_read_b128 v[214:217], v156 offset:7168
	global_load_lds_dwordx4 v[150:151], off
	v_lshl_add_u64 v[150:151], s[38:39], 0, v[140:141]
	s_add_i32 m0, s31, 0xe000
	s_nop 0
	global_load_lds_dwordx4 v[150:151], off
	s_waitcnt vmcnt(8)
	s_waitcnt lgkmcnt(0)
	s_barrier
	s_setprio 0
	v_mfma_f32_16x16x32_bf16 v[126:129], v[146:149], v[186:189], v[126:129]
	v_mfma_f32_16x16x32_bf16 v[122:125], v[162:165], v[186:189], v[122:125]
	v_mfma_f32_16x16x32_bf16 v[110:113], v[146:149], v[194:197], v[110:113]
	v_mfma_f32_16x16x32_bf16 v[106:109], v[162:165], v[194:197], v[106:109]
	v_mfma_f32_16x16x32_bf16 v[94:97], v[146:149], v[202:205], v[94:97]
	v_mfma_f32_16x16x32_bf16 v[90:93], v[162:165], v[202:205], v[90:93]
	v_mfma_f32_16x16x32_bf16 v[78:81], v[146:149], v[210:213], v[78:81]
	v_mfma_f32_16x16x32_bf16 v[74:77], v[162:165], v[210:213], v[74:77]
	v_mfma_f32_16x16x32_bf16 v[126:129], v[158:161], v[190:193], v[126:129]
	v_mfma_f32_16x16x32_bf16 v[122:125], v[166:169], v[190:193], v[122:125]
	v_mfma_f32_16x16x32_bf16 v[110:113], v[158:161], v[198:201], v[110:113]
	v_mfma_f32_16x16x32_bf16 v[106:109], v[166:169], v[198:201], v[106:109]
	v_mfma_f32_16x16x32_bf16 v[94:97], v[158:161], v[206:209], v[94:97]
	v_mfma_f32_16x16x32_bf16 v[90:93], v[166:169], v[206:209], v[90:93]
	v_mfma_f32_16x16x32_bf16 v[78:81], v[158:161], v[214:217], v[78:81]
	v_mfma_f32_16x16x32_bf16 v[74:77], v[166:169], v[214:217], v[74:77]
	v_mfma_f32_16x16x32_bf16 v[118:121], v[170:173], v[186:189], v[118:121]
	v_mfma_f32_16x16x32_bf16 v[114:117], v[178:181], v[186:189], v[114:117]
	v_mfma_f32_16x16x32_bf16 v[102:105], v[170:173], v[194:197], v[102:105]
	v_mfma_f32_16x16x32_bf16 v[98:101], v[178:181], v[194:197], v[98:101]
	v_mfma_f32_16x16x32_bf16 v[86:89], v[170:173], v[202:205], v[86:89]
	v_mfma_f32_16x16x32_bf16 v[82:85], v[178:181], v[202:205], v[82:85]
	v_mfma_f32_16x16x32_bf16 v[70:73], v[170:173], v[210:213], v[70:73]
	v_mfma_f32_16x16x32_bf16 v[66:69], v[178:181], v[210:213], v[66:69]
	v_mfma_f32_16x16x32_bf16 v[118:121], v[174:177], v[190:193], v[118:121]
	v_mfma_f32_16x16x32_bf16 v[114:117], v[182:185], v[190:193], v[114:117]
	v_mfma_f32_16x16x32_bf16 v[102:105], v[174:177], v[198:201], v[102:105]
	v_mfma_f32_16x16x32_bf16 v[98:101], v[182:185], v[198:201], v[98:101]
	v_mfma_f32_16x16x32_bf16 v[86:89], v[174:177], v[206:209], v[86:89]
	v_mfma_f32_16x16x32_bf16 v[82:85], v[182:185], v[206:209], v[82:85]
	v_mfma_f32_16x16x32_bf16 v[70:73], v[174:177], v[214:217], v[70:73]
	v_mfma_f32_16x16x32_bf16 v[66:69], v[182:185], v[214:217], v[66:69]
	s_barrier
	s_setprio 1
	s_add_i32 s62, s57, s30
	v_lshl_add_u64 v[150:151], s[40:41], 0, v[132:133]
	s_mov_b32 m0, s62
	ds_read_b128 v[186:189], v156 offset:16384
	ds_read_b128 v[190:193], v156 offset:17408
	ds_read_b128 v[194:197], v156 offset:18432
	ds_read_b128 v[198:201], v156 offset:19456
	ds_read_b128 v[202:205], v156 offset:20480
	ds_read_b128 v[206:209], v156 offset:21504
	ds_read_b128 v[210:213], v156 offset:22528
	ds_read_b128 v[214:217], v156 offset:23552
	global_load_lds_dwordx4 v[150:151], off
	s_add_i32 m0, s62, 0x2000
	s_add_u32 s62, s40, 0x10000
	v_lshl_add_u64 v[218:219], s[40:41], 0, v[136:137]
	s_addc_u32 s63, s41, 0
	s_add_i32 s64, s58, s30
	global_load_lds_dwordx4 v[218:219], off
	v_lshl_add_u64 v[220:221], s[62:63], 0, v[132:133]
	s_mov_b32 m0, s64
	v_lshl_add_u64 v[222:223], s[42:43], 0, v[134:135]
	global_load_lds_dwordx4 v[220:221], off
	v_lshl_add_u64 v[220:221], s[62:63], 0, v[136:137]
	s_add_i32 m0, s64, 0x2000
	s_nop 0
	global_load_lds_dwordx4 v[220:221], off
	v_lshl_add_u64 v[220:221], s[42:43], 0, v[130:131]
	s_mov_b32 m0, s31
	s_nop 0
	global_load_lds_dwordx4 v[220:221], off
	s_mov_b32 m0, s33
	s_nop 0
	global_load_lds_dwordx4 v[222:223], off
	s_waitcnt vmcnt(8)
	s_waitcnt lgkmcnt(0)
	s_barrier
; #define PG8_STAGE(bufoff, gbase, voff) do { _Pragma("unroll") for (int _i = 0; _i < 2; ++_i) \
;         __builtin_amdgcn_global_load_lds((const unsigned*)((const char*)(gbase) + (voff)[_i]), (PG8_LAS unsigned*)(lds + (bufoff) + ldsw + _i * 8192), 16, 0, 0); } while (0)
; #define PG8_LDA(dst, b, h) do { _Pragma("unroll") for (int m = 0; m < 4; ++m) _Pragma("unroll") for (int k = 0; k < 2; ++k) dst[m][k] = *(const PG8_LAS bf16x8*)(lds + PG8_SA(b, h) + aoff + m * 2048 + k * 1024); } while (0)
; #define PG8_LDB(dst, b, h) do { _Pragma("unroll") for (int n = 0; n < 2; ++n) _Pragma("unroll") for (int k = 0; k < 2; ++k) dst[n][k] = *(const PG8_LAS bf16x8*)(lds + PG8_SB(b, h) + boff + n * 2048 + k * 1024); } while (0)
; #define PG8_MMA(ai, bj, At, Bt) do { __builtin_amdgcn_s_setprio(1); _Pragma("unroll") for (int m = 0; m < 4; ++m) _Pragma("unroll") for (int n = 0; n < 2; ++n) _Pragma("unroll") for (int k = 0; k < 2; ++k) \
;         acc[ai][bj][m][n] = __builtin_amdgcn_mfma_f32_16x16x32_bf16(Bt[n][k], At[m][k], acc[ai][bj][m][n], 0, 0, 0); __builtin_amdgcn_s_setprio(0); } while (0)
; #define PG8_WAIT_V(n) asm volatile("s_waitcnt vmcnt(" #n ")" ::: "memory")
; #define PG8_WAIT_L(n) asm volatile("s_waitcnt lgkmcnt(" #n ")" ::: "memory")
; #define PG8_BAR __builtin_amdgcn_s_barrier()
; #define PG8_SCHED __builtin_amdgcn_sched_barrier(0)
; template <class Epi, class Sched, bool ALIGN_EPI = false, bool SP2 = false>
; __device__ __forceinline__ void gemm_phase(PG8_LAS unsigned char* lds, const Gemm g, const Sched& S, const Epi& E) {
;     ...
;             PG8_WAIT_V(8); PG8_WAIT_L(0); PG8_BAR; PG8_MMA(1, 0, At, B0); PG8_MMA(1, 1, At, B1); PG8_BAR; PG8_SCHED;
;             PG8_LDB(B0, 1, 0); PG8_LDB(B1, 1, 1); PG8_SCHED; PG8_LDA(At, 1, 0); PG8_STAGE(PG8_SA(0, 1), a2 + hstep, voffA);
;             PG8_WAIT_V(8); PG8_WAIT_L(0); PG8_BAR; PG8_MMA(0, 0, At, B0); PG8_MMA(0, 1, At, B1); PG8_BAR; PG8_SCHED;
	s_setprio 0
	v_mfma_f32_16x16x32_bf16 v[62:65], v[146:149], v[186:189], v[62:65]
	v_mfma_f32_16x16x32_bf16 v[58:61], v[162:165], v[186:189], v[58:61]
	v_mfma_f32_16x16x32_bf16 v[46:49], v[146:149], v[194:197], v[46:49]
	v_mfma_f32_16x16x32_bf16 v[42:45], v[162:165], v[194:197], v[42:45]
	v_mfma_f32_16x16x32_bf16 v[30:33], v[146:149], v[202:205], v[30:33]
	v_mfma_f32_16x16x32_bf16 v[26:29], v[162:165], v[202:205], v[26:29]
	v_mfma_f32_16x16x32_bf16 v[14:17], v[146:149], v[210:213], v[14:17]
	v_mfma_f32_16x16x32_bf16 v[10:13], v[162:165], v[210:213], v[10:13]
	v_mfma_f32_16x16x32_bf16 v[62:65], v[158:161], v[190:193], v[62:65]
	v_mfma_f32_16x16x32_bf16 v[58:61], v[166:169], v[190:193], v[58:61]
	v_mfma_f32_16x16x32_bf16 v[46:49], v[158:161], v[198:201], v[46:49]
	v_mfma_f32_16x16x32_bf16 v[42:45], v[166:169], v[198:201], v[42:45]
	v_mfma_f32_16x16x32_bf16 v[30:33], v[158:161], v[206:209], v[30:33]
	v_mfma_f32_16x16x32_bf16 v[26:29], v[166:169], v[206:209], v[26:29]
	v_mfma_f32_16x16x32_bf16 v[14:17], v[158:161], v[214:217], v[14:17]
	v_mfma_f32_16x16x32_bf16 v[10:13], v[166:169], v[214:217], v[10:13]
	v_mfma_f32_16x16x32_bf16 v[54:57], v[170:173], v[186:189], v[54:57]
	v_mfma_f32_16x16x32_bf16 v[50:53], v[178:181], v[186:189], v[50:53]
	v_mfma_f32_16x16x32_bf16 v[38:41], v[170:173], v[194:197], v[38:41]
	v_mfma_f32_16x16x32_bf16 v[34:37], v[178:181], v[194:197], v[34:37]
	v_mfma_f32_16x16x32_bf16 v[22:25], v[170:173], v[202:205], v[22:25]
	v_mfma_f32_16x16x32_bf16 v[18:21], v[178:181], v[202:205], v[18:21]
	v_mfma_f32_16x16x32_bf16 v[6:9], v[170:173], v[210:213], v[6:9]
	v_mfma_f32_16x16x32_bf16 v[2:5], v[178:181], v[210:213], v[2:5]
	v_mfma_f32_16x16x32_bf16 v[54:57], v[174:177], v[190:193], v[54:57]
	v_mfma_f32_16x16x32_bf16 v[50:53], v[182:185], v[190:193], v[50:53]
	v_mfma_f32_16x16x32_bf16 v[38:41], v[174:177], v[198:201], v[38:41]
	v_mfma_f32_16x16x32_bf16 v[34:37], v[182:185], v[198:201], v[34:37]
	v_mfma_f32_16x16x32_bf16 v[22:25], v[174:177], v[206:209], v[22:25]
	v_mfma_f32_16x16x32_bf16 v[18:21], v[182:185], v[206:209], v[18:21]
	v_mfma_f32_16x16x32_bf16 v[6:9], v[174:177], v[214:217], v[6:9]
	v_mfma_f32_16x16x32_bf16 v[2:5], v[182:185], v[214:217], v[2:5]
	s_barrier
	s_setprio 1
	s_add_i32 s62, 0, 0x18000
	v_add_u32_e32 v157, s62, v152
	s_add_i32 s63, 0, 0x1c000
	ds_read_b128 v[146:149], v157
	ds_read_b128 v[158:161], v157 offset:1024
	ds_read_b128 v[162:165], v157 offset:2048
	ds_read_b128 v[166:169], v157 offset:3072
	v_add_u32_e32 v157, s63, v152
	ds_read_b128 v[170:173], v157
	ds_read_b128 v[174:177], v157 offset:1024
	ds_read_b128 v[178:181], v157 offset:2048
	ds_read_b128 v[182:185], v157 offset:3072
	s_add_u32 s42, s42, 0x40000
	s_addc_u32 s43, s43, 0
	s_mov_b32 m0, s44
	v_lshl_add_u64 v[224:225], s[42:43], 0, v[130:131]
	ds_read_b128 v[186:189], v156 offset:32768
	ds_read_b128 v[190:193], v156 offset:33792
	ds_read_b128 v[194:197], v156 offset:34816
	ds_read_b128 v[198:201], v156 offset:35840
	ds_read_b128 v[202:205], v156 offset:36864
	ds_read_b128 v[206:209], v156 offset:37888
	ds_read_b128 v[210:213], v156 offset:38912
	ds_read_b128 v[214:217], v156 offset:39936
	global_load_lds_dwordx4 v[224:225], off
	v_lshl_add_u64 v[224:225], s[42:43], 0, v[134:135]
	s_mov_b32 m0, s45
	s_nop 0
	global_load_lds_dwordx4 v[224:225], off
	s_waitcnt vmcnt(8)
	s_waitcnt lgkmcnt(0)
	s_barrier
	s_setprio 0
	v_mfma_f32_16x16x32_bf16 v[126:129], v[146:149], v[186:189], v[126:129]
	v_mfma_f32_16x16x32_bf16 v[122:125], v[162:165], v[186:189], v[122:125]
	v_mfma_f32_16x16x32_bf16 v[110:113], v[146:149], v[194:197], v[110:113]
	v_mfma_f32_16x16x32_bf16 v[106:109], v[162:165], v[194:197], v[106:109]
	v_mfma_f32_16x16x32_bf16 v[94:97], v[146:149], v[202:205], v[94:97]
	v_mfma_f32_16x16x32_bf16 v[90:93], v[162:165], v[202:205], v[90:93]
	v_mfma_f32_16x16x32_bf16 v[78:81], v[146:149], v[210:213], v[78:81]
	v_mfma_f32_16x16x32_bf16 v[74:77], v[162:165], v[210:213], v[74:77]
	v_mfma_f32_16x16x32_bf16 v[126:129], v[158:161], v[190:193], v[126:129]
	v_mfma_f32_16x16x32_bf16 v[122:125], v[166:169], v[190:193], v[122:125]
	v_mfma_f32_16x16x32_bf16 v[110:113], v[158:161], v[198:201], v[110:113]
	v_mfma_f32_16x16x32_bf16 v[106:109], v[166:169], v[198:201], v[106:109]
	v_mfma_f32_16x16x32_bf16 v[94:97], v[158:161], v[206:209], v[94:97]
	v_mfma_f32_16x16x32_bf16 v[90:93], v[166:169], v[206:209], v[90:93]
	v_mfma_f32_16x16x32_bf16 v[78:81], v[158:161], v[214:217], v[78:81]
	v_mfma_f32_16x16x32_bf16 v[74:77], v[166:169], v[214:217], v[74:77]
	v_mfma_f32_16x16x32_bf16 v[118:121], v[170:173], v[186:189], v[118:121]
	v_mfma_f32_16x16x32_bf16 v[114:117], v[178:181], v[186:189], v[114:117]
	v_mfma_f32_16x16x32_bf16 v[102:105], v[170:173], v[194:197], v[102:105]
	v_mfma_f32_16x16x32_bf16 v[98:101], v[178:181], v[194:197], v[98:101]
	v_mfma_f32_16x16x32_bf16 v[86:89], v[170:173], v[202:205], v[86:89]
	v_mfma_f32_16x16x32_bf16 v[82:85], v[178:181], v[202:205], v[82:85]
	v_mfma_f32_16x16x32_bf16 v[70:73], v[170:173], v[210:213], v[70:73]
	v_mfma_f32_16x16x32_bf16 v[66:69], v[178:181], v[210:213], v[66:69]
	v_mfma_f32_16x16x32_bf16 v[118:121], v[174:177], v[190:193], v[118:121]
	v_mfma_f32_16x16x32_bf16 v[114:117], v[182:185], v[190:193], v[114:117]
	v_mfma_f32_16x16x32_bf16 v[102:105], v[174:177], v[198:201], v[102:105]
	v_mfma_f32_16x16x32_bf16 v[98:101], v[182:185], v[198:201], v[98:101]
	v_mfma_f32_16x16x32_bf16 v[86:89], v[174:177], v[206:209], v[86:89]
	v_mfma_f32_16x16x32_bf16 v[82:85], v[182:185], v[206:209], v[82:85]
	v_mfma_f32_16x16x32_bf16 v[70:73], v[174:177], v[214:217], v[70:73]
	v_mfma_f32_16x16x32_bf16 v[66:69], v[182:185], v[214:217], v[66:69]
	s_barrier
; #define PG8_STAGE(bufoff, gbase, voff) do { _Pragma("unroll") for (int _i = 0; _i < 2; ++_i) \
;         __builtin_amdgcn_global_load_lds((const unsigned*)((const char*)(gbase) + (voff)[_i]), (PG8_LAS unsigned*)(lds + (bufoff) + ldsw + _i * 8192), 16, 0, 0); } while (0)
; #define PG8_LDA(dst, b, h) do { _Pragma("unroll") for (int m = 0; m < 4; ++m) _Pragma("unroll") for (int k = 0; k < 2; ++k) dst[m][k] = *(const PG8_LAS bf16x8*)(lds + PG8_SA(b, h) + aoff + m * 2048 + k * 1024); } while (0)
; #define PG8_MMA(ai, bj, At, Bt) do { __builtin_amdgcn_s_setprio(1); _Pragma("unroll") for (int m = 0; m < 4; ++m) _Pragma("unroll") for (int n = 0; n < 2; ++n) _Pragma("unroll") for (int k = 0; k < 2; ++k) \
;         acc[ai][bj][m][n] = __builtin_amdgcn_mfma_f32_16x16x32_bf16(Bt[n][k], At[m][k], acc[ai][bj][m][n], 0, 0, 0); __builtin_amdgcn_s_setprio(0); } while (0)
; #define PG8_WAIT_V(n) asm volatile("s_waitcnt vmcnt(" #n ")" ::: "memory")
; #define PG8_WAIT_L(n) asm volatile("s_waitcnt lgkmcnt(" #n ")" ::: "memory")
; #define PG8_BAR __builtin_amdgcn_s_barrier()
; #define PG8_SCHED __builtin_amdgcn_sched_barrier(0)
; template <class Epi, class Sched, bool ALIGN_EPI = false, bool SP2 = false>
; __device__ __forceinline__ void gemm_phase(PG8_LAS unsigned char* lds, const Gemm g, const Sched& S, const Epi& E) {
;     ...
;             PG8_LDA(At, 1, 1); PG8_STAGE(PG8_SB(1, 0), b3, voffB); PG8_STAGE(PG8_SB(1, 1), b3 + hstepB, voffB); PG8_STAGE(PG8_SA(1, 0), a3, voffA);
;             PG8_WAIT_V(8); PG8_WAIT_L(0); PG8_BAR; PG8_MMA(1, 0, At, B0); PG8_MMA(1, 1, At, B1); PG8_BAR; PG8_SCHED;
;     ...
;         if constexpr (ALIGN_EPI) { if (wr == 0) PG8_BAR; }
	s_setprio 1
	s_add_i32 s42, s62, s30
	v_lshl_add_u64 v[150:151], v[150:151], 0, s[10:11]
	s_mov_b32 m0, s42
	ds_read_b128 v[186:189], v156 offset:49152
	ds_read_b128 v[190:193], v156 offset:50176
	ds_read_b128 v[194:197], v156 offset:51200
	ds_read_b128 v[198:201], v156 offset:52224
	ds_read_b128 v[202:205], v156 offset:53248
	ds_read_b128 v[206:209], v156 offset:54272
	ds_read_b128 v[210:213], v156 offset:55296
	ds_read_b128 v[214:217], v156 offset:56320
	global_load_lds_dwordx4 v[150:151], off
	s_add_i32 m0, s42, 0x2000
	s_add_u32 s40, s40, 0x10080
	v_lshl_add_u64 v[150:151], v[218:219], 0, s[10:11]
	s_addc_u32 s41, s41, 0
	s_add_i32 s42, s63, s30
	global_load_lds_dwordx4 v[150:151], off
	v_lshl_add_u64 v[150:151], s[40:41], 0, v[132:133]
	s_mov_b32 m0, s42
	s_nop 0
	global_load_lds_dwordx4 v[150:151], off
	v_lshl_add_u64 v[150:151], s[40:41], 0, v[136:137]
	s_add_i32 m0, s42, 0x2000
	s_nop 0
	global_load_lds_dwordx4 v[150:151], off
	v_lshl_add_u64 v[150:151], v[220:221], 0, s[10:11]
	s_mov_b32 m0, s47
	s_nop 0
	global_load_lds_dwordx4 v[150:151], off
	v_lshl_add_u64 v[150:151], v[222:223], 0, s[10:11]
	s_mov_b32 m0, s54
	s_nop 0
	global_load_lds_dwordx4 v[150:151], off
	s_waitcnt vmcnt(8)
	s_waitcnt lgkmcnt(0)
	s_barrier
	s_setprio 0
	v_mfma_f32_16x16x32_bf16 v[62:65], v[146:149], v[186:189], v[62:65]
	v_mfma_f32_16x16x32_bf16 v[58:61], v[162:165], v[186:189], v[58:61]
	v_mfma_f32_16x16x32_bf16 v[46:49], v[146:149], v[194:197], v[46:49]
	v_mfma_f32_16x16x32_bf16 v[42:45], v[162:165], v[194:197], v[42:45]
	v_mfma_f32_16x16x32_bf16 v[30:33], v[146:149], v[202:205], v[30:33]
	v_mfma_f32_16x16x32_bf16 v[26:29], v[162:165], v[202:205], v[26:29]
	v_mfma_f32_16x16x32_bf16 v[14:17], v[146:149], v[210:213], v[14:17]
	v_mfma_f32_16x16x32_bf16 v[10:13], v[162:165], v[210:213], v[10:13]
	v_mfma_f32_16x16x32_bf16 v[62:65], v[158:161], v[190:193], v[62:65]
	v_mfma_f32_16x16x32_bf16 v[58:61], v[166:169], v[190:193], v[58:61]
	v_mfma_f32_16x16x32_bf16 v[46:49], v[158:161], v[198:201], v[46:49]
	v_mfma_f32_16x16x32_bf16 v[42:45], v[166:169], v[198:201], v[42:45]
	v_mfma_f32_16x16x32_bf16 v[30:33], v[158:161], v[206:209], v[30:33]
	v_mfma_f32_16x16x32_bf16 v[26:29], v[166:169], v[206:209], v[26:29]
	v_mfma_f32_16x16x32_bf16 v[14:17], v[158:161], v[214:217], v[14:17]
	v_mfma_f32_16x16x32_bf16 v[10:13], v[166:169], v[214:217], v[10:13]
	v_mfma_f32_16x16x32_bf16 v[54:57], v[170:173], v[186:189], v[54:57]
	v_mfma_f32_16x16x32_bf16 v[50:53], v[178:181], v[186:189], v[50:53]
	v_mfma_f32_16x16x32_bf16 v[38:41], v[170:173], v[194:197], v[38:41]
	v_mfma_f32_16x16x32_bf16 v[34:37], v[178:181], v[194:197], v[34:37]
	v_mfma_f32_16x16x32_bf16 v[22:25], v[170:173], v[202:205], v[22:25]
	v_mfma_f32_16x16x32_bf16 v[18:21], v[178:181], v[202:205], v[18:21]
	v_mfma_f32_16x16x32_bf16 v[6:9], v[170:173], v[210:213], v[6:9]
	v_mfma_f32_16x16x32_bf16 v[2:5], v[178:181], v[210:213], v[2:5]
	v_mfma_f32_16x16x32_bf16 v[54:57], v[174:177], v[190:193], v[54:57]
	v_mfma_f32_16x16x32_bf16 v[50:53], v[182:185], v[190:193], v[50:53]
	v_mfma_f32_16x16x32_bf16 v[38:41], v[174:177], v[198:201], v[38:41]
	v_mfma_f32_16x16x32_bf16 v[34:37], v[182:185], v[198:201], v[34:37]
	v_mfma_f32_16x16x32_bf16 v[22:25], v[174:177], v[206:209], v[22:25]
	v_mfma_f32_16x16x32_bf16 v[18:21], v[182:185], v[206:209], v[18:21]
	v_mfma_f32_16x16x32_bf16 v[6:9], v[174:177], v[214:217], v[6:9]
	v_mfma_f32_16x16x32_bf16 v[2:5], v[182:185], v[214:217], v[2:5]
	s_barrier
	s_setprio 1
	s_add_i32 s61, s61, 2
	s_add_u32 s38, s38, 0x100
	s_addc_u32 s39, s39, 0
	s_add_u32 s59, s59, 0x100
	s_addc_u32 s60, s60, 0
	s_cmp_gt_u32 s61, 13
	s_cbranch_scc0 .LBB0_1313
	s_and_b64 vcc, exec, s[14:15]
	s_cbranch_vccz .LBB0_1316
	s_barrier

; #define PG8_STAGE(bufoff, gbase, voff) do { _Pragma("unroll") for (int _i = 0; _i < 2; ++_i) \
;         __builtin_amdgcn_global_load_lds((const unsigned*)((const char*)(gbase) + (voff)[_i]), (PG8_LAS unsigned*)(lds + (bufoff) + ldsw + _i * 8192), 16, 0, 0); } while (0)
; #define PG8_LDA(dst, b, h) do { _Pragma("unroll") for (int m = 0; m < 4; ++m) _Pragma("unroll") for (int k = 0; k < 2; ++k) dst[m][k] = *(const PG8_LAS bf16x8*)(lds + PG8_SA(b, h) + aoff + m * 2048 + k * 1024); } while (0)
; #define PG8_LDB(dst, b, h) do { _Pragma("unroll") for (int n = 0; n < 2; ++n) _Pragma("unroll") for (int k = 0; k < 2; ++k) dst[n][k] = *(const PG8_LAS bf16x8*)(lds + PG8_SB(b, h) + boff + n * 2048 + k * 1024); } while (0)
; #define PG8_MMA(ai, bj, At, Bt) do { __builtin_amdgcn_s_setprio(1); _Pragma("unroll") for (int m = 0; m < 4; ++m) _Pragma("unroll") for (int n = 0; n < 2; ++n) _Pragma("unroll") for (int k = 0; k < 2; ++k) \
;         acc[ai][bj][m][n] = __builtin_amdgcn_mfma_f32_16x16x32_bf16(Bt[n][k], At[m][k], acc[ai][bj][m][n], 0, 0, 0); __builtin_amdgcn_s_setprio(0); } while (0)
; #define PG8_WAIT_V(n) asm volatile("s_waitcnt vmcnt(" #n ")" ::: "memory")
; #define PG8_WAIT_L(n) asm volatile("s_waitcnt lgkmcnt(" #n ")" ::: "memory")
; #define PG8_BAR __builtin_amdgcn_s_barrier()
; #define PG8_SCHED __builtin_amdgcn_sched_barrier(0)
; template <class Epi, class Sched, bool ALIGN_EPI = false, bool SP2 = false>
; __device__ __forceinline__ void gemm_phase(PG8_LAS unsigned char* lds, const Gemm g, const Sched& S, const Epi& E) {
;     ...
;             const bool last = (t == nt - 2);
;             const char* a1 = cA + (size_t)(t + 1) * kstep;
;             const char* a2 = last ? nA : cA + (size_t)(t + 2) * kstep; const char* b2 = last ? nB : cB + (size_t)(t + 2) * kstep;
;             const char* a3 = a2 + kstep; const char* b3 = b2 + kstep;
;             if (last && has_next) S.a_ready(nxt);
;             if constexpr (SP2) {
;             PG8_LDB(B0, 0, 0); PG8_LDB(B1, 0, 1); PG8_SCHED; PG8_LDA(At, 0, 0); PG8_STAGE(PG8_SA(1, 1), a1 + hstep, voffA);
;             PG8_WAIT_V(8); PG8_WAIT_L(0); PG8_BAR; PG8_MMA(0, 0, At, B0); PG8_MMA(0, 1, At, B1); PG8_BAR; PG8_SCHED;
;             PG8_LDA(At, 0, 1); PG8_STAGE(PG8_SB(0, 0), b2, voffB); PG8_STAGE(PG8_SB(0, 1), b2 + hstepB, voffB); PG8_STAGE(PG8_SA(0, 0), a2, voffA);
.LBB0_1429:
	v_add_u32_e32 v164, s43, v150
	v_add_u32_e32 v180, s44, v150
	s_add_u32 s26, s8, s24
	ds_read_b128 v[152:155], v164
	ds_read_b128 v[156:159], v164 offset:1024
	ds_read_b128 v[160:163], v164 offset:2048
	ds_read_b128 v[164:167], v164 offset:3072
	ds_read_b128 v[168:171], v180
	ds_read_b128 v[172:175], v180 offset:1024
	ds_read_b128 v[176:179], v180 offset:2048
	ds_read_b128 v[180:183], v180 offset:3072
	s_addc_u32 s27, s9, s25
	s_add_u32 s26, s26, 0x100
	s_addc_u32 s27, s27, 0
	s_add_u32 s55, s21, s24
	s_addc_u32 s56, s45, s25
	s_cmpk_eq_i32 s24, 0x1f00
	s_cselect_b32 s29, s17, s27
	s_cselect_b32 s28, s46, s26
	s_cselect_b32 s27, s15, s56
	s_cselect_b32 s26, s47, s55
	v_lshl_add_u64 v[212:213], v[146:147], 0, s[24:25]
	s_add_i32 m0, s35, 0xc000
	ds_read_b128 v[184:187], v151
	ds_read_b128 v[188:191], v151 offset:1024
	ds_read_b128 v[192:195], v151 offset:2048
	ds_read_b128 v[196:199], v151 offset:3072
	ds_read_b128 v[200:203], v151 offset:4096
	ds_read_b128 v[204:207], v151 offset:5120
	ds_read_b128 v[208:211], v151 offset:6144
	ds_read_b128 v[218:221], v151 offset:7168
	global_load_lds_dwordx4 v[212:213], off
	v_lshl_add_u64 v[212:213], v[148:149], 0, s[24:25]
	s_add_i32 m0, s35, 0xe000
	s_nop 0
	global_load_lds_dwordx4 v[212:213], off
	s_waitcnt vmcnt(8)
	s_waitcnt lgkmcnt(0)
	s_barrier
	s_setprio 0
	v_mfma_f32_16x16x32_bf16 v[126:129], v[152:155], v[184:187], v[126:129]
	v_mfma_f32_16x16x32_bf16 v[122:125], v[160:163], v[184:187], v[122:125]
	v_mfma_f32_16x16x32_bf16 v[110:113], v[152:155], v[192:195], v[110:113]
	v_mfma_f32_16x16x32_bf16 v[106:109], v[160:163], v[192:195], v[106:109]
	v_mfma_f32_16x16x32_bf16 v[94:97], v[152:155], v[200:203], v[94:97]
	v_mfma_f32_16x16x32_bf16 v[90:93], v[160:163], v[200:203], v[90:93]
	v_mfma_f32_16x16x32_bf16 v[78:81], v[152:155], v[208:211], v[78:81]
	v_mfma_f32_16x16x32_bf16 v[74:77], v[160:163], v[208:211], v[74:77]
	v_mfma_f32_16x16x32_bf16 v[126:129], v[156:159], v[188:191], v[126:129]
	v_mfma_f32_16x16x32_bf16 v[122:125], v[164:167], v[188:191], v[122:125]
	v_mfma_f32_16x16x32_bf16 v[110:113], v[156:159], v[196:199], v[110:113]
	v_mfma_f32_16x16x32_bf16 v[106:109], v[164:167], v[196:199], v[106:109]
	v_mfma_f32_16x16x32_bf16 v[94:97], v[156:159], v[204:207], v[94:97]
	v_mfma_f32_16x16x32_bf16 v[90:93], v[164:167], v[204:207], v[90:93]
	v_mfma_f32_16x16x32_bf16 v[78:81], v[156:159], v[218:221], v[78:81]
	v_mfma_f32_16x16x32_bf16 v[74:77], v[164:167], v[218:221], v[74:77]
	v_mfma_f32_16x16x32_bf16 v[118:121], v[168:171], v[184:187], v[118:121]
	v_mfma_f32_16x16x32_bf16 v[114:117], v[176:179], v[184:187], v[114:117]
	v_mfma_f32_16x16x32_bf16 v[102:105], v[168:171], v[192:195], v[102:105]
	v_mfma_f32_16x16x32_bf16 v[98:101], v[176:179], v[192:195], v[98:101]
	v_mfma_f32_16x16x32_bf16 v[86:89], v[168:171], v[200:203], v[86:89]
	v_mfma_f32_16x16x32_bf16 v[82:85], v[176:179], v[200:203], v[82:85]
	v_mfma_f32_16x16x32_bf16 v[70:73], v[168:171], v[208:211], v[70:73]
	v_mfma_f32_16x16x32_bf16 v[66:69], v[176:179], v[208:211], v[66:69]
	v_mfma_f32_16x16x32_bf16 v[118:121], v[172:175], v[188:191], v[118:121]
	v_mfma_f32_16x16x32_bf16 v[114:117], v[180:183], v[188:191], v[114:117]
	v_mfma_f32_16x16x32_bf16 v[102:105], v[172:175], v[196:199], v[102:105]
	v_mfma_f32_16x16x32_bf16 v[98:101], v[180:183], v[196:199], v[98:101]
	v_mfma_f32_16x16x32_bf16 v[86:89], v[172:175], v[204:207], v[86:89]
	v_mfma_f32_16x16x32_bf16 v[82:85], v[180:183], v[204:207], v[82:85]
	v_mfma_f32_16x16x32_bf16 v[70:73], v[172:175], v[218:221], v[70:73]
	v_mfma_f32_16x16x32_bf16 v[66:69], v[180:183], v[218:221], v[66:69]
	s_barrier
	s_setprio 1
	s_add_i32 s55, s43, s34
	v_lshl_add_u64 v[212:213], s[26:27], 0, v[132:133]
	s_mov_b32 m0, s55
	ds_read_b128 v[184:187], v151 offset:16384
	ds_read_b128 v[188:191], v151 offset:17408
	ds_read_b128 v[192:195], v151 offset:18432
	ds_read_b128 v[196:199], v151 offset:19456
	ds_read_b128 v[200:203], v151 offset:20480
	ds_read_b128 v[204:207], v151 offset:21504
	ds_read_b128 v[208:211], v151 offset:22528
	ds_read_b128 v[218:221], v151 offset:23552
	global_load_lds_dwordx4 v[212:213], off
	s_add_i32 m0, s55, 0x2000
	s_add_u32 s56, s26, 0x40000
	v_lshl_add_u64 v[222:223], s[26:27], 0, v[136:137]
	s_addc_u32 s57, s27, 0
	s_add_i32 s55, s44, s34
	global_load_lds_dwordx4 v[222:223], off
	v_lshl_add_u64 v[224:225], s[56:57], 0, v[132:133]
	s_mov_b32 m0, s55
	v_lshl_add_u64 v[226:227], s[28:29], 0, v[134:135]
	global_load_lds_dwordx4 v[224:225], off
	v_lshl_add_u64 v[224:225], s[56:57], 0, v[136:137]
	s_add_i32 m0, s55, 0x2000
	s_nop 0
	global_load_lds_dwordx4 v[224:225], off
	v_lshl_add_u64 v[224:225], s[28:29], 0, v[130:131]
	s_mov_b32 m0, s35
	s_nop 0
	global_load_lds_dwordx4 v[224:225], off
	s_mov_b32 m0, s36
	s_nop 0
	global_load_lds_dwordx4 v[226:227], off
	s_waitcnt vmcnt(8)
	s_waitcnt lgkmcnt(0)
	s_barrier
; #define PG8_STAGE(bufoff, gbase, voff) do { _Pragma("unroll") for (int _i = 0; _i < 2; ++_i) \
;         __builtin_amdgcn_global_load_lds((const unsigned*)((const char*)(gbase) + (voff)[_i]), (PG8_LAS unsigned*)(lds + (bufoff) + ldsw + _i * 8192), 16, 0, 0); } while (0)
; #define PG8_LDA(dst, b, h) do { _Pragma("unroll") for (int m = 0; m < 4; ++m) _Pragma("unroll") for (int k = 0; k < 2; ++k) dst[m][k] = *(const PG8_LAS bf16x8*)(lds + PG8_SA(b, h) + aoff + m * 2048 + k * 1024); } while (0)
; #define PG8_LDB(dst, b, h) do { _Pragma("unroll") for (int n = 0; n < 2; ++n) _Pragma("unroll") for (int k = 0; k < 2; ++k) dst[n][k] = *(const PG8_LAS bf16x8*)(lds + PG8_SB(b, h) + boff + n * 2048 + k * 1024); } while (0)
; #define PG8_MMA(ai, bj, At, Bt) do { __builtin_amdgcn_s_setprio(1); _Pragma("unroll") for (int m = 0; m < 4; ++m) _Pragma("unroll") for (int n = 0; n < 2; ++n) _Pragma("unroll") for (int k = 0; k < 2; ++k) \
;         acc[ai][bj][m][n] = __builtin_amdgcn_mfma_f32_16x16x32_bf16(Bt[n][k], At[m][k], acc[ai][bj][m][n], 0, 0, 0); __builtin_amdgcn_s_setprio(0); } while (0)
; #define PG8_WAIT_V(n) asm volatile("s_waitcnt vmcnt(" #n ")" ::: "memory")
; #define PG8_WAIT_L(n) asm volatile("s_waitcnt lgkmcnt(" #n ")" ::: "memory")
; #define PG8_BAR __builtin_amdgcn_s_barrier()
; #define PG8_SCHED __builtin_amdgcn_sched_barrier(0)
; template <class Epi, class Sched, bool ALIGN_EPI = false, bool SP2 = false>
; __device__ __forceinline__ void gemm_phase(PG8_LAS unsigned char* lds, const Gemm g, const Sched& S, const Epi& E) {
;     ...
;             PG8_WAIT_V(8); PG8_WAIT_L(0); PG8_BAR; PG8_MMA(1, 0, At, B0); PG8_MMA(1, 1, At, B1); PG8_BAR; PG8_SCHED;
;             PG8_LDB(B0, 1, 0); PG8_LDB(B1, 1, 1); PG8_SCHED; PG8_LDA(At, 1, 0); PG8_STAGE(PG8_SA(0, 1), a2 + hstep, voffA);
;             PG8_WAIT_V(8); PG8_WAIT_L(0); PG8_BAR; PG8_MMA(0, 0, At, B0); PG8_MMA(0, 1, At, B1); PG8_BAR; PG8_SCHED;
	s_setprio 0
	v_mfma_f32_16x16x32_bf16 v[62:65], v[152:155], v[184:187], v[62:65]
	v_mfma_f32_16x16x32_bf16 v[58:61], v[160:163], v[184:187], v[58:61]
	v_mfma_f32_16x16x32_bf16 v[46:49], v[152:155], v[192:195], v[46:49]
	v_mfma_f32_16x16x32_bf16 v[42:45], v[160:163], v[192:195], v[42:45]
	v_mfma_f32_16x16x32_bf16 v[30:33], v[152:155], v[200:203], v[30:33]
	v_mfma_f32_16x16x32_bf16 v[26:29], v[160:163], v[200:203], v[26:29]
	v_mfma_f32_16x16x32_bf16 v[14:17], v[152:155], v[208:211], v[14:17]
	v_mfma_f32_16x16x32_bf16 v[10:13], v[160:163], v[208:211], v[10:13]
	v_mfma_f32_16x16x32_bf16 v[62:65], v[156:159], v[188:191], v[62:65]
	v_mfma_f32_16x16x32_bf16 v[58:61], v[164:167], v[188:191], v[58:61]
	v_mfma_f32_16x16x32_bf16 v[46:49], v[156:159], v[196:199], v[46:49]
	v_mfma_f32_16x16x32_bf16 v[42:45], v[164:167], v[196:199], v[42:45]
	v_mfma_f32_16x16x32_bf16 v[30:33], v[156:159], v[204:207], v[30:33]
	v_mfma_f32_16x16x32_bf16 v[26:29], v[164:167], v[204:207], v[26:29]
	v_mfma_f32_16x16x32_bf16 v[14:17], v[156:159], v[218:221], v[14:17]
	v_mfma_f32_16x16x32_bf16 v[10:13], v[164:167], v[218:221], v[10:13]
	v_mfma_f32_16x16x32_bf16 v[54:57], v[168:171], v[184:187], v[54:57]
	v_mfma_f32_16x16x32_bf16 v[50:53], v[176:179], v[184:187], v[50:53]
	v_mfma_f32_16x16x32_bf16 v[38:41], v[168:171], v[192:195], v[38:41]
	v_mfma_f32_16x16x32_bf16 v[34:37], v[176:179], v[192:195], v[34:37]
	v_mfma_f32_16x16x32_bf16 v[22:25], v[168:171], v[200:203], v[22:25]
	v_mfma_f32_16x16x32_bf16 v[18:21], v[176:179], v[200:203], v[18:21]
	v_mfma_f32_16x16x32_bf16 v[6:9], v[168:171], v[208:211], v[6:9]
	v_mfma_f32_16x16x32_bf16 v[2:5], v[176:179], v[208:211], v[2:5]
	v_mfma_f32_16x16x32_bf16 v[54:57], v[172:175], v[188:191], v[54:57]
	v_mfma_f32_16x16x32_bf16 v[50:53], v[180:183], v[188:191], v[50:53]
	v_mfma_f32_16x16x32_bf16 v[38:41], v[172:175], v[196:199], v[38:41]
	v_mfma_f32_16x16x32_bf16 v[34:37], v[180:183], v[196:199], v[34:37]
	v_mfma_f32_16x16x32_bf16 v[22:25], v[172:175], v[204:207], v[22:25]
	v_mfma_f32_16x16x32_bf16 v[18:21], v[180:183], v[204:207], v[18:21]
	v_mfma_f32_16x16x32_bf16 v[6:9], v[172:175], v[218:221], v[6:9]
	v_mfma_f32_16x16x32_bf16 v[2:5], v[180:183], v[218:221], v[2:5]
	s_barrier
	s_setprio 1
	s_add_i32 s55, 0, 0x18000
	s_add_i32 s56, 0, 0x1c000
	v_add_u32_e32 v164, s55, v150
	v_add_u32_e32 v180, s56, v150
	ds_read_b128 v[152:155], v164
	ds_read_b128 v[156:159], v164 offset:1024
	ds_read_b128 v[160:163], v164 offset:2048
	ds_read_b128 v[164:167], v164 offset:3072
	ds_read_b128 v[168:171], v180
	ds_read_b128 v[172:175], v180 offset:1024
	ds_read_b128 v[176:179], v180 offset:2048
	ds_read_b128 v[180:183], v180 offset:3072
	s_add_u32 s28, s28, 0x100000
	s_addc_u32 s29, s29, 0
	s_mov_b32 m0, s37
	v_lshl_add_u64 v[228:229], s[28:29], 0, v[130:131]
	ds_read_b128 v[184:187], v151 offset:32768
	ds_read_b128 v[188:191], v151 offset:33792
	ds_read_b128 v[192:195], v151 offset:34816
	ds_read_b128 v[196:199], v151 offset:35840
	ds_read_b128 v[200:203], v151 offset:36864
	ds_read_b128 v[204:207], v151 offset:37888
	ds_read_b128 v[208:211], v151 offset:38912
	ds_read_b128 v[218:221], v151 offset:39936
	global_load_lds_dwordx4 v[228:229], off
	v_lshl_add_u64 v[228:229], s[28:29], 0, v[134:135]
	s_mov_b32 m0, s39
	s_nop 0
	global_load_lds_dwordx4 v[228:229], off
	s_waitcnt vmcnt(8)
	s_waitcnt lgkmcnt(0)
	s_barrier
	s_setprio 0
	v_mfma_f32_16x16x32_bf16 v[126:129], v[152:155], v[184:187], v[126:129]
	v_mfma_f32_16x16x32_bf16 v[122:125], v[160:163], v[184:187], v[122:125]
	v_mfma_f32_16x16x32_bf16 v[110:113], v[152:155], v[192:195], v[110:113]
	v_mfma_f32_16x16x32_bf16 v[106:109], v[160:163], v[192:195], v[106:109]
	v_mfma_f32_16x16x32_bf16 v[94:97], v[152:155], v[200:203], v[94:97]
	v_mfma_f32_16x16x32_bf16 v[90:93], v[160:163], v[200:203], v[90:93]
	v_mfma_f32_16x16x32_bf16 v[78:81], v[152:155], v[208:211], v[78:81]
	v_mfma_f32_16x16x32_bf16 v[74:77], v[160:163], v[208:211], v[74:77]
	v_mfma_f32_16x16x32_bf16 v[126:129], v[156:159], v[188:191], v[126:129]
	v_mfma_f32_16x16x32_bf16 v[122:125], v[164:167], v[188:191], v[122:125]
	v_mfma_f32_16x16x32_bf16 v[110:113], v[156:159], v[196:199], v[110:113]
	v_mfma_f32_16x16x32_bf16 v[106:109], v[164:167], v[196:199], v[106:109]
	v_mfma_f32_16x16x32_bf16 v[94:97], v[156:159], v[204:207], v[94:97]
	v_mfma_f32_16x16x32_bf16 v[90:93], v[164:167], v[204:207], v[90:93]
	v_mfma_f32_16x16x32_bf16 v[78:81], v[156:159], v[218:221], v[78:81]
	v_mfma_f32_16x16x32_bf16 v[74:77], v[164:167], v[218:221], v[74:77]
	v_mfma_f32_16x16x32_bf16 v[118:121], v[168:171], v[184:187], v[118:121]
	v_mfma_f32_16x16x32_bf16 v[114:117], v[176:179], v[184:187], v[114:117]
	v_mfma_f32_16x16x32_bf16 v[102:105], v[168:171], v[192:195], v[102:105]
	v_mfma_f32_16x16x32_bf16 v[98:101], v[176:179], v[192:195], v[98:101]
	v_mfma_f32_16x16x32_bf16 v[86:89], v[168:171], v[200:203], v[86:89]
	v_mfma_f32_16x16x32_bf16 v[82:85], v[176:179], v[200:203], v[82:85]
	v_mfma_f32_16x16x32_bf16 v[70:73], v[168:171], v[208:211], v[70:73]
	v_mfma_f32_16x16x32_bf16 v[66:69], v[176:179], v[208:211], v[66:69]
	v_mfma_f32_16x16x32_bf16 v[118:121], v[172:175], v[188:191], v[118:121]
	v_mfma_f32_16x16x32_bf16 v[114:117], v[180:183], v[188:191], v[114:117]
	v_mfma_f32_16x16x32_bf16 v[102:105], v[172:175], v[196:199], v[102:105]
	v_mfma_f32_16x16x32_bf16 v[98:101], v[180:183], v[196:199], v[98:101]
	v_mfma_f32_16x16x32_bf16 v[86:89], v[172:175], v[204:207], v[86:89]
	v_mfma_f32_16x16x32_bf16 v[82:85], v[180:183], v[204:207], v[82:85]
	v_mfma_f32_16x16x32_bf16 v[70:73], v[172:175], v[218:221], v[70:73]
	v_mfma_f32_16x16x32_bf16 v[66:69], v[180:183], v[218:221], v[66:69]
	s_barrier
; #define PG8_STAGE(bufoff, gbase, voff) do { _Pragma("unroll") for (int _i = 0; _i < 2; ++_i) \
;         __builtin_amdgcn_global_load_lds((const unsigned*)((const char*)(gbase) + (voff)[_i]), (PG8_LAS unsigned*)(lds + (bufoff) + ldsw + _i * 8192), 16, 0, 0); } while (0)
; #define PG8_LDA(dst, b, h) do { _Pragma("unroll") for (int m = 0; m < 4; ++m) _Pragma("unroll") for (int k = 0; k < 2; ++k) dst[m][k] = *(const PG8_LAS bf16x8*)(lds + PG8_SA(b, h) + aoff + m * 2048 + k * 1024); } while (0)
; #define PG8_MMA(ai, bj, At, Bt) do { __builtin_amdgcn_s_setprio(1); _Pragma("unroll") for (int m = 0; m < 4; ++m) _Pragma("unroll") for (int n = 0; n < 2; ++n) _Pragma("unroll") for (int k = 0; k < 2; ++k) \
;         acc[ai][bj][m][n] = __builtin_amdgcn_mfma_f32_16x16x32_bf16(Bt[n][k], At[m][k], acc[ai][bj][m][n], 0, 0, 0); __builtin_amdgcn_s_setprio(0); } while (0)
; #define PG8_WAIT_V(n) asm volatile("s_waitcnt vmcnt(" #n ")" ::: "memory")
; #define PG8_WAIT_L(n) asm volatile("s_waitcnt lgkmcnt(" #n ")" ::: "memory")
; #define PG8_BAR __builtin_amdgcn_s_barrier()
; #define PG8_SCHED __builtin_amdgcn_sched_barrier(0)
; template <class Epi, class Sched, bool ALIGN_EPI = false, bool SP2 = false>
; __device__ __forceinline__ void gemm_phase(PG8_LAS unsigned char* lds, const Gemm g, const Sched& S, const Epi& E) {
;     ...
;             PG8_LDA(At, 1, 1); PG8_STAGE(PG8_SB(1, 0), b3, voffB); PG8_STAGE(PG8_SB(1, 1), b3 + hstepB, voffB); PG8_STAGE(PG8_SA(1, 0), a3, voffA);
;             PG8_WAIT_V(8); PG8_WAIT_L(0); PG8_BAR; PG8_MMA(1, 0, At, B0); PG8_MMA(1, 1, At, B1); PG8_BAR; PG8_SCHED;
;     ...
; #pragma unroll
;         for (int a = 0; a < 2; ++a)
; #pragma unroll
;             for (int b = 0; b < 2; ++b)
; #pragma unroll
;                 for (int m = 0; m < 4; ++m)
; #pragma unroll
;                     for (int n = 0; n < 2; ++n) acc[a][b][m][n] = (f32x4){0.f, 0.f, 0.f, 0.f};
	s_setprio 1
	s_add_i32 s28, s55, s34
	v_lshl_add_u64 v[212:213], v[212:213], 0, s[10:11]
	s_mov_b32 m0, s28
	ds_read_b128 v[184:187], v151 offset:49152
	ds_read_b128 v[188:191], v151 offset:50176
	ds_read_b128 v[192:195], v151 offset:51200
	ds_read_b128 v[196:199], v151 offset:52224
	ds_read_b128 v[200:203], v151 offset:53248
	ds_read_b128 v[204:207], v151 offset:54272
	ds_read_b128 v[208:211], v151 offset:55296
	ds_read_b128 v[218:221], v151 offset:56320
	global_load_lds_dwordx4 v[212:213], off
	s_add_i32 m0, s28, 0x2000
	s_add_u32 s26, s26, 0x40080
	v_lshl_add_u64 v[212:213], v[222:223], 0, s[10:11]
	s_addc_u32 s27, s27, 0
	s_add_i32 s28, s56, s34
	global_load_lds_dwordx4 v[212:213], off
	v_lshl_add_u64 v[212:213], s[26:27], 0, v[132:133]
	s_mov_b32 m0, s28
	s_nop 0
	global_load_lds_dwordx4 v[212:213], off
	v_lshl_add_u64 v[212:213], s[26:27], 0, v[136:137]
	s_add_i32 m0, s28, 0x2000
	s_nop 0
	global_load_lds_dwordx4 v[212:213], off
	v_lshl_add_u64 v[212:213], v[224:225], 0, s[10:11]
	s_mov_b32 m0, s40
	s_nop 0
	global_load_lds_dwordx4 v[212:213], off
	v_lshl_add_u64 v[212:213], v[226:227], 0, s[10:11]
	s_mov_b32 m0, s41
	s_nop 0
	global_load_lds_dwordx4 v[212:213], off
	s_waitcnt vmcnt(8)
	s_waitcnt lgkmcnt(0)
	s_barrier
	s_setprio 0
	v_mfma_f32_16x16x32_bf16 v[62:65], v[152:155], v[184:187], v[62:65]
	v_mfma_f32_16x16x32_bf16 v[58:61], v[160:163], v[184:187], v[58:61]
	v_mfma_f32_16x16x32_bf16 v[46:49], v[152:155], v[192:195], v[46:49]
	v_mfma_f32_16x16x32_bf16 v[42:45], v[160:163], v[192:195], v[42:45]
	v_mfma_f32_16x16x32_bf16 v[30:33], v[152:155], v[200:203], v[30:33]
	v_mfma_f32_16x16x32_bf16 v[26:29], v[160:163], v[200:203], v[26:29]
	v_mfma_f32_16x16x32_bf16 v[14:17], v[152:155], v[208:211], v[14:17]
	v_mfma_f32_16x16x32_bf16 v[10:13], v[160:163], v[208:211], v[10:13]
	v_mfma_f32_16x16x32_bf16 v[62:65], v[156:159], v[188:191], v[62:65]
	v_mfma_f32_16x16x32_bf16 v[58:61], v[164:167], v[188:191], v[58:61]
	v_mfma_f32_16x16x32_bf16 v[46:49], v[156:159], v[196:199], v[46:49]
	v_mfma_f32_16x16x32_bf16 v[42:45], v[164:167], v[196:199], v[42:45]
	v_mfma_f32_16x16x32_bf16 v[30:33], v[156:159], v[204:207], v[30:33]
	v_mfma_f32_16x16x32_bf16 v[26:29], v[164:167], v[204:207], v[26:29]
	v_mfma_f32_16x16x32_bf16 v[14:17], v[156:159], v[218:221], v[14:17]
	v_mfma_f32_16x16x32_bf16 v[10:13], v[164:167], v[218:221], v[10:13]
	v_mfma_f32_16x16x32_bf16 v[54:57], v[168:171], v[184:187], v[54:57]
	v_mfma_f32_16x16x32_bf16 v[50:53], v[176:179], v[184:187], v[50:53]
	v_mfma_f32_16x16x32_bf16 v[38:41], v[168:171], v[192:195], v[38:41]
	v_mfma_f32_16x16x32_bf16 v[34:37], v[176:179], v[192:195], v[34:37]
	v_mfma_f32_16x16x32_bf16 v[22:25], v[168:171], v[200:203], v[22:25]
	v_mfma_f32_16x16x32_bf16 v[18:21], v[176:179], v[200:203], v[18:21]
	v_mfma_f32_16x16x32_bf16 v[6:9], v[168:171], v[208:211], v[6:9]
	v_mfma_f32_16x16x32_bf16 v[2:5], v[176:179], v[208:211], v[2:5]
	v_mfma_f32_16x16x32_bf16 v[54:57], v[172:175], v[188:191], v[54:57]
	v_mfma_f32_16x16x32_bf16 v[50:53], v[180:183], v[188:191], v[50:53]
	v_mfma_f32_16x16x32_bf16 v[38:41], v[172:175], v[196:199], v[38:41]
	v_mfma_f32_16x16x32_bf16 v[34:37], v[180:183], v[196:199], v[34:37]
	v_mfma_f32_16x16x32_bf16 v[22:25], v[172:175], v[204:207], v[22:25]
	v_mfma_f32_16x16x32_bf16 v[18:21], v[180:183], v[204:207], v[18:21]
	v_mfma_f32_16x16x32_bf16 v[6:9], v[172:175], v[218:221], v[6:9]
	v_mfma_f32_16x16x32_bf16 v[2:5], v[180:183], v[218:221], v[2:5]
	s_barrier
	s_setprio 1
	s_add_i32 s54, s54, 2
	s_add_u32 s24, s24, 0x100
	s_addc_u32 s25, s25, 0
	s_cmp_gt_u32 s54, 61
	s_cbranch_scc0 .LBB0_1429
	s_add_u32 s24, s21, 0xffffff00
	s_addc_u32 s25, s45, -1
	s_andn2_b64 vcc, exec, s[2:3]
	s_cbranch_vccnz .LBB0_1420
	v_mov_b32_e32 v2, 0
	s_mov_b32 s6, s14
	s_mov_b32 s4, s16
	s_mov_b64 s[8:9], s[22:23]
	s_mov_b32 s42, s20
	v_mov_b32_e32 v3, v2
	v_mov_b32_e32 v4, v2
	v_mov_b32_e32 v5, v2
	v_mov_b32_e32 v6, v2
	v_mov_b32_e32 v7, v2
	v_mov_b32_e32 v8, v2
	v_mov_b32_e32 v9, v2
	v_mov_b32_e32 v18, v2
	v_mov_b32_e32 v19, v2
	v_mov_b32_e32 v20, v2
	v_mov_b32_e32 v21, v2
	v_mov_b32_e32 v22, v2
	v_mov_b32_e32 v23, v2
	v_mov_b32_e32 v24, v2
	v_mov_b32_e32 v25, v2
	v_mov_b32_e32 v34, v2
	v_mov_b32_e32 v35, v2
	v_mov_b32_e32 v36, v2
	v_mov_b32_e32 v37, v2
	v_mov_b32_e32 v38, v2
	v_mov_b32_e32 v39, v2
	v_mov_b32_e32 v40, v2
	v_mov_b32_e32 v41, v2
	v_mov_b32_e32 v50, v2
	v_mov_b32_e32 v51, v2
	v_mov_b32_e32 v52, v2
	v_mov_b32_e32 v53, v2
	v_mov_b32_e32 v54, v2
	v_mov_b32_e32 v55, v2
	v_mov_b32_e32 v56, v2
	v_mov_b32_e32 v57, v2
	v_mov_b32_e32 v10, v2
	v_mov_b32_e32 v11, v2
	v_mov_b32_e32 v12, v2
	v_mov_b32_e32 v13, v2
	v_mov_b32_e32 v14, v2
	v_mov_b32_e32 v15, v2
	v_mov_b32_e32 v16, v2
	v_mov_b32_e32 v17, v2
	v_mov_b32_e32 v26, v2
	v_mov_b32_e32 v27, v2
	v_mov_b32_e32 v28, v2
	v_mov_b32_e32 v29, v2
	v_mov_b32_e32 v30, v2
	v_mov_b32_e32 v31, v2
	v_mov_b32_e32 v32, v2
	v_mov_b32_e32 v33, v2
	v_mov_b32_e32 v42, v2
	v_mov_b32_e32 v43, v2
	v_mov_b32_e32 v44, v2
	v_mov_b32_e32 v45, v2
	v_mov_b32_e32 v46, v2
	v_mov_b32_e32 v47, v2
	v_mov_b32_e32 v48, v2
	v_mov_b32_e32 v49, v2
	v_mov_b32_e32 v58, v2
	v_mov_b32_e32 v59, v2
	v_mov_b32_e32 v60, v2
	v_mov_b32_e32 v61, v2
	v_mov_b32_e32 v62, v2
	v_mov_b32_e32 v63, v2
	v_mov_b32_e32 v64, v2
	v_mov_b32_e32 v65, v2
	v_mov_b32_e32 v66, v2
	v_mov_b32_e32 v67, v2
	v_mov_b32_e32 v68, v2
	v_mov_b32_e32 v69, v2
	v_mov_b32_e32 v70, v2
	v_mov_b32_e32 v71, v2
	v_mov_b32_e32 v72, v2
	v_mov_b32_e32 v73, v2
	v_mov_b32_e32 v82, v2
	v_mov_b32_e32 v83, v2
	v_mov_b32_e32 v84, v2
	v_mov_b32_e32 v85, v2
	v_mov_b32_e32 v86, v2
	v_mov_b32_e32 v87, v2
	v_mov_b32_e32 v88, v2
	v_mov_b32_e32 v89, v2
	v_mov_b32_e32 v98, v2
	v_mov_b32_e32 v99, v2
	v_mov_b32_e32 v100, v2
	v_mov_b32_e32 v101, v2
	v_mov_b32_e32 v102, v2
	v_mov_b32_e32 v103, v2
	v_mov_b32_e32 v104, v2
	v_mov_b32_e32 v105, v2
	v_mov_b32_e32 v114, v2
	v_mov_b32_e32 v115, v2
	v_mov_b32_e32 v116, v2
	v_mov_b32_e32 v117, v2
	v_mov_b32_e32 v118, v2
	v_mov_b32_e32 v119, v2
	v_mov_b32_e32 v120, v2
	v_mov_b32_e32 v121, v2
	v_mov_b32_e32 v74, v2
	v_mov_b32_e32 v75, v2
	v_mov_b32_e32 v76, v2
	v_mov_b32_e32 v77, v2
	v_mov_b32_e32 v78, v2
	v_mov_b32_e32 v79, v2
	v_mov_b32_e32 v80, v2
	v_mov_b32_e32 v81, v2
	v_mov_b32_e32 v90, v2
	v_mov_b32_e32 v91, v2
	v_mov_b32_e32 v92, v2
	v_mov_b32_e32 v93, v2
	v_mov_b32_e32 v94, v2
	v_mov_b32_e32 v95, v2
	v_mov_b32_e32 v96, v2
	v_mov_b32_e32 v97, v2
	v_mov_b32_e32 v106, v2
	v_mov_b32_e32 v107, v2
	v_mov_b32_e32 v108, v2
	v_mov_b32_e32 v109, v2
	v_mov_b32_e32 v110, v2
	v_mov_b32_e32 v111, v2
	v_mov_b32_e32 v112, v2
	v_mov_b32_e32 v113, v2
	v_mov_b32_e32 v122, v2
	v_mov_b32_e32 v123, v2
	v_mov_b32_e32 v124, v2
	v_mov_b32_e32 v125, v2
	v_mov_b32_e32 v126, v2
	v_mov_b32_e32 v127, v2
	v_mov_b32_e32 v128, v2
	v_mov_b32_e32 v129, v2
	s_andn2_b64 vcc, exec, s[0:1]
	s_cbranch_vccnz .LBB0_1421
